# b0move
# speedup vs baseline: 1.0055x; 1.0055x over previous
; #define STAGE_A(P, br, kt) do { const char* _base = (const char*)(((kt) < G.ksplit ? G.A1 : A2m) + (long)(br) * G.lda + (long)(kt) * BK); \
;     __builtin_amdgcn_global_load_lds((const unsigned*)(_base + aoff0), (unsigned*)((char*)(P) + sb0), 16, 0, 0); \
;     __builtin_amdgcn_global_load_lds((const unsigned*)(_base + aoff1), (unsigned*)((char*)(P) + sb1), 16, 0, 0); } while (0)
; #define STAGE_B(P, br, kt) do { const char* _base = (const char*)(G.Bt + (long)(br) * G.ldb + (long)(kt) * BK); \
;     __builtin_amdgcn_global_load_lds((const unsigned*)(_base + boff0), (unsigned*)((char*)(P) + sb0), 16, 0, 0); \
;     __builtin_amdgcn_global_load_lds((const unsigned*)(_base + boff1), (unsigned*)((char*)(P) + sb1), 16, 0, 0); } while (0)
; #define LDA(dst, b, h) for (int m = 0; m < 4; ++m) for (int k = 0; k < 2; ++k) \
;     dst[m][k] = *reinterpret_cast<const bf16x8*>(a_rd + ((b) * 2 + (h)) * (HT * 2) + m * 2048 + k * 1024)
; #define LDB(dst, b, h) for (int n = 0; n < 2; ++n) for (int k = 0; k < 2; ++k) \
;     dst[n][k] = *reinterpret_cast<const bf16x8*>(b_rd + ((b) * 2 + (h)) * (HT * 2) + n * 2048 + k * 1024)
;     ...
;   const int K = G.K;
;   const u16* A2m = G.A2 - (long)G.ksplit * BK;
;   int t1 = otid();
;   const int wid = t1 >> 6, lane = t1 & 63, wr = wid >> 2, wc = wid & 3, fr = lane & 15, fq = lane >> 4;
;   const int sb0 = t1 * 16, sb1 = sb0 + 8192;
;   const int swz_ = lds_byte(fr, fq * 8);
;   const char* a_rd = shmc + wr * 8192 + swz_;
;   const char* b_rd = shmc + 4 * (HT * 2) + wc * 4096 + swz_;
;   int r0_, c0_, r1_, c1_; stage_rc(sb0, r0_, c0_); stage_rc(sb1, r1_, c1_);
;   const unsigned aoff0 = (unsigned)(r0_ * G.lda + c0_) * 2u, aoff1 = (unsigned)(r1_ * G.lda + c1_) * 2u;
;   const unsigned boff0 = (unsigned)(r0_ * G.ldb + c0_) * 2u, boff1 = (unsigned)(r1_ * G.ldb + c1_) * 2u;
;   f32x4 acc[2][2][4][2] = {};
;   bf16x8 At[4][2], B0[2][2], B1[2][2];
;   const int nt = K / BK;
;   if (EPI == EPI_RESID || first) {
;     STAGE_B(SB(0, 0), bcol, 0); STAGE_A(SA(0, 0), brow, 0);
;     STAGE_B(SB(0, 1), bcol + HALF, 0); STAGE_A(SA(0, 1), brow + HALF, 0);
;   }
;   if (wr == 1) BAR;
;   WAIT_V(0); BAR;
;   STAGE_B(SB(1, 0), bcol, 1); STAGE_A(SA(1, 0), brow, 1); STAGE_B(SB(1, 1), bcol + HALF, 1);
;   WAIT_V(6); BAR;
;   for (int t = 0; t < nt - 2; t += 2) {
;     LDB(B0, 0, 0); SCHED; LDA(At, 0, 0); STAGE_A(SA(1, 1), brow + HALF, t + 1);
.LBB0_745:
	s_or_b64 exec, exec, s[10:11]
	v_and_b32_e32 v150, 15, v144
	v_lshlrev_b32_e32 v10, 2, v144
	s_ashr_i32 s9, s8, 31
	v_and_b32_e32 v8, 48, v144
	v_lshlrev_b32_e32 v9, 6, v150
	v_and_b32_e32 v10, 32, v10
	s_add_i32 s10, 32, 0x10000
	s_lshl_b32 s36, s52, 8
	s_lshl_b64 s[44:45], s[8:9], 1
	v_bitop3_b32 v10, v9, v10, v8 bitop3:0x36
	v_lshlrev_b32_e32 v8, 6, v144
	s_add_u32 s46, s49, s44
	v_readlane_b32 s9, v253, 46
	v_and_b32_e32 v8, 0x3000, v8
	s_addc_u32 s47, s50, s45
	v_add_u32_e32 v152, s9, v146
	v_add_u32_e32 v12, s10, v8
	v_lshl_add_u64 v[8:9], s[46:47], 0, v[180:181]
	s_mov_b64 vcc, 0x80
	v_readfirstlane_b32 s9, v152
	v_lshl_add_u64 v[8:9], v[8:9], 0, vcc
	s_mov_b32 m0, s9
	v_mov_b32_e32 v129, v181
	v_add_u32_e32 v153, 0x2000, v152
	s_add_u32 s42, s12, s42
	s_waitcnt vmcnt(0)
	s_barrier
	global_load_lds_dwordx4 v[8:9], off
	v_lshl_add_u64 v[8:9], s[46:47], 0, v[128:129]
	v_readfirstlane_b32 s9, v153
	s_addc_u32 s43, s13, s37
	s_or_b32 s37, s36, 0x80
	v_lshl_add_u64 v[8:9], v[8:9], 0, vcc
	s_mov_b32 m0, s9
	v_add_u32_e32 v154, 0x8000, v149
	s_mul_i32 s46, s37, 0x840
	global_load_lds_dwordx4 v[8:9], off
	v_lshl_add_u64 v[8:9], s[42:43], 0, v[180:181]
	v_readfirstlane_b32 s9, v154
	v_add_u32_e32 v156, 0xa000, v149
	s_ashr_i32 s47, s46, 31
	v_lshl_add_u64 v[8:9], v[8:9], 0, vcc
	s_mov_b32 m0, s9
	v_readfirstlane_b32 s9, v156
	s_lshl_b64 s[46:47], s[46:47], 1
	global_load_lds_dwordx4 v[8:9], off
	v_lshl_add_u64 v[8:9], s[42:43], 0, v[128:129]
	s_mov_b32 m0, s9
	s_add_u32 s46, s49, s46
	v_readlane_b32 s9, v253, 47
	v_lshl_add_u64 v[8:9], v[8:9], 0, vcc
	s_addc_u32 s47, s50, s47
	v_add_u32_e32 v157, s9, v146
	global_load_lds_dwordx4 v[8:9], off
	v_lshl_add_u64 v[8:9], s[46:47], 0, v[180:181]
	v_readfirstlane_b32 s9, v157
	v_lshl_add_u64 v[8:9], v[8:9], 0, vcc
	s_mov_b32 m0, s9
	v_add_u32_e32 v158, 0x2000, v157
	global_load_lds_dwordx4 v[8:9], off
	v_lshl_add_u64 v[8:9], s[46:47], 0, v[128:129]
	v_readfirstlane_b32 s9, v158
	v_lshl_add_u64 v[8:9], v[8:9], 0, vcc
	s_mov_b32 m0, s9
	s_movk_i32 s9, 0x840
	global_load_lds_dwordx4 v[8:9], off
	v_lshrrev_b32_e32 v8, 1, v0
	v_mul_lo_u32 v0, v2, s9
	v_mad_u64_u32 v[8:9], s[46:47], v8, s84, v[0:1]
	s_add_u32 s44, s14, s44
	v_or_b32_e32 v0, v8, v3
	s_addc_u32 s45, s15, s45
	s_add_i32 s8, s8, 0x40000
	v_add_lshl_u32 v2, v0, v4, 1
	v_lshrrev_b32_e32 v1, 1, v1
	v_mul_lo_u32 v0, v5, s9
	s_ashr_i32 s9, s8, 31
	v_mad_u64_u32 v[0:1], s[46:47], v1, s84, v[0:1]
	s_lshl_b64 s[8:9], s[8:9], 1
	v_or_b32_e32 v0, v0, v6
	s_add_u32 s8, s14, s8
	s_waitcnt vmcnt(6)
	v_add_lshl_u32 v0, v0, v7, 1
	v_mov_b32_e32 v1, v181
	s_addc_u32 s9, s15, s9
	v_lshl_add_u32 v11, v148, 13, 32
	v_mov_b32_e32 v3, v181
	v_lshl_add_u64 v[132:133], s[44:45], 0, v[0:1]
	v_lshl_add_u64 v[136:137], s[42:43], 0, v[0:1]
	v_lshl_add_u64 v[140:141], s[8:9], 0, v[0:1]
	v_mov_b32_e32 v0, 0
	v_lshl_add_u64 v[130:131], s[44:45], 0, v[2:3]
	v_lshl_add_u64 v[134:135], s[42:43], 0, v[2:3]
	v_lshl_add_u64 v[138:139], s[8:9], 0, v[2:3]
	s_mov_b32 s11, -2
	s_mov_b64 s[8:9], 0
	v_add_u32_e32 v155, v12, v10
	v_add_u32_e32 v151, v11, v10
	v_mov_b32_e32 v1, v0
	v_mov_b32_e32 v2, v0
	v_mov_b32_e32 v3, v0
	v_mov_b32_e32 v4, v0
	v_mov_b32_e32 v5, v0
	v_mov_b32_e32 v6, v0
	v_mov_b32_e32 v7, v0
	v_mov_b32_e32 v8, v0
	v_mov_b32_e32 v9, v0
	v_mov_b32_e32 v10, v0
	v_mov_b32_e32 v11, v0
	v_mov_b32_e32 v12, v0
	v_mov_b32_e32 v13, v0
	v_mov_b32_e32 v14, v0
	v_mov_b32_e32 v15, v0
	v_mov_b32_e32 v16, v0
	v_mov_b32_e32 v17, v0
	v_mov_b32_e32 v18, v0
	v_mov_b32_e32 v19, v0
	v_mov_b32_e32 v20, v0
	v_mov_b32_e32 v21, v0
	v_mov_b32_e32 v22, v0
	v_mov_b32_e32 v23, v0
	v_mov_b32_e32 v24, v0
	v_mov_b32_e32 v25, v0
	v_mov_b32_e32 v26, v0
	v_mov_b32_e32 v27, v0
	s_waitcnt vmcnt(0)
	v_mov_b32_e32 v28, v0
	v_mov_b32_e32 v29, v0
	v_mov_b32_e32 v30, v0
	v_mov_b32_e32 v31, v0
	v_mov_b32_e32 v32, v0
	v_mov_b32_e32 v33, v0
	v_mov_b32_e32 v34, v0
	v_mov_b32_e32 v35, v0
	v_mov_b32_e32 v36, v0
	v_mov_b32_e32 v37, v0
	v_mov_b32_e32 v38, v0
	v_mov_b32_e32 v39, v0
	v_mov_b32_e32 v40, v0
	v_mov_b32_e32 v41, v0
	v_mov_b32_e32 v42, v0
	v_mov_b32_e32 v43, v0
	v_mov_b32_e32 v44, v0
	v_mov_b32_e32 v45, v0
	v_mov_b32_e32 v46, v0
	v_mov_b32_e32 v47, v0
	v_mov_b32_e32 v48, v0
	v_mov_b32_e32 v49, v0
	v_mov_b32_e32 v50, v0
	v_mov_b32_e32 v51, v0
	v_mov_b32_e32 v52, v0
	v_mov_b32_e32 v53, v0
	v_mov_b32_e32 v54, v0
	v_mov_b32_e32 v55, v0
	v_mov_b32_e32 v56, v0
	v_mov_b32_e32 v57, v0
	v_mov_b32_e32 v58, v0
	v_mov_b32_e32 v59, v0
	v_mov_b32_e32 v60, v0
	v_mov_b32_e32 v61, v0
	v_mov_b32_e32 v62, v0
	v_mov_b32_e32 v63, v0
	v_mov_b32_e32 v64, v0
	v_mov_b32_e32 v65, v0
	v_mov_b32_e32 v66, v0
	v_mov_b32_e32 v67, v0
	v_mov_b32_e32 v68, v0
	v_mov_b32_e32 v69, v0
	v_mov_b32_e32 v70, v0
	v_mov_b32_e32 v71, v0
	v_mov_b32_e32 v72, v0
	v_mov_b32_e32 v73, v0
	v_mov_b32_e32 v74, v0
	v_mov_b32_e32 v75, v0
	v_mov_b32_e32 v76, v0
	v_mov_b32_e32 v77, v0
	v_mov_b32_e32 v78, v0
	v_mov_b32_e32 v79, v0
	v_mov_b32_e32 v80, v0
	v_mov_b32_e32 v81, v0
	v_mov_b32_e32 v82, v0
	v_mov_b32_e32 v83, v0
	v_mov_b32_e32 v84, v0
	v_mov_b32_e32 v85, v0
	v_mov_b32_e32 v86, v0
	v_mov_b32_e32 v87, v0
	v_mov_b32_e32 v88, v0
	v_mov_b32_e32 v89, v0
	v_mov_b32_e32 v90, v0
	v_mov_b32_e32 v91, v0
	v_mov_b32_e32 v92, v0
	v_mov_b32_e32 v93, v0
	v_mov_b32_e32 v94, v0
	v_mov_b32_e32 v95, v0
	v_mov_b32_e32 v96, v0
	v_mov_b32_e32 v97, v0
	v_mov_b32_e32 v98, v0
	v_mov_b32_e32 v99, v0
	v_mov_b32_e32 v100, v0
	v_mov_b32_e32 v101, v0
	v_mov_b32_e32 v102, v0
	v_mov_b32_e32 v103, v0
	v_mov_b32_e32 v104, v0
	v_mov_b32_e32 v105, v0
	v_mov_b32_e32 v106, v0
	v_mov_b32_e32 v107, v0
	v_mov_b32_e32 v108, v0
	v_mov_b32_e32 v109, v0
	v_mov_b32_e32 v110, v0
	v_mov_b32_e32 v111, v0
	v_mov_b32_e32 v112, v0
	v_mov_b32_e32 v113, v0
	v_mov_b32_e32 v114, v0
	v_mov_b32_e32 v115, v0
	v_mov_b32_e32 v116, v0
	v_mov_b32_e32 v117, v0
	v_mov_b32_e32 v118, v0
	v_mov_b32_e32 v119, v0
	v_mov_b32_e32 v120, v0
	v_mov_b32_e32 v121, v0
	v_mov_b32_e32 v122, v0
	v_mov_b32_e32 v123, v0
	v_mov_b32_e32 v124, v0
	v_mov_b32_e32 v125, v0
	v_mov_b32_e32 v126, v0
	v_mov_b32_e32 v127, v0
	s_mov_b64 s[44:45], 0x84080
	s_mov_b64 s[46:47], 0x4360100
	s_mov_b64 vcc, 0x4364100
	s_mov_b64 s[64:65], 0x84100
	s_mov_b64 s[22:23], 0x4360180
	s_mov_b64 s[24:25], 0x4364180
	s_barrier
	ds_read_b128 v[164:167], v155
	ds_read_b128 v[168:171], v155 offset:1024
	ds_read_b128 v[172:175], v155 offset:2048
	ds_read_b128 v[176:179], v155 offset:3072
; #define STAGE_A(P, br, kt) do { const char* _base = (const char*)(((kt) < G.ksplit ? G.A1 : A2m) + (long)(br) * G.lda + (long)(kt) * BK); \
;     __builtin_amdgcn_global_load_lds((const unsigned*)(_base + aoff0), (unsigned*)((char*)(P) + sb0), 16, 0, 0); \
;     __builtin_amdgcn_global_load_lds((const unsigned*)(_base + aoff1), (unsigned*)((char*)(P) + sb1), 16, 0, 0); } while (0)
; #define STAGE_B(P, br, kt) do { const char* _base = (const char*)(G.Bt + (long)(br) * G.ldb + (long)(kt) * BK); \
;     __builtin_amdgcn_global_load_lds((const unsigned*)(_base + boff0), (unsigned*)((char*)(P) + sb0), 16, 0, 0); \
;     __builtin_amdgcn_global_load_lds((const unsigned*)(_base + boff1), (unsigned*)((char*)(P) + sb1), 16, 0, 0); } while (0)
; #define LDA(dst, b, h) for (int m = 0; m < 4; ++m) for (int k = 0; k < 2; ++k) \
;     dst[m][k] = *reinterpret_cast<const bf16x8*>(a_rd + ((b) * 2 + (h)) * (HT * 2) + m * 2048 + k * 1024)
; #define LDB(dst, b, h) for (int n = 0; n < 2; ++n) for (int k = 0; k < 2; ++k) \
;     dst[n][k] = *reinterpret_cast<const bf16x8*>(b_rd + ((b) * 2 + (h)) * (HT * 2) + n * 2048 + k * 1024)
; #define MMA(ai, bj, At_, Bt_) do { __builtin_amdgcn_s_setprio(1); \
;     for (int m = 0; m < 4; ++m) for (int n = 0; n < 2; ++n) for (int k = 0; k < 2; ++k) \
;       acc[ai][bj][m][n] = __builtin_amdgcn_mfma_f32_16x16x32_bf16(Bt_[n][k], At_[m][k], acc[ai][bj][m][n], 0, 0, 0); \
;     __builtin_amdgcn_s_setprio(0); } while (0)
; #define WAIT_L(n) asm volatile("s_waitcnt lgkmcnt(" #n ")" ::: "memory")
; #define BAR __builtin_amdgcn_s_barrier()
; #define SCHED __builtin_amdgcn_sched_barrier(0)
;     ...
;     LDB(B0, 0, 0); SCHED; LDA(At, 0, 0); STAGE_A(SA(1, 1), brow + HALF, t + 1);
;     WAIT_L(8); BAR; WAIT_L(0); MMA(0, 0, At, B0); BAR; SCHED;
;     LDB(B1, 0, 1); STAGE_B(SB(0, 0), bcol, t + 2);
;     BAR; WAIT_L(0); MMA(0, 1, At, B1); BAR;
;     LDA(At, 0, 1); STAGE_A(SA(0, 0), brow, t + 2);
;     BAR; WAIT_L(0); MMA(1, 0, At, B0); BAR; SCHED;
.LBB0_746:
	v_add_u32_e32 v162, 0xc000, v149
	v_lshl_add_u64 v[222:223], v[134:135], 0, s[8:9]
	v_readfirstlane_b32 s42, v162
	v_add_u32_e32 v163, 0xe000, v149
	v_lshl_add_u64 v[160:161], v[222:223], 0, s[44:45]
	s_mov_b32 m0, s42
	v_lshl_add_u64 v[234:235], v[136:137], 0, s[8:9]
	v_readfirstlane_b32 s42, v163
	ds_read_b128 v[182:185], v151
	ds_read_b128 v[186:189], v151 offset:1024
	ds_read_b128 v[190:193], v151 offset:2048
	ds_read_b128 v[194:197], v151 offset:3072
	ds_read_b128 v[198:201], v151 offset:4096
	ds_read_b128 v[202:205], v151 offset:5120
	ds_read_b128 v[206:209], v151 offset:6144
	ds_read_b128 v[210:213], v151 offset:7168
	global_load_lds_dwordx4 v[160:161], off
	v_lshl_add_u64 v[160:161], v[234:235], 0, s[44:45]
	s_mov_b32 m0, s42
	s_nop 0
	global_load_lds_dwordx4 v[160:161], off
	s_waitcnt lgkmcnt(8)
	s_barrier
	s_waitcnt lgkmcnt(0)
	s_setprio 1
	s_waitcnt lgkmcnt(0)
	v_mfma_f32_16x16x32_bf16 v[124:127], v[164:167], v[182:185], v[124:127]
	v_mfma_f32_16x16x32_bf16 v[120:123], v[172:175], v[182:185], v[120:123]
	v_mfma_f32_16x16x32_bf16 v[116:119], v[164:167], v[190:193], v[116:119]
	v_mfma_f32_16x16x32_bf16 v[112:115], v[172:175], v[190:193], v[112:115]
	v_mfma_f32_16x16x32_bf16 v[108:111], v[164:167], v[198:201], v[108:111]
	v_mfma_f32_16x16x32_bf16 v[104:107], v[172:175], v[198:201], v[104:107]
	v_mfma_f32_16x16x32_bf16 v[100:103], v[164:167], v[206:209], v[100:103]
	v_mfma_f32_16x16x32_bf16 v[96:99], v[172:175], v[206:209], v[96:99]
	v_mfma_f32_16x16x32_bf16 v[124:127], v[168:171], v[186:189], v[124:127]
	v_mfma_f32_16x16x32_bf16 v[120:123], v[176:179], v[186:189], v[120:123]
	v_mfma_f32_16x16x32_bf16 v[116:119], v[168:171], v[194:197], v[116:119]
	v_mfma_f32_16x16x32_bf16 v[112:115], v[176:179], v[194:197], v[112:115]
	v_mfma_f32_16x16x32_bf16 v[108:111], v[168:171], v[202:205], v[108:111]
	v_mfma_f32_16x16x32_bf16 v[104:107], v[176:179], v[202:205], v[104:107]
	s_setprio 2
	s_barrier
	v_mfma_f32_16x16x32_bf16 v[100:103], v[168:171], v[210:213], v[100:103]
	v_mfma_f32_16x16x32_bf16 v[96:99], v[176:179], v[210:213], v[96:99]
	s_setprio 0
	v_add_u32_e32 v159, s10, v146
	v_lshl_add_u64 v[236:237], v[130:131], 0, s[8:9]
	v_readfirstlane_b32 s42, v159
	v_lshl_add_u64 v[160:161], v[236:237], 0, s[46:47]
	s_mov_b32 m0, s42
	ds_read_b128 v[214:217], v155 offset:16384
	ds_read_b128 v[218:221], v155 offset:17408
	ds_read_b128 v[230:233], v155 offset:18432
	ds_read_b128 v[238:241], v155 offset:19456
	global_load_lds_dwordx4 v[160:161], off
	v_add_u32_e32 v160, 0x2000, v159
	v_lshl_add_u64 v[246:247], v[132:133], 0, s[8:9]
	v_readfirstlane_b32 s42, v160
	v_lshl_add_u64 v[248:249], v[246:247], 0, s[46:47]
	s_mov_b32 m0, s42
	s_nop 0
	global_load_lds_dwordx4 v[248:249], off
	s_barrier
	s_waitcnt lgkmcnt(0)
	s_setprio 1
	s_waitcnt lgkmcnt(0)
	v_mfma_f32_16x16x32_bf16 v[92:95], v[214:217], v[182:185], v[92:95]
	v_mfma_f32_16x16x32_bf16 v[88:91], v[230:233], v[182:185], v[88:91]
	v_mfma_f32_16x16x32_bf16 v[84:87], v[214:217], v[190:193], v[84:87]
	v_mfma_f32_16x16x32_bf16 v[80:83], v[230:233], v[190:193], v[80:83]
	v_mfma_f32_16x16x32_bf16 v[76:79], v[214:217], v[198:201], v[76:79]
	v_mfma_f32_16x16x32_bf16 v[72:75], v[230:233], v[198:201], v[72:75]
	v_mfma_f32_16x16x32_bf16 v[68:71], v[214:217], v[206:209], v[68:71]
	v_mfma_f32_16x16x32_bf16 v[64:67], v[230:233], v[206:209], v[64:67]
	v_mfma_f32_16x16x32_bf16 v[92:95], v[218:221], v[186:189], v[92:95]
	v_mfma_f32_16x16x32_bf16 v[88:91], v[238:241], v[186:189], v[88:91]
	v_mfma_f32_16x16x32_bf16 v[84:87], v[218:221], v[194:197], v[84:87]
	v_mfma_f32_16x16x32_bf16 v[80:83], v[238:241], v[194:197], v[80:83]
	v_mfma_f32_16x16x32_bf16 v[76:79], v[218:221], v[202:205], v[76:79]
	v_mfma_f32_16x16x32_bf16 v[72:75], v[238:241], v[202:205], v[72:75]
	s_setprio 2
	s_barrier
	v_mfma_f32_16x16x32_bf16 v[68:71], v[218:221], v[210:213], v[68:71]
	v_mfma_f32_16x16x32_bf16 v[64:67], v[238:241], v[210:213], v[64:67]
	s_setprio 0
	v_readfirstlane_b32 s42, v149
	v_lshl_add_u64 v[248:249], v[222:223], 0, s[90:91]
	s_mov_b32 m0, s42
	v_readfirstlane_b32 s42, v147
	ds_read_b128 v[182:185], v151 offset:16384
	ds_read_b128 v[186:189], v151 offset:17408
	ds_read_b128 v[190:193], v151 offset:18432
	ds_read_b128 v[194:197], v151 offset:19456
	ds_read_b128 v[198:201], v151 offset:20480
	ds_read_b128 v[202:205], v151 offset:21504
	ds_read_b128 v[206:209], v151 offset:22528
	ds_read_b128 v[210:213], v151 offset:23552
	global_load_lds_dwordx4 v[248:249], off
	v_lshl_add_u64 v[248:249], v[234:235], 0, s[90:91]
	s_mov_b32 m0, s42
	s_nop 0
	global_load_lds_dwordx4 v[248:249], off
	s_waitcnt vmcnt(10)
	s_barrier
	s_waitcnt lgkmcnt(0)
	s_setprio 1
	s_waitcnt lgkmcnt(0)
	v_mfma_f32_16x16x32_bf16 v[60:63], v[164:167], v[182:185], v[60:63]
	v_mfma_f32_16x16x32_bf16 v[56:59], v[172:175], v[182:185], v[56:59]
	v_mfma_f32_16x16x32_bf16 v[52:55], v[164:167], v[190:193], v[52:55]
	v_mfma_f32_16x16x32_bf16 v[48:51], v[172:175], v[190:193], v[48:51]
	v_mfma_f32_16x16x32_bf16 v[44:47], v[164:167], v[198:201], v[44:47]
	v_mfma_f32_16x16x32_bf16 v[40:43], v[172:175], v[198:201], v[40:43]
	v_mfma_f32_16x16x32_bf16 v[36:39], v[164:167], v[206:209], v[36:39]
	v_mfma_f32_16x16x32_bf16 v[32:35], v[172:175], v[206:209], v[32:35]
	v_mfma_f32_16x16x32_bf16 v[60:63], v[168:171], v[186:189], v[60:63]
	v_mfma_f32_16x16x32_bf16 v[56:59], v[176:179], v[186:189], v[56:59]
	v_mfma_f32_16x16x32_bf16 v[52:55], v[168:171], v[194:197], v[52:55]
	v_mfma_f32_16x16x32_bf16 v[48:51], v[176:179], v[194:197], v[48:51]
	v_mfma_f32_16x16x32_bf16 v[44:47], v[168:171], v[202:205], v[44:47]
	v_mfma_f32_16x16x32_bf16 v[40:43], v[176:179], v[202:205], v[40:43]
	s_setprio 2
	s_barrier
; #define STAGE_A(P, br, kt) do { const char* _base = (const char*)(((kt) < G.ksplit ? G.A1 : A2m) + (long)(br) * G.lda + (long)(kt) * BK); \
;     __builtin_amdgcn_global_load_lds((const unsigned*)(_base + aoff0), (unsigned*)((char*)(P) + sb0), 16, 0, 0); \
;     __builtin_amdgcn_global_load_lds((const unsigned*)(_base + aoff1), (unsigned*)((char*)(P) + sb1), 16, 0, 0); } while (0)
; #define STAGE_B(P, br, kt) do { const char* _base = (const char*)(G.Bt + (long)(br) * G.ldb + (long)(kt) * BK); \
;     __builtin_amdgcn_global_load_lds((const unsigned*)(_base + boff0), (unsigned*)((char*)(P) + sb0), 16, 0, 0); \
;     __builtin_amdgcn_global_load_lds((const unsigned*)(_base + boff1), (unsigned*)((char*)(P) + sb1), 16, 0, 0); } while (0)
; #define LDA(dst, b, h) for (int m = 0; m < 4; ++m) for (int k = 0; k < 2; ++k) \
;     dst[m][k] = *reinterpret_cast<const bf16x8*>(a_rd + ((b) * 2 + (h)) * (HT * 2) + m * 2048 + k * 1024)
; #define LDB(dst, b, h) for (int n = 0; n < 2; ++n) for (int k = 0; k < 2; ++k) \
;     dst[n][k] = *reinterpret_cast<const bf16x8*>(b_rd + ((b) * 2 + (h)) * (HT * 2) + n * 2048 + k * 1024)
; #define MMA(ai, bj, At_, Bt_) do { __builtin_amdgcn_s_setprio(1); \
;     for (int m = 0; m < 4; ++m) for (int n = 0; n < 2; ++n) for (int k = 0; k < 2; ++k) \
;       acc[ai][bj][m][n] = __builtin_amdgcn_mfma_f32_16x16x32_bf16(Bt_[n][k], At_[m][k], acc[ai][bj][m][n], 0, 0, 0); \
;     __builtin_amdgcn_s_setprio(0); } while (0)
; #define WAIT_V(n) asm volatile("s_waitcnt vmcnt(" #n ")" ::: "memory")
; #define WAIT_L(n) asm volatile("s_waitcnt lgkmcnt(" #n ")" ::: "memory")
; #define BAR __builtin_amdgcn_s_barrier()
; #define SCHED __builtin_amdgcn_sched_barrier(0)
;     ...
;     BAR; WAIT_L(0); MMA(1, 0, At, B0); BAR; SCHED;
;     STAGE_B(SB(0, 1), bcol + HALF, t + 2);
;     WAIT_V(6); BAR; MMA(1, 1, At, B1); BAR;
;     LDB(B0, 1, 0); SCHED; LDA(At, 1, 0); STAGE_A(SA(0, 1), brow + HALF, t + 2);
;     WAIT_L(8); BAR; WAIT_L(0); MMA(0, 0, At, B0); BAR; SCHED;
;     LDB(B1, 1, 1); STAGE_B(SB(1, 0), bcol, t + 3);
;     BAR; WAIT_L(0); MMA(0, 1, At, B1); BAR;
	v_mfma_f32_16x16x32_bf16 v[36:39], v[168:171], v[210:213], v[36:39]
	v_mfma_f32_16x16x32_bf16 v[32:35], v[176:179], v[210:213], v[32:35]
	s_setprio 0
	v_lshl_add_u64 v[248:249], v[138:139], 0, s[8:9]
	v_readfirstlane_b32 s42, v145
	v_add_u32_e32 v161, 0x2000, v145
	v_lshl_add_u64 v[164:165], v[248:249], 0, vcc
	s_mov_b32 m0, s42
	v_lshl_add_u64 v[226:227], v[140:141], 0, s[8:9]
	v_readfirstlane_b32 s42, v161
	global_load_lds_dwordx4 v[164:165], off
	v_lshl_add_u64 v[164:165], v[226:227], 0, vcc
	s_mov_b32 m0, s42
	s_nop 0
	global_load_lds_dwordx4 v[164:165], off
	ds_read_b128 v[164:167], v155 offset:32768
	ds_read_b128 v[168:171], v155 offset:33792
	ds_read_b128 v[172:175], v155 offset:34816
	ds_read_b128 v[176:179], v155 offset:35840
	s_waitcnt vmcnt(6)
	s_barrier
	s_setprio 1
	v_mfma_f32_16x16x32_bf16 v[28:31], v[214:217], v[182:185], v[28:31]
	v_mfma_f32_16x16x32_bf16 v[24:27], v[230:233], v[182:185], v[24:27]
	v_mfma_f32_16x16x32_bf16 v[20:23], v[214:217], v[190:193], v[20:23]
	v_mfma_f32_16x16x32_bf16 v[16:19], v[230:233], v[190:193], v[16:19]
	v_mfma_f32_16x16x32_bf16 v[12:15], v[214:217], v[198:201], v[12:15]
	v_mfma_f32_16x16x32_bf16 v[8:11], v[230:233], v[198:201], v[8:11]
	v_mfma_f32_16x16x32_bf16 v[4:7], v[214:217], v[206:209], v[4:7]
	v_mfma_f32_16x16x32_bf16 v[0:3], v[230:233], v[206:209], v[0:3]
	v_mfma_f32_16x16x32_bf16 v[28:31], v[218:221], v[186:189], v[28:31]
	v_mfma_f32_16x16x32_bf16 v[24:27], v[238:241], v[186:189], v[24:27]
	v_mfma_f32_16x16x32_bf16 v[20:23], v[218:221], v[194:197], v[20:23]
	v_mfma_f32_16x16x32_bf16 v[16:19], v[238:241], v[194:197], v[16:19]
	v_mfma_f32_16x16x32_bf16 v[12:15], v[218:221], v[202:205], v[12:15]
	v_mfma_f32_16x16x32_bf16 v[8:11], v[238:241], v[202:205], v[8:11]
	s_setprio 2
	s_barrier
	v_mfma_f32_16x16x32_bf16 v[4:7], v[218:221], v[210:213], v[4:7]
	v_mfma_f32_16x16x32_bf16 v[0:3], v[238:241], v[210:213], v[0:3]
	s_setprio 0
	v_readfirstlane_b32 s42, v143
	v_lshl_add_u64 v[214:215], v[222:223], 0, s[64:65]
	s_mov_b32 m0, s42
	v_readfirstlane_b32 s42, v142
	ds_read_b128 v[182:185], v151 offset:32768
	ds_read_b128 v[186:189], v151 offset:33792
	ds_read_b128 v[190:193], v151 offset:34816
	ds_read_b128 v[194:197], v151 offset:35840
	ds_read_b128 v[198:201], v151 offset:36864
	ds_read_b128 v[202:205], v151 offset:37888
	ds_read_b128 v[206:209], v151 offset:38912
	ds_read_b128 v[210:213], v151 offset:39936
	global_load_lds_dwordx4 v[214:215], off
	v_lshl_add_u64 v[214:215], v[234:235], 0, s[64:65]
	s_mov_b32 m0, s42
	s_nop 0
	global_load_lds_dwordx4 v[214:215], off
	s_waitcnt lgkmcnt(8)
	s_barrier
	s_waitcnt lgkmcnt(0)
	s_setprio 1
	s_waitcnt lgkmcnt(0)
	v_mfma_f32_16x16x32_bf16 v[124:127], v[164:167], v[182:185], v[124:127]
	v_mfma_f32_16x16x32_bf16 v[120:123], v[172:175], v[182:185], v[120:123]
	v_mfma_f32_16x16x32_bf16 v[116:119], v[164:167], v[190:193], v[116:119]
	v_mfma_f32_16x16x32_bf16 v[112:115], v[172:175], v[190:193], v[112:115]
	v_mfma_f32_16x16x32_bf16 v[108:111], v[164:167], v[198:201], v[108:111]
	v_mfma_f32_16x16x32_bf16 v[104:107], v[172:175], v[198:201], v[104:107]
	v_mfma_f32_16x16x32_bf16 v[100:103], v[164:167], v[206:209], v[100:103]
	v_mfma_f32_16x16x32_bf16 v[96:99], v[172:175], v[206:209], v[96:99]
	v_mfma_f32_16x16x32_bf16 v[124:127], v[168:171], v[186:189], v[124:127]
	v_mfma_f32_16x16x32_bf16 v[120:123], v[176:179], v[186:189], v[120:123]
	v_mfma_f32_16x16x32_bf16 v[116:119], v[168:171], v[194:197], v[116:119]
	v_mfma_f32_16x16x32_bf16 v[112:115], v[176:179], v[194:197], v[112:115]
	v_mfma_f32_16x16x32_bf16 v[108:111], v[168:171], v[202:205], v[108:111]
	v_mfma_f32_16x16x32_bf16 v[104:107], v[176:179], v[202:205], v[104:107]
	s_setprio 2
	s_barrier
	v_mfma_f32_16x16x32_bf16 v[100:103], v[168:171], v[210:213], v[100:103]
	v_mfma_f32_16x16x32_bf16 v[96:99], v[176:179], v[210:213], v[96:99]
	s_setprio 0
	v_readfirstlane_b32 s42, v152
	v_lshl_add_u64 v[236:237], v[236:237], 0, s[22:23]
	s_mov_b32 m0, s42
	v_readfirstlane_b32 s42, v153
	ds_read_b128 v[214:217], v155 offset:49152
	ds_read_b128 v[218:221], v155 offset:50176
	ds_read_b128 v[230:233], v155 offset:51200
	ds_read_b128 v[238:241], v155 offset:52224
	global_load_lds_dwordx4 v[236:237], off
	v_lshl_add_u64 v[236:237], v[246:247], 0, s[22:23]
	s_mov_b32 m0, s42
	s_nop 0
	global_load_lds_dwordx4 v[236:237], off
	s_barrier
	s_waitcnt lgkmcnt(0)
	s_setprio 1
	s_waitcnt lgkmcnt(0)
	v_mfma_f32_16x16x32_bf16 v[92:95], v[214:217], v[182:185], v[92:95]
	v_mfma_f32_16x16x32_bf16 v[88:91], v[230:233], v[182:185], v[88:91]
	v_mfma_f32_16x16x32_bf16 v[84:87], v[214:217], v[190:193], v[84:87]
	v_mfma_f32_16x16x32_bf16 v[80:83], v[230:233], v[190:193], v[80:83]
	v_mfma_f32_16x16x32_bf16 v[76:79], v[214:217], v[198:201], v[76:79]
	v_mfma_f32_16x16x32_bf16 v[72:75], v[230:233], v[198:201], v[72:75]
	v_mfma_f32_16x16x32_bf16 v[68:71], v[214:217], v[206:209], v[68:71]
	v_mfma_f32_16x16x32_bf16 v[64:67], v[230:233], v[206:209], v[64:67]
	v_mfma_f32_16x16x32_bf16 v[92:95], v[218:221], v[186:189], v[92:95]
	v_mfma_f32_16x16x32_bf16 v[88:91], v[238:241], v[186:189], v[88:91]
	v_mfma_f32_16x16x32_bf16 v[84:87], v[218:221], v[194:197], v[84:87]
	v_mfma_f32_16x16x32_bf16 v[80:83], v[238:241], v[194:197], v[80:83]
	v_mfma_f32_16x16x32_bf16 v[76:79], v[218:221], v[202:205], v[76:79]
	v_mfma_f32_16x16x32_bf16 v[72:75], v[238:241], v[202:205], v[72:75]
	s_setprio 2
	s_barrier
; #define STAGE_A(P, br, kt) do { const char* _base = (const char*)(((kt) < G.ksplit ? G.A1 : A2m) + (long)(br) * G.lda + (long)(kt) * BK); \
;     __builtin_amdgcn_global_load_lds((const unsigned*)(_base + aoff0), (unsigned*)((char*)(P) + sb0), 16, 0, 0); \
;     __builtin_amdgcn_global_load_lds((const unsigned*)(_base + aoff1), (unsigned*)((char*)(P) + sb1), 16, 0, 0); } while (0)
; #define STAGE_B(P, br, kt) do { const char* _base = (const char*)(G.Bt + (long)(br) * G.ldb + (long)(kt) * BK); \
;     __builtin_amdgcn_global_load_lds((const unsigned*)(_base + boff0), (unsigned*)((char*)(P) + sb0), 16, 0, 0); \
;     __builtin_amdgcn_global_load_lds((const unsigned*)(_base + boff1), (unsigned*)((char*)(P) + sb1), 16, 0, 0); } while (0)
; #define LDA(dst, b, h) for (int m = 0; m < 4; ++m) for (int k = 0; k < 2; ++k) \
;     dst[m][k] = *reinterpret_cast<const bf16x8*>(a_rd + ((b) * 2 + (h)) * (HT * 2) + m * 2048 + k * 1024)
; #define LDB(dst, b, h) for (int n = 0; n < 2; ++n) for (int k = 0; k < 2; ++k) \
;     dst[n][k] = *reinterpret_cast<const bf16x8*>(b_rd + ((b) * 2 + (h)) * (HT * 2) + n * 2048 + k * 1024)
; #define MMA(ai, bj, At_, Bt_) do { __builtin_amdgcn_s_setprio(1); \
;     for (int m = 0; m < 4; ++m) for (int n = 0; n < 2; ++n) for (int k = 0; k < 2; ++k) \
;       acc[ai][bj][m][n] = __builtin_amdgcn_mfma_f32_16x16x32_bf16(Bt_[n][k], At_[m][k], acc[ai][bj][m][n], 0, 0, 0); \
;     __builtin_amdgcn_s_setprio(0); } while (0)
; #define WAIT_V(n) asm volatile("s_waitcnt vmcnt(" #n ")" ::: "memory")
; #define WAIT_L(n) asm volatile("s_waitcnt lgkmcnt(" #n ")" ::: "memory")
; #define BAR __builtin_amdgcn_s_barrier()
; #define SCHED __builtin_amdgcn_sched_barrier(0)
;     ...
;     LDB(B1, 1, 1); STAGE_B(SB(1, 0), bcol, t + 3);
;     BAR; WAIT_L(0); MMA(0, 1, At, B1); BAR;
;     LDA(At, 1, 1); STAGE_A(SA(1, 0), brow, t + 3);
;     BAR; WAIT_L(0); MMA(1, 0, At, B0); BAR; SCHED;
;     STAGE_B(SB(1, 1), bcol + HALF, t + 3);
;     WAIT_V(6); BAR; MMA(1, 1, At, B1); BAR;
;   }
;   float ssv[2][4] = {};
;   if constexpr (EPI == EPI_GU || EPI == EPI_EVIN || EPI == EPI_ODIN) {
; #pragma unroll
;     for (int ai = 0; ai < 2; ++ai)
; #pragma unroll
;       for (int m = 0; m < 4; ++m) ssv[ai][m] = G.ssr[brow + ai * HALF + wr * 64 + m * 16 + fr];
;   }
;   { LDB(B0, 0, 0); LDA(At, 0, 0); STAGE_A(SA(1, 1), brow + HALF, nt - 1);
	v_mfma_f32_16x16x32_bf16 v[68:71], v[218:221], v[210:213], v[68:71]
	v_mfma_f32_16x16x32_bf16 v[64:67], v[238:241], v[210:213], v[64:67]
	s_setprio 0
	v_readfirstlane_b32 s42, v154
	v_lshl_add_u64 v[222:223], v[222:223], 0, s[88:89]
	s_mov_b32 m0, s42
	v_readfirstlane_b32 s42, v156
	ds_read_b128 v[182:185], v151 offset:49152
	ds_read_b128 v[186:189], v151 offset:50176
	ds_read_b128 v[190:193], v151 offset:51200
	ds_read_b128 v[194:197], v151 offset:52224
	ds_read_b128 v[198:201], v151 offset:53248
	ds_read_b128 v[202:205], v151 offset:54272
	ds_read_b128 v[206:209], v151 offset:55296
	ds_read_b128 v[210:213], v151 offset:56320
	global_load_lds_dwordx4 v[222:223], off
	v_lshl_add_u64 v[222:223], v[234:235], 0, s[88:89]
	s_mov_b32 m0, s42
	s_nop 0
	global_load_lds_dwordx4 v[222:223], off
	s_waitcnt vmcnt(10)
	s_barrier
	s_waitcnt lgkmcnt(0)
	s_setprio 1
	s_waitcnt lgkmcnt(0)
	v_mfma_f32_16x16x32_bf16 v[60:63], v[164:167], v[182:185], v[60:63]
	v_mfma_f32_16x16x32_bf16 v[56:59], v[172:175], v[182:185], v[56:59]
	v_mfma_f32_16x16x32_bf16 v[52:55], v[164:167], v[190:193], v[52:55]
	v_mfma_f32_16x16x32_bf16 v[48:51], v[172:175], v[190:193], v[48:51]
	v_mfma_f32_16x16x32_bf16 v[44:47], v[164:167], v[198:201], v[44:47]
	v_mfma_f32_16x16x32_bf16 v[40:43], v[172:175], v[198:201], v[40:43]
	v_mfma_f32_16x16x32_bf16 v[36:39], v[164:167], v[206:209], v[36:39]
	v_mfma_f32_16x16x32_bf16 v[32:35], v[172:175], v[206:209], v[32:35]
	v_mfma_f32_16x16x32_bf16 v[60:63], v[168:171], v[186:189], v[60:63]
	v_mfma_f32_16x16x32_bf16 v[56:59], v[176:179], v[186:189], v[56:59]
	v_mfma_f32_16x16x32_bf16 v[52:55], v[168:171], v[194:197], v[52:55]
	v_mfma_f32_16x16x32_bf16 v[48:51], v[176:179], v[194:197], v[48:51]
	v_mfma_f32_16x16x32_bf16 v[44:47], v[168:171], v[202:205], v[44:47]
	v_mfma_f32_16x16x32_bf16 v[40:43], v[176:179], v[202:205], v[40:43]
	s_setprio 2
	s_barrier
	v_mfma_f32_16x16x32_bf16 v[36:39], v[168:171], v[210:213], v[36:39]
	v_mfma_f32_16x16x32_bf16 v[32:35], v[176:179], v[210:213], v[32:35]
	s_setprio 0
	v_readfirstlane_b32 s42, v157
	v_lshl_add_u64 v[164:165], v[248:249], 0, s[24:25]
	s_mov_b32 m0, s42
	v_readfirstlane_b32 s42, v158
	global_load_lds_dwordx4 v[164:165], off
	v_lshl_add_u64 v[164:165], v[226:227], 0, s[24:25]
	s_mov_b32 m0, s42
	s_nop 0
	global_load_lds_dwordx4 v[164:165], off
	ds_read_b128 v[164:167], v155
	ds_read_b128 v[168:171], v155 offset:1024
	ds_read_b128 v[172:175], v155 offset:2048
	ds_read_b128 v[176:179], v155 offset:3072
	s_waitcnt vmcnt(6)
	s_barrier
	s_setprio 1
	v_mfma_f32_16x16x32_bf16 v[28:31], v[214:217], v[182:185], v[28:31]
	v_mfma_f32_16x16x32_bf16 v[24:27], v[230:233], v[182:185], v[24:27]
	v_mfma_f32_16x16x32_bf16 v[20:23], v[214:217], v[190:193], v[20:23]
	v_mfma_f32_16x16x32_bf16 v[16:19], v[230:233], v[190:193], v[16:19]
	v_mfma_f32_16x16x32_bf16 v[12:15], v[214:217], v[198:201], v[12:15]
	v_mfma_f32_16x16x32_bf16 v[8:11], v[230:233], v[198:201], v[8:11]
	v_mfma_f32_16x16x32_bf16 v[4:7], v[214:217], v[206:209], v[4:7]
	v_mfma_f32_16x16x32_bf16 v[0:3], v[230:233], v[206:209], v[0:3]
	v_mfma_f32_16x16x32_bf16 v[28:31], v[218:221], v[186:189], v[28:31]
	v_mfma_f32_16x16x32_bf16 v[24:27], v[238:241], v[186:189], v[24:27]
	v_mfma_f32_16x16x32_bf16 v[20:23], v[218:221], v[194:197], v[20:23]
	v_mfma_f32_16x16x32_bf16 v[16:19], v[238:241], v[194:197], v[16:19]
	v_mfma_f32_16x16x32_bf16 v[12:15], v[218:221], v[202:205], v[12:15]
	v_mfma_f32_16x16x32_bf16 v[8:11], v[238:241], v[202:205], v[8:11]
	s_setprio 2
	s_barrier
	v_mfma_f32_16x16x32_bf16 v[4:7], v[218:221], v[210:213], v[4:7]
	v_mfma_f32_16x16x32_bf16 v[0:3], v[238:241], v[210:213], v[0:3]
	s_setprio 0
	s_add_i32 s11, s11, 2
	s_add_u32 s8, s8, 0x100
	s_addc_u32 s9, s9, 0
	s_cmp_lt_u32 s11, 28
	s_cbranch_scc1 .LBB0_746
	s_waitcnt lgkmcnt(0)
	v_or_b32_e32 v130, s40, v150
	v_lshl_add_u32 v130, v148, 6, v130
	v_ashrrev_i32_e32 v131, 31, v130
	v_lshl_add_u64 v[132:133], v[130:131], 2, s[30:31]
	v_add_u32_e32 v134, 0x80, v130
	v_add_u32_e32 v136, 0x90, v130
	v_add_u32_e32 v138, 0xa0, v130
	v_add_u32_e32 v130, 0xb0, v130
	s_or_b32 s57, s40, 0x80
	v_ashrrev_i32_e32 v135, 31, v134
	v_ashrrev_i32_e32 v137, 31, v136
	v_ashrrev_i32_e32 v139, 31, v138
	v_ashrrev_i32_e32 v131, 31, v130
	s_mul_i32 s8, s57, 0x1080
	v_lshl_add_u64 v[134:135], v[134:135], 2, s[30:31]
	v_lshl_add_u64 v[136:137], v[136:137], 2, s[30:31]
	v_lshl_add_u64 v[138:139], v[138:139], 2, s[30:31]
	v_lshl_add_u64 v[140:141], v[130:131], 2, s[30:31]
	global_load_dword v130, v[132:133], off
	global_load_dword v146, v[132:133], off offset:64
	global_load_dword v148, v[132:133], off offset:128
	global_load_dword v156, v[132:133], off offset:192
	global_load_dword v154, v[134:135], off
	global_load_dword v153, v[136:137], off
	global_load_dword v152, v[138:139], off
	global_load_dword v150, v[140:141], off
	s_mul_hi_i32 s9, s57, 0x1080
	s_add_u32 s8, s12, s8
	s_addc_u32 s9, s13, s9
	v_lshl_add_u64 v[140:141], s[8:9], 0, v[180:181]
	s_mov_b64 s[22:23], 0xf80
	v_readfirstlane_b32 s10, v162
	v_lshl_add_u64 v[140:141], v[140:141], 0, s[22:23]
	s_mov_b32 m0, s10
	ds_read_b128 v[132:135], v155
	ds_read_b128 v[136:139], v155 offset:1024
	ds_read_b128 v[164:167], v155 offset:2048
	ds_read_b128 v[168:171], v155 offset:3072
	ds_read_b128 v[172:175], v151
	ds_read_b128 v[176:179], v151 offset:1024
	ds_read_b128 v[182:185], v151 offset:2048
	ds_read_b128 v[186:189], v151 offset:3072
	ds_read_b128 v[190:193], v151 offset:4096
	ds_read_b128 v[194:197], v151 offset:5120
	ds_read_b128 v[198:201], v151 offset:6144
	ds_read_b128 v[202:205], v151 offset:7168
	global_load_lds_dwordx4 v[140:141], off
	v_lshl_add_u64 v[140:141], s[8:9], 0, v[128:129]
	v_readfirstlane_b32 s8, v163
	v_lshl_add_u64 v[140:141], v[140:141], 0, s[22:23]
	s_mov_b32 m0, s8
	s_nop 0
	global_load_lds_dwordx4 v[140:141], off
	s_barrier
; #define STAGE_A(P, br, kt) do { const char* _base = (const char*)(((kt) < G.ksplit ? G.A1 : A2m) + (long)(br) * G.lda + (long)(kt) * BK); \
;     __builtin_amdgcn_global_load_lds((const unsigned*)(_base + aoff0), (unsigned*)((char*)(P) + sb0), 16, 0, 0); \
;     __builtin_amdgcn_global_load_lds((const unsigned*)(_base + aoff1), (unsigned*)((char*)(P) + sb1), 16, 0, 0); } while (0)
; #define LDA(dst, b, h) for (int m = 0; m < 4; ++m) for (int k = 0; k < 2; ++k) \
;     dst[m][k] = *reinterpret_cast<const bf16x8*>(a_rd + ((b) * 2 + (h)) * (HT * 2) + m * 2048 + k * 1024)
; #define LDB(dst, b, h) for (int n = 0; n < 2; ++n) for (int k = 0; k < 2; ++k) \
;     dst[n][k] = *reinterpret_cast<const bf16x8*>(b_rd + ((b) * 2 + (h)) * (HT * 2) + n * 2048 + k * 1024)
; #define MMA(ai, bj, At_, Bt_) do { __builtin_amdgcn_s_setprio(1); \
;     for (int m = 0; m < 4; ++m) for (int n = 0; n < 2; ++n) for (int k = 0; k < 2; ++k) \
;       acc[ai][bj][m][n] = __builtin_amdgcn_mfma_f32_16x16x32_bf16(Bt_[n][k], At_[m][k], acc[ai][bj][m][n], 0, 0, 0); \
;     __builtin_amdgcn_s_setprio(0); } while (0)
; #define WAIT_V(n) asm volatile("s_waitcnt vmcnt(" #n ")" ::: "memory")
; #define WAIT_L(n) asm volatile("s_waitcnt lgkmcnt(" #n ")" ::: "memory")
; #define BAR __builtin_amdgcn_s_barrier()
;     ...
;   { LDB(B0, 0, 0); LDA(At, 0, 0); STAGE_A(SA(1, 1), brow + HALF, nt - 1);
;     BAR; WAIT_L(0); MMA(0, 0, At, B0); BAR;
;     LDB(B1, 0, 1); BAR; WAIT_L(0); MMA(0, 1, At, B1); BAR;
;     LDA(At, 0, 1); WAIT_V(4); BAR; WAIT_L(0); MMA(1, 0, At, B0); MMA(1, 1, At, B1); BAR; }
;   { LDB(B0, 1, 0); LDA(At, 1, 0); WAIT_V(2); BAR; WAIT_L(0); MMA(0, 0, At, B0); BAR;
	s_waitcnt lgkmcnt(0)
	s_setprio 1
	s_waitcnt lgkmcnt(0)
	v_mfma_f32_16x16x32_bf16 v[124:127], v[132:135], v[172:175], v[124:127]
	v_mfma_f32_16x16x32_bf16 v[120:123], v[164:167], v[172:175], v[120:123]
	v_mfma_f32_16x16x32_bf16 v[116:119], v[132:135], v[182:185], v[116:119]
	v_mfma_f32_16x16x32_bf16 v[112:115], v[164:167], v[182:185], v[112:115]
	v_mfma_f32_16x16x32_bf16 v[108:111], v[132:135], v[190:193], v[108:111]
	v_mfma_f32_16x16x32_bf16 v[104:107], v[164:167], v[190:193], v[104:107]
	v_mfma_f32_16x16x32_bf16 v[100:103], v[132:135], v[198:201], v[100:103]
	v_mfma_f32_16x16x32_bf16 v[96:99], v[164:167], v[198:201], v[96:99]
	v_mfma_f32_16x16x32_bf16 v[124:127], v[136:139], v[176:179], v[124:127]
	v_mfma_f32_16x16x32_bf16 v[120:123], v[168:171], v[176:179], v[120:123]
	v_mfma_f32_16x16x32_bf16 v[116:119], v[136:139], v[186:189], v[116:119]
	v_mfma_f32_16x16x32_bf16 v[112:115], v[168:171], v[186:189], v[112:115]
	v_mfma_f32_16x16x32_bf16 v[108:111], v[136:139], v[194:197], v[108:111]
	v_mfma_f32_16x16x32_bf16 v[104:107], v[168:171], v[194:197], v[104:107]
	s_setprio 2
	s_barrier
	v_mfma_f32_16x16x32_bf16 v[100:103], v[136:139], v[202:205], v[100:103]
	v_mfma_f32_16x16x32_bf16 v[96:99], v[168:171], v[202:205], v[96:99]
	s_setprio 0
	ds_read_b128 v[206:209], v155 offset:16384
	ds_read_b128 v[210:213], v155 offset:17408
	ds_read_b128 v[214:217], v155 offset:18432
	ds_read_b128 v[218:221], v155 offset:19456
	s_barrier
	s_waitcnt lgkmcnt(0)
	s_setprio 1
	s_waitcnt lgkmcnt(0)
	v_mfma_f32_16x16x32_bf16 v[92:95], v[206:209], v[172:175], v[92:95]
	v_mfma_f32_16x16x32_bf16 v[88:91], v[214:217], v[172:175], v[88:91]
	v_mfma_f32_16x16x32_bf16 v[84:87], v[206:209], v[182:185], v[84:87]
	v_mfma_f32_16x16x32_bf16 v[80:83], v[214:217], v[182:185], v[80:83]
	v_mfma_f32_16x16x32_bf16 v[76:79], v[206:209], v[190:193], v[76:79]
	v_mfma_f32_16x16x32_bf16 v[72:75], v[214:217], v[190:193], v[72:75]
	v_mfma_f32_16x16x32_bf16 v[68:71], v[206:209], v[198:201], v[68:71]
	v_mfma_f32_16x16x32_bf16 v[64:67], v[214:217], v[198:201], v[64:67]
	v_mfma_f32_16x16x32_bf16 v[92:95], v[210:213], v[176:179], v[92:95]
	v_mfma_f32_16x16x32_bf16 v[88:91], v[218:221], v[176:179], v[88:91]
	v_mfma_f32_16x16x32_bf16 v[84:87], v[210:213], v[186:189], v[84:87]
	v_mfma_f32_16x16x32_bf16 v[80:83], v[218:221], v[186:189], v[80:83]
	v_mfma_f32_16x16x32_bf16 v[76:79], v[210:213], v[194:197], v[76:79]
	v_mfma_f32_16x16x32_bf16 v[72:75], v[218:221], v[194:197], v[72:75]
	s_setprio 2
	s_barrier
	v_mfma_f32_16x16x32_bf16 v[68:71], v[210:213], v[202:205], v[68:71]
	v_mfma_f32_16x16x32_bf16 v[64:67], v[218:221], v[202:205], v[64:67]
	s_setprio 0
	ds_read_b128 v[172:175], v151 offset:16384
	ds_read_b128 v[176:179], v151 offset:17408
	ds_read_b128 v[182:185], v151 offset:18432
	ds_read_b128 v[186:189], v151 offset:19456
	ds_read_b128 v[190:193], v151 offset:20480
	ds_read_b128 v[194:197], v151 offset:21504
	ds_read_b128 v[198:201], v151 offset:22528
	ds_read_b128 v[202:205], v151 offset:23552
	s_waitcnt vmcnt(4)
	s_barrier
	s_waitcnt lgkmcnt(0)
	s_setprio 1
	s_waitcnt lgkmcnt(0)
	v_mfma_f32_16x16x32_bf16 v[60:63], v[132:135], v[172:175], v[60:63]
	v_mfma_f32_16x16x32_bf16 v[56:59], v[164:167], v[172:175], v[56:59]
	v_mfma_f32_16x16x32_bf16 v[52:55], v[132:135], v[182:185], v[52:55]
	v_mfma_f32_16x16x32_bf16 v[48:51], v[164:167], v[182:185], v[48:51]
	v_mfma_f32_16x16x32_bf16 v[44:47], v[132:135], v[190:193], v[44:47]
	v_mfma_f32_16x16x32_bf16 v[40:43], v[164:167], v[190:193], v[40:43]
	v_mfma_f32_16x16x32_bf16 v[36:39], v[132:135], v[198:201], v[36:39]
	v_mfma_f32_16x16x32_bf16 v[32:35], v[164:167], v[198:201], v[32:35]
	v_mfma_f32_16x16x32_bf16 v[60:63], v[136:139], v[176:179], v[60:63]
	v_mfma_f32_16x16x32_bf16 v[56:59], v[168:171], v[176:179], v[56:59]
	v_mfma_f32_16x16x32_bf16 v[52:55], v[136:139], v[186:189], v[52:55]
	v_mfma_f32_16x16x32_bf16 v[48:51], v[168:171], v[186:189], v[48:51]
	v_mfma_f32_16x16x32_bf16 v[44:47], v[136:139], v[194:197], v[44:47]
	v_mfma_f32_16x16x32_bf16 v[40:43], v[168:171], v[194:197], v[40:43]
	v_mfma_f32_16x16x32_bf16 v[36:39], v[136:139], v[202:205], v[36:39]
	v_mfma_f32_16x16x32_bf16 v[32:35], v[168:171], v[202:205], v[32:35]
	s_setprio 0
	s_setprio 1
	v_mfma_f32_16x16x32_bf16 v[28:31], v[206:209], v[172:175], v[28:31]
	v_mfma_f32_16x16x32_bf16 v[24:27], v[214:217], v[172:175], v[24:27]
	v_mfma_f32_16x16x32_bf16 v[20:23], v[206:209], v[182:185], v[20:23]
	v_mfma_f32_16x16x32_bf16 v[16:19], v[214:217], v[182:185], v[16:19]
	v_mfma_f32_16x16x32_bf16 v[12:15], v[206:209], v[190:193], v[12:15]
	v_mfma_f32_16x16x32_bf16 v[8:11], v[214:217], v[190:193], v[8:11]
	v_mfma_f32_16x16x32_bf16 v[4:7], v[206:209], v[198:201], v[4:7]
	v_mfma_f32_16x16x32_bf16 v[0:3], v[214:217], v[198:201], v[0:3]
	v_mfma_f32_16x16x32_bf16 v[28:31], v[210:213], v[176:179], v[28:31]
	v_mfma_f32_16x16x32_bf16 v[24:27], v[218:221], v[176:179], v[24:27]
	v_mfma_f32_16x16x32_bf16 v[20:23], v[210:213], v[186:189], v[20:23]
	v_mfma_f32_16x16x32_bf16 v[16:19], v[218:221], v[186:189], v[16:19]
	v_mfma_f32_16x16x32_bf16 v[12:15], v[210:213], v[194:197], v[12:15]
	v_mfma_f32_16x16x32_bf16 v[8:11], v[218:221], v[194:197], v[8:11]
	s_setprio 2
	s_barrier
	v_mfma_f32_16x16x32_bf16 v[4:7], v[210:213], v[202:205], v[4:7]
	v_mfma_f32_16x16x32_bf16 v[0:3], v[218:221], v[202:205], v[0:3]
	s_setprio 0
	ds_read_b128 v[132:135], v155 offset:32768
	ds_read_b128 v[136:139], v155 offset:33792
	ds_read_b128 v[162:165], v155 offset:34816
	ds_read_b128 v[166:169], v155 offset:35840
	ds_read_b128 v[170:173], v151 offset:32768
	ds_read_b128 v[174:177], v151 offset:33792
	ds_read_b128 v[182:185], v151 offset:34816
	ds_read_b128 v[186:189], v151 offset:35840
	ds_read_b128 v[190:193], v151 offset:36864
	ds_read_b128 v[194:197], v151 offset:37888
	ds_read_b128 v[198:201], v151 offset:38912
	ds_read_b128 v[202:205], v151 offset:39936
	s_waitcnt vmcnt(2)
	s_barrier
; #define LDA(dst, b, h) for (int m = 0; m < 4; ++m) for (int k = 0; k < 2; ++k) \
;     dst[m][k] = *reinterpret_cast<const bf16x8*>(a_rd + ((b) * 2 + (h)) * (HT * 2) + m * 2048 + k * 1024)
; #define LDB(dst, b, h) for (int n = 0; n < 2; ++n) for (int k = 0; k < 2; ++k) \
;     dst[n][k] = *reinterpret_cast<const bf16x8*>(b_rd + ((b) * 2 + (h)) * (HT * 2) + n * 2048 + k * 1024)
; #define MMA(ai, bj, At_, Bt_) do { __builtin_amdgcn_s_setprio(1); \
;     for (int m = 0; m < 4; ++m) for (int n = 0; n < 2; ++n) for (int k = 0; k < 2; ++k) \
;       acc[ai][bj][m][n] = __builtin_amdgcn_mfma_f32_16x16x32_bf16(Bt_[n][k], At_[m][k], acc[ai][bj][m][n], 0, 0, 0); \
;     __builtin_amdgcn_s_setprio(0); } while (0)
; #define WAIT_V(n) asm volatile("s_waitcnt vmcnt(" #n ")" ::: "memory")
; #define WAIT_L(n) asm volatile("s_waitcnt lgkmcnt(" #n ")" ::: "memory")
; #define BAR __builtin_amdgcn_s_barrier()
;     ...
;   { LDB(B0, 1, 0); LDA(At, 1, 0); WAIT_V(2); BAR; WAIT_L(0); MMA(0, 0, At, B0); BAR;
;     LDB(B1, 1, 1); WAIT_V(0); BAR; WAIT_L(0); MMA(0, 1, At, B1); BAR;
;     LDA(At, 1, 1); BAR; WAIT_L(0); MMA(1, 0, At, B0); MMA(1, 1, At, B1); BAR; }
;   if (wr == 0) BAR;
	s_waitcnt lgkmcnt(0)
	s_setprio 1
	s_waitcnt lgkmcnt(0)
	v_mfma_f32_16x16x32_bf16 v[124:127], v[132:135], v[170:173], v[124:127]
	v_mfma_f32_16x16x32_bf16 v[120:123], v[162:165], v[170:173], v[120:123]
	v_mfma_f32_16x16x32_bf16 v[116:119], v[132:135], v[182:185], v[116:119]
	v_mfma_f32_16x16x32_bf16 v[112:115], v[162:165], v[182:185], v[112:115]
	v_mfma_f32_16x16x32_bf16 v[108:111], v[132:135], v[190:193], v[108:111]
	v_mfma_f32_16x16x32_bf16 v[104:107], v[162:165], v[190:193], v[104:107]
	v_mfma_f32_16x16x32_bf16 v[100:103], v[132:135], v[198:201], v[100:103]
	v_mfma_f32_16x16x32_bf16 v[96:99], v[162:165], v[198:201], v[96:99]
	v_mfma_f32_16x16x32_bf16 v[124:127], v[136:139], v[174:177], v[124:127]
	v_mfma_f32_16x16x32_bf16 v[120:123], v[166:169], v[174:177], v[120:123]
	v_mfma_f32_16x16x32_bf16 v[116:119], v[136:139], v[186:189], v[116:119]
	v_mfma_f32_16x16x32_bf16 v[112:115], v[166:169], v[186:189], v[112:115]
	v_mfma_f32_16x16x32_bf16 v[108:111], v[136:139], v[194:197], v[108:111]
	v_mfma_f32_16x16x32_bf16 v[104:107], v[166:169], v[194:197], v[104:107]
	s_setprio 2
	s_barrier
	v_mfma_f32_16x16x32_bf16 v[100:103], v[136:139], v[202:205], v[100:103]
	v_mfma_f32_16x16x32_bf16 v[96:99], v[166:169], v[202:205], v[96:99]
	s_setprio 0
	ds_read_b128 v[206:209], v155 offset:49152
	ds_read_b128 v[210:213], v155 offset:50176
	ds_read_b128 v[214:217], v155 offset:51200
	ds_read_b128 v[218:221], v155 offset:52224
	s_waitcnt vmcnt(0)
	s_barrier
	s_waitcnt lgkmcnt(0)
	s_setprio 1
	s_waitcnt lgkmcnt(0)
	v_mfma_f32_16x16x32_bf16 v[92:95], v[206:209], v[170:173], v[92:95]
	v_mfma_f32_16x16x32_bf16 v[88:91], v[214:217], v[170:173], v[88:91]
	v_mfma_f32_16x16x32_bf16 v[84:87], v[206:209], v[182:185], v[84:87]
	v_mfma_f32_16x16x32_bf16 v[80:83], v[214:217], v[182:185], v[80:83]
	v_mfma_f32_16x16x32_bf16 v[76:79], v[206:209], v[190:193], v[76:79]
	v_mfma_f32_16x16x32_bf16 v[72:75], v[214:217], v[190:193], v[72:75]
	v_mfma_f32_16x16x32_bf16 v[68:71], v[206:209], v[198:201], v[68:71]
	v_mfma_f32_16x16x32_bf16 v[64:67], v[214:217], v[198:201], v[64:67]
	v_mfma_f32_16x16x32_bf16 v[92:95], v[210:213], v[174:177], v[92:95]
	v_mfma_f32_16x16x32_bf16 v[88:91], v[218:221], v[174:177], v[88:91]
	v_mfma_f32_16x16x32_bf16 v[84:87], v[210:213], v[186:189], v[84:87]
	v_mfma_f32_16x16x32_bf16 v[80:83], v[218:221], v[186:189], v[80:83]
	v_mfma_f32_16x16x32_bf16 v[76:79], v[210:213], v[194:197], v[76:79]
	v_mfma_f32_16x16x32_bf16 v[72:75], v[218:221], v[194:197], v[72:75]
	s_setprio 2
	s_barrier
	v_mfma_f32_16x16x32_bf16 v[68:71], v[210:213], v[202:205], v[68:71]
	v_mfma_f32_16x16x32_bf16 v[64:67], v[218:221], v[202:205], v[64:67]
	s_setprio 0
	ds_read_b128 v[170:173], v151 offset:49152
	ds_read_b128 v[174:177], v151 offset:50176
	ds_read_b128 v[182:185], v151 offset:51200
	ds_read_b128 v[186:189], v151 offset:52224
	ds_read_b128 v[190:193], v151 offset:53248
	ds_read_b128 v[194:197], v151 offset:54272
	ds_read_b128 v[198:201], v151 offset:55296
	ds_read_b128 v[202:205], v151 offset:56320
	s_barrier
	s_waitcnt lgkmcnt(0)
	s_setprio 1
	s_waitcnt lgkmcnt(0)
	v_mfma_f32_16x16x32_bf16 v[60:63], v[132:135], v[170:173], v[60:63]
	v_mfma_f32_16x16x32_bf16 v[56:59], v[162:165], v[170:173], v[56:59]
	v_mfma_f32_16x16x32_bf16 v[52:55], v[132:135], v[182:185], v[52:55]
	v_mfma_f32_16x16x32_bf16 v[48:51], v[162:165], v[182:185], v[48:51]
	v_mfma_f32_16x16x32_bf16 v[44:47], v[132:135], v[190:193], v[44:47]
	v_mfma_f32_16x16x32_bf16 v[40:43], v[162:165], v[190:193], v[40:43]
	v_mfma_f32_16x16x32_bf16 v[36:39], v[132:135], v[198:201], v[36:39]
	v_mfma_f32_16x16x32_bf16 v[32:35], v[162:165], v[198:201], v[32:35]
	v_mfma_f32_16x16x32_bf16 v[60:63], v[136:139], v[174:177], v[60:63]
	v_mfma_f32_16x16x32_bf16 v[56:59], v[166:169], v[174:177], v[56:59]
	v_mfma_f32_16x16x32_bf16 v[52:55], v[136:139], v[186:189], v[52:55]
	v_mfma_f32_16x16x32_bf16 v[48:51], v[166:169], v[186:189], v[48:51]
	v_mfma_f32_16x16x32_bf16 v[44:47], v[136:139], v[194:197], v[44:47]
	v_mfma_f32_16x16x32_bf16 v[40:43], v[166:169], v[194:197], v[40:43]
	v_mfma_f32_16x16x32_bf16 v[36:39], v[136:139], v[202:205], v[36:39]
	v_mfma_f32_16x16x32_bf16 v[32:35], v[166:169], v[202:205], v[32:35]
	s_setprio 0
	s_setprio 1
	v_mfma_f32_16x16x32_bf16 v[28:31], v[206:209], v[170:173], v[28:31]
	v_mfma_f32_16x16x32_bf16 v[24:27], v[214:217], v[170:173], v[24:27]
	v_mfma_f32_16x16x32_bf16 v[20:23], v[206:209], v[182:185], v[20:23]
	v_mfma_f32_16x16x32_bf16 v[16:19], v[214:217], v[182:185], v[16:19]
	v_mfma_f32_16x16x32_bf16 v[12:15], v[206:209], v[190:193], v[12:15]
	v_mfma_f32_16x16x32_bf16 v[8:11], v[214:217], v[190:193], v[8:11]
	v_mfma_f32_16x16x32_bf16 v[4:7], v[206:209], v[198:201], v[4:7]
	v_mfma_f32_16x16x32_bf16 v[0:3], v[214:217], v[198:201], v[0:3]
	v_mfma_f32_16x16x32_bf16 v[28:31], v[210:213], v[174:177], v[28:31]
	v_mfma_f32_16x16x32_bf16 v[24:27], v[218:221], v[174:177], v[24:27]
	v_mfma_f32_16x16x32_bf16 v[20:23], v[210:213], v[186:189], v[20:23]
	v_mfma_f32_16x16x32_bf16 v[16:19], v[218:221], v[186:189], v[16:19]
	v_mfma_f32_16x16x32_bf16 v[12:15], v[210:213], v[194:197], v[12:15]
	v_mfma_f32_16x16x32_bf16 v[8:11], v[218:221], v[194:197], v[8:11]
	s_setprio 2
	s_barrier
	v_mfma_f32_16x16x32_bf16 v[4:7], v[210:213], v[202:205], v[4:7]
	v_mfma_f32_16x16x32_bf16 v[0:3], v[218:221], v[202:205], v[0:3]
	s_setprio 0
	v_cmp_gt_u32_e32 vcc, s60, v144
	s_and_saveexec_b64 s[8:9], vcc
	s_cbranch_execz .LBB0_749
	s_barrier

; #define STAGE_A(P, br, kt) do { const char* _base = (const char*)(((kt) < G.ksplit ? G.A1 : A2m) + (long)(br) * G.lda + (long)(kt) * BK); \
;     __builtin_amdgcn_global_load_lds((const unsigned*)(_base + aoff0), (unsigned*)((char*)(P) + sb0), 16, 0, 0); \
;     __builtin_amdgcn_global_load_lds((const unsigned*)(_base + aoff1), (unsigned*)((char*)(P) + sb1), 16, 0, 0); } while (0)
; #define STAGE_B(P, br, kt) do { const char* _base = (const char*)(G.Bt + (long)(br) * G.ldb + (long)(kt) * BK); \
;     __builtin_amdgcn_global_load_lds((const unsigned*)(_base + boff0), (unsigned*)((char*)(P) + sb0), 16, 0, 0); \
;     __builtin_amdgcn_global_load_lds((const unsigned*)(_base + boff1), (unsigned*)((char*)(P) + sb1), 16, 0, 0); } while (0)
; #define LDA(dst, b, h) for (int m = 0; m < 4; ++m) for (int k = 0; k < 2; ++k) \
;     dst[m][k] = *reinterpret_cast<const bf16x8*>(a_rd + ((b) * 2 + (h)) * (HT * 2) + m * 2048 + k * 1024)
; #define LDB(dst, b, h) for (int n = 0; n < 2; ++n) for (int k = 0; k < 2; ++k) \
;     dst[n][k] = *reinterpret_cast<const bf16x8*>(b_rd + ((b) * 2 + (h)) * (HT * 2) + n * 2048 + k * 1024)
;     ...
;   const int K = G.K;
;   const u16* A2m = G.A2 - (long)G.ksplit * BK;
;   int t1 = otid();
;   const int wid = t1 >> 6, lane = t1 & 63, wr = wid >> 2, wc = wid & 3, fr = lane & 15, fq = lane >> 4;
;   const int sb0 = t1 * 16, sb1 = sb0 + 8192;
;   const int swz_ = lds_byte(fr, fq * 8);
;   const char* a_rd = shmc + wr * 8192 + swz_;
;   const char* b_rd = shmc + 4 * (HT * 2) + wc * 4096 + swz_;
;   int r0_, c0_, r1_, c1_; stage_rc(sb0, r0_, c0_); stage_rc(sb1, r1_, c1_);
;   const unsigned aoff0 = (unsigned)(r0_ * G.lda + c0_) * 2u, aoff1 = (unsigned)(r1_ * G.lda + c1_) * 2u;
;   const unsigned boff0 = (unsigned)(r0_ * G.ldb + c0_) * 2u, boff1 = (unsigned)(r1_ * G.ldb + c1_) * 2u;
;   f32x4 acc[2][2][4][2] = {};
;   bf16x8 At[4][2], B0[2][2], B1[2][2];
;   const int nt = K / BK;
;   if (EPI == EPI_RESID || first) {
;     STAGE_B(SB(0, 0), bcol, 0); STAGE_A(SA(0, 0), brow, 0);
;     STAGE_B(SB(0, 1), bcol + HALF, 0); STAGE_A(SA(0, 1), brow + HALF, 0);
;   }
;   if (wr == 1) BAR;
;   WAIT_V(0); BAR;
;   STAGE_B(SB(1, 0), bcol, 1); STAGE_A(SA(1, 0), brow, 1); STAGE_B(SB(1, 1), bcol + HALF, 1);
;   WAIT_V(6); BAR;
;   for (int t = 0; t < nt - 2; t += 2) {
;     LDB(B0, 0, 0); SCHED; LDA(At, 0, 0); STAGE_A(SA(1, 1), brow + HALF, t + 1);
.LBB0_1800:
	s_or_b64 exec, exec, s[8:9]
	v_and_b32_e32 v20, 15, v144
	v_lshlrev_b32_e32 v22, 2, v144
	v_and_b32_e32 v21, 48, v144
	v_lshlrev_b32_e32 v20, 6, v20
	v_and_b32_e32 v22, 32, v22
	v_bitop3_b32 v20, v20, v22, v21 bitop3:0x36
	v_lshlrev_b32_e32 v21, 6, v144
	v_and_b32_e32 v21, 0x3000, v21
	v_add_u32_e32 v21, s37, v21
	v_readlane_b32 s37, v253, 46
	s_mov_b64 s[40:41], 0x80
	v_lshl_add_u64 v[2:3], v[2:3], 0, s[40:41]
	v_add_u32_e32 v153, s37, v12
	v_add_u32_e32 v154, 0x2000, v153
	v_readfirstlane_b32 s37, v153
	s_mov_b32 m0, s37
	v_readfirstlane_b32 s37, v154
	v_add_u32_e32 v155, 0x8000, v147
	s_waitcnt vmcnt(0)
	s_barrier
	global_load_lds_dwordx4 v[2:3], off
	v_lshl_add_u64 v[2:3], v[4:5], 0, s[40:41]
	s_mov_b32 m0, s37
	v_readfirstlane_b32 s37, v155
	v_add_u32_e32 v156, 0xa000, v147
	global_load_lds_dwordx4 v[2:3], off
	v_lshl_add_u64 v[2:3], v[6:7], 0, s[40:41]
	s_mov_b32 m0, s37
	v_readfirstlane_b32 s37, v156
	s_lshl_b64 s[8:9], s[20:21], 10
	global_load_lds_dwordx4 v[2:3], off
	s_mov_b32 m0, s37
	v_readlane_b32 s37, v253, 47
	s_add_u32 s38, s38, 0x84080
	v_lshl_add_u64 v[2:3], v[8:9], 0, s[40:41]
	v_add_u32_e32 v157, s37, v12
	s_addc_u32 s39, s39, 0
	v_readfirstlane_b32 s37, v157
	v_add_u32_e32 v158, 0x2000, v157
	global_load_lds_dwordx4 v[2:3], off
	v_lshl_add_u64 v[2:3], s[38:39], 0, v[180:181]
	s_mov_b32 m0, s37
	v_readfirstlane_b32 s37, v158
	global_load_lds_dwordx4 v[2:3], off
	v_lshl_add_u64 v[0:1], s[38:39], 0, v[0:1]
	s_mov_b32 m0, s37
	v_lshrrev_b32_e32 v2, 1, v11
	global_load_lds_dwordx4 v[0:1], off
	v_lshrrev_b32_e32 v1, 1, v10
	v_mul_lo_u32 v0, v13, s62
	v_mad_u64_u32 v[0:1], s[38:39], v1, s84, v[0:1]
	v_or_b32_e32 v0, v0, v14
	v_add_lshl_u32 v180, v0, v16, 1
	v_mul_lo_u32 v0, v15, s62
	v_lshlrev_b32_e32 v3, 11, v15
	v_mad_u64_u32 v[0:1], s[38:39], v2, s84, v[0:1]
	v_lshl_add_u32 v2, v2, 15, v3
	v_and_b32_e32 v3, 1, v11
	s_add_u32 s26, s14, s26
	v_lshl_or_b32 v2, v3, 6, v2
	s_addc_u32 s27, s15, s27
	v_lshl_add_u32 v2, v17, 1, v2
	v_mov_b32_e32 v3, v181
	v_or_b32_e32 v0, v0, v18
	v_lshl_add_u64 v[136:137], s[10:11], 0, v[130:131]
	v_lshl_add_u64 v[138:139], s[10:11], 0, v[2:3]
	s_add_u32 s10, s14, s24
	s_waitcnt vmcnt(6)
	v_add_lshl_u32 v0, v0, v17, 1
	v_mov_b32_e32 v1, v181
	s_addc_u32 s11, s15, s25
	v_lshl_add_u32 v19, v19, 13, 32
	v_lshl_add_u64 v[134:135], s[26:27], 0, v[0:1]
	v_lshl_add_u64 v[142:143], s[10:11], 0, v[0:1]
	v_mov_b32_e32 v0, 0
	v_mov_b32_e32 v245, 0x80003fff
	v_lshl_add_u64 v[132:133], s[26:27], 0, v[180:181]
	v_lshl_add_u64 v[140:141], s[10:11], 0, v[180:181]
	s_mov_b32 s24, -2
	s_mov_b64 s[10:11], 0
	v_add_u32_e32 v149, v21, v20
	v_add_u32_e32 v146, v19, v20
	v_mov_b32_e32 v1, v0
	v_mov_b32_e32 v2, v0
	v_mov_b32_e32 v3, v0
	v_mov_b32_e32 v4, v0
	v_mov_b32_e32 v5, v0
	v_mov_b32_e32 v6, v0
	v_mov_b32_e32 v7, v0
	v_mov_b32_e32 v8, v0
	v_mov_b32_e32 v9, v0
	v_mov_b32_e32 v10, v0
	v_mov_b32_e32 v11, v0
	v_mov_b32_e32 v12, v0
	v_mov_b32_e32 v13, v0
	v_mov_b32_e32 v14, v0
	v_mov_b32_e32 v15, v0
	v_mov_b32_e32 v16, v0
	v_mov_b32_e32 v17, v0
	v_mov_b32_e32 v18, v0
	v_mov_b32_e32 v19, v0
	v_mov_b32_e32 v20, v0
	v_mov_b32_e32 v21, v0
	v_mov_b32_e32 v22, v0
	v_mov_b32_e32 v23, v0
	s_waitcnt vmcnt(0)
	v_mov_b32_e32 v24, v0
	v_mov_b32_e32 v25, v0
	v_mov_b32_e32 v26, v0
	v_mov_b32_e32 v27, v0
	v_mov_b32_e32 v28, v0
	v_mov_b32_e32 v29, v0
	v_mov_b32_e32 v30, v0
	v_mov_b32_e32 v31, v0
	v_mov_b32_e32 v32, v0
	v_mov_b32_e32 v33, v0
	v_mov_b32_e32 v34, v0
	v_mov_b32_e32 v35, v0
	v_mov_b32_e32 v36, v0
	v_mov_b32_e32 v37, v0
	v_mov_b32_e32 v38, v0
	v_mov_b32_e32 v39, v0
	v_mov_b32_e32 v40, v0
	v_mov_b32_e32 v41, v0
	v_mov_b32_e32 v42, v0
	v_mov_b32_e32 v43, v0
	v_mov_b32_e32 v44, v0
	v_mov_b32_e32 v45, v0
	v_mov_b32_e32 v46, v0
	v_mov_b32_e32 v47, v0
	v_mov_b32_e32 v48, v0
	v_mov_b32_e32 v49, v0
	v_mov_b32_e32 v50, v0
	v_mov_b32_e32 v51, v0
	v_mov_b32_e32 v52, v0
	v_mov_b32_e32 v53, v0
	v_mov_b32_e32 v54, v0
	v_mov_b32_e32 v55, v0
	v_mov_b32_e32 v56, v0
	v_mov_b32_e32 v57, v0
	v_mov_b32_e32 v58, v0
	v_mov_b32_e32 v59, v0
	v_mov_b32_e32 v60, v0
	v_mov_b32_e32 v61, v0
	v_mov_b32_e32 v62, v0
	v_mov_b32_e32 v63, v0
	v_mov_b32_e32 v64, v0
	v_mov_b32_e32 v65, v0
	v_mov_b32_e32 v66, v0
	v_mov_b32_e32 v67, v0
	v_mov_b32_e32 v68, v0
	v_mov_b32_e32 v69, v0
	v_mov_b32_e32 v70, v0
	v_mov_b32_e32 v71, v0
	v_mov_b32_e32 v72, v0
	v_mov_b32_e32 v73, v0
	v_mov_b32_e32 v74, v0
	v_mov_b32_e32 v75, v0
	v_mov_b32_e32 v76, v0
	v_mov_b32_e32 v77, v0
	v_mov_b32_e32 v78, v0
	v_mov_b32_e32 v79, v0
	v_mov_b32_e32 v80, v0
	v_mov_b32_e32 v81, v0
	v_mov_b32_e32 v82, v0
	v_mov_b32_e32 v83, v0
	v_mov_b32_e32 v84, v0
	v_mov_b32_e32 v85, v0
	v_mov_b32_e32 v86, v0
	v_mov_b32_e32 v87, v0
	v_mov_b32_e32 v88, v0
	v_mov_b32_e32 v89, v0
	v_mov_b32_e32 v90, v0
	v_mov_b32_e32 v91, v0
	v_mov_b32_e32 v92, v0
	v_mov_b32_e32 v93, v0
	v_mov_b32_e32 v94, v0
	v_mov_b32_e32 v95, v0
	v_mov_b32_e32 v96, v0
	v_mov_b32_e32 v97, v0
	v_mov_b32_e32 v98, v0
	v_mov_b32_e32 v99, v0
	v_mov_b32_e32 v100, v0
	v_mov_b32_e32 v101, v0
	v_mov_b32_e32 v102, v0
	v_mov_b32_e32 v103, v0
	v_mov_b32_e32 v104, v0
	v_mov_b32_e32 v105, v0
	v_mov_b32_e32 v106, v0
	v_mov_b32_e32 v107, v0
	v_mov_b32_e32 v108, v0
	v_mov_b32_e32 v109, v0
	v_mov_b32_e32 v110, v0
	v_mov_b32_e32 v111, v0
	v_mov_b32_e32 v112, v0
	v_mov_b32_e32 v113, v0
	v_mov_b32_e32 v114, v0
	v_mov_b32_e32 v115, v0
	v_mov_b32_e32 v116, v0
	v_mov_b32_e32 v117, v0
	v_mov_b32_e32 v118, v0
	v_mov_b32_e32 v119, v0
	v_mov_b32_e32 v120, v0
	v_mov_b32_e32 v121, v0
	v_mov_b32_e32 v122, v0
	v_mov_b32_e32 v123, v0
	v_mov_b32_e32 v124, v0
	v_mov_b32_e32 v125, v0
	v_mov_b32_e32 v126, v0
	v_mov_b32_e32 v127, v0
	s_mov_b64 s[38:39], 0x40080
	s_mov_b64 s[40:41], 0x54e8100
	s_mov_b64 s[42:43], 0x556c100
	s_mov_b64 s[44:45], 0x40100
	s_mov_b64 s[46:47], 0x54e8180
	s_mov_b64 s[48:49], 0x556c180
	s_barrier
	ds_read_b128 v[162:165], v149
	ds_read_b128 v[166:169], v149 offset:1024
	ds_read_b128 v[170:173], v149 offset:2048
	ds_read_b128 v[174:177], v149 offset:3072
; #define STAGE_A(P, br, kt) do { const char* _base = (const char*)(((kt) < G.ksplit ? G.A1 : A2m) + (long)(br) * G.lda + (long)(kt) * BK); \
;     __builtin_amdgcn_global_load_lds((const unsigned*)(_base + aoff0), (unsigned*)((char*)(P) + sb0), 16, 0, 0); \
;     __builtin_amdgcn_global_load_lds((const unsigned*)(_base + aoff1), (unsigned*)((char*)(P) + sb1), 16, 0, 0); } while (0)
; #define STAGE_B(P, br, kt) do { const char* _base = (const char*)(G.Bt + (long)(br) * G.ldb + (long)(kt) * BK); \
;     __builtin_amdgcn_global_load_lds((const unsigned*)(_base + boff0), (unsigned*)((char*)(P) + sb0), 16, 0, 0); \
;     __builtin_amdgcn_global_load_lds((const unsigned*)(_base + boff1), (unsigned*)((char*)(P) + sb1), 16, 0, 0); } while (0)
; #define LDA(dst, b, h) for (int m = 0; m < 4; ++m) for (int k = 0; k < 2; ++k) \
;     dst[m][k] = *reinterpret_cast<const bf16x8*>(a_rd + ((b) * 2 + (h)) * (HT * 2) + m * 2048 + k * 1024)
; #define LDB(dst, b, h) for (int n = 0; n < 2; ++n) for (int k = 0; k < 2; ++k) \
;     dst[n][k] = *reinterpret_cast<const bf16x8*>(b_rd + ((b) * 2 + (h)) * (HT * 2) + n * 2048 + k * 1024)
; #define MMA(ai, bj, At_, Bt_) do { __builtin_amdgcn_s_setprio(1); \
;     for (int m = 0; m < 4; ++m) for (int n = 0; n < 2; ++n) for (int k = 0; k < 2; ++k) \
;       acc[ai][bj][m][n] = __builtin_amdgcn_mfma_f32_16x16x32_bf16(Bt_[n][k], At_[m][k], acc[ai][bj][m][n], 0, 0, 0); \
;     __builtin_amdgcn_s_setprio(0); } while (0)
; #define WAIT_L(n) asm volatile("s_waitcnt lgkmcnt(" #n ")" ::: "memory")
; #define BAR __builtin_amdgcn_s_barrier()
; #define SCHED __builtin_amdgcn_sched_barrier(0)
;     ...
;     LDB(B0, 0, 0); SCHED; LDA(At, 0, 0); STAGE_A(SA(1, 1), brow + HALF, t + 1);
;     WAIT_L(8); BAR; WAIT_L(0); MMA(0, 0, At, B0); BAR; SCHED;
;     LDB(B1, 0, 1); STAGE_B(SB(0, 0), bcol, t + 2);
;     BAR; WAIT_L(0); MMA(0, 1, At, B1); BAR;
;     LDA(At, 0, 1); STAGE_A(SA(0, 0), brow, t + 2);
;     BAR; WAIT_L(0); MMA(1, 0, At, B0); BAR; SCHED;
.LBB0_1801:
	s_add_i32 s24, s24, 2
	s_cmp_lt_u32 s24, 16
	s_cselect_b32 s27, s30, s36
	s_cselect_b32 s26, s29, s35
	v_lshl_add_u64 v[160:161], s[26:27], 0, v[136:137]
	v_add_u32_e32 v159, 0xc000, v147
	v_lshl_add_u64 v[160:161], v[160:161], 0, s[10:11]
	v_readfirstlane_b32 s25, v159
	v_lshl_add_u64 v[160:161], v[160:161], 0, s[38:39]
	s_mov_b32 m0, s25
	ds_read_b128 v[182:185], v146
	ds_read_b128 v[186:189], v146 offset:1024
	ds_read_b128 v[190:193], v146 offset:2048
	ds_read_b128 v[194:197], v146 offset:3072
	ds_read_b128 v[198:201], v146 offset:4096
	ds_read_b128 v[202:205], v146 offset:5120
	ds_read_b128 v[206:209], v146 offset:6144
	ds_read_b128 v[210:213], v146 offset:7168
	global_load_lds_dwordx4 v[160:161], off
	v_lshl_add_u64 v[160:161], s[26:27], 0, v[138:139]
	v_lshl_add_u64 v[160:161], v[160:161], 0, s[10:11]
	v_lshl_add_u64 v[178:179], v[160:161], 0, s[38:39]
	v_add_u32_e32 v160, 0xe000, v147
	s_nop 0
	v_readfirstlane_b32 s25, v160
	s_mov_b32 m0, s25
	s_nop 0
	global_load_lds_dwordx4 v[178:179], off
	s_waitcnt lgkmcnt(8)
	s_barrier
	s_waitcnt lgkmcnt(0)
	s_setprio 1
	s_waitcnt lgkmcnt(0)
	v_mfma_f32_16x16x32_bf16 v[124:127], v[162:165], v[182:185], v[124:127]
	v_mfma_f32_16x16x32_bf16 v[120:123], v[170:173], v[182:185], v[120:123]
	v_mfma_f32_16x16x32_bf16 v[116:119], v[162:165], v[190:193], v[116:119]
	v_mfma_f32_16x16x32_bf16 v[112:115], v[170:173], v[190:193], v[112:115]
	v_mfma_f32_16x16x32_bf16 v[108:111], v[162:165], v[198:201], v[108:111]
	v_mfma_f32_16x16x32_bf16 v[104:107], v[170:173], v[198:201], v[104:107]
	v_mfma_f32_16x16x32_bf16 v[100:103], v[162:165], v[206:209], v[100:103]
	v_mfma_f32_16x16x32_bf16 v[96:99], v[170:173], v[206:209], v[96:99]
	v_mfma_f32_16x16x32_bf16 v[124:127], v[166:169], v[186:189], v[124:127]
	v_mfma_f32_16x16x32_bf16 v[120:123], v[174:177], v[186:189], v[120:123]
	v_mfma_f32_16x16x32_bf16 v[116:119], v[166:169], v[194:197], v[116:119]
	v_mfma_f32_16x16x32_bf16 v[112:115], v[174:177], v[194:197], v[112:115]
	v_mfma_f32_16x16x32_bf16 v[108:111], v[166:169], v[202:205], v[108:111]
	v_mfma_f32_16x16x32_bf16 v[104:107], v[174:177], v[202:205], v[104:107]
	s_setprio 2
	s_barrier
	v_mfma_f32_16x16x32_bf16 v[100:103], v[166:169], v[210:213], v[100:103]
	v_mfma_f32_16x16x32_bf16 v[96:99], v[174:177], v[210:213], v[96:99]
	s_setprio 0
	v_lshl_add_u64 v[178:179], v[132:133], 0, s[10:11]
	v_readfirstlane_b32 s25, v145
	v_lshl_add_u64 v[222:223], v[178:179], 0, s[40:41]
	s_mov_b32 m0, s25
	v_add_u32_e32 v161, 0x2000, v145
	ds_read_b128 v[214:217], v149 offset:16384
	ds_read_b128 v[218:221], v149 offset:17408
	ds_read_b128 v[230:233], v149 offset:18432
	ds_read_b128 v[238:241], v149 offset:19456
	global_load_lds_dwordx4 v[222:223], off
	v_lshl_add_u64 v[222:223], v[134:135], 0, s[10:11]
	v_readfirstlane_b32 s25, v161
	v_lshl_add_u64 v[226:227], v[222:223], 0, s[40:41]
	s_mov_b32 m0, s25
	s_nop 0
	global_load_lds_dwordx4 v[226:227], off
	s_barrier
	s_waitcnt lgkmcnt(0)
	s_setprio 1
	s_waitcnt lgkmcnt(0)
	v_mfma_f32_16x16x32_bf16 v[92:95], v[214:217], v[182:185], v[92:95]
	v_mfma_f32_16x16x32_bf16 v[88:91], v[230:233], v[182:185], v[88:91]
	v_mfma_f32_16x16x32_bf16 v[84:87], v[214:217], v[190:193], v[84:87]
	v_mfma_f32_16x16x32_bf16 v[80:83], v[230:233], v[190:193], v[80:83]
	v_mfma_f32_16x16x32_bf16 v[76:79], v[214:217], v[198:201], v[76:79]
	v_mfma_f32_16x16x32_bf16 v[72:75], v[230:233], v[198:201], v[72:75]
	v_mfma_f32_16x16x32_bf16 v[68:71], v[214:217], v[206:209], v[68:71]
	v_mfma_f32_16x16x32_bf16 v[64:67], v[230:233], v[206:209], v[64:67]
	v_mfma_f32_16x16x32_bf16 v[92:95], v[218:221], v[186:189], v[92:95]
	v_mfma_f32_16x16x32_bf16 v[88:91], v[238:241], v[186:189], v[88:91]
	v_mfma_f32_16x16x32_bf16 v[84:87], v[218:221], v[194:197], v[84:87]
	v_mfma_f32_16x16x32_bf16 v[80:83], v[238:241], v[194:197], v[80:83]
	v_mfma_f32_16x16x32_bf16 v[76:79], v[218:221], v[202:205], v[76:79]
	v_mfma_f32_16x16x32_bf16 v[72:75], v[238:241], v[202:205], v[72:75]
	s_setprio 2
	s_barrier
	v_mfma_f32_16x16x32_bf16 v[68:71], v[218:221], v[210:213], v[68:71]
	v_mfma_f32_16x16x32_bf16 v[64:67], v[238:241], v[210:213], v[64:67]
	s_setprio 0
	s_cmp_lt_u32 s24, 14
	s_cselect_b32 s27, s30, s36
	s_cselect_b32 s26, s29, s35
	v_lshl_add_u64 v[226:227], s[26:27], 0, v[136:137]
	v_lshl_add_u64 v[226:227], v[226:227], 0, s[10:11]
	v_readfirstlane_b32 s25, v147
	v_lshl_add_u64 v[234:235], v[226:227], 0, s[90:91]
	s_mov_b32 m0, s25
	ds_read_b128 v[182:185], v146 offset:16384
	ds_read_b128 v[186:189], v146 offset:17408
	ds_read_b128 v[190:193], v146 offset:18432
	ds_read_b128 v[194:197], v146 offset:19456
	ds_read_b128 v[198:201], v146 offset:20480
	ds_read_b128 v[202:205], v146 offset:21504
	ds_read_b128 v[206:209], v146 offset:22528
	ds_read_b128 v[210:213], v146 offset:23552
	global_load_lds_dwordx4 v[234:235], off
	v_lshl_add_u64 v[234:235], s[26:27], 0, v[138:139]
	v_lshl_add_u64 v[234:235], v[234:235], 0, s[10:11]
	v_readfirstlane_b32 s25, v148
	v_lshl_add_u64 v[236:237], v[234:235], 0, s[90:91]
	s_mov_b32 m0, s25
	s_nop 0
	global_load_lds_dwordx4 v[236:237], off
	s_waitcnt vmcnt(10)
	s_barrier
	s_waitcnt lgkmcnt(0)
	s_setprio 1
	s_waitcnt lgkmcnt(0)
	v_mfma_f32_16x16x32_bf16 v[60:63], v[162:165], v[182:185], v[60:63]
	v_mfma_f32_16x16x32_bf16 v[56:59], v[170:173], v[182:185], v[56:59]
	v_mfma_f32_16x16x32_bf16 v[52:55], v[162:165], v[190:193], v[52:55]
	v_mfma_f32_16x16x32_bf16 v[48:51], v[170:173], v[190:193], v[48:51]
	v_mfma_f32_16x16x32_bf16 v[44:47], v[162:165], v[198:201], v[44:47]
	v_mfma_f32_16x16x32_bf16 v[40:43], v[170:173], v[198:201], v[40:43]
	v_mfma_f32_16x16x32_bf16 v[36:39], v[162:165], v[206:209], v[36:39]
	v_mfma_f32_16x16x32_bf16 v[32:35], v[170:173], v[206:209], v[32:35]
	v_mfma_f32_16x16x32_bf16 v[60:63], v[166:169], v[186:189], v[60:63]
	v_mfma_f32_16x16x32_bf16 v[56:59], v[174:177], v[186:189], v[56:59]
	v_mfma_f32_16x16x32_bf16 v[52:55], v[166:169], v[194:197], v[52:55]
	v_mfma_f32_16x16x32_bf16 v[48:51], v[174:177], v[194:197], v[48:51]
	v_mfma_f32_16x16x32_bf16 v[44:47], v[166:169], v[202:205], v[44:47]
	v_mfma_f32_16x16x32_bf16 v[40:43], v[174:177], v[202:205], v[40:43]
	s_setprio 2
	s_barrier
; #define STAGE_A(P, br, kt) do { const char* _base = (const char*)(((kt) < G.ksplit ? G.A1 : A2m) + (long)(br) * G.lda + (long)(kt) * BK); \
;     __builtin_amdgcn_global_load_lds((const unsigned*)(_base + aoff0), (unsigned*)((char*)(P) + sb0), 16, 0, 0); \
;     __builtin_amdgcn_global_load_lds((const unsigned*)(_base + aoff1), (unsigned*)((char*)(P) + sb1), 16, 0, 0); } while (0)
; #define STAGE_B(P, br, kt) do { const char* _base = (const char*)(G.Bt + (long)(br) * G.ldb + (long)(kt) * BK); \
;     __builtin_amdgcn_global_load_lds((const unsigned*)(_base + boff0), (unsigned*)((char*)(P) + sb0), 16, 0, 0); \
;     __builtin_amdgcn_global_load_lds((const unsigned*)(_base + boff1), (unsigned*)((char*)(P) + sb1), 16, 0, 0); } while (0)
; #define LDA(dst, b, h) for (int m = 0; m < 4; ++m) for (int k = 0; k < 2; ++k) \
;     dst[m][k] = *reinterpret_cast<const bf16x8*>(a_rd + ((b) * 2 + (h)) * (HT * 2) + m * 2048 + k * 1024)
; #define LDB(dst, b, h) for (int n = 0; n < 2; ++n) for (int k = 0; k < 2; ++k) \
;     dst[n][k] = *reinterpret_cast<const bf16x8*>(b_rd + ((b) * 2 + (h)) * (HT * 2) + n * 2048 + k * 1024)
; #define MMA(ai, bj, At_, Bt_) do { __builtin_amdgcn_s_setprio(1); \
;     for (int m = 0; m < 4; ++m) for (int n = 0; n < 2; ++n) for (int k = 0; k < 2; ++k) \
;       acc[ai][bj][m][n] = __builtin_amdgcn_mfma_f32_16x16x32_bf16(Bt_[n][k], At_[m][k], acc[ai][bj][m][n], 0, 0, 0); \
;     __builtin_amdgcn_s_setprio(0); } while (0)
; #define WAIT_V(n) asm volatile("s_waitcnt vmcnt(" #n ")" ::: "memory")
; #define WAIT_L(n) asm volatile("s_waitcnt lgkmcnt(" #n ")" ::: "memory")
; #define BAR __builtin_amdgcn_s_barrier()
; #define SCHED __builtin_amdgcn_sched_barrier(0)
;     ...
;     BAR; WAIT_L(0); MMA(1, 0, At, B0); BAR; SCHED;
;     STAGE_B(SB(0, 1), bcol + HALF, t + 2);
;     WAIT_V(6); BAR; MMA(1, 1, At, B1); BAR;
;     LDB(B0, 1, 0); SCHED; LDA(At, 1, 0); STAGE_A(SA(0, 1), brow + HALF, t + 2);
;     WAIT_L(8); BAR; WAIT_L(0); MMA(0, 0, At, B0); BAR; SCHED;
;     LDB(B1, 1, 1); STAGE_B(SB(1, 0), bcol, t + 3);
;     BAR; WAIT_L(0); MMA(0, 1, At, B1); BAR;
	v_mfma_f32_16x16x32_bf16 v[36:39], v[166:169], v[210:213], v[36:39]
	v_mfma_f32_16x16x32_bf16 v[32:35], v[174:177], v[210:213], v[32:35]
	s_setprio 0
	v_lshl_add_u64 v[236:237], v[140:141], 0, s[10:11]
	v_readfirstlane_b32 s25, v150
	v_add_u32_e32 v161, 0x2000, v150
	v_lshl_add_u64 v[162:163], v[236:237], 0, s[42:43]
	s_mov_b32 m0, s25
	v_lshl_add_u64 v[246:247], v[142:143], 0, s[10:11]
	v_readfirstlane_b32 s25, v161
	global_load_lds_dwordx4 v[162:163], off
	v_lshl_add_u64 v[162:163], v[246:247], 0, s[42:43]
	s_mov_b32 m0, s25
	s_nop 0
	global_load_lds_dwordx4 v[162:163], off
	ds_read_b128 v[162:165], v149 offset:32768
	ds_read_b128 v[166:169], v149 offset:33792
	ds_read_b128 v[170:173], v149 offset:34816
	ds_read_b128 v[174:177], v149 offset:35840
	s_waitcnt vmcnt(6)
	s_barrier
	s_setprio 1
	v_mfma_f32_16x16x32_bf16 v[28:31], v[214:217], v[182:185], v[28:31]
	v_mfma_f32_16x16x32_bf16 v[24:27], v[230:233], v[182:185], v[24:27]
	v_mfma_f32_16x16x32_bf16 v[20:23], v[214:217], v[190:193], v[20:23]
	v_mfma_f32_16x16x32_bf16 v[16:19], v[230:233], v[190:193], v[16:19]
	v_mfma_f32_16x16x32_bf16 v[12:15], v[214:217], v[198:201], v[12:15]
	v_mfma_f32_16x16x32_bf16 v[8:11], v[230:233], v[198:201], v[8:11]
	v_mfma_f32_16x16x32_bf16 v[4:7], v[214:217], v[206:209], v[4:7]
	v_mfma_f32_16x16x32_bf16 v[0:3], v[230:233], v[206:209], v[0:3]
	v_mfma_f32_16x16x32_bf16 v[28:31], v[218:221], v[186:189], v[28:31]
	v_mfma_f32_16x16x32_bf16 v[24:27], v[238:241], v[186:189], v[24:27]
	v_mfma_f32_16x16x32_bf16 v[20:23], v[218:221], v[194:197], v[20:23]
	v_mfma_f32_16x16x32_bf16 v[16:19], v[238:241], v[194:197], v[16:19]
	v_mfma_f32_16x16x32_bf16 v[12:15], v[218:221], v[202:205], v[12:15]
	v_mfma_f32_16x16x32_bf16 v[8:11], v[238:241], v[202:205], v[8:11]
	s_setprio 2
	s_barrier
	v_mfma_f32_16x16x32_bf16 v[4:7], v[218:221], v[210:213], v[4:7]
	v_mfma_f32_16x16x32_bf16 v[0:3], v[238:241], v[210:213], v[0:3]
	s_setprio 0
	v_readfirstlane_b32 s25, v151
	v_lshl_add_u64 v[214:215], v[226:227], 0, s[44:45]
	s_mov_b32 m0, s25
	v_readfirstlane_b32 s25, v152
	ds_read_b128 v[182:185], v146 offset:32768
	ds_read_b128 v[186:189], v146 offset:33792
	ds_read_b128 v[190:193], v146 offset:34816
	ds_read_b128 v[194:197], v146 offset:35840
	ds_read_b128 v[198:201], v146 offset:36864
	ds_read_b128 v[202:205], v146 offset:37888
	ds_read_b128 v[206:209], v146 offset:38912
	ds_read_b128 v[210:213], v146 offset:39936
	global_load_lds_dwordx4 v[214:215], off
	v_lshl_add_u64 v[214:215], v[234:235], 0, s[44:45]
	s_mov_b32 m0, s25
	s_nop 0
	global_load_lds_dwordx4 v[214:215], off
	s_waitcnt lgkmcnt(8)
	s_barrier
	s_waitcnt lgkmcnt(0)
	s_setprio 1
	s_waitcnt lgkmcnt(0)
	v_mfma_f32_16x16x32_bf16 v[124:127], v[162:165], v[182:185], v[124:127]
	v_mfma_f32_16x16x32_bf16 v[120:123], v[170:173], v[182:185], v[120:123]
	v_mfma_f32_16x16x32_bf16 v[116:119], v[162:165], v[190:193], v[116:119]
	v_mfma_f32_16x16x32_bf16 v[112:115], v[170:173], v[190:193], v[112:115]
	v_mfma_f32_16x16x32_bf16 v[108:111], v[162:165], v[198:201], v[108:111]
	v_mfma_f32_16x16x32_bf16 v[104:107], v[170:173], v[198:201], v[104:107]
	v_mfma_f32_16x16x32_bf16 v[100:103], v[162:165], v[206:209], v[100:103]
	v_mfma_f32_16x16x32_bf16 v[96:99], v[170:173], v[206:209], v[96:99]
	v_mfma_f32_16x16x32_bf16 v[124:127], v[166:169], v[186:189], v[124:127]
	v_mfma_f32_16x16x32_bf16 v[120:123], v[174:177], v[186:189], v[120:123]
	v_mfma_f32_16x16x32_bf16 v[116:119], v[166:169], v[194:197], v[116:119]
	v_mfma_f32_16x16x32_bf16 v[112:115], v[174:177], v[194:197], v[112:115]
	v_mfma_f32_16x16x32_bf16 v[108:111], v[166:169], v[202:205], v[108:111]
	v_mfma_f32_16x16x32_bf16 v[104:107], v[174:177], v[202:205], v[104:107]
	s_setprio 2
	s_barrier
	v_mfma_f32_16x16x32_bf16 v[100:103], v[166:169], v[210:213], v[100:103]
	v_mfma_f32_16x16x32_bf16 v[96:99], v[174:177], v[210:213], v[96:99]
	s_setprio 0
	v_readfirstlane_b32 s25, v153
	v_lshl_add_u64 v[178:179], v[178:179], 0, s[46:47]
	s_mov_b32 m0, s25
	v_readfirstlane_b32 s25, v154
	ds_read_b128 v[214:217], v149 offset:49152
	ds_read_b128 v[218:221], v149 offset:50176
	ds_read_b128 v[230:233], v149 offset:51200
	ds_read_b128 v[238:241], v149 offset:52224
	global_load_lds_dwordx4 v[178:179], off
	v_lshl_add_u64 v[178:179], v[222:223], 0, s[46:47]
	s_mov_b32 m0, s25
	s_nop 0
	global_load_lds_dwordx4 v[178:179], off
	s_barrier
	s_waitcnt lgkmcnt(0)
	s_setprio 1
	s_waitcnt lgkmcnt(0)
	v_mfma_f32_16x16x32_bf16 v[92:95], v[214:217], v[182:185], v[92:95]
	v_mfma_f32_16x16x32_bf16 v[88:91], v[230:233], v[182:185], v[88:91]
	v_mfma_f32_16x16x32_bf16 v[84:87], v[214:217], v[190:193], v[84:87]
	v_mfma_f32_16x16x32_bf16 v[80:83], v[230:233], v[190:193], v[80:83]
	v_mfma_f32_16x16x32_bf16 v[76:79], v[214:217], v[198:201], v[76:79]
	v_mfma_f32_16x16x32_bf16 v[72:75], v[230:233], v[198:201], v[72:75]
	v_mfma_f32_16x16x32_bf16 v[68:71], v[214:217], v[206:209], v[68:71]
	v_mfma_f32_16x16x32_bf16 v[64:67], v[230:233], v[206:209], v[64:67]
	v_mfma_f32_16x16x32_bf16 v[92:95], v[218:221], v[186:189], v[92:95]
	v_mfma_f32_16x16x32_bf16 v[88:91], v[238:241], v[186:189], v[88:91]
	v_mfma_f32_16x16x32_bf16 v[84:87], v[218:221], v[194:197], v[84:87]
	v_mfma_f32_16x16x32_bf16 v[80:83], v[238:241], v[194:197], v[80:83]
	v_mfma_f32_16x16x32_bf16 v[76:79], v[218:221], v[202:205], v[76:79]
	v_mfma_f32_16x16x32_bf16 v[72:75], v[238:241], v[202:205], v[72:75]
	s_setprio 2
	s_barrier
; #define STAGE_A(P, br, kt) do { const char* _base = (const char*)(((kt) < G.ksplit ? G.A1 : A2m) + (long)(br) * G.lda + (long)(kt) * BK); \
;     __builtin_amdgcn_global_load_lds((const unsigned*)(_base + aoff0), (unsigned*)((char*)(P) + sb0), 16, 0, 0); \
;     __builtin_amdgcn_global_load_lds((const unsigned*)(_base + aoff1), (unsigned*)((char*)(P) + sb1), 16, 0, 0); } while (0)
; #define STAGE_B(P, br, kt) do { const char* _base = (const char*)(G.Bt + (long)(br) * G.ldb + (long)(kt) * BK); \
;     __builtin_amdgcn_global_load_lds((const unsigned*)(_base + boff0), (unsigned*)((char*)(P) + sb0), 16, 0, 0); \
;     __builtin_amdgcn_global_load_lds((const unsigned*)(_base + boff1), (unsigned*)((char*)(P) + sb1), 16, 0, 0); } while (0)
; #define LDA(dst, b, h) for (int m = 0; m < 4; ++m) for (int k = 0; k < 2; ++k) \
;     dst[m][k] = *reinterpret_cast<const bf16x8*>(a_rd + ((b) * 2 + (h)) * (HT * 2) + m * 2048 + k * 1024)
; #define LDB(dst, b, h) for (int n = 0; n < 2; ++n) for (int k = 0; k < 2; ++k) \
;     dst[n][k] = *reinterpret_cast<const bf16x8*>(b_rd + ((b) * 2 + (h)) * (HT * 2) + n * 2048 + k * 1024)
; #define MMA(ai, bj, At_, Bt_) do { __builtin_amdgcn_s_setprio(1); \
;     for (int m = 0; m < 4; ++m) for (int n = 0; n < 2; ++n) for (int k = 0; k < 2; ++k) \
;       acc[ai][bj][m][n] = __builtin_amdgcn_mfma_f32_16x16x32_bf16(Bt_[n][k], At_[m][k], acc[ai][bj][m][n], 0, 0, 0); \
;     __builtin_amdgcn_s_setprio(0); } while (0)
; #define WAIT_V(n) asm volatile("s_waitcnt vmcnt(" #n ")" ::: "memory")
; #define WAIT_L(n) asm volatile("s_waitcnt lgkmcnt(" #n ")" ::: "memory")
; #define BAR __builtin_amdgcn_s_barrier()
; #define SCHED __builtin_amdgcn_sched_barrier(0)
;     ...
;     LDB(B1, 1, 1); STAGE_B(SB(1, 0), bcol, t + 3);
;     BAR; WAIT_L(0); MMA(0, 1, At, B1); BAR;
;     LDA(At, 1, 1); STAGE_A(SA(1, 0), brow, t + 3);
;     BAR; WAIT_L(0); MMA(1, 0, At, B0); BAR; SCHED;
;     STAGE_B(SB(1, 1), bcol + HALF, t + 3);
;     WAIT_V(6); BAR; MMA(1, 1, At, B1); BAR;
;   }
;   float ssv[2][4] = {};
;   if constexpr (EPI == EPI_GU || EPI == EPI_EVIN || EPI == EPI_ODIN) {
; #pragma unroll
;     for (int ai = 0; ai < 2; ++ai)
; #pragma unroll
;       for (int m = 0; m < 4; ++m) ssv[ai][m] = G.ssr[brow + ai * HALF + wr * 64 + m * 16 + fr];
;   }
;   { LDB(B0, 0, 0); LDA(At, 0, 0); STAGE_A(SA(1, 1), brow + HALF, nt - 1);
;     BAR; WAIT_L(0); MMA(0, 0, At, B0); BAR;
	v_mfma_f32_16x16x32_bf16 v[68:71], v[218:221], v[210:213], v[68:71]
	v_mfma_f32_16x16x32_bf16 v[64:67], v[238:241], v[210:213], v[64:67]
	s_setprio 0
	s_cmp_lt_u32 s24, 13
	s_cselect_b32 s27, s30, s36
	s_cselect_b32 s26, s29, s35
	v_lshl_add_u64 v[178:179], s[26:27], 0, v[136:137]
	v_lshl_add_u64 v[178:179], v[178:179], 0, s[10:11]
	v_readfirstlane_b32 s25, v155
	v_lshl_add_u64 v[178:179], v[178:179], 0, s[88:89]
	s_mov_b32 m0, s25
	ds_read_b128 v[182:185], v146 offset:49152
	ds_read_b128 v[186:189], v146 offset:50176
	ds_read_b128 v[190:193], v146 offset:51200
	ds_read_b128 v[194:197], v146 offset:52224
	ds_read_b128 v[198:201], v146 offset:53248
	ds_read_b128 v[202:205], v146 offset:54272
	ds_read_b128 v[206:209], v146 offset:55296
	ds_read_b128 v[210:213], v146 offset:56320
	global_load_lds_dwordx4 v[178:179], off
	v_lshl_add_u64 v[178:179], s[26:27], 0, v[138:139]
	v_lshl_add_u64 v[178:179], v[178:179], 0, s[10:11]
	v_readfirstlane_b32 s25, v156
	v_lshl_add_u64 v[178:179], v[178:179], 0, s[88:89]
	s_mov_b32 m0, s25
	s_nop 0
	global_load_lds_dwordx4 v[178:179], off
	s_waitcnt vmcnt(10)
	s_barrier
	s_waitcnt lgkmcnt(0)
	s_setprio 1
	s_waitcnt lgkmcnt(0)
	v_mfma_f32_16x16x32_bf16 v[60:63], v[162:165], v[182:185], v[60:63]
	v_mfma_f32_16x16x32_bf16 v[56:59], v[170:173], v[182:185], v[56:59]
	v_mfma_f32_16x16x32_bf16 v[52:55], v[162:165], v[190:193], v[52:55]
	v_mfma_f32_16x16x32_bf16 v[48:51], v[170:173], v[190:193], v[48:51]
	v_mfma_f32_16x16x32_bf16 v[44:47], v[162:165], v[198:201], v[44:47]
	v_mfma_f32_16x16x32_bf16 v[40:43], v[170:173], v[198:201], v[40:43]
	v_mfma_f32_16x16x32_bf16 v[36:39], v[162:165], v[206:209], v[36:39]
	v_mfma_f32_16x16x32_bf16 v[32:35], v[170:173], v[206:209], v[32:35]
	v_mfma_f32_16x16x32_bf16 v[60:63], v[166:169], v[186:189], v[60:63]
	v_mfma_f32_16x16x32_bf16 v[56:59], v[174:177], v[186:189], v[56:59]
	v_mfma_f32_16x16x32_bf16 v[52:55], v[166:169], v[194:197], v[52:55]
	v_mfma_f32_16x16x32_bf16 v[48:51], v[174:177], v[194:197], v[48:51]
	v_mfma_f32_16x16x32_bf16 v[44:47], v[166:169], v[202:205], v[44:47]
	v_mfma_f32_16x16x32_bf16 v[40:43], v[174:177], v[202:205], v[40:43]
	s_setprio 2
	s_barrier
	v_mfma_f32_16x16x32_bf16 v[36:39], v[166:169], v[210:213], v[36:39]
	v_mfma_f32_16x16x32_bf16 v[32:35], v[174:177], v[210:213], v[32:35]
	s_setprio 0
	v_readfirstlane_b32 s25, v157
	v_lshl_add_u64 v[162:163], v[236:237], 0, s[48:49]
	s_mov_b32 m0, s25
	v_readfirstlane_b32 s25, v158
	global_load_lds_dwordx4 v[162:163], off
	v_lshl_add_u64 v[162:163], v[246:247], 0, s[48:49]
	s_mov_b32 m0, s25
	s_nop 0
	global_load_lds_dwordx4 v[162:163], off
	ds_read_b128 v[162:165], v149
	ds_read_b128 v[166:169], v149 offset:1024
	ds_read_b128 v[170:173], v149 offset:2048
	ds_read_b128 v[174:177], v149 offset:3072
	s_waitcnt vmcnt(6)
	s_barrier
	s_setprio 1
	v_mfma_f32_16x16x32_bf16 v[28:31], v[214:217], v[182:185], v[28:31]
	v_mfma_f32_16x16x32_bf16 v[24:27], v[230:233], v[182:185], v[24:27]
	v_mfma_f32_16x16x32_bf16 v[20:23], v[214:217], v[190:193], v[20:23]
	v_mfma_f32_16x16x32_bf16 v[16:19], v[230:233], v[190:193], v[16:19]
	v_mfma_f32_16x16x32_bf16 v[12:15], v[214:217], v[198:201], v[12:15]
	v_mfma_f32_16x16x32_bf16 v[8:11], v[230:233], v[198:201], v[8:11]
	v_mfma_f32_16x16x32_bf16 v[4:7], v[214:217], v[206:209], v[4:7]
	v_mfma_f32_16x16x32_bf16 v[0:3], v[230:233], v[206:209], v[0:3]
	v_mfma_f32_16x16x32_bf16 v[28:31], v[218:221], v[186:189], v[28:31]
	v_mfma_f32_16x16x32_bf16 v[24:27], v[238:241], v[186:189], v[24:27]
	v_mfma_f32_16x16x32_bf16 v[20:23], v[218:221], v[194:197], v[20:23]
	v_mfma_f32_16x16x32_bf16 v[16:19], v[238:241], v[194:197], v[16:19]
	v_mfma_f32_16x16x32_bf16 v[12:15], v[218:221], v[202:205], v[12:15]
	v_mfma_f32_16x16x32_bf16 v[8:11], v[238:241], v[202:205], v[8:11]
	s_setprio 2
	s_barrier
	v_mfma_f32_16x16x32_bf16 v[4:7], v[218:221], v[210:213], v[4:7]
	v_mfma_f32_16x16x32_bf16 v[0:3], v[238:241], v[210:213], v[0:3]
	s_setprio 0
	s_add_u32 s10, s10, 0x100
	s_addc_u32 s11, s11, 0
	s_cmp_lt_u32 s24, 28
	s_cbranch_scc1 .LBB0_1801
	s_waitcnt lgkmcnt(0)
	s_lshl_b64 s[8:9], s[8:9], 1
	s_add_u32 s8, s35, s8
	s_addc_u32 s9, s36, s9
	v_lshl_add_u64 v[130:131], s[8:9], 0, v[130:131]
	s_mov_b64 s[24:25], 0xf80
	v_readfirstlane_b32 s10, v159
	v_lshl_add_u64 v[130:131], v[130:131], 0, s[24:25]
	s_mov_b32 m0, s10
	v_lshl_add_u64 v[128:129], s[8:9], 0, v[128:129]
	v_readfirstlane_b32 s8, v160
	ds_read_b128 v[132:135], v149
	ds_read_b128 v[136:139], v149 offset:1024
	ds_read_b128 v[140:143], v149 offset:2048
	ds_read_b128 v[150:153], v149 offset:3072
	ds_read_b128 v[154:157], v146
	ds_read_b128 v[162:165], v146 offset:1024
	ds_read_b128 v[166:169], v146 offset:2048
	ds_read_b128 v[170:173], v146 offset:3072
	ds_read_b128 v[174:177], v146 offset:4096
	ds_read_b128 v[182:185], v146 offset:5120
	ds_read_b128 v[186:189], v146 offset:6144
	ds_read_b128 v[190:193], v146 offset:7168
	global_load_lds_dwordx4 v[130:131], off
	v_lshl_add_u64 v[128:129], v[128:129], 0, s[24:25]
	s_mov_b32 m0, s8
	s_nop 0
	global_load_lds_dwordx4 v[128:129], off
	s_barrier
	s_waitcnt lgkmcnt(0)
	s_setprio 1
	s_waitcnt lgkmcnt(0)
	v_mfma_f32_16x16x32_bf16 v[124:127], v[132:135], v[154:157], v[124:127]
	v_mfma_f32_16x16x32_bf16 v[120:123], v[140:143], v[154:157], v[120:123]
	v_mfma_f32_16x16x32_bf16 v[116:119], v[132:135], v[166:169], v[116:119]
	v_mfma_f32_16x16x32_bf16 v[112:115], v[140:143], v[166:169], v[112:115]
	v_mfma_f32_16x16x32_bf16 v[108:111], v[132:135], v[174:177], v[108:111]
	v_mfma_f32_16x16x32_bf16 v[104:107], v[140:143], v[174:177], v[104:107]
	v_mfma_f32_16x16x32_bf16 v[100:103], v[132:135], v[186:189], v[100:103]
	v_mfma_f32_16x16x32_bf16 v[96:99], v[140:143], v[186:189], v[96:99]
	v_mfma_f32_16x16x32_bf16 v[124:127], v[136:139], v[162:165], v[124:127]
	v_mfma_f32_16x16x32_bf16 v[120:123], v[150:153], v[162:165], v[120:123]
	v_mfma_f32_16x16x32_bf16 v[116:119], v[136:139], v[170:173], v[116:119]
	v_mfma_f32_16x16x32_bf16 v[112:115], v[150:153], v[170:173], v[112:115]
	v_mfma_f32_16x16x32_bf16 v[108:111], v[136:139], v[182:185], v[108:111]
	v_mfma_f32_16x16x32_bf16 v[104:107], v[150:153], v[182:185], v[104:107]
	s_setprio 2
	s_barrier
; #define LDA(dst, b, h) for (int m = 0; m < 4; ++m) for (int k = 0; k < 2; ++k) \
;     dst[m][k] = *reinterpret_cast<const bf16x8*>(a_rd + ((b) * 2 + (h)) * (HT * 2) + m * 2048 + k * 1024)
; #define LDB(dst, b, h) for (int n = 0; n < 2; ++n) for (int k = 0; k < 2; ++k) \
;     dst[n][k] = *reinterpret_cast<const bf16x8*>(b_rd + ((b) * 2 + (h)) * (HT * 2) + n * 2048 + k * 1024)
; #define MMA(ai, bj, At_, Bt_) do { __builtin_amdgcn_s_setprio(1); \
;     for (int m = 0; m < 4; ++m) for (int n = 0; n < 2; ++n) for (int k = 0; k < 2; ++k) \
;       acc[ai][bj][m][n] = __builtin_amdgcn_mfma_f32_16x16x32_bf16(Bt_[n][k], At_[m][k], acc[ai][bj][m][n], 0, 0, 0); \
;     __builtin_amdgcn_s_setprio(0); } while (0)
; #define WAIT_V(n) asm volatile("s_waitcnt vmcnt(" #n ")" ::: "memory")
; #define WAIT_L(n) asm volatile("s_waitcnt lgkmcnt(" #n ")" ::: "memory")
; #define BAR __builtin_amdgcn_s_barrier()
;     ...
;     BAR; WAIT_L(0); MMA(0, 0, At, B0); BAR;
;     LDB(B1, 0, 1); BAR; WAIT_L(0); MMA(0, 1, At, B1); BAR;
;     LDA(At, 0, 1); WAIT_V(4); BAR; WAIT_L(0); MMA(1, 0, At, B0); MMA(1, 1, At, B1); BAR; }
;   { LDB(B0, 1, 0); LDA(At, 1, 0); WAIT_V(2); BAR; WAIT_L(0); MMA(0, 0, At, B0); BAR;
	v_mfma_f32_16x16x32_bf16 v[100:103], v[136:139], v[190:193], v[100:103]
	v_mfma_f32_16x16x32_bf16 v[96:99], v[150:153], v[190:193], v[96:99]
	s_setprio 0
	ds_read_b128 v[128:131], v149 offset:16384
	ds_read_b128 v[158:161], v149 offset:17408
	ds_read_b128 v[194:197], v149 offset:18432
	ds_read_b128 v[198:201], v149 offset:19456
	s_barrier
	s_waitcnt lgkmcnt(0)
	s_setprio 1
	s_waitcnt lgkmcnt(0)
	v_mfma_f32_16x16x32_bf16 v[92:95], v[128:131], v[154:157], v[92:95]
	v_mfma_f32_16x16x32_bf16 v[88:91], v[194:197], v[154:157], v[88:91]
	v_mfma_f32_16x16x32_bf16 v[84:87], v[128:131], v[166:169], v[84:87]
	v_mfma_f32_16x16x32_bf16 v[80:83], v[194:197], v[166:169], v[80:83]
	v_mfma_f32_16x16x32_bf16 v[76:79], v[128:131], v[174:177], v[76:79]
	v_mfma_f32_16x16x32_bf16 v[72:75], v[194:197], v[174:177], v[72:75]
	v_mfma_f32_16x16x32_bf16 v[68:71], v[128:131], v[186:189], v[68:71]
	v_mfma_f32_16x16x32_bf16 v[64:67], v[194:197], v[186:189], v[64:67]
	v_mfma_f32_16x16x32_bf16 v[202:205], v[158:161], v[162:165], v[92:95]
	v_mfma_f32_16x16x32_bf16 v[154:157], v[198:201], v[162:165], v[88:91]
	v_mfma_f32_16x16x32_bf16 v[162:165], v[158:161], v[170:173], v[84:87]
	v_mfma_f32_16x16x32_bf16 v[166:169], v[198:201], v[170:173], v[80:83]
	v_mfma_f32_16x16x32_bf16 v[170:173], v[158:161], v[182:185], v[76:79]
	v_mfma_f32_16x16x32_bf16 v[174:177], v[198:201], v[182:185], v[72:75]
	s_setprio 2
	s_barrier
	v_mfma_f32_16x16x32_bf16 v[182:185], v[158:161], v[190:193], v[68:71]
	v_mfma_f32_16x16x32_bf16 v[186:189], v[198:201], v[190:193], v[64:67]
	s_setprio 0
	s_nop 0
	ds_read_b128 v[64:67], v146 offset:16384
	ds_read_b128 v[68:71], v146 offset:17408
	ds_read_b128 v[72:75], v146 offset:18432
	ds_read_b128 v[76:79], v146 offset:19456
	ds_read_b128 v[80:83], v146 offset:20480
	ds_read_b128 v[84:87], v146 offset:21504
	ds_read_b128 v[88:91], v146 offset:22528
	ds_read_b128 v[92:95], v146 offset:23552
	s_waitcnt vmcnt(4)
	s_barrier
	s_waitcnt lgkmcnt(0)
	s_setprio 1
	s_waitcnt lgkmcnt(0)
	v_mfma_f32_16x16x32_bf16 v[60:63], v[132:135], v[64:67], v[60:63]
	v_mfma_f32_16x16x32_bf16 v[56:59], v[140:143], v[64:67], v[56:59]
	v_mfma_f32_16x16x32_bf16 v[52:55], v[132:135], v[72:75], v[52:55]
	v_mfma_f32_16x16x32_bf16 v[48:51], v[140:143], v[72:75], v[48:51]
	v_mfma_f32_16x16x32_bf16 v[44:47], v[132:135], v[80:83], v[44:47]
	v_mfma_f32_16x16x32_bf16 v[40:43], v[140:143], v[80:83], v[40:43]
	v_mfma_f32_16x16x32_bf16 v[36:39], v[132:135], v[88:91], v[36:39]
	v_mfma_f32_16x16x32_bf16 v[32:35], v[140:143], v[88:91], v[32:35]
	v_mfma_f32_16x16x32_bf16 v[60:63], v[136:139], v[68:71], v[60:63]
	v_mfma_f32_16x16x32_bf16 v[56:59], v[150:153], v[68:71], v[56:59]
	v_mfma_f32_16x16x32_bf16 v[52:55], v[136:139], v[76:79], v[52:55]
	v_mfma_f32_16x16x32_bf16 v[48:51], v[150:153], v[76:79], v[48:51]
	v_mfma_f32_16x16x32_bf16 v[44:47], v[136:139], v[84:87], v[44:47]
	v_mfma_f32_16x16x32_bf16 v[40:43], v[150:153], v[84:87], v[40:43]
	v_mfma_f32_16x16x32_bf16 v[36:39], v[136:139], v[92:95], v[36:39]
	v_mfma_f32_16x16x32_bf16 v[32:35], v[150:153], v[92:95], v[32:35]
	s_setprio 0
	s_setprio 1
	v_mfma_f32_16x16x32_bf16 v[28:31], v[128:131], v[64:67], v[28:31]
	v_mfma_f32_16x16x32_bf16 v[24:27], v[194:197], v[64:67], v[24:27]
	v_mfma_f32_16x16x32_bf16 v[20:23], v[128:131], v[72:75], v[20:23]
	v_mfma_f32_16x16x32_bf16 v[16:19], v[194:197], v[72:75], v[16:19]
	v_mfma_f32_16x16x32_bf16 v[12:15], v[128:131], v[80:83], v[12:15]
	v_mfma_f32_16x16x32_bf16 v[8:11], v[194:197], v[80:83], v[8:11]
	v_mfma_f32_16x16x32_bf16 v[4:7], v[128:131], v[88:91], v[4:7]
	v_mfma_f32_16x16x32_bf16 v[0:3], v[194:197], v[88:91], v[0:3]
	v_mfma_f32_16x16x32_bf16 v[132:135], v[158:161], v[68:71], v[28:31]
	v_mfma_f32_16x16x32_bf16 v[136:139], v[198:201], v[68:71], v[24:27]
	v_mfma_f32_16x16x32_bf16 v[140:143], v[158:161], v[76:79], v[20:23]
	v_mfma_f32_16x16x32_bf16 v[150:153], v[198:201], v[76:79], v[16:19]
	v_mfma_f32_16x16x32_bf16 v[190:193], v[158:161], v[84:87], v[12:15]
	v_mfma_f32_16x16x32_bf16 v[206:209], v[198:201], v[84:87], v[8:11]
	s_setprio 2
	s_barrier
	v_mfma_f32_16x16x32_bf16 v[128:131], v[158:161], v[92:95], v[4:7]
	v_mfma_f32_16x16x32_bf16 v[158:161], v[198:201], v[92:95], v[0:3]
	s_setprio 0
	ds_read_b128 v[24:27], v149 offset:32768
	ds_read_b128 v[28:31], v149 offset:33792
	ds_read_b128 v[194:197], v149 offset:34816
	ds_read_b128 v[198:201], v149 offset:35840
	ds_read_b128 v[0:3], v146 offset:32768
	ds_read_b128 v[4:7], v146 offset:33792
	ds_read_b128 v[8:11], v146 offset:34816
	ds_read_b128 v[12:15], v146 offset:35840
	ds_read_b128 v[16:19], v146 offset:36864
	ds_read_b128 v[20:23], v146 offset:37888
	ds_read_b128 v[210:213], v146 offset:38912
	ds_read_b128 v[214:217], v146 offset:39936
	s_waitcnt vmcnt(2)
	s_barrier
; #define LDA(dst, b, h) for (int m = 0; m < 4; ++m) for (int k = 0; k < 2; ++k) \
;     dst[m][k] = *reinterpret_cast<const bf16x8*>(a_rd + ((b) * 2 + (h)) * (HT * 2) + m * 2048 + k * 1024)
; #define LDB(dst, b, h) for (int n = 0; n < 2; ++n) for (int k = 0; k < 2; ++k) \
;     dst[n][k] = *reinterpret_cast<const bf16x8*>(b_rd + ((b) * 2 + (h)) * (HT * 2) + n * 2048 + k * 1024)
; #define MMA(ai, bj, At_, Bt_) do { __builtin_amdgcn_s_setprio(1); \
;     for (int m = 0; m < 4; ++m) for (int n = 0; n < 2; ++n) for (int k = 0; k < 2; ++k) \
;       acc[ai][bj][m][n] = __builtin_amdgcn_mfma_f32_16x16x32_bf16(Bt_[n][k], At_[m][k], acc[ai][bj][m][n], 0, 0, 0); \
;     __builtin_amdgcn_s_setprio(0); } while (0)
; #define WAIT_V(n) asm volatile("s_waitcnt vmcnt(" #n ")" ::: "memory")
; #define WAIT_L(n) asm volatile("s_waitcnt lgkmcnt(" #n ")" ::: "memory")
; #define BAR __builtin_amdgcn_s_barrier()
;     ...
;   { LDB(B0, 1, 0); LDA(At, 1, 0); WAIT_V(2); BAR; WAIT_L(0); MMA(0, 0, At, B0); BAR;
;     LDB(B1, 1, 1); WAIT_V(0); BAR; WAIT_L(0); MMA(0, 1, At, B1); BAR;
;     LDA(At, 1, 1); BAR; WAIT_L(0); MMA(1, 0, At, B0); MMA(1, 1, At, B1); BAR; }
;   if (wr == 0) BAR;
	s_waitcnt lgkmcnt(0)
	s_setprio 1
	s_waitcnt lgkmcnt(0)
	v_mfma_f32_16x16x32_bf16 v[64:67], v[24:27], v[0:3], v[124:127]
	v_mfma_f32_16x16x32_bf16 v[68:71], v[194:197], v[0:3], v[120:123]
	v_mfma_f32_16x16x32_bf16 v[72:75], v[24:27], v[8:11], v[116:119]
	v_mfma_f32_16x16x32_bf16 v[76:79], v[194:197], v[8:11], v[112:115]
	v_mfma_f32_16x16x32_bf16 v[80:83], v[24:27], v[16:19], v[108:111]
	v_mfma_f32_16x16x32_bf16 v[84:87], v[194:197], v[16:19], v[104:107]
	v_mfma_f32_16x16x32_bf16 v[88:91], v[24:27], v[210:213], v[100:103]
	v_mfma_f32_16x16x32_bf16 v[92:95], v[194:197], v[210:213], v[96:99]
	v_mfma_f32_16x16x32_bf16 v[64:67], v[28:31], v[4:7], v[64:67]
	v_mfma_f32_16x16x32_bf16 v[68:71], v[198:201], v[4:7], v[68:71]
	v_mfma_f32_16x16x32_bf16 v[72:75], v[28:31], v[12:15], v[72:75]
	v_mfma_f32_16x16x32_bf16 v[76:79], v[198:201], v[12:15], v[76:79]
	v_mfma_f32_16x16x32_bf16 v[80:83], v[28:31], v[20:23], v[80:83]
	v_mfma_f32_16x16x32_bf16 v[84:87], v[198:201], v[20:23], v[84:87]
	s_setprio 2
	s_barrier
	v_mfma_f32_16x16x32_bf16 v[88:91], v[28:31], v[214:217], v[88:91]
	v_mfma_f32_16x16x32_bf16 v[92:95], v[198:201], v[214:217], v[92:95]
	s_setprio 0
	ds_read_b128 v[218:221], v149 offset:49152
	ds_read_b128 v[230:233], v149 offset:50176
	ds_read_b128 v[238:241], v149 offset:51200
	ds_read_b128 v[246:249], v149 offset:52224
	s_waitcnt vmcnt(0)
	s_barrier
	s_waitcnt lgkmcnt(0)
	s_setprio 1
	s_waitcnt lgkmcnt(0)
	v_mfma_f32_16x16x32_bf16 v[96:99], v[218:221], v[0:3], v[202:205]
	v_mfma_f32_16x16x32_bf16 v[0:3], v[238:241], v[0:3], v[154:157]
	v_mfma_f32_16x16x32_bf16 v[100:103], v[246:249], v[4:7], v[0:3]
	v_mfma_f32_16x16x32_bf16 v[0:3], v[218:221], v[8:11], v[162:165]
	v_mfma_f32_16x16x32_bf16 v[104:107], v[230:233], v[12:15], v[0:3]
	v_mfma_f32_16x16x32_bf16 v[0:3], v[238:241], v[8:11], v[166:169]
	v_mfma_f32_16x16x32_bf16 v[108:111], v[246:249], v[12:15], v[0:3]
	v_mfma_f32_16x16x32_bf16 v[0:3], v[218:221], v[16:19], v[170:173]
	v_mfma_f32_16x16x32_bf16 v[112:115], v[230:233], v[20:23], v[0:3]
	v_mfma_f32_16x16x32_bf16 v[0:3], v[238:241], v[16:19], v[174:177]
	v_mfma_f32_16x16x32_bf16 v[116:119], v[246:249], v[20:23], v[0:3]
	v_mfma_f32_16x16x32_bf16 v[0:3], v[218:221], v[210:213], v[182:185]
	v_mfma_f32_16x16x32_bf16 v[120:123], v[230:233], v[214:217], v[0:3]
	v_mfma_f32_16x16x32_bf16 v[0:3], v[238:241], v[210:213], v[186:189]
	s_setprio 2
	s_barrier
	v_mfma_f32_16x16x32_bf16 v[96:99], v[230:233], v[4:7], v[96:99]
	v_mfma_f32_16x16x32_bf16 v[124:127], v[246:249], v[214:217], v[0:3]
	s_setprio 0
	ds_read_b128 v[154:157], v146 offset:49152
	ds_read_b128 v[162:165], v146 offset:50176
	ds_read_b128 v[166:169], v146 offset:51200
	ds_read_b128 v[170:173], v146 offset:52224
	ds_read_b128 v[174:177], v146 offset:53248
	ds_read_b128 v[182:185], v146 offset:54272
	ds_read_b128 v[186:189], v146 offset:55296
	ds_read_b128 v[146:149], v146 offset:56320
	s_barrier
	s_waitcnt lgkmcnt(0)
	s_setprio 1
	s_waitcnt lgkmcnt(0)
	v_mfma_f32_16x16x32_bf16 v[0:3], v[24:27], v[154:157], v[60:63]
	v_mfma_f32_16x16x32_bf16 v[8:11], v[24:27], v[166:169], v[52:55]
	v_mfma_f32_16x16x32_bf16 v[16:19], v[24:27], v[174:177], v[44:47]
	v_mfma_f32_16x16x32_bf16 v[24:27], v[24:27], v[186:189], v[36:39]
	v_mfma_f32_16x16x32_bf16 v[0:3], v[28:31], v[162:165], v[0:3]
	v_mfma_f32_16x16x32_bf16 v[4:7], v[194:197], v[154:157], v[56:59]
	v_mfma_f32_16x16x32_bf16 v[8:11], v[28:31], v[170:173], v[8:11]
	v_mfma_f32_16x16x32_bf16 v[12:15], v[194:197], v[166:169], v[48:51]
	v_mfma_f32_16x16x32_bf16 v[16:19], v[28:31], v[182:185], v[16:19]
	v_mfma_f32_16x16x32_bf16 v[20:23], v[194:197], v[174:177], v[40:43]
	v_mfma_f32_16x16x32_bf16 v[24:27], v[28:31], v[146:149], v[24:27]
	v_mfma_f32_16x16x32_bf16 v[28:31], v[194:197], v[186:189], v[32:35]
	v_mfma_f32_16x16x32_bf16 v[4:7], v[198:201], v[162:165], v[4:7]
	v_mfma_f32_16x16x32_bf16 v[12:15], v[198:201], v[170:173], v[12:15]
	v_mfma_f32_16x16x32_bf16 v[20:23], v[198:201], v[182:185], v[20:23]
	v_mfma_f32_16x16x32_bf16 v[28:31], v[198:201], v[146:149], v[28:31]
	s_setprio 0
	s_setprio 1
	v_mfma_f32_16x16x32_bf16 v[32:35], v[218:221], v[154:157], v[132:135]
	v_mfma_f32_16x16x32_bf16 v[36:39], v[238:241], v[154:157], v[136:139]
	v_mfma_f32_16x16x32_bf16 v[40:43], v[218:221], v[166:169], v[140:143]
	v_mfma_f32_16x16x32_bf16 v[44:47], v[238:241], v[166:169], v[150:153]
	v_mfma_f32_16x16x32_bf16 v[48:51], v[218:221], v[174:177], v[190:193]
	v_mfma_f32_16x16x32_bf16 v[52:55], v[238:241], v[174:177], v[206:209]
	v_mfma_f32_16x16x32_bf16 v[56:59], v[218:221], v[186:189], v[128:131]
	v_mfma_f32_16x16x32_bf16 v[60:63], v[238:241], v[186:189], v[158:161]
	v_mfma_f32_16x16x32_bf16 v[32:35], v[230:233], v[162:165], v[32:35]
	v_mfma_f32_16x16x32_bf16 v[36:39], v[246:249], v[162:165], v[36:39]
	v_mfma_f32_16x16x32_bf16 v[40:43], v[230:233], v[170:173], v[40:43]
	v_mfma_f32_16x16x32_bf16 v[44:47], v[246:249], v[170:173], v[44:47]
	v_mfma_f32_16x16x32_bf16 v[48:51], v[230:233], v[182:185], v[48:51]
	v_mfma_f32_16x16x32_bf16 v[52:55], v[246:249], v[182:185], v[52:55]
	s_setprio 2
	s_barrier
	v_mfma_f32_16x16x32_bf16 v[56:59], v[230:233], v[146:149], v[56:59]
	v_mfma_f32_16x16x32_bf16 v[60:63], v[246:249], v[146:149], v[60:63]
	s_setprio 0
	v_cmp_gt_u32_e32 vcc, s60, v144
	s_and_saveexec_b64 s[8:9], vcc
	s_cbranch_execz .LBB0_1804
	s_barrier

; #define STAGE_A(P, br, kt) do { const char* _base = (const char*)(((kt) < G.ksplit ? G.A1 : A2m) + (long)(br) * G.lda + (long)(kt) * BK); \
;     __builtin_amdgcn_global_load_lds((const unsigned*)(_base + aoff0), (unsigned*)((char*)(P) + sb0), 16, 0, 0); \
;     __builtin_amdgcn_global_load_lds((const unsigned*)(_base + aoff1), (unsigned*)((char*)(P) + sb1), 16, 0, 0); } while (0)
; #define STAGE_B(P, br, kt) do { const char* _base = (const char*)(G.Bt + (long)(br) * G.ldb + (long)(kt) * BK); \
;     __builtin_amdgcn_global_load_lds((const unsigned*)(_base + boff0), (unsigned*)((char*)(P) + sb0), 16, 0, 0); \
;     __builtin_amdgcn_global_load_lds((const unsigned*)(_base + boff1), (unsigned*)((char*)(P) + sb1), 16, 0, 0); } while (0)
; #define LDA(dst, b, h) for (int m = 0; m < 4; ++m) for (int k = 0; k < 2; ++k) \
;     dst[m][k] = *reinterpret_cast<const bf16x8*>(a_rd + ((b) * 2 + (h)) * (HT * 2) + m * 2048 + k * 1024)
; #define LDB(dst, b, h) for (int n = 0; n < 2; ++n) for (int k = 0; k < 2; ++k) \
;     dst[n][k] = *reinterpret_cast<const bf16x8*>(b_rd + ((b) * 2 + (h)) * (HT * 2) + n * 2048 + k * 1024)
;     ...
;   const int K = G.K;
;   const u16* A2m = G.A2 - (long)G.ksplit * BK;
;   int t1 = otid();
;   const int wid = t1 >> 6, lane = t1 & 63, wr = wid >> 2, wc = wid & 3, fr = lane & 15, fq = lane >> 4;
;   const int sb0 = t1 * 16, sb1 = sb0 + 8192;
;   const int swz_ = lds_byte(fr, fq * 8);
;   const char* a_rd = shmc + wr * 8192 + swz_;
;   const char* b_rd = shmc + 4 * (HT * 2) + wc * 4096 + swz_;
;   int r0_, c0_, r1_, c1_; stage_rc(sb0, r0_, c0_); stage_rc(sb1, r1_, c1_);
;   const unsigned aoff0 = (unsigned)(r0_ * G.lda + c0_) * 2u, aoff1 = (unsigned)(r1_ * G.lda + c1_) * 2u;
;   const unsigned boff0 = (unsigned)(r0_ * G.ldb + c0_) * 2u, boff1 = (unsigned)(r1_ * G.ldb + c1_) * 2u;
;   f32x4 acc[2][2][4][2] = {};
;   bf16x8 At[4][2], B0[2][2], B1[2][2];
;   const int nt = K / BK;
;   if (EPI == EPI_RESID || first) {
;     STAGE_B(SB(0, 0), bcol, 0); STAGE_A(SA(0, 0), brow, 0);
;     STAGE_B(SB(0, 1), bcol + HALF, 0); STAGE_A(SA(0, 1), brow + HALF, 0);
;   }
;   if (wr == 1) BAR;
;   WAIT_V(0); BAR;
;   STAGE_B(SB(1, 0), bcol, 1); STAGE_A(SA(1, 0), brow, 1); STAGE_B(SB(1, 1), bcol + HALF, 1);
;   WAIT_V(6); BAR;
;   for (int t = 0; t < nt - 2; t += 2) {
;     LDB(B0, 0, 0); SCHED; LDA(At, 0, 0); STAGE_A(SA(1, 1), brow + HALF, t + 1);
.LBB0_1864:
	s_or_b64 exec, exec, s[24:25]
	v_and_b32_e32 v144, 15, v139
	v_lshlrev_b32_e32 v10, 2, v139
	s_ashr_i32 s27, s26, 31
	s_lshr_b32 s25, s30, 3
	v_and_b32_e32 v8, 48, v139
	v_lshlrev_b32_e32 v9, 6, v144
	v_and_b32_e32 v10, 32, v10
	s_add_i32 s30, 32, 0x10000
	s_lshl_b32 s24, s31, 8
	s_lshl_b64 s[26:27], s[26:27], 1
	v_bitop3_b32 v10, v9, v10, v8 bitop3:0x36
	v_lshlrev_b32_e32 v8, 6, v139
	s_add_u32 s44, s39, s26
	v_readlane_b32 s31, v253, 46
	v_and_b32_e32 v8, 0x3000, v8
	s_addc_u32 s45, s40, s27
	v_add_u32_e32 v145, s31, v142
	s_waitcnt vmcnt(0)
	v_add_u32_e32 v12, s30, v8
	v_lshl_add_u64 v[8:9], s[44:45], 0, v[180:181]
	s_mov_b64 s[46:47], 0x80
	v_readfirstlane_b32 s31, v145
	v_lshl_add_u64 v[8:9], v[8:9], 0, s[46:47]
	s_mov_b32 m0, s31
	v_mov_b32_e32 v129, v181
	v_add_u32_e32 v150, 0x2000, v145
	s_waitcnt vmcnt(0)
	s_barrier
	global_load_lds_dwordx4 v[8:9], off
	v_lshl_add_u64 v[8:9], s[44:45], 0, v[128:129]
	v_readfirstlane_b32 s31, v150
	s_add_u32 s42, s37, s42
	v_lshl_add_u64 v[8:9], v[8:9], 0, s[46:47]
	s_mov_b32 m0, s31
	s_addc_u32 s43, s38, s35
	v_add_u32_e32 v151, 0x8000, v147
	global_load_lds_dwordx4 v[8:9], off
	v_lshl_add_u64 v[8:9], s[42:43], 0, v[180:181]
	v_readfirstlane_b32 s31, v151
	v_add_u32_e32 v152, 0xa000, v147
	v_lshl_add_u64 v[8:9], v[8:9], 0, s[46:47]
	s_mov_b32 m0, s31
	v_readfirstlane_b32 s31, v152
	global_load_lds_dwordx4 v[8:9], off
	s_mov_b32 m0, s31
	s_or_b32 s31, s24, 0x80
	v_lshl_add_u64 v[8:9], s[42:43], 0, v[128:129]
	s_mul_i32 s42, s31, 0x840
	s_ashr_i32 s43, s42, 31
	s_lshl_b64 s[42:43], s[42:43], 1
	s_add_u32 s42, s39, s42
	v_readlane_b32 s31, v253, 47
	v_lshl_add_u64 v[8:9], v[8:9], 0, s[46:47]
	s_addc_u32 s43, s40, s43
	v_add_u32_e32 v153, s31, v142
	global_load_lds_dwordx4 v[8:9], off
	v_lshl_add_u64 v[8:9], s[42:43], 0, v[180:181]
	v_readfirstlane_b32 s31, v153
	v_lshl_add_u64 v[8:9], v[8:9], 0, s[46:47]
	s_mov_b32 m0, s31
	v_add_u32_e32 v154, 0x2000, v153
	global_load_lds_dwordx4 v[8:9], off
	v_lshl_add_u64 v[8:9], s[42:43], 0, v[128:129]
	v_readfirstlane_b32 s31, v154
	v_lshl_add_u64 v[8:9], v[8:9], 0, s[46:47]
	s_mov_b32 m0, s31
	v_lshl_add_u32 v11, v143, 13, 32
	global_load_lds_dwordx4 v[8:9], off
	v_lshrrev_b32_e32 v8, 1, v0
	v_mul_lo_u32 v0, v1, s62
	v_mad_u64_u32 v[0:1], s[42:43], v8, s84, v[0:1]
	v_or_b32_e32 v0, v0, v2
	v_add_lshl_u32 v0, v0, v3, 1
	v_lshrrev_b32_e32 v3, 1, v4
	v_mul_lo_u32 v2, v5, s62
	v_mad_u64_u32 v[2:3], s[42:43], v3, s84, v[2:3]
	v_or_b32_e32 v2, v2, v6
	s_waitcnt vmcnt(6)
	v_mov_b32_e32 v1, v181
	v_add_lshl_u32 v2, v2, v7, 1
	v_mov_b32_e32 v3, v181
	v_lshl_add_u64 v[130:131], s[26:27], 0, v[0:1]
	v_lshl_add_u64 v[132:133], s[26:27], 0, v[2:3]
	v_mad_i64_i32 v[134:135], s[26:27], s29, v243, v[0:1]
	v_mad_i64_i32 v[136:137], s[26:27], s29, v243, v[2:3]
	v_mov_b32_e32 v0, 0
	s_mov_b32 s31, -2
	v_add_u32_e32 v149, v12, v10
	v_add_u32_e32 v148, v11, v10
	s_mov_b64 s[26:27], s[10:11]
	v_mov_b32_e32 v1, v0
	v_mov_b32_e32 v2, v0
	v_mov_b32_e32 v3, v0
	v_mov_b32_e32 v4, v0
	v_mov_b32_e32 v5, v0
	v_mov_b32_e32 v6, v0
	v_mov_b32_e32 v7, v0
	v_mov_b32_e32 v8, v0
	v_mov_b32_e32 v9, v0
	v_mov_b32_e32 v10, v0
	v_mov_b32_e32 v11, v0
	v_mov_b32_e32 v12, v0
	v_mov_b32_e32 v13, v0
	v_mov_b32_e32 v14, v0
	v_mov_b32_e32 v15, v0
	v_mov_b32_e32 v16, v0
	v_mov_b32_e32 v17, v0
	v_mov_b32_e32 v18, v0
	v_mov_b32_e32 v19, v0
	v_mov_b32_e32 v20, v0
	v_mov_b32_e32 v21, v0
	v_mov_b32_e32 v22, v0
	v_mov_b32_e32 v23, v0
	v_mov_b32_e32 v24, v0
	v_mov_b32_e32 v25, v0
	v_mov_b32_e32 v26, v0
	v_mov_b32_e32 v27, v0
	v_mov_b32_e32 v28, v0
	v_mov_b32_e32 v29, v0
	v_mov_b32_e32 v30, v0
	v_mov_b32_e32 v31, v0
	v_mov_b32_e32 v32, v0
	v_mov_b32_e32 v33, v0
	v_mov_b32_e32 v34, v0
	v_mov_b32_e32 v35, v0
	v_mov_b32_e32 v36, v0
	v_mov_b32_e32 v37, v0
	v_mov_b32_e32 v38, v0
	v_mov_b32_e32 v39, v0
	v_mov_b32_e32 v40, v0
	v_mov_b32_e32 v41, v0
	v_mov_b32_e32 v42, v0
	v_mov_b32_e32 v43, v0
	v_mov_b32_e32 v44, v0
	v_mov_b32_e32 v45, v0
	v_mov_b32_e32 v46, v0
	v_mov_b32_e32 v47, v0
	v_mov_b32_e32 v48, v0
	v_mov_b32_e32 v49, v0
	v_mov_b32_e32 v50, v0
	v_mov_b32_e32 v51, v0
	v_mov_b32_e32 v52, v0
	v_mov_b32_e32 v53, v0
	v_mov_b32_e32 v54, v0
	v_mov_b32_e32 v55, v0
	v_mov_b32_e32 v56, v0
	v_mov_b32_e32 v57, v0
	v_mov_b32_e32 v58, v0
	v_mov_b32_e32 v59, v0
	v_mov_b32_e32 v60, v0
	v_mov_b32_e32 v61, v0
	v_mov_b32_e32 v62, v0
	v_mov_b32_e32 v63, v0
	v_mov_b32_e32 v64, v0
	v_mov_b32_e32 v65, v0
	v_mov_b32_e32 v66, v0
	v_mov_b32_e32 v67, v0
	v_mov_b32_e32 v68, v0
	v_mov_b32_e32 v69, v0
	v_mov_b32_e32 v70, v0
	v_mov_b32_e32 v71, v0
	v_mov_b32_e32 v72, v0
	v_mov_b32_e32 v73, v0
	v_mov_b32_e32 v74, v0
	v_mov_b32_e32 v75, v0
	v_mov_b32_e32 v76, v0
	v_mov_b32_e32 v77, v0
	v_mov_b32_e32 v78, v0
	v_mov_b32_e32 v79, v0
	v_mov_b32_e32 v80, v0
	v_mov_b32_e32 v81, v0
	v_mov_b32_e32 v82, v0
	v_mov_b32_e32 v83, v0
	v_mov_b32_e32 v84, v0
	v_mov_b32_e32 v85, v0
	v_mov_b32_e32 v86, v0
	v_mov_b32_e32 v87, v0
	v_mov_b32_e32 v88, v0
	v_mov_b32_e32 v89, v0
	v_mov_b32_e32 v90, v0
	v_mov_b32_e32 v91, v0
	v_mov_b32_e32 v92, v0
	v_mov_b32_e32 v93, v0
	v_mov_b32_e32 v94, v0
	v_mov_b32_e32 v95, v0
	v_mov_b32_e32 v96, v0
	v_mov_b32_e32 v97, v0
	v_mov_b32_e32 v98, v0
	v_mov_b32_e32 v99, v0
	v_mov_b32_e32 v100, v0
	v_mov_b32_e32 v101, v0
	v_mov_b32_e32 v102, v0
	v_mov_b32_e32 v103, v0
	v_mov_b32_e32 v104, v0
	v_mov_b32_e32 v105, v0
	v_mov_b32_e32 v106, v0
	v_mov_b32_e32 v107, v0
	v_mov_b32_e32 v108, v0
	v_mov_b32_e32 v109, v0
	v_mov_b32_e32 v110, v0
	v_mov_b32_e32 v111, v0
	v_mov_b32_e32 v112, v0
	v_mov_b32_e32 v113, v0
	v_mov_b32_e32 v114, v0
	v_mov_b32_e32 v115, v0
	v_mov_b32_e32 v116, v0
	v_mov_b32_e32 v117, v0
	v_mov_b32_e32 v118, v0
	v_mov_b32_e32 v119, v0
	v_mov_b32_e32 v120, v0
	v_mov_b32_e32 v121, v0
	v_mov_b32_e32 v122, v0
	v_mov_b32_e32 v123, v0
	v_mov_b32_e32 v124, v0
	v_mov_b32_e32 v125, v0
	v_mov_b32_e32 v126, v0
	v_mov_b32_e32 v127, v0
	s_mov_b64 s[42:43], 0x4360100
	s_mov_b64 s[44:45], 0x4360180
	s_mov_b64 s[46:47], 0x43e4100
	s_mov_b64 s[48:49], 0x43e4180
	s_barrier
	ds_read_b128 v[160:163], v149
	ds_read_b128 v[164:167], v149 offset:1024
	ds_read_b128 v[168:171], v149 offset:2048
	ds_read_b128 v[172:175], v149 offset:3072
; #define STAGE_A(P, br, kt) do { const char* _base = (const char*)(((kt) < G.ksplit ? G.A1 : A2m) + (long)(br) * G.lda + (long)(kt) * BK); \
;     __builtin_amdgcn_global_load_lds((const unsigned*)(_base + aoff0), (unsigned*)((char*)(P) + sb0), 16, 0, 0); \
;     __builtin_amdgcn_global_load_lds((const unsigned*)(_base + aoff1), (unsigned*)((char*)(P) + sb1), 16, 0, 0); } while (0)
; #define STAGE_B(P, br, kt) do { const char* _base = (const char*)(G.Bt + (long)(br) * G.ldb + (long)(kt) * BK); \
;     __builtin_amdgcn_global_load_lds((const unsigned*)(_base + boff0), (unsigned*)((char*)(P) + sb0), 16, 0, 0); \
;     __builtin_amdgcn_global_load_lds((const unsigned*)(_base + boff1), (unsigned*)((char*)(P) + sb1), 16, 0, 0); } while (0)
; #define LDA(dst, b, h) for (int m = 0; m < 4; ++m) for (int k = 0; k < 2; ++k) \
;     dst[m][k] = *reinterpret_cast<const bf16x8*>(a_rd + ((b) * 2 + (h)) * (HT * 2) + m * 2048 + k * 1024)
; #define LDB(dst, b, h) for (int n = 0; n < 2; ++n) for (int k = 0; k < 2; ++k) \
;     dst[n][k] = *reinterpret_cast<const bf16x8*>(b_rd + ((b) * 2 + (h)) * (HT * 2) + n * 2048 + k * 1024)
; #define MMA(ai, bj, At_, Bt_) do { __builtin_amdgcn_s_setprio(1); \
;     for (int m = 0; m < 4; ++m) for (int n = 0; n < 2; ++n) for (int k = 0; k < 2; ++k) \
;       acc[ai][bj][m][n] = __builtin_amdgcn_mfma_f32_16x16x32_bf16(Bt_[n][k], At_[m][k], acc[ai][bj][m][n], 0, 0, 0); \
;     __builtin_amdgcn_s_setprio(0); } while (0)
; #define WAIT_L(n) asm volatile("s_waitcnt lgkmcnt(" #n ")" ::: "memory")
; #define BAR __builtin_amdgcn_s_barrier()
; #define SCHED __builtin_amdgcn_sched_barrier(0)
;     ...
;     LDB(B0, 0, 0); SCHED; LDA(At, 0, 0); STAGE_A(SA(1, 1), brow + HALF, t + 1);
;     WAIT_L(8); BAR; WAIT_L(0); MMA(0, 0, At, B0); BAR; SCHED;
;     LDB(B1, 0, 1); STAGE_B(SB(0, 0), bcol, t + 2);
;     BAR; WAIT_L(0); MMA(0, 1, At, B1); BAR;
;     LDA(At, 0, 1); STAGE_A(SA(0, 0), brow, t + 2);
;     BAR; WAIT_L(0); MMA(1, 0, At, B0); BAR; SCHED;
.LBB0_1865:
	v_add_u32_e32 v158, 0xc000, v147
	v_lshl_add_u64 v[222:223], s[26:27], 0, v[134:135]
	v_readfirstlane_b32 s35, v158
	v_add_u32_e32 v159, 0xe000, v147
	v_lshl_add_u64 v[156:157], v[222:223], 0, s[94:95]
	s_mov_b32 m0, s35
	v_lshl_add_u64 v[230:231], s[26:27], 0, v[136:137]
	v_readfirstlane_b32 s35, v159
	ds_read_b128 v[176:179], v148
	ds_read_b128 v[182:185], v148 offset:1024
	ds_read_b128 v[186:189], v148 offset:2048
	ds_read_b128 v[190:193], v148 offset:3072
	ds_read_b128 v[194:197], v148 offset:4096
	ds_read_b128 v[198:201], v148 offset:5120
	ds_read_b128 v[202:205], v148 offset:6144
	ds_read_b128 v[206:209], v148 offset:7168
	global_load_lds_dwordx4 v[156:157], off
	v_lshl_add_u64 v[156:157], v[230:231], 0, s[94:95]
	s_mov_b32 m0, s35
	s_nop 0
	global_load_lds_dwordx4 v[156:157], off
	s_waitcnt lgkmcnt(8)
	s_barrier
	s_waitcnt lgkmcnt(0)
	s_setprio 1
	s_waitcnt lgkmcnt(0)
	v_mfma_f32_16x16x32_bf16 v[124:127], v[160:163], v[176:179], v[124:127]
	v_mfma_f32_16x16x32_bf16 v[120:123], v[168:171], v[176:179], v[120:123]
	v_mfma_f32_16x16x32_bf16 v[116:119], v[160:163], v[186:189], v[116:119]
	v_mfma_f32_16x16x32_bf16 v[112:115], v[168:171], v[186:189], v[112:115]
	v_mfma_f32_16x16x32_bf16 v[108:111], v[160:163], v[194:197], v[108:111]
	v_mfma_f32_16x16x32_bf16 v[104:107], v[168:171], v[194:197], v[104:107]
	v_mfma_f32_16x16x32_bf16 v[100:103], v[160:163], v[202:205], v[100:103]
	v_mfma_f32_16x16x32_bf16 v[96:99], v[168:171], v[202:205], v[96:99]
	v_mfma_f32_16x16x32_bf16 v[124:127], v[164:167], v[182:185], v[124:127]
	v_mfma_f32_16x16x32_bf16 v[120:123], v[172:175], v[182:185], v[120:123]
	v_mfma_f32_16x16x32_bf16 v[116:119], v[164:167], v[190:193], v[116:119]
	v_mfma_f32_16x16x32_bf16 v[112:115], v[172:175], v[190:193], v[112:115]
	v_mfma_f32_16x16x32_bf16 v[108:111], v[164:167], v[198:201], v[108:111]
	v_mfma_f32_16x16x32_bf16 v[104:107], v[172:175], v[198:201], v[104:107]
	s_setprio 2
	s_barrier
	v_mfma_f32_16x16x32_bf16 v[100:103], v[164:167], v[206:209], v[100:103]
	v_mfma_f32_16x16x32_bf16 v[96:99], v[172:175], v[206:209], v[96:99]
	s_setprio 0
	v_add_u32_e32 v155, s30, v142
	v_lshl_add_u64 v[232:233], s[26:27], 0, v[130:131]
	v_readfirstlane_b32 s35, v155
	v_lshl_add_u64 v[156:157], v[232:233], 0, s[42:43]
	s_mov_b32 m0, s35
	ds_read_b128 v[210:213], v149 offset:16384
	ds_read_b128 v[214:217], v149 offset:17408
	ds_read_b128 v[218:221], v149 offset:18432
	ds_read_b128 v[246:249], v149 offset:19456
	global_load_lds_dwordx4 v[156:157], off
	v_add_u32_e32 v156, 0x2000, v155
	v_lshl_add_u64 v[234:235], s[26:27], 0, v[132:133]
	v_readfirstlane_b32 s35, v156
	v_lshl_add_u64 v[236:237], v[234:235], 0, s[42:43]
	s_mov_b32 m0, s35
	s_nop 0
	global_load_lds_dwordx4 v[236:237], off
	s_barrier
	s_waitcnt lgkmcnt(0)
	s_setprio 1
	s_waitcnt lgkmcnt(0)
	v_mfma_f32_16x16x32_bf16 v[92:95], v[210:213], v[176:179], v[92:95]
	v_mfma_f32_16x16x32_bf16 v[88:91], v[218:221], v[176:179], v[88:91]
	v_mfma_f32_16x16x32_bf16 v[84:87], v[210:213], v[186:189], v[84:87]
	v_mfma_f32_16x16x32_bf16 v[80:83], v[218:221], v[186:189], v[80:83]
	v_mfma_f32_16x16x32_bf16 v[76:79], v[210:213], v[194:197], v[76:79]
	v_mfma_f32_16x16x32_bf16 v[72:75], v[218:221], v[194:197], v[72:75]
	v_mfma_f32_16x16x32_bf16 v[68:71], v[210:213], v[202:205], v[68:71]
	v_mfma_f32_16x16x32_bf16 v[64:67], v[218:221], v[202:205], v[64:67]
	v_mfma_f32_16x16x32_bf16 v[92:95], v[214:217], v[182:185], v[92:95]
	v_mfma_f32_16x16x32_bf16 v[88:91], v[246:249], v[182:185], v[88:91]
	v_mfma_f32_16x16x32_bf16 v[84:87], v[214:217], v[190:193], v[84:87]
	v_mfma_f32_16x16x32_bf16 v[80:83], v[246:249], v[190:193], v[80:83]
	v_mfma_f32_16x16x32_bf16 v[76:79], v[214:217], v[198:201], v[76:79]
	v_mfma_f32_16x16x32_bf16 v[72:75], v[246:249], v[198:201], v[72:75]
	s_setprio 2
	s_barrier
	v_mfma_f32_16x16x32_bf16 v[68:71], v[214:217], v[206:209], v[68:71]
	v_mfma_f32_16x16x32_bf16 v[64:67], v[246:249], v[206:209], v[64:67]
	s_setprio 0
	v_readfirstlane_b32 s35, v147
	v_lshl_add_u64 v[236:237], v[222:223], 0, s[4:5]
	s_mov_b32 m0, s35
	v_readfirstlane_b32 s35, v146
	ds_read_b128 v[176:179], v148 offset:16384
	ds_read_b128 v[182:185], v148 offset:17408
	ds_read_b128 v[186:189], v148 offset:18432
	ds_read_b128 v[190:193], v148 offset:19456
	ds_read_b128 v[194:197], v148 offset:20480
	ds_read_b128 v[198:201], v148 offset:21504
	ds_read_b128 v[202:205], v148 offset:22528
	ds_read_b128 v[206:209], v148 offset:23552
	global_load_lds_dwordx4 v[236:237], off
	v_lshl_add_u64 v[236:237], v[230:231], 0, s[4:5]
	s_mov_b32 m0, s35
	s_nop 0
	global_load_lds_dwordx4 v[236:237], off
	s_waitcnt vmcnt(10)
	s_barrier
	s_waitcnt lgkmcnt(0)
	s_setprio 1
	s_waitcnt lgkmcnt(0)
	v_mfma_f32_16x16x32_bf16 v[60:63], v[160:163], v[176:179], v[60:63]
	v_mfma_f32_16x16x32_bf16 v[56:59], v[168:171], v[176:179], v[56:59]
	v_mfma_f32_16x16x32_bf16 v[52:55], v[160:163], v[186:189], v[52:55]
	v_mfma_f32_16x16x32_bf16 v[48:51], v[168:171], v[186:189], v[48:51]
	v_mfma_f32_16x16x32_bf16 v[44:47], v[160:163], v[194:197], v[44:47]
	v_mfma_f32_16x16x32_bf16 v[40:43], v[168:171], v[194:197], v[40:43]
	v_mfma_f32_16x16x32_bf16 v[36:39], v[160:163], v[202:205], v[36:39]
	v_mfma_f32_16x16x32_bf16 v[32:35], v[168:171], v[202:205], v[32:35]
	v_mfma_f32_16x16x32_bf16 v[60:63], v[164:167], v[182:185], v[60:63]
	v_mfma_f32_16x16x32_bf16 v[56:59], v[172:175], v[182:185], v[56:59]
	v_mfma_f32_16x16x32_bf16 v[52:55], v[164:167], v[190:193], v[52:55]
	v_mfma_f32_16x16x32_bf16 v[48:51], v[172:175], v[190:193], v[48:51]
	v_mfma_f32_16x16x32_bf16 v[44:47], v[164:167], v[198:201], v[44:47]
	v_mfma_f32_16x16x32_bf16 v[40:43], v[172:175], v[198:201], v[40:43]
	s_setprio 2
	s_barrier
; #define STAGE_A(P, br, kt) do { const char* _base = (const char*)(((kt) < G.ksplit ? G.A1 : A2m) + (long)(br) * G.lda + (long)(kt) * BK); \
;     __builtin_amdgcn_global_load_lds((const unsigned*)(_base + aoff0), (unsigned*)((char*)(P) + sb0), 16, 0, 0); \
;     __builtin_amdgcn_global_load_lds((const unsigned*)(_base + aoff1), (unsigned*)((char*)(P) + sb1), 16, 0, 0); } while (0)
; #define STAGE_B(P, br, kt) do { const char* _base = (const char*)(G.Bt + (long)(br) * G.ldb + (long)(kt) * BK); \
;     __builtin_amdgcn_global_load_lds((const unsigned*)(_base + boff0), (unsigned*)((char*)(P) + sb0), 16, 0, 0); \
;     __builtin_amdgcn_global_load_lds((const unsigned*)(_base + boff1), (unsigned*)((char*)(P) + sb1), 16, 0, 0); } while (0)
; #define LDA(dst, b, h) for (int m = 0; m < 4; ++m) for (int k = 0; k < 2; ++k) \
;     dst[m][k] = *reinterpret_cast<const bf16x8*>(a_rd + ((b) * 2 + (h)) * (HT * 2) + m * 2048 + k * 1024)
; #define LDB(dst, b, h) for (int n = 0; n < 2; ++n) for (int k = 0; k < 2; ++k) \
;     dst[n][k] = *reinterpret_cast<const bf16x8*>(b_rd + ((b) * 2 + (h)) * (HT * 2) + n * 2048 + k * 1024)
; #define MMA(ai, bj, At_, Bt_) do { __builtin_amdgcn_s_setprio(1); \
;     for (int m = 0; m < 4; ++m) for (int n = 0; n < 2; ++n) for (int k = 0; k < 2; ++k) \
;       acc[ai][bj][m][n] = __builtin_amdgcn_mfma_f32_16x16x32_bf16(Bt_[n][k], At_[m][k], acc[ai][bj][m][n], 0, 0, 0); \
;     __builtin_amdgcn_s_setprio(0); } while (0)
; #define WAIT_V(n) asm volatile("s_waitcnt vmcnt(" #n ")" ::: "memory")
; #define WAIT_L(n) asm volatile("s_waitcnt lgkmcnt(" #n ")" ::: "memory")
; #define BAR __builtin_amdgcn_s_barrier()
; #define SCHED __builtin_amdgcn_sched_barrier(0)
;     ...
;     BAR; WAIT_L(0); MMA(1, 0, At, B0); BAR; SCHED;
;     STAGE_B(SB(0, 1), bcol + HALF, t + 2);
;     WAIT_V(6); BAR; MMA(1, 1, At, B1); BAR;
;     LDB(B0, 1, 0); SCHED; LDA(At, 1, 0); STAGE_A(SA(0, 1), brow + HALF, t + 2);
;     WAIT_L(8); BAR; WAIT_L(0); MMA(0, 0, At, B0); BAR; SCHED;
;     LDB(B1, 1, 1); STAGE_B(SB(1, 0), bcol, t + 3);
;     BAR; WAIT_L(0); MMA(0, 1, At, B1); BAR;
	v_mfma_f32_16x16x32_bf16 v[36:39], v[164:167], v[206:209], v[36:39]
	v_mfma_f32_16x16x32_bf16 v[32:35], v[172:175], v[206:209], v[32:35]
	s_setprio 0
	v_readfirstlane_b32 s35, v141
	v_add_u32_e32 v157, 0x2000, v141
	v_lshl_add_u64 v[160:161], v[232:233], 0, s[46:47]
	s_mov_b32 m0, s35
	v_readfirstlane_b32 s35, v157
	global_load_lds_dwordx4 v[160:161], off
	v_lshl_add_u64 v[160:161], v[234:235], 0, s[46:47]
	s_mov_b32 m0, s35
	s_nop 0
	global_load_lds_dwordx4 v[160:161], off
	ds_read_b128 v[160:163], v149 offset:32768
	ds_read_b128 v[164:167], v149 offset:33792
	ds_read_b128 v[168:171], v149 offset:34816
	ds_read_b128 v[172:175], v149 offset:35840
	s_waitcnt vmcnt(6)
	s_barrier
	s_setprio 1
	v_mfma_f32_16x16x32_bf16 v[28:31], v[210:213], v[176:179], v[28:31]
	v_mfma_f32_16x16x32_bf16 v[24:27], v[218:221], v[176:179], v[24:27]
	v_mfma_f32_16x16x32_bf16 v[20:23], v[210:213], v[186:189], v[20:23]
	v_mfma_f32_16x16x32_bf16 v[16:19], v[218:221], v[186:189], v[16:19]
	v_mfma_f32_16x16x32_bf16 v[12:15], v[210:213], v[194:197], v[12:15]
	v_mfma_f32_16x16x32_bf16 v[8:11], v[218:221], v[194:197], v[8:11]
	v_mfma_f32_16x16x32_bf16 v[4:7], v[210:213], v[202:205], v[4:7]
	v_mfma_f32_16x16x32_bf16 v[0:3], v[218:221], v[202:205], v[0:3]
	v_mfma_f32_16x16x32_bf16 v[28:31], v[214:217], v[182:185], v[28:31]
	v_mfma_f32_16x16x32_bf16 v[24:27], v[246:249], v[182:185], v[24:27]
	v_mfma_f32_16x16x32_bf16 v[20:23], v[214:217], v[190:193], v[20:23]
	v_mfma_f32_16x16x32_bf16 v[16:19], v[246:249], v[190:193], v[16:19]
	v_mfma_f32_16x16x32_bf16 v[12:15], v[214:217], v[198:201], v[12:15]
	v_mfma_f32_16x16x32_bf16 v[8:11], v[246:249], v[198:201], v[8:11]
	s_setprio 2
	s_barrier
	v_mfma_f32_16x16x32_bf16 v[4:7], v[214:217], v[206:209], v[4:7]
	v_mfma_f32_16x16x32_bf16 v[0:3], v[246:249], v[206:209], v[0:3]
	s_setprio 0
	v_readfirstlane_b32 s35, v140
	v_lshl_add_u64 v[210:211], v[222:223], 0, s[96:97]
	s_mov_b32 m0, s35
	v_readfirstlane_b32 s35, v138
	ds_read_b128 v[176:179], v148 offset:32768
	ds_read_b128 v[182:185], v148 offset:33792
	ds_read_b128 v[186:189], v148 offset:34816
	ds_read_b128 v[190:193], v148 offset:35840
	ds_read_b128 v[194:197], v148 offset:36864
	ds_read_b128 v[198:201], v148 offset:37888
	ds_read_b128 v[202:205], v148 offset:38912
	ds_read_b128 v[206:209], v148 offset:39936
	global_load_lds_dwordx4 v[210:211], off
	v_lshl_add_u64 v[210:211], v[230:231], 0, s[96:97]
	s_mov_b32 m0, s35
	s_nop 0
	global_load_lds_dwordx4 v[210:211], off
	s_waitcnt lgkmcnt(8)
	s_barrier
	s_waitcnt lgkmcnt(0)
	s_setprio 1
	s_waitcnt lgkmcnt(0)
	v_mfma_f32_16x16x32_bf16 v[124:127], v[160:163], v[176:179], v[124:127]
	v_mfma_f32_16x16x32_bf16 v[120:123], v[168:171], v[176:179], v[120:123]
	v_mfma_f32_16x16x32_bf16 v[116:119], v[160:163], v[186:189], v[116:119]
	v_mfma_f32_16x16x32_bf16 v[112:115], v[168:171], v[186:189], v[112:115]
	v_mfma_f32_16x16x32_bf16 v[108:111], v[160:163], v[194:197], v[108:111]
	v_mfma_f32_16x16x32_bf16 v[104:107], v[168:171], v[194:197], v[104:107]
	v_mfma_f32_16x16x32_bf16 v[100:103], v[160:163], v[202:205], v[100:103]
	v_mfma_f32_16x16x32_bf16 v[96:99], v[168:171], v[202:205], v[96:99]
	v_mfma_f32_16x16x32_bf16 v[124:127], v[164:167], v[182:185], v[124:127]
	v_mfma_f32_16x16x32_bf16 v[120:123], v[172:175], v[182:185], v[120:123]
	v_mfma_f32_16x16x32_bf16 v[116:119], v[164:167], v[190:193], v[116:119]
	v_mfma_f32_16x16x32_bf16 v[112:115], v[172:175], v[190:193], v[112:115]
	v_mfma_f32_16x16x32_bf16 v[108:111], v[164:167], v[198:201], v[108:111]
	v_mfma_f32_16x16x32_bf16 v[104:107], v[172:175], v[198:201], v[104:107]
	s_setprio 2
	s_barrier
	v_mfma_f32_16x16x32_bf16 v[100:103], v[164:167], v[206:209], v[100:103]
	v_mfma_f32_16x16x32_bf16 v[96:99], v[172:175], v[206:209], v[96:99]
	s_setprio 0
	v_readfirstlane_b32 s35, v145
	v_lshl_add_u64 v[236:237], v[232:233], 0, s[44:45]
	s_mov_b32 m0, s35
	v_readfirstlane_b32 s35, v150
	ds_read_b128 v[210:213], v149 offset:49152
	ds_read_b128 v[214:217], v149 offset:50176
	ds_read_b128 v[218:221], v149 offset:51200
	ds_read_b128 v[246:249], v149 offset:52224
	global_load_lds_dwordx4 v[236:237], off
	v_lshl_add_u64 v[236:237], v[234:235], 0, s[44:45]
	s_mov_b32 m0, s35
	s_nop 0
	global_load_lds_dwordx4 v[236:237], off
	s_barrier
	s_waitcnt lgkmcnt(0)
	s_setprio 1
	s_waitcnt lgkmcnt(0)
	v_mfma_f32_16x16x32_bf16 v[92:95], v[210:213], v[176:179], v[92:95]
	v_mfma_f32_16x16x32_bf16 v[88:91], v[218:221], v[176:179], v[88:91]
	v_mfma_f32_16x16x32_bf16 v[84:87], v[210:213], v[186:189], v[84:87]
	v_mfma_f32_16x16x32_bf16 v[80:83], v[218:221], v[186:189], v[80:83]
	v_mfma_f32_16x16x32_bf16 v[76:79], v[210:213], v[194:197], v[76:79]
	v_mfma_f32_16x16x32_bf16 v[72:75], v[218:221], v[194:197], v[72:75]
	v_mfma_f32_16x16x32_bf16 v[68:71], v[210:213], v[202:205], v[68:71]
	v_mfma_f32_16x16x32_bf16 v[64:67], v[218:221], v[202:205], v[64:67]
	v_mfma_f32_16x16x32_bf16 v[92:95], v[214:217], v[182:185], v[92:95]
	v_mfma_f32_16x16x32_bf16 v[88:91], v[246:249], v[182:185], v[88:91]
	v_mfma_f32_16x16x32_bf16 v[84:87], v[214:217], v[190:193], v[84:87]
	v_mfma_f32_16x16x32_bf16 v[80:83], v[246:249], v[190:193], v[80:83]
	v_mfma_f32_16x16x32_bf16 v[76:79], v[214:217], v[198:201], v[76:79]
	v_mfma_f32_16x16x32_bf16 v[72:75], v[246:249], v[198:201], v[72:75]
	s_setprio 2
	s_barrier
; #define STAGE_A(P, br, kt) do { const char* _base = (const char*)(((kt) < G.ksplit ? G.A1 : A2m) + (long)(br) * G.lda + (long)(kt) * BK); \
;     __builtin_amdgcn_global_load_lds((const unsigned*)(_base + aoff0), (unsigned*)((char*)(P) + sb0), 16, 0, 0); \
;     __builtin_amdgcn_global_load_lds((const unsigned*)(_base + aoff1), (unsigned*)((char*)(P) + sb1), 16, 0, 0); } while (0)
; #define STAGE_B(P, br, kt) do { const char* _base = (const char*)(G.Bt + (long)(br) * G.ldb + (long)(kt) * BK); \
;     __builtin_amdgcn_global_load_lds((const unsigned*)(_base + boff0), (unsigned*)((char*)(P) + sb0), 16, 0, 0); \
;     __builtin_amdgcn_global_load_lds((const unsigned*)(_base + boff1), (unsigned*)((char*)(P) + sb1), 16, 0, 0); } while (0)
; #define LDA(dst, b, h) for (int m = 0; m < 4; ++m) for (int k = 0; k < 2; ++k) \
;     dst[m][k] = *reinterpret_cast<const bf16x8*>(a_rd + ((b) * 2 + (h)) * (HT * 2) + m * 2048 + k * 1024)
; #define LDB(dst, b, h) for (int n = 0; n < 2; ++n) for (int k = 0; k < 2; ++k) \
;     dst[n][k] = *reinterpret_cast<const bf16x8*>(b_rd + ((b) * 2 + (h)) * (HT * 2) + n * 2048 + k * 1024)
; #define MMA(ai, bj, At_, Bt_) do { __builtin_amdgcn_s_setprio(1); \
;     for (int m = 0; m < 4; ++m) for (int n = 0; n < 2; ++n) for (int k = 0; k < 2; ++k) \
;       acc[ai][bj][m][n] = __builtin_amdgcn_mfma_f32_16x16x32_bf16(Bt_[n][k], At_[m][k], acc[ai][bj][m][n], 0, 0, 0); \
;     __builtin_amdgcn_s_setprio(0); } while (0)
; #define WAIT_V(n) asm volatile("s_waitcnt vmcnt(" #n ")" ::: "memory")
; #define WAIT_L(n) asm volatile("s_waitcnt lgkmcnt(" #n ")" ::: "memory")
; #define BAR __builtin_amdgcn_s_barrier()
; #define SCHED __builtin_amdgcn_sched_barrier(0)
;     ...
;     LDB(B1, 1, 1); STAGE_B(SB(1, 0), bcol, t + 3);
;     BAR; WAIT_L(0); MMA(0, 1, At, B1); BAR;
;     LDA(At, 1, 1); STAGE_A(SA(1, 0), brow, t + 3);
;     BAR; WAIT_L(0); MMA(1, 0, At, B0); BAR; SCHED;
;     STAGE_B(SB(1, 1), bcol + HALF, t + 3);
;     WAIT_V(6); BAR; MMA(1, 1, At, B1); BAR;
;   }
;   float ssv[2][4] = {};
;   if constexpr (EPI == EPI_GU || EPI == EPI_EVIN || EPI == EPI_ODIN) {
; #pragma unroll
;     for (int ai = 0; ai < 2; ++ai)
; #pragma unroll
;       for (int m = 0; m < 4; ++m) ssv[ai][m] = G.ssr[brow + ai * HALF + wr * 64 + m * 16 + fr];
;   }
;   { LDB(B0, 0, 0); LDA(At, 0, 0); STAGE_A(SA(1, 1), brow + HALF, nt - 1);
	v_mfma_f32_16x16x32_bf16 v[68:71], v[214:217], v[206:209], v[68:71]
	v_mfma_f32_16x16x32_bf16 v[64:67], v[246:249], v[206:209], v[64:67]
	s_setprio 0
	v_readfirstlane_b32 s35, v151
	v_lshl_add_u64 v[222:223], v[222:223], 0, s[2:3]
	s_mov_b32 m0, s35
	v_readfirstlane_b32 s35, v152
	ds_read_b128 v[176:179], v148 offset:49152
	ds_read_b128 v[182:185], v148 offset:50176
	ds_read_b128 v[186:189], v148 offset:51200
	ds_read_b128 v[190:193], v148 offset:52224
	ds_read_b128 v[194:197], v148 offset:53248
	ds_read_b128 v[198:201], v148 offset:54272
	ds_read_b128 v[202:205], v148 offset:55296
	ds_read_b128 v[206:209], v148 offset:56320
	global_load_lds_dwordx4 v[222:223], off
	v_lshl_add_u64 v[222:223], v[230:231], 0, s[2:3]
	s_mov_b32 m0, s35
	s_nop 0
	global_load_lds_dwordx4 v[222:223], off
	s_waitcnt vmcnt(10)
	s_barrier
	s_waitcnt lgkmcnt(0)
	s_setprio 1
	s_waitcnt lgkmcnt(0)
	v_mfma_f32_16x16x32_bf16 v[60:63], v[160:163], v[176:179], v[60:63]
	v_mfma_f32_16x16x32_bf16 v[56:59], v[168:171], v[176:179], v[56:59]
	v_mfma_f32_16x16x32_bf16 v[52:55], v[160:163], v[186:189], v[52:55]
	v_mfma_f32_16x16x32_bf16 v[48:51], v[168:171], v[186:189], v[48:51]
	v_mfma_f32_16x16x32_bf16 v[44:47], v[160:163], v[194:197], v[44:47]
	v_mfma_f32_16x16x32_bf16 v[40:43], v[168:171], v[194:197], v[40:43]
	v_mfma_f32_16x16x32_bf16 v[36:39], v[160:163], v[202:205], v[36:39]
	v_mfma_f32_16x16x32_bf16 v[32:35], v[168:171], v[202:205], v[32:35]
	v_mfma_f32_16x16x32_bf16 v[60:63], v[164:167], v[182:185], v[60:63]
	v_mfma_f32_16x16x32_bf16 v[56:59], v[172:175], v[182:185], v[56:59]
	v_mfma_f32_16x16x32_bf16 v[52:55], v[164:167], v[190:193], v[52:55]
	v_mfma_f32_16x16x32_bf16 v[48:51], v[172:175], v[190:193], v[48:51]
	v_mfma_f32_16x16x32_bf16 v[44:47], v[164:167], v[198:201], v[44:47]
	v_mfma_f32_16x16x32_bf16 v[40:43], v[172:175], v[198:201], v[40:43]
	s_setprio 2
	s_barrier
	v_mfma_f32_16x16x32_bf16 v[36:39], v[164:167], v[206:209], v[36:39]
	v_mfma_f32_16x16x32_bf16 v[32:35], v[172:175], v[206:209], v[32:35]
	s_setprio 0
	v_readfirstlane_b32 s35, v153
	v_lshl_add_u64 v[160:161], v[232:233], 0, s[48:49]
	s_mov_b32 m0, s35
	v_readfirstlane_b32 s35, v154
	global_load_lds_dwordx4 v[160:161], off
	v_lshl_add_u64 v[160:161], v[234:235], 0, s[48:49]
	s_mov_b32 m0, s35
	s_nop 0
	global_load_lds_dwordx4 v[160:161], off
	ds_read_b128 v[160:163], v149
	ds_read_b128 v[164:167], v149 offset:1024
	ds_read_b128 v[168:171], v149 offset:2048
	ds_read_b128 v[172:175], v149 offset:3072
	s_waitcnt vmcnt(6)
	s_barrier
	s_setprio 1
	v_mfma_f32_16x16x32_bf16 v[28:31], v[210:213], v[176:179], v[28:31]
	v_mfma_f32_16x16x32_bf16 v[24:27], v[218:221], v[176:179], v[24:27]
	v_mfma_f32_16x16x32_bf16 v[20:23], v[210:213], v[186:189], v[20:23]
	v_mfma_f32_16x16x32_bf16 v[16:19], v[218:221], v[186:189], v[16:19]
	v_mfma_f32_16x16x32_bf16 v[12:15], v[210:213], v[194:197], v[12:15]
	v_mfma_f32_16x16x32_bf16 v[8:11], v[218:221], v[194:197], v[8:11]
	v_mfma_f32_16x16x32_bf16 v[4:7], v[210:213], v[202:205], v[4:7]
	v_mfma_f32_16x16x32_bf16 v[0:3], v[218:221], v[202:205], v[0:3]
	v_mfma_f32_16x16x32_bf16 v[28:31], v[214:217], v[182:185], v[28:31]
	v_mfma_f32_16x16x32_bf16 v[24:27], v[246:249], v[182:185], v[24:27]
	v_mfma_f32_16x16x32_bf16 v[20:23], v[214:217], v[190:193], v[20:23]
	v_mfma_f32_16x16x32_bf16 v[16:19], v[246:249], v[190:193], v[16:19]
	v_mfma_f32_16x16x32_bf16 v[12:15], v[214:217], v[198:201], v[12:15]
	v_mfma_f32_16x16x32_bf16 v[8:11], v[246:249], v[198:201], v[8:11]
	s_setprio 2
	s_barrier
	v_mfma_f32_16x16x32_bf16 v[4:7], v[214:217], v[206:209], v[4:7]
	v_mfma_f32_16x16x32_bf16 v[0:3], v[246:249], v[206:209], v[0:3]
	s_setprio 0
	s_add_i32 s31, s31, 2
	s_add_u32 s26, s26, 0x100
	s_addc_u32 s27, s27, 0
	s_cmp_lt_u32 s31, 28
	s_cbranch_scc1 .LBB0_1865
	s_waitcnt lgkmcnt(0)
	v_or_b32_e32 v130, s29, v144
	v_lshl_add_u32 v130, v143, 6, v130
	v_ashrrev_i32_e32 v131, 31, v130
	v_add_u32_e32 v142, 0xa0, v130
	v_lshl_add_u64 v[132:133], v[130:131], 2, s[20:21]
	v_add_u32_e32 v134, 0x80, v130
	v_add_u32_e32 v136, 0x90, v130
	v_ashrrev_i32_e32 v143, 31, v142
	v_add_u32_e32 v130, 0xb0, v130
	s_or_b32 s42, s29, 0x80
	v_ashrrev_i32_e32 v135, 31, v134
	v_ashrrev_i32_e32 v137, 31, v136
	v_lshl_add_u64 v[142:143], v[142:143], 2, s[20:21]
	v_ashrrev_i32_e32 v131, 31, v130
	s_mul_i32 s26, s42, 0x1080
	v_lshl_add_u64 v[134:135], v[134:135], 2, s[20:21]
	v_lshl_add_u64 v[136:137], v[136:137], 2, s[20:21]
	v_lshl_add_u64 v[160:161], v[130:131], 2, s[20:21]
	global_load_dword v130, v[132:133], off
	global_load_dword v152, v[132:133], off offset:64
	global_load_dword v151, v[132:133], off offset:128
	global_load_dword v150, v[132:133], off offset:192
	global_load_dword v145, v[134:135], off
	global_load_dword v144, v[136:137], off
	s_nop 0
	global_load_dword v143, v[142:143], off
	s_nop 0
	global_load_dword v142, v[160:161], off
	s_mul_hi_i32 s27, s42, 0x1080
	s_add_u32 s26, s37, s26
	s_addc_u32 s27, s38, s27
	v_lshl_add_u64 v[136:137], s[26:27], 0, v[180:181]
	s_mov_b64 s[44:45], 0xf80
	v_readfirstlane_b32 s30, v158
	v_lshl_add_u64 v[136:137], v[136:137], 0, s[44:45]
	s_mov_b32 m0, s30
	ds_read_b128 v[132:135], v149
	ds_read_b128 v[160:163], v149 offset:1024
	ds_read_b128 v[164:167], v149 offset:2048
	ds_read_b128 v[168:171], v149 offset:3072
	ds_read_b128 v[172:175], v148
	ds_read_b128 v[176:179], v148 offset:1024
	ds_read_b128 v[182:185], v148 offset:2048
	ds_read_b128 v[186:189], v148 offset:3072
	ds_read_b128 v[190:193], v148 offset:4096
	ds_read_b128 v[194:197], v148 offset:5120
	ds_read_b128 v[198:201], v148 offset:6144
	ds_read_b128 v[202:205], v148 offset:7168
	global_load_lds_dwordx4 v[136:137], off
	v_lshl_add_u64 v[136:137], s[26:27], 0, v[128:129]
	v_readfirstlane_b32 s26, v159
	v_lshl_add_u64 v[136:137], v[136:137], 0, s[44:45]
	s_mov_b32 m0, s26
	s_nop 0
	global_load_lds_dwordx4 v[136:137], off
	s_barrier
; #define STAGE_A(P, br, kt) do { const char* _base = (const char*)(((kt) < G.ksplit ? G.A1 : A2m) + (long)(br) * G.lda + (long)(kt) * BK); \
;     __builtin_amdgcn_global_load_lds((const unsigned*)(_base + aoff0), (unsigned*)((char*)(P) + sb0), 16, 0, 0); \
;     __builtin_amdgcn_global_load_lds((const unsigned*)(_base + aoff1), (unsigned*)((char*)(P) + sb1), 16, 0, 0); } while (0)
; #define LDA(dst, b, h) for (int m = 0; m < 4; ++m) for (int k = 0; k < 2; ++k) \
;     dst[m][k] = *reinterpret_cast<const bf16x8*>(a_rd + ((b) * 2 + (h)) * (HT * 2) + m * 2048 + k * 1024)
; #define LDB(dst, b, h) for (int n = 0; n < 2; ++n) for (int k = 0; k < 2; ++k) \
;     dst[n][k] = *reinterpret_cast<const bf16x8*>(b_rd + ((b) * 2 + (h)) * (HT * 2) + n * 2048 + k * 1024)
; #define MMA(ai, bj, At_, Bt_) do { __builtin_amdgcn_s_setprio(1); \
;     for (int m = 0; m < 4; ++m) for (int n = 0; n < 2; ++n) for (int k = 0; k < 2; ++k) \
;       acc[ai][bj][m][n] = __builtin_amdgcn_mfma_f32_16x16x32_bf16(Bt_[n][k], At_[m][k], acc[ai][bj][m][n], 0, 0, 0); \
;     __builtin_amdgcn_s_setprio(0); } while (0)
; #define WAIT_V(n) asm volatile("s_waitcnt vmcnt(" #n ")" ::: "memory")
; #define WAIT_L(n) asm volatile("s_waitcnt lgkmcnt(" #n ")" ::: "memory")
; #define BAR __builtin_amdgcn_s_barrier()
;     ...
;   { LDB(B0, 0, 0); LDA(At, 0, 0); STAGE_A(SA(1, 1), brow + HALF, nt - 1);
;     BAR; WAIT_L(0); MMA(0, 0, At, B0); BAR;
;     LDB(B1, 0, 1); BAR; WAIT_L(0); MMA(0, 1, At, B1); BAR;
;     LDA(At, 0, 1); WAIT_V(4); BAR; WAIT_L(0); MMA(1, 0, At, B0); MMA(1, 1, At, B1); BAR; }
;   { LDB(B0, 1, 0); LDA(At, 1, 0); WAIT_V(2); BAR; WAIT_L(0); MMA(0, 0, At, B0); BAR;
	s_waitcnt lgkmcnt(0)
	s_setprio 1
	s_waitcnt lgkmcnt(0)
	v_mfma_f32_16x16x32_bf16 v[124:127], v[132:135], v[172:175], v[124:127]
	v_mfma_f32_16x16x32_bf16 v[120:123], v[164:167], v[172:175], v[120:123]
	v_mfma_f32_16x16x32_bf16 v[116:119], v[132:135], v[182:185], v[116:119]
	v_mfma_f32_16x16x32_bf16 v[112:115], v[164:167], v[182:185], v[112:115]
	v_mfma_f32_16x16x32_bf16 v[108:111], v[132:135], v[190:193], v[108:111]
	v_mfma_f32_16x16x32_bf16 v[104:107], v[164:167], v[190:193], v[104:107]
	v_mfma_f32_16x16x32_bf16 v[100:103], v[132:135], v[198:201], v[100:103]
	v_mfma_f32_16x16x32_bf16 v[96:99], v[164:167], v[198:201], v[96:99]
	v_mfma_f32_16x16x32_bf16 v[124:127], v[160:163], v[176:179], v[124:127]
	v_mfma_f32_16x16x32_bf16 v[120:123], v[168:171], v[176:179], v[120:123]
	v_mfma_f32_16x16x32_bf16 v[116:119], v[160:163], v[186:189], v[116:119]
	v_mfma_f32_16x16x32_bf16 v[112:115], v[168:171], v[186:189], v[112:115]
	v_mfma_f32_16x16x32_bf16 v[108:111], v[160:163], v[194:197], v[108:111]
	v_mfma_f32_16x16x32_bf16 v[104:107], v[168:171], v[194:197], v[104:107]
	s_setprio 2
	s_barrier
	v_mfma_f32_16x16x32_bf16 v[100:103], v[160:163], v[202:205], v[100:103]
	v_mfma_f32_16x16x32_bf16 v[96:99], v[168:171], v[202:205], v[96:99]
	s_setprio 0
	ds_read_b128 v[206:209], v149 offset:16384
	ds_read_b128 v[210:213], v149 offset:17408
	ds_read_b128 v[214:217], v149 offset:18432
	ds_read_b128 v[218:221], v149 offset:19456
	s_barrier
	s_waitcnt lgkmcnt(0)
	s_setprio 1
	s_waitcnt lgkmcnt(0)
	v_mfma_f32_16x16x32_bf16 v[92:95], v[206:209], v[172:175], v[92:95]
	v_mfma_f32_16x16x32_bf16 v[88:91], v[214:217], v[172:175], v[88:91]
	v_mfma_f32_16x16x32_bf16 v[84:87], v[206:209], v[182:185], v[84:87]
	v_mfma_f32_16x16x32_bf16 v[80:83], v[214:217], v[182:185], v[80:83]
	v_mfma_f32_16x16x32_bf16 v[76:79], v[206:209], v[190:193], v[76:79]
	v_mfma_f32_16x16x32_bf16 v[72:75], v[214:217], v[190:193], v[72:75]
	v_mfma_f32_16x16x32_bf16 v[68:71], v[206:209], v[198:201], v[68:71]
	v_mfma_f32_16x16x32_bf16 v[64:67], v[214:217], v[198:201], v[64:67]
	v_mfma_f32_16x16x32_bf16 v[92:95], v[210:213], v[176:179], v[92:95]
	v_mfma_f32_16x16x32_bf16 v[88:91], v[218:221], v[176:179], v[88:91]
	v_mfma_f32_16x16x32_bf16 v[84:87], v[210:213], v[186:189], v[84:87]
	v_mfma_f32_16x16x32_bf16 v[80:83], v[218:221], v[186:189], v[80:83]
	v_mfma_f32_16x16x32_bf16 v[76:79], v[210:213], v[194:197], v[76:79]
	v_mfma_f32_16x16x32_bf16 v[72:75], v[218:221], v[194:197], v[72:75]
	s_setprio 2
	s_barrier
	v_mfma_f32_16x16x32_bf16 v[68:71], v[210:213], v[202:205], v[68:71]
	v_mfma_f32_16x16x32_bf16 v[64:67], v[218:221], v[202:205], v[64:67]
	s_setprio 0
	ds_read_b128 v[172:175], v148 offset:16384
	ds_read_b128 v[176:179], v148 offset:17408
	ds_read_b128 v[182:185], v148 offset:18432
	ds_read_b128 v[186:189], v148 offset:19456
	ds_read_b128 v[190:193], v148 offset:20480
	ds_read_b128 v[194:197], v148 offset:21504
	ds_read_b128 v[198:201], v148 offset:22528
	ds_read_b128 v[202:205], v148 offset:23552
	s_waitcnt vmcnt(4)
	s_barrier
	s_waitcnt lgkmcnt(0)
	s_setprio 1
	s_waitcnt lgkmcnt(0)
	v_mfma_f32_16x16x32_bf16 v[60:63], v[132:135], v[172:175], v[60:63]
	v_mfma_f32_16x16x32_bf16 v[56:59], v[164:167], v[172:175], v[56:59]
	v_mfma_f32_16x16x32_bf16 v[52:55], v[132:135], v[182:185], v[52:55]
	v_mfma_f32_16x16x32_bf16 v[48:51], v[164:167], v[182:185], v[48:51]
	v_mfma_f32_16x16x32_bf16 v[44:47], v[132:135], v[190:193], v[44:47]
	v_mfma_f32_16x16x32_bf16 v[40:43], v[164:167], v[190:193], v[40:43]
	v_mfma_f32_16x16x32_bf16 v[36:39], v[132:135], v[198:201], v[36:39]
	v_mfma_f32_16x16x32_bf16 v[32:35], v[164:167], v[198:201], v[32:35]
	v_mfma_f32_16x16x32_bf16 v[60:63], v[160:163], v[176:179], v[60:63]
	v_mfma_f32_16x16x32_bf16 v[56:59], v[168:171], v[176:179], v[56:59]
	v_mfma_f32_16x16x32_bf16 v[52:55], v[160:163], v[186:189], v[52:55]
	v_mfma_f32_16x16x32_bf16 v[48:51], v[168:171], v[186:189], v[48:51]
	v_mfma_f32_16x16x32_bf16 v[44:47], v[160:163], v[194:197], v[44:47]
	v_mfma_f32_16x16x32_bf16 v[40:43], v[168:171], v[194:197], v[40:43]
	v_mfma_f32_16x16x32_bf16 v[36:39], v[160:163], v[202:205], v[36:39]
	v_mfma_f32_16x16x32_bf16 v[32:35], v[168:171], v[202:205], v[32:35]
	s_setprio 0
	s_setprio 1
	v_mfma_f32_16x16x32_bf16 v[28:31], v[206:209], v[172:175], v[28:31]
	v_mfma_f32_16x16x32_bf16 v[24:27], v[214:217], v[172:175], v[24:27]
	v_mfma_f32_16x16x32_bf16 v[20:23], v[206:209], v[182:185], v[20:23]
	v_mfma_f32_16x16x32_bf16 v[16:19], v[214:217], v[182:185], v[16:19]
	v_mfma_f32_16x16x32_bf16 v[12:15], v[206:209], v[190:193], v[12:15]
	v_mfma_f32_16x16x32_bf16 v[8:11], v[214:217], v[190:193], v[8:11]
	v_mfma_f32_16x16x32_bf16 v[4:7], v[206:209], v[198:201], v[4:7]
	v_mfma_f32_16x16x32_bf16 v[0:3], v[214:217], v[198:201], v[0:3]
	v_mfma_f32_16x16x32_bf16 v[28:31], v[210:213], v[176:179], v[28:31]
	v_mfma_f32_16x16x32_bf16 v[24:27], v[218:221], v[176:179], v[24:27]
	v_mfma_f32_16x16x32_bf16 v[20:23], v[210:213], v[186:189], v[20:23]
	v_mfma_f32_16x16x32_bf16 v[16:19], v[218:221], v[186:189], v[16:19]
	v_mfma_f32_16x16x32_bf16 v[12:15], v[210:213], v[194:197], v[12:15]
	v_mfma_f32_16x16x32_bf16 v[8:11], v[218:221], v[194:197], v[8:11]
	s_setprio 2
	s_barrier
	v_mfma_f32_16x16x32_bf16 v[4:7], v[210:213], v[202:205], v[4:7]
	v_mfma_f32_16x16x32_bf16 v[0:3], v[218:221], v[202:205], v[0:3]
	s_setprio 0
	ds_read_b128 v[132:135], v149 offset:32768
	ds_read_b128 v[158:161], v149 offset:33792
	ds_read_b128 v[162:165], v149 offset:34816
	ds_read_b128 v[166:169], v149 offset:35840
	ds_read_b128 v[170:173], v148 offset:32768
	ds_read_b128 v[174:177], v148 offset:33792
	ds_read_b128 v[182:185], v148 offset:34816
	ds_read_b128 v[186:189], v148 offset:35840
	ds_read_b128 v[190:193], v148 offset:36864
	ds_read_b128 v[194:197], v148 offset:37888
	ds_read_b128 v[198:201], v148 offset:38912
	ds_read_b128 v[202:205], v148 offset:39936
	s_waitcnt vmcnt(2)
	s_barrier
; #define LDA(dst, b, h) for (int m = 0; m < 4; ++m) for (int k = 0; k < 2; ++k) \
;     dst[m][k] = *reinterpret_cast<const bf16x8*>(a_rd + ((b) * 2 + (h)) * (HT * 2) + m * 2048 + k * 1024)
; #define LDB(dst, b, h) for (int n = 0; n < 2; ++n) for (int k = 0; k < 2; ++k) \
;     dst[n][k] = *reinterpret_cast<const bf16x8*>(b_rd + ((b) * 2 + (h)) * (HT * 2) + n * 2048 + k * 1024)
; #define MMA(ai, bj, At_, Bt_) do { __builtin_amdgcn_s_setprio(1); \
;     for (int m = 0; m < 4; ++m) for (int n = 0; n < 2; ++n) for (int k = 0; k < 2; ++k) \
;       acc[ai][bj][m][n] = __builtin_amdgcn_mfma_f32_16x16x32_bf16(Bt_[n][k], At_[m][k], acc[ai][bj][m][n], 0, 0, 0); \
;     __builtin_amdgcn_s_setprio(0); } while (0)
; #define WAIT_V(n) asm volatile("s_waitcnt vmcnt(" #n ")" ::: "memory")
; #define WAIT_L(n) asm volatile("s_waitcnt lgkmcnt(" #n ")" ::: "memory")
; #define BAR __builtin_amdgcn_s_barrier()
;     ...
;   { LDB(B0, 1, 0); LDA(At, 1, 0); WAIT_V(2); BAR; WAIT_L(0); MMA(0, 0, At, B0); BAR;
;     LDB(B1, 1, 1); WAIT_V(0); BAR; WAIT_L(0); MMA(0, 1, At, B1); BAR;
;     LDA(At, 1, 1); BAR; WAIT_L(0); MMA(1, 0, At, B0); MMA(1, 1, At, B1); BAR; }
;   if (wr == 0) BAR;
	s_waitcnt lgkmcnt(0)
	s_setprio 1
	s_waitcnt lgkmcnt(0)
	v_mfma_f32_16x16x32_bf16 v[124:127], v[132:135], v[170:173], v[124:127]
	v_mfma_f32_16x16x32_bf16 v[120:123], v[162:165], v[170:173], v[120:123]
	v_mfma_f32_16x16x32_bf16 v[116:119], v[132:135], v[182:185], v[116:119]
	v_mfma_f32_16x16x32_bf16 v[112:115], v[162:165], v[182:185], v[112:115]
	v_mfma_f32_16x16x32_bf16 v[108:111], v[132:135], v[190:193], v[108:111]
	v_mfma_f32_16x16x32_bf16 v[104:107], v[162:165], v[190:193], v[104:107]
	v_mfma_f32_16x16x32_bf16 v[100:103], v[132:135], v[198:201], v[100:103]
	v_mfma_f32_16x16x32_bf16 v[96:99], v[162:165], v[198:201], v[96:99]
	v_mfma_f32_16x16x32_bf16 v[124:127], v[158:161], v[174:177], v[124:127]
	v_mfma_f32_16x16x32_bf16 v[120:123], v[166:169], v[174:177], v[120:123]
	v_mfma_f32_16x16x32_bf16 v[116:119], v[158:161], v[186:189], v[116:119]
	v_mfma_f32_16x16x32_bf16 v[112:115], v[166:169], v[186:189], v[112:115]
	v_mfma_f32_16x16x32_bf16 v[108:111], v[158:161], v[194:197], v[108:111]
	v_mfma_f32_16x16x32_bf16 v[104:107], v[166:169], v[194:197], v[104:107]
	s_setprio 2
	s_barrier
	v_mfma_f32_16x16x32_bf16 v[100:103], v[158:161], v[202:205], v[100:103]
	v_mfma_f32_16x16x32_bf16 v[96:99], v[166:169], v[202:205], v[96:99]
	s_setprio 0
	ds_read_b128 v[206:209], v149 offset:49152
	ds_read_b128 v[210:213], v149 offset:50176
	ds_read_b128 v[214:217], v149 offset:51200
	ds_read_b128 v[218:221], v149 offset:52224
	s_waitcnt vmcnt(0)
	s_barrier
	s_waitcnt lgkmcnt(0)
	s_setprio 1
	s_waitcnt lgkmcnt(0)
	v_mfma_f32_16x16x32_bf16 v[92:95], v[206:209], v[170:173], v[92:95]
	v_mfma_f32_16x16x32_bf16 v[88:91], v[214:217], v[170:173], v[88:91]
	v_mfma_f32_16x16x32_bf16 v[84:87], v[206:209], v[182:185], v[84:87]
	v_mfma_f32_16x16x32_bf16 v[80:83], v[214:217], v[182:185], v[80:83]
	v_mfma_f32_16x16x32_bf16 v[76:79], v[206:209], v[190:193], v[76:79]
	v_mfma_f32_16x16x32_bf16 v[72:75], v[214:217], v[190:193], v[72:75]
	v_mfma_f32_16x16x32_bf16 v[68:71], v[206:209], v[198:201], v[68:71]
	v_mfma_f32_16x16x32_bf16 v[64:67], v[214:217], v[198:201], v[64:67]
	v_mfma_f32_16x16x32_bf16 v[92:95], v[210:213], v[174:177], v[92:95]
	v_mfma_f32_16x16x32_bf16 v[88:91], v[218:221], v[174:177], v[88:91]
	v_mfma_f32_16x16x32_bf16 v[84:87], v[210:213], v[186:189], v[84:87]
	v_mfma_f32_16x16x32_bf16 v[80:83], v[218:221], v[186:189], v[80:83]
	v_mfma_f32_16x16x32_bf16 v[76:79], v[210:213], v[194:197], v[76:79]
	v_mfma_f32_16x16x32_bf16 v[72:75], v[218:221], v[194:197], v[72:75]
	s_setprio 2
	s_barrier
	v_mfma_f32_16x16x32_bf16 v[68:71], v[210:213], v[202:205], v[68:71]
	v_mfma_f32_16x16x32_bf16 v[64:67], v[218:221], v[202:205], v[64:67]
	s_setprio 0
	ds_read_b128 v[170:173], v148 offset:49152
	ds_read_b128 v[174:177], v148 offset:50176
	ds_read_b128 v[182:185], v148 offset:51200
	ds_read_b128 v[186:189], v148 offset:52224
	ds_read_b128 v[190:193], v148 offset:53248
	ds_read_b128 v[194:197], v148 offset:54272
	ds_read_b128 v[198:201], v148 offset:55296
	ds_read_b128 v[202:205], v148 offset:56320
	s_barrier
	s_waitcnt lgkmcnt(0)
	s_setprio 1
	s_waitcnt lgkmcnt(0)
	v_mfma_f32_16x16x32_bf16 v[60:63], v[132:135], v[170:173], v[60:63]
	v_mfma_f32_16x16x32_bf16 v[56:59], v[162:165], v[170:173], v[56:59]
	v_mfma_f32_16x16x32_bf16 v[52:55], v[132:135], v[182:185], v[52:55]
	v_mfma_f32_16x16x32_bf16 v[48:51], v[162:165], v[182:185], v[48:51]
	v_mfma_f32_16x16x32_bf16 v[44:47], v[132:135], v[190:193], v[44:47]
	v_mfma_f32_16x16x32_bf16 v[40:43], v[162:165], v[190:193], v[40:43]
	v_mfma_f32_16x16x32_bf16 v[36:39], v[132:135], v[198:201], v[36:39]
	v_mfma_f32_16x16x32_bf16 v[32:35], v[162:165], v[198:201], v[32:35]
	v_mfma_f32_16x16x32_bf16 v[60:63], v[158:161], v[174:177], v[60:63]
	v_mfma_f32_16x16x32_bf16 v[56:59], v[166:169], v[174:177], v[56:59]
	v_mfma_f32_16x16x32_bf16 v[52:55], v[158:161], v[186:189], v[52:55]
	v_mfma_f32_16x16x32_bf16 v[48:51], v[166:169], v[186:189], v[48:51]
	v_mfma_f32_16x16x32_bf16 v[44:47], v[158:161], v[194:197], v[44:47]
	v_mfma_f32_16x16x32_bf16 v[40:43], v[166:169], v[194:197], v[40:43]
	v_mfma_f32_16x16x32_bf16 v[36:39], v[158:161], v[202:205], v[36:39]
	v_mfma_f32_16x16x32_bf16 v[32:35], v[166:169], v[202:205], v[32:35]
	s_setprio 0
	s_setprio 1
	v_mfma_f32_16x16x32_bf16 v[28:31], v[206:209], v[170:173], v[28:31]
	v_mfma_f32_16x16x32_bf16 v[24:27], v[214:217], v[170:173], v[24:27]
	v_mfma_f32_16x16x32_bf16 v[20:23], v[206:209], v[182:185], v[20:23]
	v_mfma_f32_16x16x32_bf16 v[16:19], v[214:217], v[182:185], v[16:19]
	v_mfma_f32_16x16x32_bf16 v[12:15], v[206:209], v[190:193], v[12:15]
	v_mfma_f32_16x16x32_bf16 v[8:11], v[214:217], v[190:193], v[8:11]
	v_mfma_f32_16x16x32_bf16 v[4:7], v[206:209], v[198:201], v[4:7]
	v_mfma_f32_16x16x32_bf16 v[0:3], v[214:217], v[198:201], v[0:3]
	v_mfma_f32_16x16x32_bf16 v[28:31], v[210:213], v[174:177], v[28:31]
	v_mfma_f32_16x16x32_bf16 v[24:27], v[218:221], v[174:177], v[24:27]
	v_mfma_f32_16x16x32_bf16 v[20:23], v[210:213], v[186:189], v[20:23]
	v_mfma_f32_16x16x32_bf16 v[16:19], v[218:221], v[186:189], v[16:19]
	v_mfma_f32_16x16x32_bf16 v[12:15], v[210:213], v[194:197], v[12:15]
	v_mfma_f32_16x16x32_bf16 v[8:11], v[218:221], v[194:197], v[8:11]
	s_setprio 2
	s_barrier
	v_mfma_f32_16x16x32_bf16 v[4:7], v[210:213], v[202:205], v[4:7]
	v_mfma_f32_16x16x32_bf16 v[0:3], v[218:221], v[202:205], v[0:3]
	s_setprio 0
	v_cmp_gt_u32_e32 vcc, s60, v139
	s_and_saveexec_b64 s[26:27], vcc
	s_cbranch_execz .LBB0_1868
	s_barrier

; #define STAGE_A(P, br, kt) do { const char* _base = (const char*)(((kt) < G.ksplit ? G.A1 : A2m) + (long)(br) * G.lda + (long)(kt) * BK); \
;     __builtin_amdgcn_global_load_lds((const unsigned*)(_base + aoff0), (unsigned*)((char*)(P) + sb0), 16, 0, 0); \
;     __builtin_amdgcn_global_load_lds((const unsigned*)(_base + aoff1), (unsigned*)((char*)(P) + sb1), 16, 0, 0); } while (0)
; #define STAGE_B(P, br, kt) do { const char* _base = (const char*)(G.Bt + (long)(br) * G.ldb + (long)(kt) * BK); \
;     __builtin_amdgcn_global_load_lds((const unsigned*)(_base + boff0), (unsigned*)((char*)(P) + sb0), 16, 0, 0); \
;     __builtin_amdgcn_global_load_lds((const unsigned*)(_base + boff1), (unsigned*)((char*)(P) + sb1), 16, 0, 0); } while (0)
; #define LDA(dst, b, h) for (int m = 0; m < 4; ++m) for (int k = 0; k < 2; ++k) \
;     dst[m][k] = *reinterpret_cast<const bf16x8*>(a_rd + ((b) * 2 + (h)) * (HT * 2) + m * 2048 + k * 1024)
; #define LDB(dst, b, h) for (int n = 0; n < 2; ++n) for (int k = 0; k < 2; ++k) \
;     dst[n][k] = *reinterpret_cast<const bf16x8*>(b_rd + ((b) * 2 + (h)) * (HT * 2) + n * 2048 + k * 1024)
;     ...
;   const int K = G.K;
;   const u16* A2m = G.A2 - (long)G.ksplit * BK;
;   int t1 = otid();
;   const int wid = t1 >> 6, lane = t1 & 63, wr = wid >> 2, wc = wid & 3, fr = lane & 15, fq = lane >> 4;
;   const int sb0 = t1 * 16, sb1 = sb0 + 8192;
;   const int swz_ = lds_byte(fr, fq * 8);
;   const char* a_rd = shmc + wr * 8192 + swz_;
;   const char* b_rd = shmc + 4 * (HT * 2) + wc * 4096 + swz_;
;   int r0_, c0_, r1_, c1_; stage_rc(sb0, r0_, c0_); stage_rc(sb1, r1_, c1_);
;   const unsigned aoff0 = (unsigned)(r0_ * G.lda + c0_) * 2u, aoff1 = (unsigned)(r1_ * G.lda + c1_) * 2u;
;   const unsigned boff0 = (unsigned)(r0_ * G.ldb + c0_) * 2u, boff1 = (unsigned)(r1_ * G.ldb + c1_) * 2u;
;   f32x4 acc[2][2][4][2] = {};
;   bf16x8 At[4][2], B0[2][2], B1[2][2];
;   const int nt = K / BK;
;   if (EPI == EPI_RESID || first) {
;     STAGE_B(SB(0, 0), bcol, 0); STAGE_A(SA(0, 0), brow, 0);
;     STAGE_B(SB(0, 1), bcol + HALF, 0); STAGE_A(SA(0, 1), brow + HALF, 0);
;   }
;   if (wr == 1) BAR;
;   WAIT_V(0); BAR;
;   STAGE_B(SB(1, 0), bcol, 1); STAGE_A(SA(1, 0), brow, 1); STAGE_B(SB(1, 1), bcol + HALF, 1);
;   WAIT_V(6); BAR;
;   for (int t = 0; t < nt - 2; t += 2) {
;     LDB(B0, 0, 0); SCHED; LDA(At, 0, 0); STAGE_A(SA(1, 1), brow + HALF, t + 1);
.LBB0_2500:
	s_or_b64 exec, exec, s[8:9]
	v_and_b32_e32 v20, 15, v144
	v_lshlrev_b32_e32 v22, 2, v144
	v_and_b32_e32 v21, 48, v144
	v_lshlrev_b32_e32 v20, 6, v20
	v_and_b32_e32 v22, 32, v22
	v_bitop3_b32 v20, v20, v22, v21 bitop3:0x36
	v_lshlrev_b32_e32 v21, 6, v144
	v_and_b32_e32 v21, 0x3000, v21
	v_add_u32_e32 v21, s35, v21
	v_readlane_b32 s35, v253, 46
	s_mov_b64 s[38:39], 0x80
	v_lshl_add_u64 v[2:3], v[2:3], 0, s[38:39]
	v_add_u32_e32 v153, s35, v12
	v_add_u32_e32 v154, 0x2000, v153
	v_readfirstlane_b32 s35, v153
	s_mov_b32 m0, s35
	v_readfirstlane_b32 s35, v154
	v_add_u32_e32 v155, 0x8000, v147
	s_waitcnt vmcnt(0)
	s_barrier
	global_load_lds_dwordx4 v[2:3], off
	v_lshl_add_u64 v[2:3], v[4:5], 0, s[38:39]
	s_mov_b32 m0, s35
	v_readfirstlane_b32 s35, v155
	v_add_u32_e32 v156, 0xa000, v147
	global_load_lds_dwordx4 v[2:3], off
	v_lshl_add_u64 v[2:3], v[6:7], 0, s[38:39]
	s_mov_b32 m0, s35
	v_readfirstlane_b32 s35, v156
	s_lshl_b64 s[8:9], s[18:19], 10
	global_load_lds_dwordx4 v[2:3], off
	s_mov_b32 m0, s35
	v_readlane_b32 s35, v253, 47
	s_add_u32 s36, s36, 0x84080
	v_lshl_add_u64 v[2:3], v[8:9], 0, s[38:39]
	v_add_u32_e32 v157, s35, v12
	s_addc_u32 s37, s37, 0
	v_readfirstlane_b32 s35, v157
	v_add_u32_e32 v158, 0x2000, v157
	global_load_lds_dwordx4 v[2:3], off
	v_lshl_add_u64 v[2:3], s[36:37], 0, v[180:181]
	s_mov_b32 m0, s35
	v_readfirstlane_b32 s35, v158
	global_load_lds_dwordx4 v[2:3], off
	v_lshl_add_u64 v[0:1], s[36:37], 0, v[0:1]
	s_mov_b32 m0, s35
	v_lshrrev_b32_e32 v2, 1, v11
	global_load_lds_dwordx4 v[0:1], off
	v_lshrrev_b32_e32 v1, 1, v10
	v_mul_lo_u32 v0, v13, s62
	v_mad_u64_u32 v[0:1], s[36:37], v1, s84, v[0:1]
	v_or_b32_e32 v0, v0, v14
	v_add_lshl_u32 v180, v0, v16, 1
	v_mul_lo_u32 v0, v15, s62
	v_lshlrev_b32_e32 v3, 11, v15
	v_mad_u64_u32 v[0:1], s[36:37], v2, s84, v[0:1]
	v_lshl_add_u32 v2, v2, 15, v3
	v_and_b32_e32 v3, 1, v11
	s_add_u32 s24, s12, s24
	v_lshl_or_b32 v2, v3, 6, v2
	s_addc_u32 s25, s13, s25
	v_lshl_add_u32 v2, v17, 1, v2
	v_mov_b32_e32 v3, v181
	v_or_b32_e32 v0, v0, v18
	v_lshl_add_u64 v[136:137], s[10:11], 0, v[130:131]
	v_lshl_add_u64 v[138:139], s[10:11], 0, v[2:3]
	s_add_u32 s10, s12, s22
	s_waitcnt vmcnt(6)
	v_add_lshl_u32 v0, v0, v17, 1
	v_mov_b32_e32 v1, v181
	s_addc_u32 s11, s13, s23
	v_lshl_add_u32 v19, v19, 13, 32
	v_lshl_add_u64 v[134:135], s[24:25], 0, v[0:1]
	v_lshl_add_u64 v[142:143], s[10:11], 0, v[0:1]
	v_mov_b32_e32 v0, 0
	v_lshl_add_u64 v[132:133], s[24:25], 0, v[180:181]
	v_lshl_add_u64 v[140:141], s[10:11], 0, v[180:181]
	s_mov_b32 s22, -2
	s_mov_b64 s[10:11], 0
	v_add_u32_e32 v149, v21, v20
	v_add_u32_e32 v146, v19, v20
	v_mov_b32_e32 v1, v0
	v_mov_b32_e32 v2, v0
	v_mov_b32_e32 v3, v0
	v_mov_b32_e32 v4, v0
	v_mov_b32_e32 v5, v0
	v_mov_b32_e32 v6, v0
	v_mov_b32_e32 v7, v0
	v_mov_b32_e32 v8, v0
	v_mov_b32_e32 v9, v0
	v_mov_b32_e32 v10, v0
	v_mov_b32_e32 v11, v0
	v_mov_b32_e32 v12, v0
	v_mov_b32_e32 v13, v0
	v_mov_b32_e32 v14, v0
	v_mov_b32_e32 v15, v0
	v_mov_b32_e32 v16, v0
	v_mov_b32_e32 v17, v0
	v_mov_b32_e32 v18, v0
	v_mov_b32_e32 v19, v0
	v_mov_b32_e32 v20, v0
	v_mov_b32_e32 v21, v0
	v_mov_b32_e32 v22, v0
	v_mov_b32_e32 v23, v0
	s_waitcnt vmcnt(0)
	v_mov_b32_e32 v24, v0
	v_mov_b32_e32 v25, v0
	v_mov_b32_e32 v26, v0
	v_mov_b32_e32 v27, v0
	v_mov_b32_e32 v28, v0
	v_mov_b32_e32 v29, v0
	v_mov_b32_e32 v30, v0
	v_mov_b32_e32 v31, v0
	v_mov_b32_e32 v32, v0
	v_mov_b32_e32 v33, v0
	v_mov_b32_e32 v34, v0
	v_mov_b32_e32 v35, v0
	v_mov_b32_e32 v36, v0
	v_mov_b32_e32 v37, v0
	v_mov_b32_e32 v38, v0
	v_mov_b32_e32 v39, v0
	v_mov_b32_e32 v40, v0
	v_mov_b32_e32 v41, v0
	v_mov_b32_e32 v42, v0
	v_mov_b32_e32 v43, v0
	v_mov_b32_e32 v44, v0
	v_mov_b32_e32 v45, v0
	v_mov_b32_e32 v46, v0
	v_mov_b32_e32 v47, v0
	v_mov_b32_e32 v48, v0
	v_mov_b32_e32 v49, v0
	v_mov_b32_e32 v50, v0
	v_mov_b32_e32 v51, v0
	v_mov_b32_e32 v52, v0
	v_mov_b32_e32 v53, v0
	v_mov_b32_e32 v54, v0
	v_mov_b32_e32 v55, v0
	v_mov_b32_e32 v56, v0
	v_mov_b32_e32 v57, v0
	v_mov_b32_e32 v58, v0
	v_mov_b32_e32 v59, v0
	v_mov_b32_e32 v60, v0
	v_mov_b32_e32 v61, v0
	v_mov_b32_e32 v62, v0
	v_mov_b32_e32 v63, v0
	v_mov_b32_e32 v64, v0
	v_mov_b32_e32 v65, v0
	v_mov_b32_e32 v66, v0
	v_mov_b32_e32 v67, v0
	v_mov_b32_e32 v68, v0
	v_mov_b32_e32 v69, v0
	v_mov_b32_e32 v70, v0
	v_mov_b32_e32 v71, v0
	v_mov_b32_e32 v72, v0
	v_mov_b32_e32 v73, v0
	v_mov_b32_e32 v74, v0
	v_mov_b32_e32 v75, v0
	v_mov_b32_e32 v76, v0
	v_mov_b32_e32 v77, v0
	v_mov_b32_e32 v78, v0
	v_mov_b32_e32 v79, v0
	v_mov_b32_e32 v80, v0
	v_mov_b32_e32 v81, v0
	v_mov_b32_e32 v82, v0
	v_mov_b32_e32 v83, v0
	v_mov_b32_e32 v84, v0
	v_mov_b32_e32 v85, v0
	v_mov_b32_e32 v86, v0
	v_mov_b32_e32 v87, v0
	v_mov_b32_e32 v88, v0
	v_mov_b32_e32 v89, v0
	v_mov_b32_e32 v90, v0
	v_mov_b32_e32 v91, v0
	v_mov_b32_e32 v92, v0
	v_mov_b32_e32 v93, v0
	v_mov_b32_e32 v94, v0
	v_mov_b32_e32 v95, v0
	v_mov_b32_e32 v96, v0
	v_mov_b32_e32 v97, v0
	v_mov_b32_e32 v98, v0
	v_mov_b32_e32 v99, v0
	v_mov_b32_e32 v100, v0
	v_mov_b32_e32 v101, v0
	v_mov_b32_e32 v102, v0
	v_mov_b32_e32 v103, v0
	v_mov_b32_e32 v104, v0
	v_mov_b32_e32 v105, v0
	v_mov_b32_e32 v106, v0
	v_mov_b32_e32 v107, v0
	v_mov_b32_e32 v108, v0
	v_mov_b32_e32 v109, v0
	v_mov_b32_e32 v110, v0
	v_mov_b32_e32 v111, v0
	v_mov_b32_e32 v112, v0
	v_mov_b32_e32 v113, v0
	v_mov_b32_e32 v114, v0
	v_mov_b32_e32 v115, v0
	v_mov_b32_e32 v116, v0
	v_mov_b32_e32 v117, v0
	v_mov_b32_e32 v118, v0
	v_mov_b32_e32 v119, v0
	v_mov_b32_e32 v120, v0
	v_mov_b32_e32 v121, v0
	v_mov_b32_e32 v122, v0
	v_mov_b32_e32 v123, v0
	v_mov_b32_e32 v124, v0
	v_mov_b32_e32 v125, v0
	v_mov_b32_e32 v126, v0
	v_mov_b32_e32 v127, v0
	s_mov_b64 s[36:37], 0x40080
	s_mov_b64 s[38:39], 0x54e8100
	s_mov_b64 s[40:41], 0x556c100
	s_mov_b64 s[42:43], 0x40100
	s_mov_b64 s[44:45], 0x54e8180
	s_mov_b64 s[46:47], 0x556c180
	s_barrier
	ds_read_b128 v[162:165], v149
	ds_read_b128 v[166:169], v149 offset:1024
	ds_read_b128 v[170:173], v149 offset:2048
	ds_read_b128 v[174:177], v149 offset:3072
; #define STAGE_A(P, br, kt) do { const char* _base = (const char*)(((kt) < G.ksplit ? G.A1 : A2m) + (long)(br) * G.lda + (long)(kt) * BK); \
;     __builtin_amdgcn_global_load_lds((const unsigned*)(_base + aoff0), (unsigned*)((char*)(P) + sb0), 16, 0, 0); \
;     __builtin_amdgcn_global_load_lds((const unsigned*)(_base + aoff1), (unsigned*)((char*)(P) + sb1), 16, 0, 0); } while (0)
; #define STAGE_B(P, br, kt) do { const char* _base = (const char*)(G.Bt + (long)(br) * G.ldb + (long)(kt) * BK); \
;     __builtin_amdgcn_global_load_lds((const unsigned*)(_base + boff0), (unsigned*)((char*)(P) + sb0), 16, 0, 0); \
;     __builtin_amdgcn_global_load_lds((const unsigned*)(_base + boff1), (unsigned*)((char*)(P) + sb1), 16, 0, 0); } while (0)
; #define LDA(dst, b, h) for (int m = 0; m < 4; ++m) for (int k = 0; k < 2; ++k) \
;     dst[m][k] = *reinterpret_cast<const bf16x8*>(a_rd + ((b) * 2 + (h)) * (HT * 2) + m * 2048 + k * 1024)
; #define LDB(dst, b, h) for (int n = 0; n < 2; ++n) for (int k = 0; k < 2; ++k) \
;     dst[n][k] = *reinterpret_cast<const bf16x8*>(b_rd + ((b) * 2 + (h)) * (HT * 2) + n * 2048 + k * 1024)
; #define MMA(ai, bj, At_, Bt_) do { __builtin_amdgcn_s_setprio(1); \
;     for (int m = 0; m < 4; ++m) for (int n = 0; n < 2; ++n) for (int k = 0; k < 2; ++k) \
;       acc[ai][bj][m][n] = __builtin_amdgcn_mfma_f32_16x16x32_bf16(Bt_[n][k], At_[m][k], acc[ai][bj][m][n], 0, 0, 0); \
;     __builtin_amdgcn_s_setprio(0); } while (0)
; #define WAIT_L(n) asm volatile("s_waitcnt lgkmcnt(" #n ")" ::: "memory")
; #define BAR __builtin_amdgcn_s_barrier()
; #define SCHED __builtin_amdgcn_sched_barrier(0)
;     ...
;     LDB(B0, 0, 0); SCHED; LDA(At, 0, 0); STAGE_A(SA(1, 1), brow + HALF, t + 1);
;     WAIT_L(8); BAR; WAIT_L(0); MMA(0, 0, At, B0); BAR; SCHED;
;     LDB(B1, 0, 1); STAGE_B(SB(0, 0), bcol, t + 2);
;     BAR; WAIT_L(0); MMA(0, 1, At, B1); BAR;
;     LDA(At, 0, 1); STAGE_A(SA(0, 0), brow, t + 2);
;     BAR; WAIT_L(0); MMA(1, 0, At, B0); BAR; SCHED;
.LBB0_2501:
	s_add_i32 s22, s22, 2
	s_cmp_lt_u32 s22, 16
	s_cselect_b32 s25, s28, s34
	s_cselect_b32 s24, s27, s31
	v_lshl_add_u64 v[160:161], s[24:25], 0, v[136:137]
	v_add_u32_e32 v159, 0xc000, v147
	v_lshl_add_u64 v[160:161], v[160:161], 0, s[10:11]
	v_readfirstlane_b32 s23, v159
	v_lshl_add_u64 v[160:161], v[160:161], 0, s[36:37]
	s_mov_b32 m0, s23
	ds_read_b128 v[182:185], v146
	ds_read_b128 v[186:189], v146 offset:1024
	ds_read_b128 v[190:193], v146 offset:2048
	ds_read_b128 v[194:197], v146 offset:3072
	ds_read_b128 v[198:201], v146 offset:4096
	ds_read_b128 v[202:205], v146 offset:5120
	ds_read_b128 v[206:209], v146 offset:6144
	ds_read_b128 v[210:213], v146 offset:7168
	global_load_lds_dwordx4 v[160:161], off
	v_lshl_add_u64 v[160:161], s[24:25], 0, v[138:139]
	v_lshl_add_u64 v[160:161], v[160:161], 0, s[10:11]
	v_lshl_add_u64 v[178:179], v[160:161], 0, s[36:37]
	v_add_u32_e32 v160, 0xe000, v147
	s_nop 0
	v_readfirstlane_b32 s23, v160
	s_mov_b32 m0, s23
	s_nop 0
	global_load_lds_dwordx4 v[178:179], off
	s_waitcnt lgkmcnt(8)
	s_barrier
	s_waitcnt lgkmcnt(0)
	s_setprio 1
	s_waitcnt lgkmcnt(0)
	v_mfma_f32_16x16x32_bf16 v[124:127], v[162:165], v[182:185], v[124:127]
	v_mfma_f32_16x16x32_bf16 v[120:123], v[170:173], v[182:185], v[120:123]
	v_mfma_f32_16x16x32_bf16 v[116:119], v[162:165], v[190:193], v[116:119]
	v_mfma_f32_16x16x32_bf16 v[112:115], v[170:173], v[190:193], v[112:115]
	v_mfma_f32_16x16x32_bf16 v[108:111], v[162:165], v[198:201], v[108:111]
	v_mfma_f32_16x16x32_bf16 v[104:107], v[170:173], v[198:201], v[104:107]
	v_mfma_f32_16x16x32_bf16 v[100:103], v[162:165], v[206:209], v[100:103]
	v_mfma_f32_16x16x32_bf16 v[96:99], v[170:173], v[206:209], v[96:99]
	v_mfma_f32_16x16x32_bf16 v[124:127], v[166:169], v[186:189], v[124:127]
	v_mfma_f32_16x16x32_bf16 v[120:123], v[174:177], v[186:189], v[120:123]
	v_mfma_f32_16x16x32_bf16 v[116:119], v[166:169], v[194:197], v[116:119]
	v_mfma_f32_16x16x32_bf16 v[112:115], v[174:177], v[194:197], v[112:115]
	v_mfma_f32_16x16x32_bf16 v[108:111], v[166:169], v[202:205], v[108:111]
	v_mfma_f32_16x16x32_bf16 v[104:107], v[174:177], v[202:205], v[104:107]
	s_setprio 2
	s_barrier
	v_mfma_f32_16x16x32_bf16 v[100:103], v[166:169], v[210:213], v[100:103]
	v_mfma_f32_16x16x32_bf16 v[96:99], v[174:177], v[210:213], v[96:99]
	s_setprio 0
	v_lshl_add_u64 v[178:179], v[132:133], 0, s[10:11]
	v_readfirstlane_b32 s23, v145
	v_lshl_add_u64 v[222:223], v[178:179], 0, s[38:39]
	s_mov_b32 m0, s23
	v_add_u32_e32 v161, 0x2000, v145
	ds_read_b128 v[214:217], v149 offset:16384
	ds_read_b128 v[218:221], v149 offset:17408
	ds_read_b128 v[246:249], v149 offset:18432
	ds_read_b128 v[230:233], v149 offset:19456
	global_load_lds_dwordx4 v[222:223], off
	v_lshl_add_u64 v[222:223], v[134:135], 0, s[10:11]
	v_readfirstlane_b32 s23, v161
	v_lshl_add_u64 v[234:235], v[222:223], 0, s[38:39]
	s_mov_b32 m0, s23
	s_nop 0
	global_load_lds_dwordx4 v[234:235], off
	s_barrier
	s_waitcnt lgkmcnt(0)
	s_setprio 1
	s_waitcnt lgkmcnt(0)
	v_mfma_f32_16x16x32_bf16 v[92:95], v[214:217], v[182:185], v[92:95]
	v_mfma_f32_16x16x32_bf16 v[88:91], v[246:249], v[182:185], v[88:91]
	v_mfma_f32_16x16x32_bf16 v[84:87], v[214:217], v[190:193], v[84:87]
	v_mfma_f32_16x16x32_bf16 v[80:83], v[246:249], v[190:193], v[80:83]
	v_mfma_f32_16x16x32_bf16 v[76:79], v[214:217], v[198:201], v[76:79]
	v_mfma_f32_16x16x32_bf16 v[72:75], v[246:249], v[198:201], v[72:75]
	v_mfma_f32_16x16x32_bf16 v[68:71], v[214:217], v[206:209], v[68:71]
	v_mfma_f32_16x16x32_bf16 v[64:67], v[246:249], v[206:209], v[64:67]
	v_mfma_f32_16x16x32_bf16 v[92:95], v[218:221], v[186:189], v[92:95]
	v_mfma_f32_16x16x32_bf16 v[88:91], v[230:233], v[186:189], v[88:91]
	v_mfma_f32_16x16x32_bf16 v[84:87], v[218:221], v[194:197], v[84:87]
	v_mfma_f32_16x16x32_bf16 v[80:83], v[230:233], v[194:197], v[80:83]
	v_mfma_f32_16x16x32_bf16 v[76:79], v[218:221], v[202:205], v[76:79]
	v_mfma_f32_16x16x32_bf16 v[72:75], v[230:233], v[202:205], v[72:75]
	s_setprio 2
	s_barrier
	v_mfma_f32_16x16x32_bf16 v[68:71], v[218:221], v[210:213], v[68:71]
	v_mfma_f32_16x16x32_bf16 v[64:67], v[230:233], v[210:213], v[64:67]
	s_setprio 0
	s_cmp_lt_u32 s22, 14
	s_cselect_b32 s25, s28, s34
	s_cselect_b32 s24, s27, s31
	v_lshl_add_u64 v[234:235], s[24:25], 0, v[136:137]
	v_lshl_add_u64 v[234:235], v[234:235], 0, s[10:11]
	v_readfirstlane_b32 s23, v147
	v_lshl_add_u64 v[236:237], v[234:235], 0, s[90:91]
	s_mov_b32 m0, s23
	ds_read_b128 v[182:185], v146 offset:16384
	ds_read_b128 v[186:189], v146 offset:17408
	ds_read_b128 v[190:193], v146 offset:18432
	ds_read_b128 v[194:197], v146 offset:19456
	ds_read_b128 v[198:201], v146 offset:20480
	ds_read_b128 v[202:205], v146 offset:21504
	ds_read_b128 v[206:209], v146 offset:22528
	ds_read_b128 v[210:213], v146 offset:23552
	global_load_lds_dwordx4 v[236:237], off
	v_lshl_add_u64 v[236:237], s[24:25], 0, v[138:139]
	v_lshl_add_u64 v[236:237], v[236:237], 0, s[10:11]
	v_readfirstlane_b32 s23, v148
	v_lshl_add_u64 v[238:239], v[236:237], 0, s[90:91]
	s_mov_b32 m0, s23
	s_nop 0
	global_load_lds_dwordx4 v[238:239], off
	s_waitcnt vmcnt(10)
	s_barrier
	s_waitcnt lgkmcnt(0)
	s_setprio 1
	s_waitcnt lgkmcnt(0)
	v_mfma_f32_16x16x32_bf16 v[60:63], v[162:165], v[182:185], v[60:63]
	v_mfma_f32_16x16x32_bf16 v[56:59], v[170:173], v[182:185], v[56:59]
	v_mfma_f32_16x16x32_bf16 v[52:55], v[162:165], v[190:193], v[52:55]
	v_mfma_f32_16x16x32_bf16 v[48:51], v[170:173], v[190:193], v[48:51]
	v_mfma_f32_16x16x32_bf16 v[44:47], v[162:165], v[198:201], v[44:47]
	v_mfma_f32_16x16x32_bf16 v[40:43], v[170:173], v[198:201], v[40:43]
	v_mfma_f32_16x16x32_bf16 v[36:39], v[162:165], v[206:209], v[36:39]
	v_mfma_f32_16x16x32_bf16 v[32:35], v[170:173], v[206:209], v[32:35]
	v_mfma_f32_16x16x32_bf16 v[60:63], v[166:169], v[186:189], v[60:63]
	v_mfma_f32_16x16x32_bf16 v[56:59], v[174:177], v[186:189], v[56:59]
	v_mfma_f32_16x16x32_bf16 v[52:55], v[166:169], v[194:197], v[52:55]
	v_mfma_f32_16x16x32_bf16 v[48:51], v[174:177], v[194:197], v[48:51]
	v_mfma_f32_16x16x32_bf16 v[44:47], v[166:169], v[202:205], v[44:47]
	v_mfma_f32_16x16x32_bf16 v[40:43], v[174:177], v[202:205], v[40:43]
	s_setprio 2
	s_barrier
; #define STAGE_A(P, br, kt) do { const char* _base = (const char*)(((kt) < G.ksplit ? G.A1 : A2m) + (long)(br) * G.lda + (long)(kt) * BK); \
;     __builtin_amdgcn_global_load_lds((const unsigned*)(_base + aoff0), (unsigned*)((char*)(P) + sb0), 16, 0, 0); \
;     __builtin_amdgcn_global_load_lds((const unsigned*)(_base + aoff1), (unsigned*)((char*)(P) + sb1), 16, 0, 0); } while (0)
; #define STAGE_B(P, br, kt) do { const char* _base = (const char*)(G.Bt + (long)(br) * G.ldb + (long)(kt) * BK); \
;     __builtin_amdgcn_global_load_lds((const unsigned*)(_base + boff0), (unsigned*)((char*)(P) + sb0), 16, 0, 0); \
;     __builtin_amdgcn_global_load_lds((const unsigned*)(_base + boff1), (unsigned*)((char*)(P) + sb1), 16, 0, 0); } while (0)
; #define LDA(dst, b, h) for (int m = 0; m < 4; ++m) for (int k = 0; k < 2; ++k) \
;     dst[m][k] = *reinterpret_cast<const bf16x8*>(a_rd + ((b) * 2 + (h)) * (HT * 2) + m * 2048 + k * 1024)
; #define LDB(dst, b, h) for (int n = 0; n < 2; ++n) for (int k = 0; k < 2; ++k) \
;     dst[n][k] = *reinterpret_cast<const bf16x8*>(b_rd + ((b) * 2 + (h)) * (HT * 2) + n * 2048 + k * 1024)
; #define MMA(ai, bj, At_, Bt_) do { __builtin_amdgcn_s_setprio(1); \
;     for (int m = 0; m < 4; ++m) for (int n = 0; n < 2; ++n) for (int k = 0; k < 2; ++k) \
;       acc[ai][bj][m][n] = __builtin_amdgcn_mfma_f32_16x16x32_bf16(Bt_[n][k], At_[m][k], acc[ai][bj][m][n], 0, 0, 0); \
;     __builtin_amdgcn_s_setprio(0); } while (0)
; #define WAIT_V(n) asm volatile("s_waitcnt vmcnt(" #n ")" ::: "memory")
; #define WAIT_L(n) asm volatile("s_waitcnt lgkmcnt(" #n ")" ::: "memory")
; #define BAR __builtin_amdgcn_s_barrier()
; #define SCHED __builtin_amdgcn_sched_barrier(0)
;     ...
;     BAR; WAIT_L(0); MMA(1, 0, At, B0); BAR; SCHED;
;     STAGE_B(SB(0, 1), bcol + HALF, t + 2);
;     WAIT_V(6); BAR; MMA(1, 1, At, B1); BAR;
;     LDB(B0, 1, 0); SCHED; LDA(At, 1, 0); STAGE_A(SA(0, 1), brow + HALF, t + 2);
;     WAIT_L(8); BAR; WAIT_L(0); MMA(0, 0, At, B0); BAR; SCHED;
;     LDB(B1, 1, 1); STAGE_B(SB(1, 0), bcol, t + 3);
;     BAR; WAIT_L(0); MMA(0, 1, At, B1); BAR;
	v_mfma_f32_16x16x32_bf16 v[36:39], v[166:169], v[210:213], v[36:39]
	v_mfma_f32_16x16x32_bf16 v[32:35], v[174:177], v[210:213], v[32:35]
	s_setprio 0
	v_lshl_add_u64 v[238:239], v[140:141], 0, s[10:11]
	v_readfirstlane_b32 s23, v150
	v_add_u32_e32 v161, 0x2000, v150
	v_lshl_add_u64 v[162:163], v[238:239], 0, s[40:41]
	s_mov_b32 m0, s23
	v_lshl_add_u64 v[240:241], v[142:143], 0, s[10:11]
	v_readfirstlane_b32 s23, v161
	global_load_lds_dwordx4 v[162:163], off
	v_lshl_add_u64 v[162:163], v[240:241], 0, s[40:41]
	s_mov_b32 m0, s23
	s_nop 0
	global_load_lds_dwordx4 v[162:163], off
	ds_read_b128 v[162:165], v149 offset:32768
	ds_read_b128 v[166:169], v149 offset:33792
	ds_read_b128 v[170:173], v149 offset:34816
	ds_read_b128 v[174:177], v149 offset:35840
	s_waitcnt vmcnt(6)
	s_barrier
	s_setprio 1
	v_mfma_f32_16x16x32_bf16 v[28:31], v[214:217], v[182:185], v[28:31]
	v_mfma_f32_16x16x32_bf16 v[24:27], v[246:249], v[182:185], v[24:27]
	v_mfma_f32_16x16x32_bf16 v[20:23], v[214:217], v[190:193], v[20:23]
	v_mfma_f32_16x16x32_bf16 v[16:19], v[246:249], v[190:193], v[16:19]
	v_mfma_f32_16x16x32_bf16 v[12:15], v[214:217], v[198:201], v[12:15]
	v_mfma_f32_16x16x32_bf16 v[8:11], v[246:249], v[198:201], v[8:11]
	v_mfma_f32_16x16x32_bf16 v[4:7], v[214:217], v[206:209], v[4:7]
	v_mfma_f32_16x16x32_bf16 v[0:3], v[246:249], v[206:209], v[0:3]
	v_mfma_f32_16x16x32_bf16 v[28:31], v[218:221], v[186:189], v[28:31]
	v_mfma_f32_16x16x32_bf16 v[24:27], v[230:233], v[186:189], v[24:27]
	v_mfma_f32_16x16x32_bf16 v[20:23], v[218:221], v[194:197], v[20:23]
	v_mfma_f32_16x16x32_bf16 v[16:19], v[230:233], v[194:197], v[16:19]
	v_mfma_f32_16x16x32_bf16 v[12:15], v[218:221], v[202:205], v[12:15]
	v_mfma_f32_16x16x32_bf16 v[8:11], v[230:233], v[202:205], v[8:11]
	s_setprio 2
	s_barrier
	v_mfma_f32_16x16x32_bf16 v[4:7], v[218:221], v[210:213], v[4:7]
	v_mfma_f32_16x16x32_bf16 v[0:3], v[230:233], v[210:213], v[0:3]
	s_setprio 0
	v_readfirstlane_b32 s23, v151
	v_lshl_add_u64 v[214:215], v[234:235], 0, s[42:43]
	s_mov_b32 m0, s23
	v_readfirstlane_b32 s23, v152
	ds_read_b128 v[182:185], v146 offset:32768
	ds_read_b128 v[186:189], v146 offset:33792
	ds_read_b128 v[190:193], v146 offset:34816
	ds_read_b128 v[194:197], v146 offset:35840
	ds_read_b128 v[198:201], v146 offset:36864
	ds_read_b128 v[202:205], v146 offset:37888
	ds_read_b128 v[206:209], v146 offset:38912
	ds_read_b128 v[210:213], v146 offset:39936
	global_load_lds_dwordx4 v[214:215], off
	v_lshl_add_u64 v[214:215], v[236:237], 0, s[42:43]
	s_mov_b32 m0, s23
	s_nop 0
	global_load_lds_dwordx4 v[214:215], off
	s_waitcnt lgkmcnt(8)
	s_barrier
	s_waitcnt lgkmcnt(0)
	s_setprio 1
	s_waitcnt lgkmcnt(0)
	v_mfma_f32_16x16x32_bf16 v[124:127], v[162:165], v[182:185], v[124:127]
	v_mfma_f32_16x16x32_bf16 v[120:123], v[170:173], v[182:185], v[120:123]
	v_mfma_f32_16x16x32_bf16 v[116:119], v[162:165], v[190:193], v[116:119]
	v_mfma_f32_16x16x32_bf16 v[112:115], v[170:173], v[190:193], v[112:115]
	v_mfma_f32_16x16x32_bf16 v[108:111], v[162:165], v[198:201], v[108:111]
	v_mfma_f32_16x16x32_bf16 v[104:107], v[170:173], v[198:201], v[104:107]
	v_mfma_f32_16x16x32_bf16 v[100:103], v[162:165], v[206:209], v[100:103]
	v_mfma_f32_16x16x32_bf16 v[96:99], v[170:173], v[206:209], v[96:99]
	v_mfma_f32_16x16x32_bf16 v[124:127], v[166:169], v[186:189], v[124:127]
	v_mfma_f32_16x16x32_bf16 v[120:123], v[174:177], v[186:189], v[120:123]
	v_mfma_f32_16x16x32_bf16 v[116:119], v[166:169], v[194:197], v[116:119]
	v_mfma_f32_16x16x32_bf16 v[112:115], v[174:177], v[194:197], v[112:115]
	v_mfma_f32_16x16x32_bf16 v[108:111], v[166:169], v[202:205], v[108:111]
	v_mfma_f32_16x16x32_bf16 v[104:107], v[174:177], v[202:205], v[104:107]
	s_setprio 2
	s_barrier
	v_mfma_f32_16x16x32_bf16 v[100:103], v[166:169], v[210:213], v[100:103]
	v_mfma_f32_16x16x32_bf16 v[96:99], v[174:177], v[210:213], v[96:99]
	s_setprio 0
	v_readfirstlane_b32 s23, v153
	v_lshl_add_u64 v[178:179], v[178:179], 0, s[44:45]
	s_mov_b32 m0, s23
	v_readfirstlane_b32 s23, v154
	ds_read_b128 v[214:217], v149 offset:49152
	ds_read_b128 v[218:221], v149 offset:50176
	ds_read_b128 v[230:233], v149 offset:51200
	ds_read_b128 v[246:249], v149 offset:52224
	global_load_lds_dwordx4 v[178:179], off
	v_lshl_add_u64 v[178:179], v[222:223], 0, s[44:45]
	s_mov_b32 m0, s23
	s_nop 0
	global_load_lds_dwordx4 v[178:179], off
	s_barrier
	s_waitcnt lgkmcnt(0)
	s_setprio 1
	s_waitcnt lgkmcnt(0)
	v_mfma_f32_16x16x32_bf16 v[92:95], v[214:217], v[182:185], v[92:95]
	v_mfma_f32_16x16x32_bf16 v[88:91], v[230:233], v[182:185], v[88:91]
	v_mfma_f32_16x16x32_bf16 v[84:87], v[214:217], v[190:193], v[84:87]
	v_mfma_f32_16x16x32_bf16 v[80:83], v[230:233], v[190:193], v[80:83]
	v_mfma_f32_16x16x32_bf16 v[76:79], v[214:217], v[198:201], v[76:79]
	v_mfma_f32_16x16x32_bf16 v[72:75], v[230:233], v[198:201], v[72:75]
	v_mfma_f32_16x16x32_bf16 v[68:71], v[214:217], v[206:209], v[68:71]
	v_mfma_f32_16x16x32_bf16 v[64:67], v[230:233], v[206:209], v[64:67]
	v_mfma_f32_16x16x32_bf16 v[92:95], v[218:221], v[186:189], v[92:95]
	v_mfma_f32_16x16x32_bf16 v[88:91], v[246:249], v[186:189], v[88:91]
	v_mfma_f32_16x16x32_bf16 v[84:87], v[218:221], v[194:197], v[84:87]
	v_mfma_f32_16x16x32_bf16 v[80:83], v[246:249], v[194:197], v[80:83]
	v_mfma_f32_16x16x32_bf16 v[76:79], v[218:221], v[202:205], v[76:79]
	v_mfma_f32_16x16x32_bf16 v[72:75], v[246:249], v[202:205], v[72:75]
	s_setprio 2
	s_barrier
; #define STAGE_A(P, br, kt) do { const char* _base = (const char*)(((kt) < G.ksplit ? G.A1 : A2m) + (long)(br) * G.lda + (long)(kt) * BK); \
;     __builtin_amdgcn_global_load_lds((const unsigned*)(_base + aoff0), (unsigned*)((char*)(P) + sb0), 16, 0, 0); \
;     __builtin_amdgcn_global_load_lds((const unsigned*)(_base + aoff1), (unsigned*)((char*)(P) + sb1), 16, 0, 0); } while (0)
; #define STAGE_B(P, br, kt) do { const char* _base = (const char*)(G.Bt + (long)(br) * G.ldb + (long)(kt) * BK); \
;     __builtin_amdgcn_global_load_lds((const unsigned*)(_base + boff0), (unsigned*)((char*)(P) + sb0), 16, 0, 0); \
;     __builtin_amdgcn_global_load_lds((const unsigned*)(_base + boff1), (unsigned*)((char*)(P) + sb1), 16, 0, 0); } while (0)
; #define LDA(dst, b, h) for (int m = 0; m < 4; ++m) for (int k = 0; k < 2; ++k) \
;     dst[m][k] = *reinterpret_cast<const bf16x8*>(a_rd + ((b) * 2 + (h)) * (HT * 2) + m * 2048 + k * 1024)
; #define LDB(dst, b, h) for (int n = 0; n < 2; ++n) for (int k = 0; k < 2; ++k) \
;     dst[n][k] = *reinterpret_cast<const bf16x8*>(b_rd + ((b) * 2 + (h)) * (HT * 2) + n * 2048 + k * 1024)
; #define MMA(ai, bj, At_, Bt_) do { __builtin_amdgcn_s_setprio(1); \
;     for (int m = 0; m < 4; ++m) for (int n = 0; n < 2; ++n) for (int k = 0; k < 2; ++k) \
;       acc[ai][bj][m][n] = __builtin_amdgcn_mfma_f32_16x16x32_bf16(Bt_[n][k], At_[m][k], acc[ai][bj][m][n], 0, 0, 0); \
;     __builtin_amdgcn_s_setprio(0); } while (0)
; #define WAIT_V(n) asm volatile("s_waitcnt vmcnt(" #n ")" ::: "memory")
; #define WAIT_L(n) asm volatile("s_waitcnt lgkmcnt(" #n ")" ::: "memory")
; #define BAR __builtin_amdgcn_s_barrier()
; #define SCHED __builtin_amdgcn_sched_barrier(0)
;     ...
;     LDA(At, 1, 1); STAGE_A(SA(1, 0), brow, t + 3);
;     BAR; WAIT_L(0); MMA(1, 0, At, B0); BAR; SCHED;
;     STAGE_B(SB(1, 1), bcol + HALF, t + 3);
;     WAIT_V(6); BAR; MMA(1, 1, At, B1); BAR;
;   }
;   float ssv[2][4] = {};
;   if constexpr (EPI == EPI_GU || EPI == EPI_EVIN || EPI == EPI_ODIN) {
; #pragma unroll
;     for (int ai = 0; ai < 2; ++ai)
; #pragma unroll
;       for (int m = 0; m < 4; ++m) ssv[ai][m] = G.ssr[brow + ai * HALF + wr * 64 + m * 16 + fr];
;   }
;   { LDB(B0, 0, 0); LDA(At, 0, 0); STAGE_A(SA(1, 1), brow + HALF, nt - 1);
;     BAR; WAIT_L(0); MMA(0, 0, At, B0); BAR;
	v_mfma_f32_16x16x32_bf16 v[68:71], v[218:221], v[210:213], v[68:71]
	v_mfma_f32_16x16x32_bf16 v[64:67], v[246:249], v[210:213], v[64:67]
	s_setprio 0
	s_cmp_lt_u32 s22, 13
	s_cselect_b32 s25, s28, s34
	s_cselect_b32 s24, s27, s31
	v_lshl_add_u64 v[178:179], s[24:25], 0, v[136:137]
	v_lshl_add_u64 v[178:179], v[178:179], 0, s[10:11]
	v_readfirstlane_b32 s23, v155
	v_lshl_add_u64 v[178:179], v[178:179], 0, s[88:89]
	s_mov_b32 m0, s23
	ds_read_b128 v[182:185], v146 offset:49152
	ds_read_b128 v[186:189], v146 offset:50176
	ds_read_b128 v[190:193], v146 offset:51200
	ds_read_b128 v[194:197], v146 offset:52224
	ds_read_b128 v[198:201], v146 offset:53248
	ds_read_b128 v[202:205], v146 offset:54272
	ds_read_b128 v[206:209], v146 offset:55296
	ds_read_b128 v[210:213], v146 offset:56320
	global_load_lds_dwordx4 v[178:179], off
	v_lshl_add_u64 v[178:179], s[24:25], 0, v[138:139]
	v_lshl_add_u64 v[178:179], v[178:179], 0, s[10:11]
	v_readfirstlane_b32 s23, v156
	v_lshl_add_u64 v[178:179], v[178:179], 0, s[88:89]
	s_mov_b32 m0, s23
	s_nop 0
	global_load_lds_dwordx4 v[178:179], off
	s_waitcnt vmcnt(10)
	s_barrier
	s_waitcnt lgkmcnt(0)
	s_setprio 1
	s_waitcnt lgkmcnt(0)
	v_mfma_f32_16x16x32_bf16 v[60:63], v[162:165], v[182:185], v[60:63]
	v_mfma_f32_16x16x32_bf16 v[56:59], v[170:173], v[182:185], v[56:59]
	v_mfma_f32_16x16x32_bf16 v[52:55], v[162:165], v[190:193], v[52:55]
	v_mfma_f32_16x16x32_bf16 v[48:51], v[170:173], v[190:193], v[48:51]
	v_mfma_f32_16x16x32_bf16 v[44:47], v[162:165], v[198:201], v[44:47]
	v_mfma_f32_16x16x32_bf16 v[40:43], v[170:173], v[198:201], v[40:43]
	v_mfma_f32_16x16x32_bf16 v[36:39], v[162:165], v[206:209], v[36:39]
	v_mfma_f32_16x16x32_bf16 v[32:35], v[170:173], v[206:209], v[32:35]
	v_mfma_f32_16x16x32_bf16 v[60:63], v[166:169], v[186:189], v[60:63]
	v_mfma_f32_16x16x32_bf16 v[56:59], v[174:177], v[186:189], v[56:59]
	v_mfma_f32_16x16x32_bf16 v[52:55], v[166:169], v[194:197], v[52:55]
	v_mfma_f32_16x16x32_bf16 v[48:51], v[174:177], v[194:197], v[48:51]
	v_mfma_f32_16x16x32_bf16 v[44:47], v[166:169], v[202:205], v[44:47]
	v_mfma_f32_16x16x32_bf16 v[40:43], v[174:177], v[202:205], v[40:43]
	s_setprio 2
	s_barrier
	v_mfma_f32_16x16x32_bf16 v[36:39], v[166:169], v[210:213], v[36:39]
	v_mfma_f32_16x16x32_bf16 v[32:35], v[174:177], v[210:213], v[32:35]
	s_setprio 0
	v_readfirstlane_b32 s23, v157
	v_lshl_add_u64 v[162:163], v[238:239], 0, s[46:47]
	s_mov_b32 m0, s23
	v_readfirstlane_b32 s23, v158
	global_load_lds_dwordx4 v[162:163], off
	v_lshl_add_u64 v[162:163], v[240:241], 0, s[46:47]
	s_mov_b32 m0, s23
	s_nop 0
	global_load_lds_dwordx4 v[162:163], off
	ds_read_b128 v[162:165], v149
	ds_read_b128 v[166:169], v149 offset:1024
	ds_read_b128 v[170:173], v149 offset:2048
	ds_read_b128 v[174:177], v149 offset:3072
	s_waitcnt vmcnt(6)
	s_barrier
	s_setprio 1
	v_mfma_f32_16x16x32_bf16 v[28:31], v[214:217], v[182:185], v[28:31]
	v_mfma_f32_16x16x32_bf16 v[24:27], v[230:233], v[182:185], v[24:27]
	v_mfma_f32_16x16x32_bf16 v[20:23], v[214:217], v[190:193], v[20:23]
	v_mfma_f32_16x16x32_bf16 v[16:19], v[230:233], v[190:193], v[16:19]
	v_mfma_f32_16x16x32_bf16 v[12:15], v[214:217], v[198:201], v[12:15]
	v_mfma_f32_16x16x32_bf16 v[8:11], v[230:233], v[198:201], v[8:11]
	v_mfma_f32_16x16x32_bf16 v[4:7], v[214:217], v[206:209], v[4:7]
	v_mfma_f32_16x16x32_bf16 v[0:3], v[230:233], v[206:209], v[0:3]
	v_mfma_f32_16x16x32_bf16 v[28:31], v[218:221], v[186:189], v[28:31]
	v_mfma_f32_16x16x32_bf16 v[24:27], v[246:249], v[186:189], v[24:27]
	v_mfma_f32_16x16x32_bf16 v[20:23], v[218:221], v[194:197], v[20:23]
	v_mfma_f32_16x16x32_bf16 v[16:19], v[246:249], v[194:197], v[16:19]
	v_mfma_f32_16x16x32_bf16 v[12:15], v[218:221], v[202:205], v[12:15]
	v_mfma_f32_16x16x32_bf16 v[8:11], v[246:249], v[202:205], v[8:11]
	s_setprio 2
	s_barrier
	v_mfma_f32_16x16x32_bf16 v[4:7], v[218:221], v[210:213], v[4:7]
	v_mfma_f32_16x16x32_bf16 v[0:3], v[246:249], v[210:213], v[0:3]
	s_setprio 0
	s_add_u32 s10, s10, 0x100
	s_addc_u32 s11, s11, 0
	s_cmp_lt_u32 s22, 28
	s_cbranch_scc1 .LBB0_2501
	s_waitcnt lgkmcnt(0)
	s_lshl_b64 s[8:9], s[8:9], 1
	s_add_u32 s8, s31, s8
	s_addc_u32 s9, s34, s9
	v_lshl_add_u64 v[130:131], s[8:9], 0, v[130:131]
	v_readfirstlane_b32 s10, v159
	v_lshl_add_u64 v[130:131], v[130:131], 0, s[52:53]
	s_mov_b32 m0, s10
	v_lshl_add_u64 v[128:129], s[8:9], 0, v[128:129]
	v_readfirstlane_b32 s8, v160
	ds_read_b128 v[132:135], v149
	ds_read_b128 v[136:139], v149 offset:1024
	ds_read_b128 v[140:143], v149 offset:2048
	ds_read_b128 v[150:153], v149 offset:3072
	ds_read_b128 v[154:157], v146
	ds_read_b128 v[162:165], v146 offset:1024
	ds_read_b128 v[166:169], v146 offset:2048
	ds_read_b128 v[170:173], v146 offset:3072
	ds_read_b128 v[174:177], v146 offset:4096
	ds_read_b128 v[182:185], v146 offset:5120
	ds_read_b128 v[186:189], v146 offset:6144
	ds_read_b128 v[190:193], v146 offset:7168
	global_load_lds_dwordx4 v[130:131], off
	v_lshl_add_u64 v[128:129], v[128:129], 0, s[52:53]
	s_mov_b32 m0, s8
	s_nop 0
	global_load_lds_dwordx4 v[128:129], off
	s_barrier
	s_waitcnt lgkmcnt(0)
	s_setprio 1
	s_waitcnt lgkmcnt(0)
	v_mfma_f32_16x16x32_bf16 v[124:127], v[132:135], v[154:157], v[124:127]
	v_mfma_f32_16x16x32_bf16 v[120:123], v[140:143], v[154:157], v[120:123]
	v_mfma_f32_16x16x32_bf16 v[116:119], v[132:135], v[166:169], v[116:119]
	v_mfma_f32_16x16x32_bf16 v[112:115], v[140:143], v[166:169], v[112:115]
	v_mfma_f32_16x16x32_bf16 v[108:111], v[132:135], v[174:177], v[108:111]
	v_mfma_f32_16x16x32_bf16 v[104:107], v[140:143], v[174:177], v[104:107]
	v_mfma_f32_16x16x32_bf16 v[100:103], v[132:135], v[186:189], v[100:103]
	v_mfma_f32_16x16x32_bf16 v[96:99], v[140:143], v[186:189], v[96:99]
	v_mfma_f32_16x16x32_bf16 v[124:127], v[136:139], v[162:165], v[124:127]
	v_mfma_f32_16x16x32_bf16 v[120:123], v[150:153], v[162:165], v[120:123]
	v_mfma_f32_16x16x32_bf16 v[116:119], v[136:139], v[170:173], v[116:119]
	v_mfma_f32_16x16x32_bf16 v[112:115], v[150:153], v[170:173], v[112:115]
	v_mfma_f32_16x16x32_bf16 v[108:111], v[136:139], v[182:185], v[108:111]
	v_mfma_f32_16x16x32_bf16 v[104:107], v[150:153], v[182:185], v[104:107]
	s_setprio 2
	s_barrier
; #define LDA(dst, b, h) for (int m = 0; m < 4; ++m) for (int k = 0; k < 2; ++k) \
;     dst[m][k] = *reinterpret_cast<const bf16x8*>(a_rd + ((b) * 2 + (h)) * (HT * 2) + m * 2048 + k * 1024)
; #define LDB(dst, b, h) for (int n = 0; n < 2; ++n) for (int k = 0; k < 2; ++k) \
;     dst[n][k] = *reinterpret_cast<const bf16x8*>(b_rd + ((b) * 2 + (h)) * (HT * 2) + n * 2048 + k * 1024)
; #define MMA(ai, bj, At_, Bt_) do { __builtin_amdgcn_s_setprio(1); \
;     for (int m = 0; m < 4; ++m) for (int n = 0; n < 2; ++n) for (int k = 0; k < 2; ++k) \
;       acc[ai][bj][m][n] = __builtin_amdgcn_mfma_f32_16x16x32_bf16(Bt_[n][k], At_[m][k], acc[ai][bj][m][n], 0, 0, 0); \
;     __builtin_amdgcn_s_setprio(0); } while (0)
; #define WAIT_V(n) asm volatile("s_waitcnt vmcnt(" #n ")" ::: "memory")
; #define WAIT_L(n) asm volatile("s_waitcnt lgkmcnt(" #n ")" ::: "memory")
; #define BAR __builtin_amdgcn_s_barrier()
;     ...
;     BAR; WAIT_L(0); MMA(0, 0, At, B0); BAR;
;     LDB(B1, 0, 1); BAR; WAIT_L(0); MMA(0, 1, At, B1); BAR;
;     LDA(At, 0, 1); WAIT_V(4); BAR; WAIT_L(0); MMA(1, 0, At, B0); MMA(1, 1, At, B1); BAR; }
;   { LDB(B0, 1, 0); LDA(At, 1, 0); WAIT_V(2); BAR; WAIT_L(0); MMA(0, 0, At, B0); BAR;
	v_mfma_f32_16x16x32_bf16 v[100:103], v[136:139], v[190:193], v[100:103]
	v_mfma_f32_16x16x32_bf16 v[96:99], v[150:153], v[190:193], v[96:99]
	s_setprio 0
	ds_read_b128 v[128:131], v149 offset:16384
	ds_read_b128 v[158:161], v149 offset:17408
	ds_read_b128 v[194:197], v149 offset:18432
	ds_read_b128 v[198:201], v149 offset:19456
	s_barrier
	s_waitcnt lgkmcnt(0)
	s_setprio 1
	s_waitcnt lgkmcnt(0)
	v_mfma_f32_16x16x32_bf16 v[92:95], v[128:131], v[154:157], v[92:95]
	v_mfma_f32_16x16x32_bf16 v[88:91], v[194:197], v[154:157], v[88:91]
	v_mfma_f32_16x16x32_bf16 v[84:87], v[128:131], v[166:169], v[84:87]
	v_mfma_f32_16x16x32_bf16 v[80:83], v[194:197], v[166:169], v[80:83]
	v_mfma_f32_16x16x32_bf16 v[76:79], v[128:131], v[174:177], v[76:79]
	v_mfma_f32_16x16x32_bf16 v[72:75], v[194:197], v[174:177], v[72:75]
	v_mfma_f32_16x16x32_bf16 v[68:71], v[128:131], v[186:189], v[68:71]
	v_mfma_f32_16x16x32_bf16 v[64:67], v[194:197], v[186:189], v[64:67]
	v_mfma_f32_16x16x32_bf16 v[202:205], v[158:161], v[162:165], v[92:95]
	v_mfma_f32_16x16x32_bf16 v[154:157], v[198:201], v[162:165], v[88:91]
	v_mfma_f32_16x16x32_bf16 v[162:165], v[158:161], v[170:173], v[84:87]
	v_mfma_f32_16x16x32_bf16 v[166:169], v[198:201], v[170:173], v[80:83]
	v_mfma_f32_16x16x32_bf16 v[170:173], v[158:161], v[182:185], v[76:79]
	v_mfma_f32_16x16x32_bf16 v[174:177], v[198:201], v[182:185], v[72:75]
	s_setprio 2
	s_barrier
	v_mfma_f32_16x16x32_bf16 v[182:185], v[158:161], v[190:193], v[68:71]
	v_mfma_f32_16x16x32_bf16 v[186:189], v[198:201], v[190:193], v[64:67]
	s_setprio 0
	s_nop 0
	ds_read_b128 v[64:67], v146 offset:16384
	ds_read_b128 v[68:71], v146 offset:17408
	ds_read_b128 v[72:75], v146 offset:18432
	ds_read_b128 v[76:79], v146 offset:19456
	ds_read_b128 v[80:83], v146 offset:20480
	ds_read_b128 v[84:87], v146 offset:21504
	ds_read_b128 v[88:91], v146 offset:22528
	ds_read_b128 v[92:95], v146 offset:23552
	s_waitcnt vmcnt(4)
	s_barrier
	s_waitcnt lgkmcnt(0)
	s_setprio 1
	s_waitcnt lgkmcnt(0)
	v_mfma_f32_16x16x32_bf16 v[60:63], v[132:135], v[64:67], v[60:63]
	v_mfma_f32_16x16x32_bf16 v[56:59], v[140:143], v[64:67], v[56:59]
	v_mfma_f32_16x16x32_bf16 v[52:55], v[132:135], v[72:75], v[52:55]
	v_mfma_f32_16x16x32_bf16 v[48:51], v[140:143], v[72:75], v[48:51]
	v_mfma_f32_16x16x32_bf16 v[44:47], v[132:135], v[80:83], v[44:47]
	v_mfma_f32_16x16x32_bf16 v[40:43], v[140:143], v[80:83], v[40:43]
	v_mfma_f32_16x16x32_bf16 v[36:39], v[132:135], v[88:91], v[36:39]
	v_mfma_f32_16x16x32_bf16 v[32:35], v[140:143], v[88:91], v[32:35]
	v_mfma_f32_16x16x32_bf16 v[60:63], v[136:139], v[68:71], v[60:63]
	v_mfma_f32_16x16x32_bf16 v[56:59], v[150:153], v[68:71], v[56:59]
	v_mfma_f32_16x16x32_bf16 v[52:55], v[136:139], v[76:79], v[52:55]
	v_mfma_f32_16x16x32_bf16 v[48:51], v[150:153], v[76:79], v[48:51]
	v_mfma_f32_16x16x32_bf16 v[44:47], v[136:139], v[84:87], v[44:47]
	v_mfma_f32_16x16x32_bf16 v[40:43], v[150:153], v[84:87], v[40:43]
	v_mfma_f32_16x16x32_bf16 v[36:39], v[136:139], v[92:95], v[36:39]
	v_mfma_f32_16x16x32_bf16 v[32:35], v[150:153], v[92:95], v[32:35]
	s_setprio 0
	s_setprio 1
	v_mfma_f32_16x16x32_bf16 v[28:31], v[128:131], v[64:67], v[28:31]
	v_mfma_f32_16x16x32_bf16 v[24:27], v[194:197], v[64:67], v[24:27]
	v_mfma_f32_16x16x32_bf16 v[20:23], v[128:131], v[72:75], v[20:23]
	v_mfma_f32_16x16x32_bf16 v[16:19], v[194:197], v[72:75], v[16:19]
	v_mfma_f32_16x16x32_bf16 v[12:15], v[128:131], v[80:83], v[12:15]
	v_mfma_f32_16x16x32_bf16 v[8:11], v[194:197], v[80:83], v[8:11]
	v_mfma_f32_16x16x32_bf16 v[4:7], v[128:131], v[88:91], v[4:7]
	v_mfma_f32_16x16x32_bf16 v[0:3], v[194:197], v[88:91], v[0:3]
	v_mfma_f32_16x16x32_bf16 v[132:135], v[158:161], v[68:71], v[28:31]
	v_mfma_f32_16x16x32_bf16 v[136:139], v[198:201], v[68:71], v[24:27]
	v_mfma_f32_16x16x32_bf16 v[140:143], v[158:161], v[76:79], v[20:23]
	v_mfma_f32_16x16x32_bf16 v[150:153], v[198:201], v[76:79], v[16:19]
	v_mfma_f32_16x16x32_bf16 v[190:193], v[158:161], v[84:87], v[12:15]
	v_mfma_f32_16x16x32_bf16 v[206:209], v[198:201], v[84:87], v[8:11]
	s_setprio 2
	s_barrier
	v_mfma_f32_16x16x32_bf16 v[128:131], v[158:161], v[92:95], v[4:7]
	v_mfma_f32_16x16x32_bf16 v[158:161], v[198:201], v[92:95], v[0:3]
	s_setprio 0
	ds_read_b128 v[24:27], v149 offset:32768
	ds_read_b128 v[28:31], v149 offset:33792
	ds_read_b128 v[194:197], v149 offset:34816
	ds_read_b128 v[198:201], v149 offset:35840
	ds_read_b128 v[0:3], v146 offset:32768
	ds_read_b128 v[4:7], v146 offset:33792
	ds_read_b128 v[8:11], v146 offset:34816
	ds_read_b128 v[12:15], v146 offset:35840
	ds_read_b128 v[16:19], v146 offset:36864
	ds_read_b128 v[20:23], v146 offset:37888
	ds_read_b128 v[210:213], v146 offset:38912
	ds_read_b128 v[214:217], v146 offset:39936
	s_waitcnt vmcnt(2)
	s_barrier
; #define LDA(dst, b, h) for (int m = 0; m < 4; ++m) for (int k = 0; k < 2; ++k) \
;     dst[m][k] = *reinterpret_cast<const bf16x8*>(a_rd + ((b) * 2 + (h)) * (HT * 2) + m * 2048 + k * 1024)
; #define LDB(dst, b, h) for (int n = 0; n < 2; ++n) for (int k = 0; k < 2; ++k) \
;     dst[n][k] = *reinterpret_cast<const bf16x8*>(b_rd + ((b) * 2 + (h)) * (HT * 2) + n * 2048 + k * 1024)
; #define MMA(ai, bj, At_, Bt_) do { __builtin_amdgcn_s_setprio(1); \
;     for (int m = 0; m < 4; ++m) for (int n = 0; n < 2; ++n) for (int k = 0; k < 2; ++k) \
;       acc[ai][bj][m][n] = __builtin_amdgcn_mfma_f32_16x16x32_bf16(Bt_[n][k], At_[m][k], acc[ai][bj][m][n], 0, 0, 0); \
;     __builtin_amdgcn_s_setprio(0); } while (0)
; #define WAIT_V(n) asm volatile("s_waitcnt vmcnt(" #n ")" ::: "memory")
; #define WAIT_L(n) asm volatile("s_waitcnt lgkmcnt(" #n ")" ::: "memory")
; #define BAR __builtin_amdgcn_s_barrier()
;     ...
;     LDA(At, 0, 1); WAIT_V(4); BAR; WAIT_L(0); MMA(1, 0, At, B0); MMA(1, 1, At, B1); BAR; }
;   { LDB(B0, 1, 0); LDA(At, 1, 0); WAIT_V(2); BAR; WAIT_L(0); MMA(0, 0, At, B0); BAR;
;     LDB(B1, 1, 1); WAIT_V(0); BAR; WAIT_L(0); MMA(0, 1, At, B1); BAR;
;     LDA(At, 1, 1); BAR; WAIT_L(0); MMA(1, 0, At, B0); MMA(1, 1, At, B1); BAR; }
;   if (wr == 0) BAR;
	s_waitcnt lgkmcnt(0)
	s_setprio 1
	s_waitcnt lgkmcnt(0)
	v_mfma_f32_16x16x32_bf16 v[64:67], v[24:27], v[0:3], v[124:127]
	v_mfma_f32_16x16x32_bf16 v[68:71], v[194:197], v[0:3], v[120:123]
	v_mfma_f32_16x16x32_bf16 v[72:75], v[24:27], v[8:11], v[116:119]
	v_mfma_f32_16x16x32_bf16 v[76:79], v[194:197], v[8:11], v[112:115]
	v_mfma_f32_16x16x32_bf16 v[80:83], v[24:27], v[16:19], v[108:111]
	v_mfma_f32_16x16x32_bf16 v[84:87], v[194:197], v[16:19], v[104:107]
	v_mfma_f32_16x16x32_bf16 v[88:91], v[24:27], v[210:213], v[100:103]
	v_mfma_f32_16x16x32_bf16 v[92:95], v[194:197], v[210:213], v[96:99]
	v_mfma_f32_16x16x32_bf16 v[64:67], v[28:31], v[4:7], v[64:67]
	v_mfma_f32_16x16x32_bf16 v[68:71], v[198:201], v[4:7], v[68:71]
	v_mfma_f32_16x16x32_bf16 v[72:75], v[28:31], v[12:15], v[72:75]
	v_mfma_f32_16x16x32_bf16 v[76:79], v[198:201], v[12:15], v[76:79]
	v_mfma_f32_16x16x32_bf16 v[80:83], v[28:31], v[20:23], v[80:83]
	v_mfma_f32_16x16x32_bf16 v[84:87], v[198:201], v[20:23], v[84:87]
	s_setprio 2
	s_barrier
	v_mfma_f32_16x16x32_bf16 v[88:91], v[28:31], v[214:217], v[88:91]
	v_mfma_f32_16x16x32_bf16 v[92:95], v[198:201], v[214:217], v[92:95]
	s_setprio 0
	ds_read_b128 v[218:221], v149 offset:49152
	ds_read_b128 v[230:233], v149 offset:50176
	ds_read_b128 v[246:249], v149 offset:51200
	ds_read_b128 v[238:241], v149 offset:52224
	s_waitcnt vmcnt(0)
	s_barrier
	s_waitcnt lgkmcnt(0)
	s_setprio 1
	s_waitcnt lgkmcnt(0)
	v_mfma_f32_16x16x32_bf16 v[96:99], v[218:221], v[0:3], v[202:205]
	v_mfma_f32_16x16x32_bf16 v[0:3], v[246:249], v[0:3], v[154:157]
	v_mfma_f32_16x16x32_bf16 v[100:103], v[238:241], v[4:7], v[0:3]
	v_mfma_f32_16x16x32_bf16 v[0:3], v[218:221], v[8:11], v[162:165]
	v_mfma_f32_16x16x32_bf16 v[104:107], v[230:233], v[12:15], v[0:3]
	v_mfma_f32_16x16x32_bf16 v[0:3], v[246:249], v[8:11], v[166:169]
	v_mfma_f32_16x16x32_bf16 v[108:111], v[238:241], v[12:15], v[0:3]
	v_mfma_f32_16x16x32_bf16 v[0:3], v[218:221], v[16:19], v[170:173]
	v_mfma_f32_16x16x32_bf16 v[112:115], v[230:233], v[20:23], v[0:3]
	v_mfma_f32_16x16x32_bf16 v[0:3], v[246:249], v[16:19], v[174:177]
	v_mfma_f32_16x16x32_bf16 v[116:119], v[238:241], v[20:23], v[0:3]
	v_mfma_f32_16x16x32_bf16 v[0:3], v[218:221], v[210:213], v[182:185]
	v_mfma_f32_16x16x32_bf16 v[120:123], v[230:233], v[214:217], v[0:3]
	v_mfma_f32_16x16x32_bf16 v[0:3], v[246:249], v[210:213], v[186:189]
	s_setprio 2
	s_barrier
	v_mfma_f32_16x16x32_bf16 v[96:99], v[230:233], v[4:7], v[96:99]
	v_mfma_f32_16x16x32_bf16 v[124:127], v[238:241], v[214:217], v[0:3]
	s_setprio 0
	ds_read_b128 v[154:157], v146 offset:49152
	ds_read_b128 v[162:165], v146 offset:50176
	ds_read_b128 v[166:169], v146 offset:51200
	ds_read_b128 v[170:173], v146 offset:52224
	ds_read_b128 v[174:177], v146 offset:53248
	ds_read_b128 v[182:185], v146 offset:54272
	ds_read_b128 v[186:189], v146 offset:55296
	ds_read_b128 v[146:149], v146 offset:56320
	s_barrier
	s_waitcnt lgkmcnt(0)
	s_setprio 1
	s_waitcnt lgkmcnt(0)
	v_mfma_f32_16x16x32_bf16 v[0:3], v[24:27], v[154:157], v[60:63]
	v_mfma_f32_16x16x32_bf16 v[8:11], v[24:27], v[166:169], v[52:55]
	v_mfma_f32_16x16x32_bf16 v[16:19], v[24:27], v[174:177], v[44:47]
	v_mfma_f32_16x16x32_bf16 v[24:27], v[24:27], v[186:189], v[36:39]
	v_mfma_f32_16x16x32_bf16 v[0:3], v[28:31], v[162:165], v[0:3]
	v_mfma_f32_16x16x32_bf16 v[4:7], v[194:197], v[154:157], v[56:59]
	v_mfma_f32_16x16x32_bf16 v[8:11], v[28:31], v[170:173], v[8:11]
	v_mfma_f32_16x16x32_bf16 v[12:15], v[194:197], v[166:169], v[48:51]
	v_mfma_f32_16x16x32_bf16 v[16:19], v[28:31], v[182:185], v[16:19]
	v_mfma_f32_16x16x32_bf16 v[20:23], v[194:197], v[174:177], v[40:43]
	v_mfma_f32_16x16x32_bf16 v[24:27], v[28:31], v[146:149], v[24:27]
	v_mfma_f32_16x16x32_bf16 v[28:31], v[194:197], v[186:189], v[32:35]
	v_mfma_f32_16x16x32_bf16 v[4:7], v[198:201], v[162:165], v[4:7]
	v_mfma_f32_16x16x32_bf16 v[12:15], v[198:201], v[170:173], v[12:15]
	v_mfma_f32_16x16x32_bf16 v[20:23], v[198:201], v[182:185], v[20:23]
	v_mfma_f32_16x16x32_bf16 v[28:31], v[198:201], v[146:149], v[28:31]
	s_setprio 0
	s_setprio 1
	v_mfma_f32_16x16x32_bf16 v[32:35], v[218:221], v[154:157], v[132:135]
	v_mfma_f32_16x16x32_bf16 v[36:39], v[246:249], v[154:157], v[136:139]
	v_mfma_f32_16x16x32_bf16 v[40:43], v[218:221], v[166:169], v[140:143]
	v_mfma_f32_16x16x32_bf16 v[44:47], v[246:249], v[166:169], v[150:153]
	v_mfma_f32_16x16x32_bf16 v[48:51], v[218:221], v[174:177], v[190:193]
	v_mfma_f32_16x16x32_bf16 v[52:55], v[246:249], v[174:177], v[206:209]
	v_mfma_f32_16x16x32_bf16 v[56:59], v[218:221], v[186:189], v[128:131]
	v_mfma_f32_16x16x32_bf16 v[60:63], v[246:249], v[186:189], v[158:161]
	v_mfma_f32_16x16x32_bf16 v[32:35], v[230:233], v[162:165], v[32:35]
	v_mfma_f32_16x16x32_bf16 v[36:39], v[238:241], v[162:165], v[36:39]
	v_mfma_f32_16x16x32_bf16 v[40:43], v[230:233], v[170:173], v[40:43]
	v_mfma_f32_16x16x32_bf16 v[44:47], v[238:241], v[170:173], v[44:47]
	v_mfma_f32_16x16x32_bf16 v[48:51], v[230:233], v[182:185], v[48:51]
	v_mfma_f32_16x16x32_bf16 v[52:55], v[238:241], v[182:185], v[52:55]
	s_setprio 2
	s_barrier
	v_mfma_f32_16x16x32_bf16 v[56:59], v[230:233], v[146:149], v[56:59]
	v_mfma_f32_16x16x32_bf16 v[60:63], v[238:241], v[146:149], v[60:63]
	s_setprio 0
	v_cmp_gt_u32_e32 vcc, s60, v144
	s_and_saveexec_b64 s[8:9], vcc
	s_cbranch_execz .LBB0_2504
	s_barrier

; #define STAGE_A(P, br, kt) do { const char* _base = (const char*)(((kt) < G.ksplit ? G.A1 : A2m) + (long)(br) * G.lda + (long)(kt) * BK); \
;     __builtin_amdgcn_global_load_lds((const unsigned*)(_base + aoff0), (unsigned*)((char*)(P) + sb0), 16, 0, 0); \
;     __builtin_amdgcn_global_load_lds((const unsigned*)(_base + aoff1), (unsigned*)((char*)(P) + sb1), 16, 0, 0); } while (0)
; #define STAGE_B(P, br, kt) do { const char* _base = (const char*)(G.Bt + (long)(br) * G.ldb + (long)(kt) * BK); \
;     __builtin_amdgcn_global_load_lds((const unsigned*)(_base + boff0), (unsigned*)((char*)(P) + sb0), 16, 0, 0); \
;     __builtin_amdgcn_global_load_lds((const unsigned*)(_base + boff1), (unsigned*)((char*)(P) + sb1), 16, 0, 0); } while (0)
; #define WAIT_V(n) asm volatile("s_waitcnt vmcnt(" #n ")" ::: "memory")
; #define BAR __builtin_amdgcn_s_barrier()
;     ...
;   const int K = G.K;
;   const u16* A2m = G.A2 - (long)G.ksplit * BK;
;   int t1 = otid();
;   const int wid = t1 >> 6, lane = t1 & 63, wr = wid >> 2, wc = wid & 3, fr = lane & 15, fq = lane >> 4;
;   const int sb0 = t1 * 16, sb1 = sb0 + 8192;
;   const int swz_ = lds_byte(fr, fq * 8);
;   const char* a_rd = shmc + wr * 8192 + swz_;
;   const char* b_rd = shmc + 4 * (HT * 2) + wc * 4096 + swz_;
;   int r0_, c0_, r1_, c1_; stage_rc(sb0, r0_, c0_); stage_rc(sb1, r1_, c1_);
;   const unsigned aoff0 = (unsigned)(r0_ * G.lda + c0_) * 2u, aoff1 = (unsigned)(r1_ * G.lda + c1_) * 2u;
;   const unsigned boff0 = (unsigned)(r0_ * G.ldb + c0_) * 2u, boff1 = (unsigned)(r1_ * G.ldb + c1_) * 2u;
;   f32x4 acc[2][2][4][2] = {};
;   bf16x8 At[4][2], B0[2][2], B1[2][2];
;   const int nt = K / BK;
;   if (EPI == EPI_RESID || first) {
;     STAGE_B(SB(0, 0), bcol, 0); STAGE_A(SA(0, 0), brow, 0);
;     STAGE_B(SB(0, 1), bcol + HALF, 0); STAGE_A(SA(0, 1), brow + HALF, 0);
;   }
;   if (wr == 1) BAR;
;   WAIT_V(0); BAR;
;   STAGE_B(SB(1, 0), bcol, 1); STAGE_A(SA(1, 0), brow, 1); STAGE_B(SB(1, 1), bcol + HALF, 1);
;   WAIT_V(6); BAR;
.LBB0_2565:
	s_or_b64 exec, exec, s[20:21]
	v_and_b32_e32 v152, 15, v144
	v_lshlrev_b32_e32 v10, 2, v144
	s_ashr_i32 s19, s18, 31
	v_and_b32_e32 v8, 48, v144
	v_lshlrev_b32_e32 v9, 6, v152
	v_and_b32_e32 v10, 32, v10
	s_add_i32 s21, 32, 0x10000
	s_lshl_b32 s29, s29, 8
	s_lshl_b64 s[36:37], s[18:19], 1
	v_bitop3_b32 v10, v9, v10, v8 bitop3:0x36
	v_lshlrev_b32_e32 v8, 6, v144
	s_add_u32 s38, s8, s36
	v_readlane_b32 s19, v253, 46
	v_and_b32_e32 v8, 0x3000, v8
	s_addc_u32 s39, s9, s37
	v_add_u32_e32 v153, s19, v148
	s_waitcnt vmcnt(0)
	v_add_u32_e32 v12, s21, v8
	v_lshl_add_u64 v[8:9], s[38:39], 0, v[180:181]
	s_mov_b64 s[44:45], 0x80
	v_readfirstlane_b32 s19, v153
	v_lshl_add_u64 v[8:9], v[8:9], 0, s[44:45]
	s_mov_b32 m0, s19
	v_mov_b32_e32 v129, v181
	v_add_u32_e32 v154, 0x2000, v153
	s_waitcnt vmcnt(0)
	s_barrier
	global_load_lds_dwordx4 v[8:9], off
	v_lshl_add_u64 v[8:9], s[38:39], 0, v[128:129]
	v_readfirstlane_b32 s19, v154
	s_add_u32 s34, s23, s34
	v_lshl_add_u64 v[8:9], v[8:9], 0, s[44:45]
	s_mov_b32 m0, s19
	s_addc_u32 s35, s24, s31
	v_add_u32_e32 v155, 0x8000, v147
	global_load_lds_dwordx4 v[8:9], off
	v_lshl_add_u64 v[8:9], s[34:35], 0, v[180:181]
	v_readfirstlane_b32 s19, v155
	v_lshl_add_u64 v[8:9], v[8:9], 0, s[44:45]
	s_mov_b32 m0, s19
	s_or_b32 s20, s29, 0x80
	global_load_lds_dwordx4 v[8:9], off
	v_lshl_add_u64 v[8:9], s[34:35], 0, v[128:129]
	s_mul_i32 s34, s20, 0x840
	v_add_u32_e32 v156, 0xa000, v147
	s_ashr_i32 s35, s34, 31
	v_readfirstlane_b32 s19, v156
	s_lshl_b64 s[34:35], s[34:35], 1
	s_mov_b32 m0, s19
	s_add_u32 s34, s8, s34
	v_readlane_b32 s19, v253, 47
	v_lshl_add_u64 v[8:9], v[8:9], 0, s[44:45]
	s_addc_u32 s35, s9, s35
	v_add_u32_e32 v157, s19, v148
	global_load_lds_dwordx4 v[8:9], off
	v_lshl_add_u64 v[8:9], s[34:35], 0, v[180:181]
	v_readfirstlane_b32 s19, v157
	v_lshl_add_u64 v[8:9], v[8:9], 0, s[44:45]
	s_mov_b32 m0, s19
	v_add_u32_e32 v158, 0x2000, v157
	global_load_lds_dwordx4 v[8:9], off
	v_lshl_add_u64 v[8:9], s[34:35], 0, v[128:129]
	v_readfirstlane_b32 s19, v158
	v_lshl_add_u64 v[8:9], v[8:9], 0, s[44:45]
	s_mov_b32 m0, s19
	s_add_i32 s18, s18, 0x40000
	global_load_lds_dwordx4 v[8:9], off
	v_lshrrev_b32_e32 v8, 1, v0
	v_mul_lo_u32 v0, v1, s41
	v_mad_u64_u32 v[0:1], s[34:35], v8, s84, v[0:1]
	v_or_b32_e32 v0, v0, v2
	v_add_lshl_u32 v0, v0, v3, 1
	v_lshrrev_b32_e32 v3, 1, v4
	v_mul_lo_u32 v2, v5, s41
	v_mad_u64_u32 v[2:3], s[34:35], v3, s84, v[2:3]
	s_ashr_i32 s19, s18, 31
	s_waitcnt vmcnt(6)
	v_mov_b32_e32 v1, v181
	v_or_b32_e32 v2, v2, v6
	s_lshl_b64 s[18:19], s[18:19], 1
	v_lshl_add_u32 v11, v151, 13, 32
	v_lshl_add_u64 v[130:131], s[36:37], 0, v[0:1]
	v_add_lshl_u32 v2, v2, v7, 1
	v_mov_b32_e32 v3, v181
	v_mad_i64_i32 v[134:135], s[34:35], s28, v243, v[0:1]
	v_lshl_add_u64 v[138:139], s[18:19], 0, v[0:1]
	v_mov_b32_e32 v0, 0
	v_mov_b32_e32 v245, 0x80003fff
	v_lshl_add_u64 v[132:133], s[36:37], 0, v[2:3]
	v_mad_i64_i32 v[136:137], s[34:35], s28, v243, v[2:3]
	v_lshl_add_u64 v[140:141], s[18:19], 0, v[2:3]
	s_mov_b32 s31, -2
	v_add_u32_e32 v150, v12, v10
	v_add_u32_e32 v149, v11, v10
	s_mov_b64 s[18:19], s[8:9]
	v_mov_b32_e32 v1, v0
	v_mov_b32_e32 v2, v0
	v_mov_b32_e32 v3, v0
	v_mov_b32_e32 v4, v0
	v_mov_b32_e32 v5, v0
	v_mov_b32_e32 v6, v0
	v_mov_b32_e32 v7, v0
	v_mov_b32_e32 v8, v0
	v_mov_b32_e32 v9, v0
	v_mov_b32_e32 v10, v0
	v_mov_b32_e32 v11, v0
	v_mov_b32_e32 v12, v0
	v_mov_b32_e32 v13, v0
	v_mov_b32_e32 v14, v0
	v_mov_b32_e32 v15, v0
	v_mov_b32_e32 v16, v0
	v_mov_b32_e32 v17, v0
	v_mov_b32_e32 v18, v0
	v_mov_b32_e32 v19, v0
	v_mov_b32_e32 v20, v0
	v_mov_b32_e32 v21, v0
	v_mov_b32_e32 v22, v0
	v_mov_b32_e32 v23, v0
	v_mov_b32_e32 v24, v0
	v_mov_b32_e32 v25, v0
	v_mov_b32_e32 v26, v0
	v_mov_b32_e32 v27, v0
	v_mov_b32_e32 v28, v0
	v_mov_b32_e32 v29, v0
	v_mov_b32_e32 v30, v0
	v_mov_b32_e32 v31, v0
	v_mov_b32_e32 v32, v0
	v_mov_b32_e32 v33, v0
	v_mov_b32_e32 v34, v0
	v_mov_b32_e32 v35, v0
	v_mov_b32_e32 v36, v0
	v_mov_b32_e32 v37, v0
	v_mov_b32_e32 v38, v0
	v_mov_b32_e32 v39, v0
	v_mov_b32_e32 v40, v0
	v_mov_b32_e32 v41, v0
	v_mov_b32_e32 v42, v0
	v_mov_b32_e32 v43, v0
	v_mov_b32_e32 v44, v0
	v_mov_b32_e32 v45, v0
	v_mov_b32_e32 v46, v0
	v_mov_b32_e32 v47, v0
	v_mov_b32_e32 v48, v0
	v_mov_b32_e32 v49, v0
	v_mov_b32_e32 v50, v0
	v_mov_b32_e32 v51, v0
	v_mov_b32_e32 v52, v0
	v_mov_b32_e32 v53, v0
	v_mov_b32_e32 v54, v0
	v_mov_b32_e32 v55, v0
	v_mov_b32_e32 v56, v0
	v_mov_b32_e32 v57, v0
	v_mov_b32_e32 v58, v0
	v_mov_b32_e32 v59, v0
	v_mov_b32_e32 v60, v0
	v_mov_b32_e32 v61, v0
	v_mov_b32_e32 v62, v0
	v_mov_b32_e32 v63, v0
	v_mov_b32_e32 v64, v0
	v_mov_b32_e32 v65, v0
	v_mov_b32_e32 v66, v0
	v_mov_b32_e32 v67, v0
	v_mov_b32_e32 v68, v0
	v_mov_b32_e32 v69, v0
	v_mov_b32_e32 v70, v0
	v_mov_b32_e32 v71, v0
	v_mov_b32_e32 v72, v0
	v_mov_b32_e32 v73, v0
	v_mov_b32_e32 v74, v0
	v_mov_b32_e32 v75, v0
	v_mov_b32_e32 v76, v0
	v_mov_b32_e32 v77, v0
	v_mov_b32_e32 v78, v0
	v_mov_b32_e32 v79, v0
	v_mov_b32_e32 v80, v0
	v_mov_b32_e32 v81, v0
	v_mov_b32_e32 v82, v0
	v_mov_b32_e32 v83, v0
	v_mov_b32_e32 v84, v0
	v_mov_b32_e32 v85, v0
	v_mov_b32_e32 v86, v0
	v_mov_b32_e32 v87, v0
	v_mov_b32_e32 v88, v0
	v_mov_b32_e32 v89, v0
	v_mov_b32_e32 v90, v0
	v_mov_b32_e32 v91, v0
	v_mov_b32_e32 v92, v0
	v_mov_b32_e32 v93, v0
	v_mov_b32_e32 v94, v0
	v_mov_b32_e32 v95, v0
	v_mov_b32_e32 v96, v0
	v_mov_b32_e32 v97, v0
	v_mov_b32_e32 v98, v0
	v_mov_b32_e32 v99, v0
	v_mov_b32_e32 v100, v0
	v_mov_b32_e32 v101, v0
	v_mov_b32_e32 v102, v0
	v_mov_b32_e32 v103, v0
	v_mov_b32_e32 v104, v0
	v_mov_b32_e32 v105, v0
	v_mov_b32_e32 v106, v0
	v_mov_b32_e32 v107, v0
	v_mov_b32_e32 v108, v0
	v_mov_b32_e32 v109, v0
	v_mov_b32_e32 v110, v0
	v_mov_b32_e32 v111, v0
	v_mov_b32_e32 v112, v0
	v_mov_b32_e32 v113, v0
	v_mov_b32_e32 v114, v0
	v_mov_b32_e32 v115, v0
	v_mov_b32_e32 v116, v0
	v_mov_b32_e32 v117, v0
	v_mov_b32_e32 v118, v0
	v_mov_b32_e32 v119, v0
	v_mov_b32_e32 v120, v0
	v_mov_b32_e32 v121, v0
	v_mov_b32_e32 v122, v0
	v_mov_b32_e32 v123, v0
	v_mov_b32_e32 v124, v0
	v_mov_b32_e32 v125, v0
	v_mov_b32_e32 v126, v0
	v_mov_b32_e32 v127, v0
	s_barrier
	ds_read_b128 v[164:167], v150
	ds_read_b128 v[168:171], v150 offset:1024
	ds_read_b128 v[172:175], v150 offset:2048
	ds_read_b128 v[176:179], v150 offset:3072
; #define STAGE_A(P, br, kt) do { const char* _base = (const char*)(((kt) < G.ksplit ? G.A1 : A2m) + (long)(br) * G.lda + (long)(kt) * BK); \
;     __builtin_amdgcn_global_load_lds((const unsigned*)(_base + aoff0), (unsigned*)((char*)(P) + sb0), 16, 0, 0); \
;     __builtin_amdgcn_global_load_lds((const unsigned*)(_base + aoff1), (unsigned*)((char*)(P) + sb1), 16, 0, 0); } while (0)
; #define STAGE_B(P, br, kt) do { const char* _base = (const char*)(G.Bt + (long)(br) * G.ldb + (long)(kt) * BK); \
;     __builtin_amdgcn_global_load_lds((const unsigned*)(_base + boff0), (unsigned*)((char*)(P) + sb0), 16, 0, 0); \
;     __builtin_amdgcn_global_load_lds((const unsigned*)(_base + boff1), (unsigned*)((char*)(P) + sb1), 16, 0, 0); } while (0)
; #define LDA(dst, b, h) for (int m = 0; m < 4; ++m) for (int k = 0; k < 2; ++k) \
;     dst[m][k] = *reinterpret_cast<const bf16x8*>(a_rd + ((b) * 2 + (h)) * (HT * 2) + m * 2048 + k * 1024)
; #define LDB(dst, b, h) for (int n = 0; n < 2; ++n) for (int k = 0; k < 2; ++k) \
;     dst[n][k] = *reinterpret_cast<const bf16x8*>(b_rd + ((b) * 2 + (h)) * (HT * 2) + n * 2048 + k * 1024)
; #define MMA(ai, bj, At_, Bt_) do { __builtin_amdgcn_s_setprio(1); \
;     for (int m = 0; m < 4; ++m) for (int n = 0; n < 2; ++n) for (int k = 0; k < 2; ++k) \
;       acc[ai][bj][m][n] = __builtin_amdgcn_mfma_f32_16x16x32_bf16(Bt_[n][k], At_[m][k], acc[ai][bj][m][n], 0, 0, 0); \
;     __builtin_amdgcn_s_setprio(0); } while (0)
; #define WAIT_L(n) asm volatile("s_waitcnt lgkmcnt(" #n ")" ::: "memory")
; #define BAR __builtin_amdgcn_s_barrier()
; #define SCHED __builtin_amdgcn_sched_barrier(0)
;     ...
;   for (int t = 0; t < nt - 2; t += 2) {
;     LDB(B0, 0, 0); SCHED; LDA(At, 0, 0); STAGE_A(SA(1, 1), brow + HALF, t + 1);
;     WAIT_L(8); BAR; WAIT_L(0); MMA(0, 0, At, B0); BAR; SCHED;
;     LDB(B1, 0, 1); STAGE_B(SB(0, 0), bcol, t + 2);
;     BAR; WAIT_L(0); MMA(0, 1, At, B1); BAR;
;     LDA(At, 0, 1); STAGE_A(SA(0, 0), brow, t + 2);
;     BAR; WAIT_L(0); MMA(1, 0, At, B0); BAR; SCHED;
.LBB0_2566:
	v_add_u32_e32 v162, 0xc000, v147
	v_lshl_add_u64 v[222:223], s[18:19], 0, v[134:135]
	v_readfirstlane_b32 s34, v162
	v_add_u32_e32 v163, 0xe000, v147
	v_lshl_add_u64 v[160:161], v[222:223], 0, s[94:95]
	s_mov_b32 m0, s34
	v_lshl_add_u64 v[226:227], s[18:19], 0, v[136:137]
	v_readfirstlane_b32 s34, v163
	ds_read_b128 v[182:185], v149
	ds_read_b128 v[186:189], v149 offset:1024
	ds_read_b128 v[190:193], v149 offset:2048
	ds_read_b128 v[194:197], v149 offset:3072
	ds_read_b128 v[198:201], v149 offset:4096
	ds_read_b128 v[202:205], v149 offset:5120
	ds_read_b128 v[206:209], v149 offset:6144
	ds_read_b128 v[210:213], v149 offset:7168
	global_load_lds_dwordx4 v[160:161], off
	v_lshl_add_u64 v[160:161], v[226:227], 0, s[94:95]
	s_mov_b32 m0, s34
	s_nop 0
	global_load_lds_dwordx4 v[160:161], off
	s_waitcnt lgkmcnt(8)
	s_barrier
	s_waitcnt lgkmcnt(0)
	s_setprio 1
	s_waitcnt lgkmcnt(0)
	v_mfma_f32_16x16x32_bf16 v[124:127], v[164:167], v[182:185], v[124:127]
	v_mfma_f32_16x16x32_bf16 v[120:123], v[172:175], v[182:185], v[120:123]
	v_mfma_f32_16x16x32_bf16 v[116:119], v[164:167], v[190:193], v[116:119]
	v_mfma_f32_16x16x32_bf16 v[112:115], v[172:175], v[190:193], v[112:115]
	v_mfma_f32_16x16x32_bf16 v[108:111], v[164:167], v[198:201], v[108:111]
	v_mfma_f32_16x16x32_bf16 v[104:107], v[172:175], v[198:201], v[104:107]
	v_mfma_f32_16x16x32_bf16 v[100:103], v[164:167], v[206:209], v[100:103]
	v_mfma_f32_16x16x32_bf16 v[96:99], v[172:175], v[206:209], v[96:99]
	v_mfma_f32_16x16x32_bf16 v[124:127], v[168:171], v[186:189], v[124:127]
	v_mfma_f32_16x16x32_bf16 v[120:123], v[176:179], v[186:189], v[120:123]
	v_mfma_f32_16x16x32_bf16 v[116:119], v[168:171], v[194:197], v[116:119]
	v_mfma_f32_16x16x32_bf16 v[112:115], v[176:179], v[194:197], v[112:115]
	v_mfma_f32_16x16x32_bf16 v[108:111], v[168:171], v[202:205], v[108:111]
	v_mfma_f32_16x16x32_bf16 v[104:107], v[176:179], v[202:205], v[104:107]
	s_setprio 2
	s_barrier
	v_mfma_f32_16x16x32_bf16 v[100:103], v[168:171], v[210:213], v[100:103]
	v_mfma_f32_16x16x32_bf16 v[96:99], v[176:179], v[210:213], v[96:99]
	s_setprio 0
	v_add_u32_e32 v159, s21, v148
	v_lshl_add_u64 v[234:235], s[18:19], 0, v[130:131]
	v_readfirstlane_b32 s34, v159
	v_lshl_add_u64 v[160:161], v[234:235], 0, s[90:91]
	s_mov_b32 m0, s34
	ds_read_b128 v[214:217], v150 offset:16384
	ds_read_b128 v[218:221], v150 offset:17408
	ds_read_b128 v[230:233], v150 offset:18432
	ds_read_b128 v[238:241], v150 offset:19456
	global_load_lds_dwordx4 v[160:161], off
	v_add_u32_e32 v160, 0x2000, v159
	v_lshl_add_u64 v[236:237], s[18:19], 0, v[132:133]
	v_readfirstlane_b32 s34, v160
	v_lshl_add_u64 v[246:247], v[236:237], 0, s[90:91]
	s_mov_b32 m0, s34
	s_nop 0
	global_load_lds_dwordx4 v[246:247], off
	s_barrier
	s_waitcnt lgkmcnt(0)
	s_setprio 1
	s_waitcnt lgkmcnt(0)
	v_mfma_f32_16x16x32_bf16 v[92:95], v[214:217], v[182:185], v[92:95]
	v_mfma_f32_16x16x32_bf16 v[88:91], v[230:233], v[182:185], v[88:91]
	v_mfma_f32_16x16x32_bf16 v[84:87], v[214:217], v[190:193], v[84:87]
	v_mfma_f32_16x16x32_bf16 v[80:83], v[230:233], v[190:193], v[80:83]
	v_mfma_f32_16x16x32_bf16 v[76:79], v[214:217], v[198:201], v[76:79]
	v_mfma_f32_16x16x32_bf16 v[72:75], v[230:233], v[198:201], v[72:75]
	v_mfma_f32_16x16x32_bf16 v[68:71], v[214:217], v[206:209], v[68:71]
	v_mfma_f32_16x16x32_bf16 v[64:67], v[230:233], v[206:209], v[64:67]
	v_mfma_f32_16x16x32_bf16 v[92:95], v[218:221], v[186:189], v[92:95]
	v_mfma_f32_16x16x32_bf16 v[88:91], v[238:241], v[186:189], v[88:91]
	v_mfma_f32_16x16x32_bf16 v[84:87], v[218:221], v[194:197], v[84:87]
	v_mfma_f32_16x16x32_bf16 v[80:83], v[238:241], v[194:197], v[80:83]
	v_mfma_f32_16x16x32_bf16 v[76:79], v[218:221], v[202:205], v[76:79]
	v_mfma_f32_16x16x32_bf16 v[72:75], v[238:241], v[202:205], v[72:75]
	s_setprio 2
	s_barrier
	v_mfma_f32_16x16x32_bf16 v[68:71], v[218:221], v[210:213], v[68:71]
	v_mfma_f32_16x16x32_bf16 v[64:67], v[238:241], v[210:213], v[64:67]
	s_setprio 0
	v_readfirstlane_b32 s34, v147
	v_lshl_add_u64 v[246:247], v[222:223], 0, s[4:5]
	s_mov_b32 m0, s34
	v_readfirstlane_b32 s34, v146
	ds_read_b128 v[182:185], v149 offset:16384
	ds_read_b128 v[186:189], v149 offset:17408
	ds_read_b128 v[190:193], v149 offset:18432
	ds_read_b128 v[194:197], v149 offset:19456
	ds_read_b128 v[198:201], v149 offset:20480
	ds_read_b128 v[202:205], v149 offset:21504
	ds_read_b128 v[206:209], v149 offset:22528
	ds_read_b128 v[210:213], v149 offset:23552
	global_load_lds_dwordx4 v[246:247], off
	v_lshl_add_u64 v[246:247], v[226:227], 0, s[4:5]
	s_mov_b32 m0, s34
	s_nop 0
	global_load_lds_dwordx4 v[246:247], off
	s_waitcnt vmcnt(10)
	s_barrier
	s_waitcnt lgkmcnt(0)
	s_setprio 1
	s_waitcnt lgkmcnt(0)
	v_mfma_f32_16x16x32_bf16 v[60:63], v[164:167], v[182:185], v[60:63]
	v_mfma_f32_16x16x32_bf16 v[56:59], v[172:175], v[182:185], v[56:59]
	v_mfma_f32_16x16x32_bf16 v[52:55], v[164:167], v[190:193], v[52:55]
	v_mfma_f32_16x16x32_bf16 v[48:51], v[172:175], v[190:193], v[48:51]
	v_mfma_f32_16x16x32_bf16 v[44:47], v[164:167], v[198:201], v[44:47]
	v_mfma_f32_16x16x32_bf16 v[40:43], v[172:175], v[198:201], v[40:43]
	v_mfma_f32_16x16x32_bf16 v[36:39], v[164:167], v[206:209], v[36:39]
	v_mfma_f32_16x16x32_bf16 v[32:35], v[172:175], v[206:209], v[32:35]
	v_mfma_f32_16x16x32_bf16 v[60:63], v[168:171], v[186:189], v[60:63]
	v_mfma_f32_16x16x32_bf16 v[56:59], v[176:179], v[186:189], v[56:59]
	v_mfma_f32_16x16x32_bf16 v[52:55], v[168:171], v[194:197], v[52:55]
	v_mfma_f32_16x16x32_bf16 v[48:51], v[176:179], v[194:197], v[48:51]
	v_mfma_f32_16x16x32_bf16 v[44:47], v[168:171], v[202:205], v[44:47]
	v_mfma_f32_16x16x32_bf16 v[40:43], v[176:179], v[202:205], v[40:43]
	s_setprio 2
	s_barrier
; #define STAGE_A(P, br, kt) do { const char* _base = (const char*)(((kt) < G.ksplit ? G.A1 : A2m) + (long)(br) * G.lda + (long)(kt) * BK); \
;     __builtin_amdgcn_global_load_lds((const unsigned*)(_base + aoff0), (unsigned*)((char*)(P) + sb0), 16, 0, 0); \
;     __builtin_amdgcn_global_load_lds((const unsigned*)(_base + aoff1), (unsigned*)((char*)(P) + sb1), 16, 0, 0); } while (0)
; #define STAGE_B(P, br, kt) do { const char* _base = (const char*)(G.Bt + (long)(br) * G.ldb + (long)(kt) * BK); \
;     __builtin_amdgcn_global_load_lds((const unsigned*)(_base + boff0), (unsigned*)((char*)(P) + sb0), 16, 0, 0); \
;     __builtin_amdgcn_global_load_lds((const unsigned*)(_base + boff1), (unsigned*)((char*)(P) + sb1), 16, 0, 0); } while (0)
; #define LDA(dst, b, h) for (int m = 0; m < 4; ++m) for (int k = 0; k < 2; ++k) \
;     dst[m][k] = *reinterpret_cast<const bf16x8*>(a_rd + ((b) * 2 + (h)) * (HT * 2) + m * 2048 + k * 1024)
; #define LDB(dst, b, h) for (int n = 0; n < 2; ++n) for (int k = 0; k < 2; ++k) \
;     dst[n][k] = *reinterpret_cast<const bf16x8*>(b_rd + ((b) * 2 + (h)) * (HT * 2) + n * 2048 + k * 1024)
; #define MMA(ai, bj, At_, Bt_) do { __builtin_amdgcn_s_setprio(1); \
;     for (int m = 0; m < 4; ++m) for (int n = 0; n < 2; ++n) for (int k = 0; k < 2; ++k) \
;       acc[ai][bj][m][n] = __builtin_amdgcn_mfma_f32_16x16x32_bf16(Bt_[n][k], At_[m][k], acc[ai][bj][m][n], 0, 0, 0); \
;     __builtin_amdgcn_s_setprio(0); } while (0)
; #define WAIT_V(n) asm volatile("s_waitcnt vmcnt(" #n ")" ::: "memory")
; #define WAIT_L(n) asm volatile("s_waitcnt lgkmcnt(" #n ")" ::: "memory")
; #define BAR __builtin_amdgcn_s_barrier()
; #define SCHED __builtin_amdgcn_sched_barrier(0)
;     ...
;     BAR; WAIT_L(0); MMA(1, 0, At, B0); BAR; SCHED;
;     STAGE_B(SB(0, 1), bcol + HALF, t + 2);
;     WAIT_V(6); BAR; MMA(1, 1, At, B1); BAR;
;     LDB(B0, 1, 0); SCHED; LDA(At, 1, 0); STAGE_A(SA(0, 1), brow + HALF, t + 2);
;     WAIT_L(8); BAR; WAIT_L(0); MMA(0, 0, At, B0); BAR; SCHED;
;     LDB(B1, 1, 1); STAGE_B(SB(1, 0), bcol, t + 3);
;     BAR; WAIT_L(0); MMA(0, 1, At, B1); BAR;
	v_mfma_f32_16x16x32_bf16 v[36:39], v[168:171], v[210:213], v[36:39]
	v_mfma_f32_16x16x32_bf16 v[32:35], v[176:179], v[210:213], v[32:35]
	s_setprio 0
	v_lshl_add_u64 v[246:247], s[18:19], 0, v[138:139]
	v_readfirstlane_b32 s34, v145
	v_add_u32_e32 v161, 0x2000, v145
	v_lshl_add_u64 v[164:165], v[246:247], 0, s[68:69]
	s_mov_b32 m0, s34
	v_lshl_add_u64 v[248:249], s[18:19], 0, v[140:141]
	v_readfirstlane_b32 s34, v161
	global_load_lds_dwordx4 v[164:165], off
	v_lshl_add_u64 v[164:165], v[248:249], 0, s[68:69]
	s_mov_b32 m0, s34
	s_nop 0
	global_load_lds_dwordx4 v[164:165], off
	ds_read_b128 v[164:167], v150 offset:32768
	ds_read_b128 v[168:171], v150 offset:33792
	ds_read_b128 v[172:175], v150 offset:34816
	ds_read_b128 v[176:179], v150 offset:35840
	s_waitcnt vmcnt(6)
	s_barrier
	s_setprio 1
	v_mfma_f32_16x16x32_bf16 v[28:31], v[214:217], v[182:185], v[28:31]
	v_mfma_f32_16x16x32_bf16 v[24:27], v[230:233], v[182:185], v[24:27]
	v_mfma_f32_16x16x32_bf16 v[20:23], v[214:217], v[190:193], v[20:23]
	v_mfma_f32_16x16x32_bf16 v[16:19], v[230:233], v[190:193], v[16:19]
	v_mfma_f32_16x16x32_bf16 v[12:15], v[214:217], v[198:201], v[12:15]
	v_mfma_f32_16x16x32_bf16 v[8:11], v[230:233], v[198:201], v[8:11]
	v_mfma_f32_16x16x32_bf16 v[4:7], v[214:217], v[206:209], v[4:7]
	v_mfma_f32_16x16x32_bf16 v[0:3], v[230:233], v[206:209], v[0:3]
	v_mfma_f32_16x16x32_bf16 v[28:31], v[218:221], v[186:189], v[28:31]
	v_mfma_f32_16x16x32_bf16 v[24:27], v[238:241], v[186:189], v[24:27]
	v_mfma_f32_16x16x32_bf16 v[20:23], v[218:221], v[194:197], v[20:23]
	v_mfma_f32_16x16x32_bf16 v[16:19], v[238:241], v[194:197], v[16:19]
	v_mfma_f32_16x16x32_bf16 v[12:15], v[218:221], v[202:205], v[12:15]
	v_mfma_f32_16x16x32_bf16 v[8:11], v[238:241], v[202:205], v[8:11]
	s_setprio 2
	s_barrier
	v_mfma_f32_16x16x32_bf16 v[4:7], v[218:221], v[210:213], v[4:7]
	v_mfma_f32_16x16x32_bf16 v[0:3], v[238:241], v[210:213], v[0:3]
	s_setprio 0
	v_readfirstlane_b32 s34, v143
	v_lshl_add_u64 v[214:215], v[222:223], 0, s[96:97]
	s_mov_b32 m0, s34
	v_readfirstlane_b32 s34, v142
	ds_read_b128 v[182:185], v149 offset:32768
	ds_read_b128 v[186:189], v149 offset:33792
	ds_read_b128 v[190:193], v149 offset:34816
	ds_read_b128 v[194:197], v149 offset:35840
	ds_read_b128 v[198:201], v149 offset:36864
	ds_read_b128 v[202:205], v149 offset:37888
	ds_read_b128 v[206:209], v149 offset:38912
	ds_read_b128 v[210:213], v149 offset:39936
	global_load_lds_dwordx4 v[214:215], off
	v_lshl_add_u64 v[214:215], v[226:227], 0, s[96:97]
	s_mov_b32 m0, s34
	s_nop 0
	global_load_lds_dwordx4 v[214:215], off
	s_waitcnt lgkmcnt(8)
	s_barrier
	s_waitcnt lgkmcnt(0)
	s_setprio 1
	s_waitcnt lgkmcnt(0)
	v_mfma_f32_16x16x32_bf16 v[124:127], v[164:167], v[182:185], v[124:127]
	v_mfma_f32_16x16x32_bf16 v[120:123], v[172:175], v[182:185], v[120:123]
	v_mfma_f32_16x16x32_bf16 v[116:119], v[164:167], v[190:193], v[116:119]
	v_mfma_f32_16x16x32_bf16 v[112:115], v[172:175], v[190:193], v[112:115]
	v_mfma_f32_16x16x32_bf16 v[108:111], v[164:167], v[198:201], v[108:111]
	v_mfma_f32_16x16x32_bf16 v[104:107], v[172:175], v[198:201], v[104:107]
	v_mfma_f32_16x16x32_bf16 v[100:103], v[164:167], v[206:209], v[100:103]
	v_mfma_f32_16x16x32_bf16 v[96:99], v[172:175], v[206:209], v[96:99]
	v_mfma_f32_16x16x32_bf16 v[124:127], v[168:171], v[186:189], v[124:127]
	v_mfma_f32_16x16x32_bf16 v[120:123], v[176:179], v[186:189], v[120:123]
	v_mfma_f32_16x16x32_bf16 v[116:119], v[168:171], v[194:197], v[116:119]
	v_mfma_f32_16x16x32_bf16 v[112:115], v[176:179], v[194:197], v[112:115]
	v_mfma_f32_16x16x32_bf16 v[108:111], v[168:171], v[202:205], v[108:111]
	v_mfma_f32_16x16x32_bf16 v[104:107], v[176:179], v[202:205], v[104:107]
	s_setprio 2
	s_barrier
	v_mfma_f32_16x16x32_bf16 v[100:103], v[168:171], v[210:213], v[100:103]
	v_mfma_f32_16x16x32_bf16 v[96:99], v[176:179], v[210:213], v[96:99]
	s_setprio 0
	v_readfirstlane_b32 s34, v153
	v_lshl_add_u64 v[234:235], v[234:235], 0, s[88:89]
	s_mov_b32 m0, s34
	v_readfirstlane_b32 s34, v154
	ds_read_b128 v[214:217], v150 offset:49152
	ds_read_b128 v[218:221], v150 offset:50176
	ds_read_b128 v[230:233], v150 offset:51200
	ds_read_b128 v[238:241], v150 offset:52224
	global_load_lds_dwordx4 v[234:235], off
	v_lshl_add_u64 v[234:235], v[236:237], 0, s[88:89]
	s_mov_b32 m0, s34
	s_nop 0
	global_load_lds_dwordx4 v[234:235], off
	s_barrier
	s_waitcnt lgkmcnt(0)
	s_setprio 1
	s_waitcnt lgkmcnt(0)
	v_mfma_f32_16x16x32_bf16 v[92:95], v[214:217], v[182:185], v[92:95]
	v_mfma_f32_16x16x32_bf16 v[88:91], v[230:233], v[182:185], v[88:91]
	v_mfma_f32_16x16x32_bf16 v[84:87], v[214:217], v[190:193], v[84:87]
	v_mfma_f32_16x16x32_bf16 v[80:83], v[230:233], v[190:193], v[80:83]
	v_mfma_f32_16x16x32_bf16 v[76:79], v[214:217], v[198:201], v[76:79]
	v_mfma_f32_16x16x32_bf16 v[72:75], v[230:233], v[198:201], v[72:75]
	v_mfma_f32_16x16x32_bf16 v[68:71], v[214:217], v[206:209], v[68:71]
	v_mfma_f32_16x16x32_bf16 v[64:67], v[230:233], v[206:209], v[64:67]
	v_mfma_f32_16x16x32_bf16 v[92:95], v[218:221], v[186:189], v[92:95]
	v_mfma_f32_16x16x32_bf16 v[88:91], v[238:241], v[186:189], v[88:91]
	v_mfma_f32_16x16x32_bf16 v[84:87], v[218:221], v[194:197], v[84:87]
	v_mfma_f32_16x16x32_bf16 v[80:83], v[238:241], v[194:197], v[80:83]
	v_mfma_f32_16x16x32_bf16 v[76:79], v[218:221], v[202:205], v[76:79]
	v_mfma_f32_16x16x32_bf16 v[72:75], v[238:241], v[202:205], v[72:75]
	s_setprio 2
	s_barrier
; #define STAGE_A(P, br, kt) do { const char* _base = (const char*)(((kt) < G.ksplit ? G.A1 : A2m) + (long)(br) * G.lda + (long)(kt) * BK); \
;     __builtin_amdgcn_global_load_lds((const unsigned*)(_base + aoff0), (unsigned*)((char*)(P) + sb0), 16, 0, 0); \
;     __builtin_amdgcn_global_load_lds((const unsigned*)(_base + aoff1), (unsigned*)((char*)(P) + sb1), 16, 0, 0); } while (0)
; #define STAGE_B(P, br, kt) do { const char* _base = (const char*)(G.Bt + (long)(br) * G.ldb + (long)(kt) * BK); \
;     __builtin_amdgcn_global_load_lds((const unsigned*)(_base + boff0), (unsigned*)((char*)(P) + sb0), 16, 0, 0); \
;     __builtin_amdgcn_global_load_lds((const unsigned*)(_base + boff1), (unsigned*)((char*)(P) + sb1), 16, 0, 0); } while (0)
; #define LDA(dst, b, h) for (int m = 0; m < 4; ++m) for (int k = 0; k < 2; ++k) \
;     dst[m][k] = *reinterpret_cast<const bf16x8*>(a_rd + ((b) * 2 + (h)) * (HT * 2) + m * 2048 + k * 1024)
; #define LDB(dst, b, h) for (int n = 0; n < 2; ++n) for (int k = 0; k < 2; ++k) \
;     dst[n][k] = *reinterpret_cast<const bf16x8*>(b_rd + ((b) * 2 + (h)) * (HT * 2) + n * 2048 + k * 1024)
; #define MMA(ai, bj, At_, Bt_) do { __builtin_amdgcn_s_setprio(1); \
;     for (int m = 0; m < 4; ++m) for (int n = 0; n < 2; ++n) for (int k = 0; k < 2; ++k) \
;       acc[ai][bj][m][n] = __builtin_amdgcn_mfma_f32_16x16x32_bf16(Bt_[n][k], At_[m][k], acc[ai][bj][m][n], 0, 0, 0); \
;     __builtin_amdgcn_s_setprio(0); } while (0)
; #define WAIT_V(n) asm volatile("s_waitcnt vmcnt(" #n ")" ::: "memory")
; #define WAIT_L(n) asm volatile("s_waitcnt lgkmcnt(" #n ")" ::: "memory")
; #define BAR __builtin_amdgcn_s_barrier()
; #define SCHED __builtin_amdgcn_sched_barrier(0)
;     ...
;     LDA(At, 1, 1); STAGE_A(SA(1, 0), brow, t + 3);
;     BAR; WAIT_L(0); MMA(1, 0, At, B0); BAR; SCHED;
;     STAGE_B(SB(1, 1), bcol + HALF, t + 3);
;     WAIT_V(6); BAR; MMA(1, 1, At, B1); BAR;
;   }
;   float ssv[2][4] = {};
;   if constexpr (EPI == EPI_GU || EPI == EPI_EVIN || EPI == EPI_ODIN) {
; #pragma unroll
;     for (int ai = 0; ai < 2; ++ai)
; #pragma unroll
;       for (int m = 0; m < 4; ++m) ssv[ai][m] = G.ssr[brow + ai * HALF + wr * 64 + m * 16 + fr];
;   }
;   { LDB(B0, 0, 0); LDA(At, 0, 0); STAGE_A(SA(1, 1), brow + HALF, nt - 1);
	v_mfma_f32_16x16x32_bf16 v[68:71], v[218:221], v[210:213], v[68:71]
	v_mfma_f32_16x16x32_bf16 v[64:67], v[238:241], v[210:213], v[64:67]
	s_setprio 0
	v_readfirstlane_b32 s34, v155
	v_lshl_add_u64 v[222:223], v[222:223], 0, s[2:3]
	s_mov_b32 m0, s34
	v_readfirstlane_b32 s34, v156
	ds_read_b128 v[182:185], v149 offset:49152
	ds_read_b128 v[186:189], v149 offset:50176
	ds_read_b128 v[190:193], v149 offset:51200
	ds_read_b128 v[194:197], v149 offset:52224
	ds_read_b128 v[198:201], v149 offset:53248
	ds_read_b128 v[202:205], v149 offset:54272
	ds_read_b128 v[206:209], v149 offset:55296
	ds_read_b128 v[210:213], v149 offset:56320
	global_load_lds_dwordx4 v[222:223], off
	v_lshl_add_u64 v[222:223], v[226:227], 0, s[2:3]
	s_mov_b32 m0, s34
	s_nop 0
	global_load_lds_dwordx4 v[222:223], off
	s_waitcnt vmcnt(10)
	s_barrier
	s_waitcnt lgkmcnt(0)
	s_setprio 1
	s_waitcnt lgkmcnt(0)
	v_mfma_f32_16x16x32_bf16 v[60:63], v[164:167], v[182:185], v[60:63]
	v_mfma_f32_16x16x32_bf16 v[56:59], v[172:175], v[182:185], v[56:59]
	v_mfma_f32_16x16x32_bf16 v[52:55], v[164:167], v[190:193], v[52:55]
	v_mfma_f32_16x16x32_bf16 v[48:51], v[172:175], v[190:193], v[48:51]
	v_mfma_f32_16x16x32_bf16 v[44:47], v[164:167], v[198:201], v[44:47]
	v_mfma_f32_16x16x32_bf16 v[40:43], v[172:175], v[198:201], v[40:43]
	v_mfma_f32_16x16x32_bf16 v[36:39], v[164:167], v[206:209], v[36:39]
	v_mfma_f32_16x16x32_bf16 v[32:35], v[172:175], v[206:209], v[32:35]
	v_mfma_f32_16x16x32_bf16 v[60:63], v[168:171], v[186:189], v[60:63]
	v_mfma_f32_16x16x32_bf16 v[56:59], v[176:179], v[186:189], v[56:59]
	v_mfma_f32_16x16x32_bf16 v[52:55], v[168:171], v[194:197], v[52:55]
	v_mfma_f32_16x16x32_bf16 v[48:51], v[176:179], v[194:197], v[48:51]
	v_mfma_f32_16x16x32_bf16 v[44:47], v[168:171], v[202:205], v[44:47]
	v_mfma_f32_16x16x32_bf16 v[40:43], v[176:179], v[202:205], v[40:43]
	s_setprio 2
	s_barrier
	v_mfma_f32_16x16x32_bf16 v[36:39], v[168:171], v[210:213], v[36:39]
	v_mfma_f32_16x16x32_bf16 v[32:35], v[176:179], v[210:213], v[32:35]
	s_setprio 0
	v_readfirstlane_b32 s34, v157
	v_lshl_add_u64 v[164:165], v[246:247], 0, s[70:71]
	s_mov_b32 m0, s34
	v_readfirstlane_b32 s34, v158
	global_load_lds_dwordx4 v[164:165], off
	v_lshl_add_u64 v[164:165], v[248:249], 0, s[70:71]
	s_mov_b32 m0, s34
	s_nop 0
	global_load_lds_dwordx4 v[164:165], off
	ds_read_b128 v[164:167], v150
	ds_read_b128 v[168:171], v150 offset:1024
	ds_read_b128 v[172:175], v150 offset:2048
	ds_read_b128 v[176:179], v150 offset:3072
	s_waitcnt vmcnt(6)
	s_barrier
	s_setprio 1
	v_mfma_f32_16x16x32_bf16 v[28:31], v[214:217], v[182:185], v[28:31]
	v_mfma_f32_16x16x32_bf16 v[24:27], v[230:233], v[182:185], v[24:27]
	v_mfma_f32_16x16x32_bf16 v[20:23], v[214:217], v[190:193], v[20:23]
	v_mfma_f32_16x16x32_bf16 v[16:19], v[230:233], v[190:193], v[16:19]
	v_mfma_f32_16x16x32_bf16 v[12:15], v[214:217], v[198:201], v[12:15]
	v_mfma_f32_16x16x32_bf16 v[8:11], v[230:233], v[198:201], v[8:11]
	v_mfma_f32_16x16x32_bf16 v[4:7], v[214:217], v[206:209], v[4:7]
	v_mfma_f32_16x16x32_bf16 v[0:3], v[230:233], v[206:209], v[0:3]
	v_mfma_f32_16x16x32_bf16 v[28:31], v[218:221], v[186:189], v[28:31]
	v_mfma_f32_16x16x32_bf16 v[24:27], v[238:241], v[186:189], v[24:27]
	v_mfma_f32_16x16x32_bf16 v[20:23], v[218:221], v[194:197], v[20:23]
	v_mfma_f32_16x16x32_bf16 v[16:19], v[238:241], v[194:197], v[16:19]
	v_mfma_f32_16x16x32_bf16 v[12:15], v[218:221], v[202:205], v[12:15]
	v_mfma_f32_16x16x32_bf16 v[8:11], v[238:241], v[202:205], v[8:11]
	s_setprio 2
	s_barrier
	v_mfma_f32_16x16x32_bf16 v[4:7], v[218:221], v[210:213], v[4:7]
	v_mfma_f32_16x16x32_bf16 v[0:3], v[238:241], v[210:213], v[0:3]
	s_setprio 0
	s_add_i32 s31, s31, 2
	s_add_u32 s18, s18, 0x100
	s_addc_u32 s19, s19, 0
	s_cmp_lt_u32 s31, 28
	s_cbranch_scc1 .LBB0_2566
	s_waitcnt lgkmcnt(0)
	v_or_b32_e32 v130, s28, v152
	v_lshl_add_u32 v130, v151, 6, v130
	v_add_u32_e32 v134, 0x80, v130
	v_ashrrev_i32_e32 v135, 31, v134
	v_lshl_add_u64 v[140:141], v[134:135], 2, s[12:13]
	v_add_u32_e32 v134, 0x90, v130
	v_ashrrev_i32_e32 v131, 31, v130
	v_ashrrev_i32_e32 v135, 31, v134
	v_lshl_add_u64 v[132:133], v[130:131], 2, s[12:13]
	v_lshl_add_u64 v[152:153], v[134:135], 2, s[12:13]
	v_add_u32_e32 v134, 0xa0, v130
	v_add_u32_e32 v130, 0xb0, v130
	s_or_b32 s21, s28, 0x80
	v_ashrrev_i32_e32 v135, 31, v134
	v_ashrrev_i32_e32 v131, 31, v130
	s_mul_i32 s18, s21, 0x1080
	v_lshl_add_u64 v[154:155], v[134:135], 2, s[12:13]
	v_lshl_add_u64 v[156:157], v[130:131], 2, s[12:13]
	global_load_dword v139, v[132:133], off
	global_load_dword v138, v[132:133], off offset:64
	global_load_dword v137, v[132:133], off offset:128
	global_load_dword v134, v[132:133], off offset:192
	s_nop 0
	global_load_dword v133, v[140:141], off
	global_load_dword v132, v[152:153], off
	global_load_dword v131, v[154:155], off
	global_load_dword v130, v[156:157], off
	s_mul_hi_i32 s19, s21, 0x1080
	s_add_u32 s18, s23, s18
	s_addc_u32 s19, s24, s19
	v_lshl_add_u64 v[140:141], s[18:19], 0, v[180:181]
	v_readfirstlane_b32 s31, v162
	v_lshl_add_u64 v[140:141], v[140:141], 0, s[46:47]
	s_mov_b32 m0, s31
	ds_read_b128 v[152:155], v150
	ds_read_b128 v[164:167], v150 offset:1024
	ds_read_b128 v[168:171], v150 offset:2048
	ds_read_b128 v[172:175], v150 offset:3072
	ds_read_b128 v[176:179], v149
	ds_read_b128 v[182:185], v149 offset:1024
	ds_read_b128 v[186:189], v149 offset:2048
	ds_read_b128 v[190:193], v149 offset:3072
	ds_read_b128 v[194:197], v149 offset:4096
	ds_read_b128 v[198:201], v149 offset:5120
	ds_read_b128 v[202:205], v149 offset:6144
	ds_read_b128 v[206:209], v149 offset:7168
	global_load_lds_dwordx4 v[140:141], off
	v_lshl_add_u64 v[140:141], s[18:19], 0, v[128:129]
	v_readfirstlane_b32 s18, v163
	v_lshl_add_u64 v[140:141], v[140:141], 0, s[46:47]
	s_mov_b32 m0, s18
	s_nop 0
	global_load_lds_dwordx4 v[140:141], off
	s_barrier
; #define STAGE_A(P, br, kt) do { const char* _base = (const char*)(((kt) < G.ksplit ? G.A1 : A2m) + (long)(br) * G.lda + (long)(kt) * BK); \
;     __builtin_amdgcn_global_load_lds((const unsigned*)(_base + aoff0), (unsigned*)((char*)(P) + sb0), 16, 0, 0); \
;     __builtin_amdgcn_global_load_lds((const unsigned*)(_base + aoff1), (unsigned*)((char*)(P) + sb1), 16, 0, 0); } while (0)
; #define LDA(dst, b, h) for (int m = 0; m < 4; ++m) for (int k = 0; k < 2; ++k) \
;     dst[m][k] = *reinterpret_cast<const bf16x8*>(a_rd + ((b) * 2 + (h)) * (HT * 2) + m * 2048 + k * 1024)
; #define LDB(dst, b, h) for (int n = 0; n < 2; ++n) for (int k = 0; k < 2; ++k) \
;     dst[n][k] = *reinterpret_cast<const bf16x8*>(b_rd + ((b) * 2 + (h)) * (HT * 2) + n * 2048 + k * 1024)
; #define MMA(ai, bj, At_, Bt_) do { __builtin_amdgcn_s_setprio(1); \
;     for (int m = 0; m < 4; ++m) for (int n = 0; n < 2; ++n) for (int k = 0; k < 2; ++k) \
;       acc[ai][bj][m][n] = __builtin_amdgcn_mfma_f32_16x16x32_bf16(Bt_[n][k], At_[m][k], acc[ai][bj][m][n], 0, 0, 0); \
;     __builtin_amdgcn_s_setprio(0); } while (0)
; #define WAIT_V(n) asm volatile("s_waitcnt vmcnt(" #n ")" ::: "memory")
; #define WAIT_L(n) asm volatile("s_waitcnt lgkmcnt(" #n ")" ::: "memory")
; #define BAR __builtin_amdgcn_s_barrier()
;     ...
;   { LDB(B0, 0, 0); LDA(At, 0, 0); STAGE_A(SA(1, 1), brow + HALF, nt - 1);
;     BAR; WAIT_L(0); MMA(0, 0, At, B0); BAR;
;     LDB(B1, 0, 1); BAR; WAIT_L(0); MMA(0, 1, At, B1); BAR;
;     LDA(At, 0, 1); WAIT_V(4); BAR; WAIT_L(0); MMA(1, 0, At, B0); MMA(1, 1, At, B1); BAR; }
;   { LDB(B0, 1, 0); LDA(At, 1, 0); WAIT_V(2); BAR; WAIT_L(0); MMA(0, 0, At, B0); BAR;
	s_waitcnt lgkmcnt(0)
	s_setprio 1
	s_waitcnt lgkmcnt(0)
	v_mfma_f32_16x16x32_bf16 v[124:127], v[152:155], v[176:179], v[124:127]
	v_mfma_f32_16x16x32_bf16 v[116:119], v[152:155], v[186:189], v[116:119]
	v_mfma_f32_16x16x32_bf16 v[108:111], v[152:155], v[194:197], v[108:111]
	v_mfma_f32_16x16x32_bf16 v[100:103], v[152:155], v[202:205], v[100:103]
	v_mfma_f32_16x16x32_bf16 v[124:127], v[164:167], v[182:185], v[124:127]
	v_mfma_f32_16x16x32_bf16 v[120:123], v[168:171], v[176:179], v[120:123]
	v_mfma_f32_16x16x32_bf16 v[116:119], v[164:167], v[190:193], v[116:119]
	v_mfma_f32_16x16x32_bf16 v[112:115], v[168:171], v[186:189], v[112:115]
	v_mfma_f32_16x16x32_bf16 v[108:111], v[164:167], v[198:201], v[108:111]
	v_mfma_f32_16x16x32_bf16 v[104:107], v[168:171], v[194:197], v[104:107]
	v_mfma_f32_16x16x32_bf16 v[100:103], v[164:167], v[206:209], v[100:103]
	v_mfma_f32_16x16x32_bf16 v[96:99], v[168:171], v[202:205], v[96:99]
	v_mfma_f32_16x16x32_bf16 v[210:213], v[172:175], v[182:185], v[120:123]
	v_mfma_f32_16x16x32_bf16 v[214:217], v[172:175], v[190:193], v[112:115]
	s_setprio 2
	s_barrier
	v_mfma_f32_16x16x32_bf16 v[218:221], v[172:175], v[198:201], v[104:107]
	v_mfma_f32_16x16x32_bf16 v[230:233], v[172:175], v[206:209], v[96:99]
	s_setprio 0
	s_nop 1
	ds_read_b128 v[96:99], v150 offset:16384
	ds_read_b128 v[104:107], v150 offset:17408
	ds_read_b128 v[112:115], v150 offset:18432
	ds_read_b128 v[120:123], v150 offset:19456
	s_barrier
	s_waitcnt lgkmcnt(0)
	s_setprio 1
	s_waitcnt lgkmcnt(0)
	v_mfma_f32_16x16x32_bf16 v[92:95], v[96:99], v[176:179], v[92:95]
	v_mfma_f32_16x16x32_bf16 v[84:87], v[96:99], v[186:189], v[84:87]
	v_mfma_f32_16x16x32_bf16 v[76:79], v[96:99], v[194:197], v[76:79]
	v_mfma_f32_16x16x32_bf16 v[68:71], v[96:99], v[202:205], v[68:71]
	v_mfma_f32_16x16x32_bf16 v[92:95], v[104:107], v[182:185], v[92:95]
	v_mfma_f32_16x16x32_bf16 v[88:91], v[112:115], v[176:179], v[88:91]
	v_mfma_f32_16x16x32_bf16 v[84:87], v[104:107], v[190:193], v[84:87]
	v_mfma_f32_16x16x32_bf16 v[80:83], v[112:115], v[186:189], v[80:83]
	v_mfma_f32_16x16x32_bf16 v[76:79], v[104:107], v[198:201], v[76:79]
	v_mfma_f32_16x16x32_bf16 v[72:75], v[112:115], v[194:197], v[72:75]
	v_mfma_f32_16x16x32_bf16 v[68:71], v[104:107], v[206:209], v[68:71]
	v_mfma_f32_16x16x32_bf16 v[64:67], v[112:115], v[202:205], v[64:67]
	v_mfma_f32_16x16x32_bf16 v[176:179], v[120:123], v[182:185], v[88:91]
	v_mfma_f32_16x16x32_bf16 v[182:185], v[120:123], v[190:193], v[80:83]
	s_setprio 2
	s_barrier
	v_mfma_f32_16x16x32_bf16 v[186:189], v[120:123], v[198:201], v[72:75]
	v_mfma_f32_16x16x32_bf16 v[190:193], v[120:123], v[206:209], v[64:67]
	s_setprio 0
	s_nop 1
	ds_read_b128 v[64:67], v149 offset:16384
	ds_read_b128 v[72:75], v149 offset:17408
	ds_read_b128 v[80:83], v149 offset:18432
	ds_read_b128 v[88:91], v149 offset:19456
	ds_read_b128 v[194:197], v149 offset:20480
	ds_read_b128 v[198:201], v149 offset:21504
	ds_read_b128 v[202:205], v149 offset:22528
	ds_read_b128 v[206:209], v149 offset:23552
	s_waitcnt vmcnt(4)
	s_barrier
	s_waitcnt lgkmcnt(0)
	s_setprio 1
	s_waitcnt lgkmcnt(0)
	v_mfma_f32_16x16x32_bf16 v[60:63], v[152:155], v[64:67], v[60:63]
	v_mfma_f32_16x16x32_bf16 v[52:55], v[152:155], v[80:83], v[52:55]
	v_mfma_f32_16x16x32_bf16 v[44:47], v[152:155], v[194:197], v[44:47]
	v_mfma_f32_16x16x32_bf16 v[36:39], v[152:155], v[202:205], v[36:39]
	v_mfma_f32_16x16x32_bf16 v[60:63], v[164:167], v[72:75], v[60:63]
	v_mfma_f32_16x16x32_bf16 v[56:59], v[168:171], v[64:67], v[56:59]
	v_mfma_f32_16x16x32_bf16 v[52:55], v[164:167], v[88:91], v[52:55]
	v_mfma_f32_16x16x32_bf16 v[48:51], v[168:171], v[80:83], v[48:51]
	v_mfma_f32_16x16x32_bf16 v[44:47], v[164:167], v[198:201], v[44:47]
	v_mfma_f32_16x16x32_bf16 v[40:43], v[168:171], v[194:197], v[40:43]
	v_mfma_f32_16x16x32_bf16 v[36:39], v[164:167], v[206:209], v[36:39]
	v_mfma_f32_16x16x32_bf16 v[32:35], v[168:171], v[202:205], v[32:35]
	v_mfma_f32_16x16x32_bf16 v[238:241], v[172:175], v[72:75], v[56:59]
	v_mfma_f32_16x16x32_bf16 v[246:249], v[172:175], v[88:91], v[48:51]
	v_mfma_f32_16x16x32_bf16 v[234:237], v[172:175], v[198:201], v[40:43]
	v_mfma_f32_16x16x32_bf16 v[152:155], v[172:175], v[206:209], v[32:35]
	s_setprio 0
	s_setprio 1
	v_mfma_f32_16x16x32_bf16 v[28:31], v[96:99], v[64:67], v[28:31]
	v_mfma_f32_16x16x32_bf16 v[20:23], v[96:99], v[80:83], v[20:23]
	v_mfma_f32_16x16x32_bf16 v[12:15], v[96:99], v[194:197], v[12:15]
	v_mfma_f32_16x16x32_bf16 v[4:7], v[96:99], v[202:205], v[4:7]
	v_mfma_f32_16x16x32_bf16 v[28:31], v[104:107], v[72:75], v[28:31]
	v_mfma_f32_16x16x32_bf16 v[24:27], v[112:115], v[64:67], v[24:27]
	v_mfma_f32_16x16x32_bf16 v[20:23], v[104:107], v[88:91], v[20:23]
	v_mfma_f32_16x16x32_bf16 v[16:19], v[112:115], v[80:83], v[16:19]
	v_mfma_f32_16x16x32_bf16 v[12:15], v[104:107], v[198:201], v[12:15]
	v_mfma_f32_16x16x32_bf16 v[8:11], v[112:115], v[194:197], v[8:11]
	v_mfma_f32_16x16x32_bf16 v[4:7], v[104:107], v[206:209], v[4:7]
	v_mfma_f32_16x16x32_bf16 v[0:3], v[112:115], v[202:205], v[0:3]
	v_mfma_f32_16x16x32_bf16 v[162:165], v[120:123], v[72:75], v[24:27]
	v_mfma_f32_16x16x32_bf16 v[166:169], v[120:123], v[88:91], v[16:19]
	s_setprio 2
	s_barrier
	v_mfma_f32_16x16x32_bf16 v[170:173], v[120:123], v[198:201], v[8:11]
	v_mfma_f32_16x16x32_bf16 v[194:197], v[120:123], v[206:209], v[0:3]
	s_setprio 0
	s_nop 1
	ds_read_b128 v[0:3], v150 offset:32768
	ds_read_b128 v[8:11], v150 offset:33792
	ds_read_b128 v[16:19], v150 offset:34816
	ds_read_b128 v[24:27], v150 offset:35840
	ds_read_b128 v[32:35], v149 offset:32768
	ds_read_b128 v[40:43], v149 offset:33792
	ds_read_b128 v[48:51], v149 offset:34816
	ds_read_b128 v[56:59], v149 offset:35840
	ds_read_b128 v[64:67], v149 offset:36864
	ds_read_b128 v[198:201], v149 offset:37888
	ds_read_b128 v[202:205], v149 offset:38912
	ds_read_b128 v[206:209], v149 offset:39936
	s_waitcnt vmcnt(2)
	s_barrier
; #define LDA(dst, b, h) for (int m = 0; m < 4; ++m) for (int k = 0; k < 2; ++k) \
;     dst[m][k] = *reinterpret_cast<const bf16x8*>(a_rd + ((b) * 2 + (h)) * (HT * 2) + m * 2048 + k * 1024)
; #define LDB(dst, b, h) for (int n = 0; n < 2; ++n) for (int k = 0; k < 2; ++k) \
;     dst[n][k] = *reinterpret_cast<const bf16x8*>(b_rd + ((b) * 2 + (h)) * (HT * 2) + n * 2048 + k * 1024)
; #define MMA(ai, bj, At_, Bt_) do { __builtin_amdgcn_s_setprio(1); \
;     for (int m = 0; m < 4; ++m) for (int n = 0; n < 2; ++n) for (int k = 0; k < 2; ++k) \
;       acc[ai][bj][m][n] = __builtin_amdgcn_mfma_f32_16x16x32_bf16(Bt_[n][k], At_[m][k], acc[ai][bj][m][n], 0, 0, 0); \
;     __builtin_amdgcn_s_setprio(0); } while (0)
; #define WAIT_V(n) asm volatile("s_waitcnt vmcnt(" #n ")" ::: "memory")
; #define WAIT_L(n) asm volatile("s_waitcnt lgkmcnt(" #n ")" ::: "memory")
; #define BAR __builtin_amdgcn_s_barrier()
;     ...
;   { LDB(B0, 1, 0); LDA(At, 1, 0); WAIT_V(2); BAR; WAIT_L(0); MMA(0, 0, At, B0); BAR;
;     LDB(B1, 1, 1); WAIT_V(0); BAR; WAIT_L(0); MMA(0, 1, At, B1); BAR;
;     LDA(At, 1, 1); BAR; WAIT_L(0); MMA(1, 0, At, B0); MMA(1, 1, At, B1); BAR; }
;   if (wr == 0) BAR;
	s_waitcnt lgkmcnt(0)
	s_setprio 1
	s_waitcnt lgkmcnt(0)
	v_mfma_f32_16x16x32_bf16 v[72:75], v[0:3], v[32:35], v[124:127]
	v_mfma_f32_16x16x32_bf16 v[120:123], v[8:11], v[40:43], v[72:75]
	v_mfma_f32_16x16x32_bf16 v[72:75], v[16:19], v[32:35], v[210:213]
	v_mfma_f32_16x16x32_bf16 v[124:127], v[24:27], v[40:43], v[72:75]
	v_mfma_f32_16x16x32_bf16 v[72:75], v[0:3], v[48:51], v[116:119]
	v_mfma_f32_16x16x32_bf16 v[112:115], v[8:11], v[56:59], v[72:75]
	v_mfma_f32_16x16x32_bf16 v[72:75], v[16:19], v[48:51], v[214:217]
	v_mfma_f32_16x16x32_bf16 v[116:119], v[24:27], v[56:59], v[72:75]
	v_mfma_f32_16x16x32_bf16 v[72:75], v[0:3], v[64:67], v[108:111]
	v_mfma_f32_16x16x32_bf16 v[104:107], v[8:11], v[198:201], v[72:75]
	v_mfma_f32_16x16x32_bf16 v[72:75], v[16:19], v[64:67], v[218:221]
	v_mfma_f32_16x16x32_bf16 v[108:111], v[24:27], v[198:201], v[72:75]
	v_mfma_f32_16x16x32_bf16 v[72:75], v[0:3], v[202:205], v[100:103]
	v_mfma_f32_16x16x32_bf16 v[96:99], v[8:11], v[206:209], v[72:75]
	s_setprio 2
	s_barrier
	v_mfma_f32_16x16x32_bf16 v[72:75], v[16:19], v[202:205], v[230:233]
	v_mfma_f32_16x16x32_bf16 v[100:103], v[24:27], v[206:209], v[72:75]
	s_setprio 0
	ds_read_b128 v[210:213], v150 offset:49152
	ds_read_b128 v[214:217], v150 offset:50176
	ds_read_b128 v[218:221], v150 offset:51200
	ds_read_b128 v[230:233], v150 offset:52224
	s_waitcnt vmcnt(0)
	s_barrier
	s_waitcnt lgkmcnt(0)
	s_setprio 1
	s_waitcnt lgkmcnt(0)
	v_mfma_f32_16x16x32_bf16 v[72:75], v[210:213], v[32:35], v[92:95]
	v_mfma_f32_16x16x32_bf16 v[32:35], v[218:221], v[32:35], v[176:179]
	v_mfma_f32_16x16x32_bf16 v[92:95], v[230:233], v[40:43], v[32:35]
	v_mfma_f32_16x16x32_bf16 v[32:35], v[210:213], v[48:51], v[84:87]
	v_mfma_f32_16x16x32_bf16 v[80:83], v[214:217], v[56:59], v[32:35]
	v_mfma_f32_16x16x32_bf16 v[32:35], v[218:221], v[48:51], v[182:185]
	v_mfma_f32_16x16x32_bf16 v[84:87], v[230:233], v[56:59], v[32:35]
	v_mfma_f32_16x16x32_bf16 v[32:35], v[210:213], v[64:67], v[76:79]
	v_mfma_f32_16x16x32_bf16 v[88:91], v[214:217], v[40:43], v[72:75]
	v_mfma_f32_16x16x32_bf16 v[72:75], v[214:217], v[198:201], v[32:35]
	v_mfma_f32_16x16x32_bf16 v[32:35], v[218:221], v[64:67], v[186:189]
	v_mfma_f32_16x16x32_bf16 v[76:79], v[230:233], v[198:201], v[32:35]
	v_mfma_f32_16x16x32_bf16 v[32:35], v[210:213], v[202:205], v[68:71]
	v_mfma_f32_16x16x32_bf16 v[64:67], v[214:217], v[206:209], v[32:35]
	s_setprio 2
	s_barrier
	v_mfma_f32_16x16x32_bf16 v[32:35], v[218:221], v[202:205], v[190:193]
	v_mfma_f32_16x16x32_bf16 v[68:71], v[230:233], v[206:209], v[32:35]
	s_setprio 0
	ds_read_b128 v[174:177], v149 offset:49152
	ds_read_b128 v[182:185], v149 offset:50176
	ds_read_b128 v[186:189], v149 offset:51200
	ds_read_b128 v[190:193], v149 offset:52224
	ds_read_b128 v[198:201], v149 offset:53248
	ds_read_b128 v[202:205], v149 offset:54272
	ds_read_b128 v[206:209], v149 offset:55296
	ds_read_b128 v[148:151], v149 offset:56320
	s_barrier
	s_waitcnt lgkmcnt(0)
	s_setprio 1
	s_waitcnt lgkmcnt(0)
	v_mfma_f32_16x16x32_bf16 v[32:35], v[0:3], v[174:177], v[60:63]
	v_mfma_f32_16x16x32_bf16 v[56:59], v[8:11], v[182:185], v[32:35]
	v_mfma_f32_16x16x32_bf16 v[32:35], v[16:19], v[174:177], v[238:241]
	v_mfma_f32_16x16x32_bf16 v[60:63], v[24:27], v[182:185], v[32:35]
	v_mfma_f32_16x16x32_bf16 v[32:35], v[0:3], v[186:189], v[52:55]
	v_mfma_f32_16x16x32_bf16 v[48:51], v[8:11], v[190:193], v[32:35]
	v_mfma_f32_16x16x32_bf16 v[32:35], v[16:19], v[186:189], v[246:249]
	v_mfma_f32_16x16x32_bf16 v[52:55], v[24:27], v[190:193], v[32:35]
	v_mfma_f32_16x16x32_bf16 v[32:35], v[0:3], v[198:201], v[44:47]
	v_mfma_f32_16x16x32_bf16 v[40:43], v[8:11], v[202:205], v[32:35]
	v_mfma_f32_16x16x32_bf16 v[32:35], v[16:19], v[198:201], v[234:237]
	v_mfma_f32_16x16x32_bf16 v[0:3], v[0:3], v[206:209], v[36:39]
	v_mfma_f32_16x16x32_bf16 v[44:47], v[24:27], v[202:205], v[32:35]
	v_mfma_f32_16x16x32_bf16 v[32:35], v[8:11], v[148:151], v[0:3]
	v_mfma_f32_16x16x32_bf16 v[0:3], v[16:19], v[206:209], v[152:155]
	v_mfma_f32_16x16x32_bf16 v[36:39], v[24:27], v[148:151], v[0:3]
	s_setprio 0
	s_setprio 1
	v_mfma_f32_16x16x32_bf16 v[0:3], v[210:213], v[174:177], v[28:31]
	v_mfma_f32_16x16x32_bf16 v[24:27], v[214:217], v[182:185], v[0:3]
	v_mfma_f32_16x16x32_bf16 v[0:3], v[218:221], v[174:177], v[162:165]
	v_mfma_f32_16x16x32_bf16 v[28:31], v[230:233], v[182:185], v[0:3]
	v_mfma_f32_16x16x32_bf16 v[0:3], v[210:213], v[186:189], v[20:23]
	v_mfma_f32_16x16x32_bf16 v[16:19], v[214:217], v[190:193], v[0:3]
	v_mfma_f32_16x16x32_bf16 v[0:3], v[218:221], v[186:189], v[166:169]
	v_mfma_f32_16x16x32_bf16 v[20:23], v[230:233], v[190:193], v[0:3]
	v_mfma_f32_16x16x32_bf16 v[0:3], v[210:213], v[198:201], v[12:15]
	v_mfma_f32_16x16x32_bf16 v[8:11], v[214:217], v[202:205], v[0:3]
	v_mfma_f32_16x16x32_bf16 v[0:3], v[218:221], v[198:201], v[170:173]
	v_mfma_f32_16x16x32_bf16 v[12:15], v[230:233], v[202:205], v[0:3]
	v_mfma_f32_16x16x32_bf16 v[0:3], v[210:213], v[206:209], v[4:7]
	v_mfma_f32_16x16x32_bf16 v[4:7], v[218:221], v[206:209], v[194:197]
	s_setprio 2
	s_barrier
	v_mfma_f32_16x16x32_bf16 v[0:3], v[214:217], v[148:151], v[0:3]
	v_mfma_f32_16x16x32_bf16 v[4:7], v[230:233], v[148:151], v[4:7]
	s_setprio 0
	v_cmp_gt_u32_e32 vcc, s60, v144
	s_and_saveexec_b64 s[18:19], vcc
	s_cbranch_execz .LBB0_2569
	s_barrier

; #define STAGE_A(P, br, kt) do { const char* _base = (const char*)(((kt) < G.ksplit ? G.A1 : A2m) + (long)(br) * G.lda + (long)(kt) * BK); \
;     __builtin_amdgcn_global_load_lds((const unsigned*)(_base + aoff0), (unsigned*)((char*)(P) + sb0), 16, 0, 0); \
;     __builtin_amdgcn_global_load_lds((const unsigned*)(_base + aoff1), (unsigned*)((char*)(P) + sb1), 16, 0, 0); } while (0)
; #define STAGE_B(P, br, kt) do { const char* _base = (const char*)(G.Bt + (long)(br) * G.ldb + (long)(kt) * BK); \
;     __builtin_amdgcn_global_load_lds((const unsigned*)(_base + boff0), (unsigned*)((char*)(P) + sb0), 16, 0, 0); \
;     __builtin_amdgcn_global_load_lds((const unsigned*)(_base + boff1), (unsigned*)((char*)(P) + sb1), 16, 0, 0); } while (0)
; #define WAIT_V(n) asm volatile("s_waitcnt vmcnt(" #n ")" ::: "memory")
; #define BAR __builtin_amdgcn_s_barrier()
;     ...
;   const int K = G.K;
;   const u16* A2m = G.A2 - (long)G.ksplit * BK;
;   int t1 = otid();
;   const int wid = t1 >> 6, lane = t1 & 63, wr = wid >> 2, wc = wid & 3, fr = lane & 15, fq = lane >> 4;
;   const int sb0 = t1 * 16, sb1 = sb0 + 8192;
;   const int swz_ = lds_byte(fr, fq * 8);
;   const char* a_rd = shmc + wr * 8192 + swz_;
;   const char* b_rd = shmc + 4 * (HT * 2) + wc * 4096 + swz_;
;   int r0_, c0_, r1_, c1_; stage_rc(sb0, r0_, c0_); stage_rc(sb1, r1_, c1_);
;   const unsigned aoff0 = (unsigned)(r0_ * G.lda + c0_) * 2u, aoff1 = (unsigned)(r1_ * G.lda + c1_) * 2u;
;   const unsigned boff0 = (unsigned)(r0_ * G.ldb + c0_) * 2u, boff1 = (unsigned)(r1_ * G.ldb + c1_) * 2u;
;   f32x4 acc[2][2][4][2] = {};
;   bf16x8 At[4][2], B0[2][2], B1[2][2];
;   const int nt = K / BK;
;   if (EPI == EPI_RESID || first) {
;     STAGE_B(SB(0, 0), bcol, 0); STAGE_A(SA(0, 0), brow, 0);
;     STAGE_B(SB(0, 1), bcol + HALF, 0); STAGE_A(SA(0, 1), brow + HALF, 0);
;   }
;   if (wr == 1) BAR;
;   WAIT_V(0); BAR;
;   STAGE_B(SB(1, 0), bcol, 1); STAGE_A(SA(1, 0), brow, 1); STAGE_B(SB(1, 1), bcol + HALF, 1);
;   WAIT_V(6); BAR;
.LBB0_2621:
	s_or_b64 exec, exec, s[12:13]
	v_readlane_b32 s12, v253, 46
	v_and_b32_e32 v18, 15, v142
	s_waitcnt vmcnt(0)
	v_lshlrev_b32_e32 v20, 2, v142
	v_add_u32_e32 v151, s12, v9
	v_and_b32_e32 v19, 48, v142
	v_lshlrev_b32_e32 v18, 6, v18
	v_and_b32_e32 v20, 32, v20
	s_mov_b64 s[22:23], 0x80
	v_readfirstlane_b32 s12, v151
	v_add_u32_e32 v152, 0x2000, v151
	v_bitop3_b32 v18, v18, v20, v19 bitop3:0x36
	v_lshlrev_b32_e32 v19, 6, v142
	v_lshl_add_u64 v[0:1], v[0:1], 0, s[22:23]
	s_mov_b32 m0, s12
	v_readfirstlane_b32 s12, v152
	v_add_u32_e32 v153, 0x8000, v145
	v_and_b32_e32 v19, 0x3000, v19
	s_waitcnt vmcnt(0)
	s_barrier
	global_load_lds_dwordx4 v[0:1], off
	v_lshl_add_u64 v[0:1], v[2:3], 0, s[22:23]
	s_mov_b32 m0, s12
	v_readfirstlane_b32 s12, v153
	v_add_u32_e32 v154, 0xa000, v145
	v_add_u32_e32 v19, s16, v19
	global_load_lds_dwordx4 v[0:1], off
	v_lshl_add_u64 v[0:1], v[4:5], 0, s[22:23]
	s_mov_b32 m0, s12
	v_readfirstlane_b32 s12, v154
	v_readlane_b32 s16, v253, 47
	global_load_lds_dwordx4 v[0:1], off
	s_mov_b32 m0, s12
	s_add_u32 s12, s17, 0x160080
	v_add_u32_e32 v155, s16, v9
	v_lshl_add_u64 v[0:1], v[6:7], 0, s[22:23]
	s_addc_u32 s13, s38, 0
	v_readfirstlane_b32 s16, v155
	global_load_lds_dwordx4 v[0:1], off
	v_lshl_add_u64 v[0:1], s[12:13], 0, v[180:181]
	s_mov_b32 m0, s16
	v_add_u32_e32 v156, 0x2000, v155
	global_load_lds_dwordx4 v[0:1], off
	v_lshl_add_u64 v[0:1], s[12:13], 0, v[128:129]
	v_readfirstlane_b32 s12, v156
	s_mov_b32 m0, s12
	s_mov_b32 s16, 0x16000
	global_load_lds_dwordx4 v[0:1], off
	v_lshrrev_b32_e32 v1, 1, v8
	v_mul_lo_u32 v0, v11, s18
	v_lshrrev_b32_e32 v3, 1, v13
	v_mul_lo_u32 v2, v15, s18
	v_mad_u64_u32 v[0:1], s[12:13], v1, s16, v[0:1]
	v_mad_u64_u32 v[2:3], s[12:13], v3, s16, v[2:3]
	v_or_b32_e32 v0, v0, v10
	v_or_b32_e32 v2, v2, v14
	v_add_lshl_u32 v0, v0, v12, 1
	v_mov_b32_e32 v1, v181
	v_add_lshl_u32 v2, v2, v16, 1
	v_mov_b32_e32 v3, v181
	v_lshl_add_u64 v[130:131], s[8:9], 0, v[0:1]
	v_lshl_add_u64 v[132:133], s[8:9], 0, v[2:3]
	s_add_u32 s8, s48, s15
	s_waitcnt vmcnt(6)
	s_addc_u32 s9, s49, s14
	v_lshl_add_u32 v17, v17, 13, 32
	v_lshl_add_u64 v[134:135], s[8:9], 0, v[0:1]
	v_lshl_add_u64 v[138:139], s[10:11], 0, v[0:1]
	v_mov_b32_e32 v0, 0
	v_lshl_add_u64 v[136:137], s[8:9], 0, v[2:3]
	v_lshl_add_u64 v[140:141], s[10:11], 0, v[2:3]
	s_mov_b32 s8, -2
	v_add_u32_e32 v147, v19, v18
	v_add_u32_e32 v144, v17, v18
	v_mov_b32_e32 v1, v0
	v_mov_b32_e32 v2, v0
	v_mov_b32_e32 v3, v0
	v_mov_b32_e32 v4, v0
	v_mov_b32_e32 v5, v0
	v_mov_b32_e32 v6, v0
	v_mov_b32_e32 v7, v0
	v_mov_b32_e32 v8, v0
	v_mov_b32_e32 v9, v0
	v_mov_b32_e32 v10, v0
	v_mov_b32_e32 v11, v0
	v_mov_b32_e32 v12, v0
	v_mov_b32_e32 v13, v0
	v_mov_b32_e32 v14, v0
	v_mov_b32_e32 v15, v0
	v_mov_b32_e32 v16, v0
	v_mov_b32_e32 v17, v0
	v_mov_b32_e32 v18, v0
	v_mov_b32_e32 v19, v0
	v_mov_b32_e32 v20, v0
	v_mov_b32_e32 v21, v0
	v_mov_b32_e32 v22, v0
	v_mov_b32_e32 v23, v0
	v_mov_b32_e32 v24, v0
	v_mov_b32_e32 v25, v0
	v_mov_b32_e32 v26, v0
	v_mov_b32_e32 v27, v0
	v_mov_b32_e32 v28, v0
	v_mov_b32_e32 v29, v0
	v_mov_b32_e32 v30, v0
	v_mov_b32_e32 v31, v0
	v_mov_b32_e32 v32, v0
	v_mov_b32_e32 v33, v0
	v_mov_b32_e32 v34, v0
	v_mov_b32_e32 v35, v0
	v_mov_b32_e32 v36, v0
	v_mov_b32_e32 v37, v0
	v_mov_b32_e32 v38, v0
	v_mov_b32_e32 v39, v0
	v_mov_b32_e32 v40, v0
	v_mov_b32_e32 v41, v0
	v_mov_b32_e32 v42, v0
	v_mov_b32_e32 v43, v0
	v_mov_b32_e32 v44, v0
	v_mov_b32_e32 v45, v0
	v_mov_b32_e32 v46, v0
	v_mov_b32_e32 v47, v0
	v_mov_b32_e32 v48, v0
	v_mov_b32_e32 v49, v0
	v_mov_b32_e32 v50, v0
	v_mov_b32_e32 v51, v0
	v_mov_b32_e32 v52, v0
	v_mov_b32_e32 v53, v0
	v_mov_b32_e32 v54, v0
	v_mov_b32_e32 v55, v0
	v_mov_b32_e32 v56, v0
	v_mov_b32_e32 v57, v0
	v_mov_b32_e32 v58, v0
	v_mov_b32_e32 v59, v0
	v_mov_b32_e32 v60, v0
	v_mov_b32_e32 v61, v0
	v_mov_b32_e32 v62, v0
	v_mov_b32_e32 v63, v0
	v_mov_b32_e32 v64, v0
	v_mov_b32_e32 v65, v0
	v_mov_b32_e32 v66, v0
	v_mov_b32_e32 v67, v0
	v_mov_b32_e32 v68, v0
	v_mov_b32_e32 v69, v0
	v_mov_b32_e32 v70, v0
	v_mov_b32_e32 v71, v0
	v_mov_b32_e32 v72, v0
	v_mov_b32_e32 v73, v0
	v_mov_b32_e32 v74, v0
	v_mov_b32_e32 v75, v0
	v_mov_b32_e32 v76, v0
	v_mov_b32_e32 v77, v0
	v_mov_b32_e32 v78, v0
	v_mov_b32_e32 v79, v0
	v_mov_b32_e32 v80, v0
	v_mov_b32_e32 v81, v0
	v_mov_b32_e32 v82, v0
	v_mov_b32_e32 v83, v0
	v_mov_b32_e32 v84, v0
	v_mov_b32_e32 v85, v0
	v_mov_b32_e32 v86, v0
	v_mov_b32_e32 v87, v0
	v_mov_b32_e32 v88, v0
	v_mov_b32_e32 v89, v0
	v_mov_b32_e32 v90, v0
	v_mov_b32_e32 v91, v0
	v_mov_b32_e32 v92, v0
	v_mov_b32_e32 v93, v0
	v_mov_b32_e32 v94, v0
	v_mov_b32_e32 v95, v0
	v_mov_b32_e32 v96, v0
	v_mov_b32_e32 v97, v0
	v_mov_b32_e32 v98, v0
	v_mov_b32_e32 v99, v0
	v_mov_b32_e32 v100, v0
	v_mov_b32_e32 v101, v0
	v_mov_b32_e32 v102, v0
	v_mov_b32_e32 v103, v0
	v_mov_b32_e32 v104, v0
	v_mov_b32_e32 v105, v0
	v_mov_b32_e32 v106, v0
	v_mov_b32_e32 v107, v0
	v_mov_b32_e32 v108, v0
	v_mov_b32_e32 v109, v0
	v_mov_b32_e32 v110, v0
	v_mov_b32_e32 v111, v0
	v_mov_b32_e32 v112, v0
	v_mov_b32_e32 v113, v0
	v_mov_b32_e32 v114, v0
	v_mov_b32_e32 v115, v0
	v_mov_b32_e32 v116, v0
	v_mov_b32_e32 v117, v0
	v_mov_b32_e32 v118, v0
	v_mov_b32_e32 v119, v0
	v_mov_b32_e32 v120, v0
	v_mov_b32_e32 v121, v0
	v_mov_b32_e32 v122, v0
	v_mov_b32_e32 v123, v0
	v_mov_b32_e32 v124, v0
	v_mov_b32_e32 v125, v0
	v_mov_b32_e32 v126, v0
	v_mov_b32_e32 v127, v0
	s_barrier
	ds_read_b128 v[160:163], v147
	ds_read_b128 v[164:167], v147 offset:1024
	ds_read_b128 v[168:171], v147 offset:2048
	ds_read_b128 v[172:175], v147 offset:3072
; #define STAGE_A(P, br, kt) do { const char* _base = (const char*)(((kt) < G.ksplit ? G.A1 : A2m) + (long)(br) * G.lda + (long)(kt) * BK); \
;     __builtin_amdgcn_global_load_lds((const unsigned*)(_base + aoff0), (unsigned*)((char*)(P) + sb0), 16, 0, 0); \
;     __builtin_amdgcn_global_load_lds((const unsigned*)(_base + aoff1), (unsigned*)((char*)(P) + sb1), 16, 0, 0); } while (0)
; #define STAGE_B(P, br, kt) do { const char* _base = (const char*)(G.Bt + (long)(br) * G.ldb + (long)(kt) * BK); \
;     __builtin_amdgcn_global_load_lds((const unsigned*)(_base + boff0), (unsigned*)((char*)(P) + sb0), 16, 0, 0); \
;     __builtin_amdgcn_global_load_lds((const unsigned*)(_base + boff1), (unsigned*)((char*)(P) + sb1), 16, 0, 0); } while (0)
; #define LDA(dst, b, h) for (int m = 0; m < 4; ++m) for (int k = 0; k < 2; ++k) \
;     dst[m][k] = *reinterpret_cast<const bf16x8*>(a_rd + ((b) * 2 + (h)) * (HT * 2) + m * 2048 + k * 1024)
; #define LDB(dst, b, h) for (int n = 0; n < 2; ++n) for (int k = 0; k < 2; ++k) \
;     dst[n][k] = *reinterpret_cast<const bf16x8*>(b_rd + ((b) * 2 + (h)) * (HT * 2) + n * 2048 + k * 1024)
; #define MMA(ai, bj, At_, Bt_) do { __builtin_amdgcn_s_setprio(1); \
;     for (int m = 0; m < 4; ++m) for (int n = 0; n < 2; ++n) for (int k = 0; k < 2; ++k) \
;       acc[ai][bj][m][n] = __builtin_amdgcn_mfma_f32_16x16x32_bf16(Bt_[n][k], At_[m][k], acc[ai][bj][m][n], 0, 0, 0); \
;     __builtin_amdgcn_s_setprio(0); } while (0)
; #define WAIT_L(n) asm volatile("s_waitcnt lgkmcnt(" #n ")" ::: "memory")
; #define BAR __builtin_amdgcn_s_barrier()
; #define SCHED __builtin_amdgcn_sched_barrier(0)
;     ...
;   for (int t = 0; t < nt - 2; t += 2) {
;     LDB(B0, 0, 0); SCHED; LDA(At, 0, 0); STAGE_A(SA(1, 1), brow + HALF, t + 1);
;     WAIT_L(8); BAR; WAIT_L(0); MMA(0, 0, At, B0); BAR; SCHED;
;     LDB(B1, 0, 1); STAGE_B(SB(0, 0), bcol, t + 2);
;     BAR; WAIT_L(0); MMA(0, 1, At, B1); BAR;
;     LDA(At, 0, 1); STAGE_A(SA(0, 0), brow, t + 2);
;     BAR; WAIT_L(0); MMA(1, 0, At, B0); BAR; SCHED;
.LBB0_2622:
	v_add_u32_e32 v157, 0xc000, v145
	v_lshl_add_u64 v[222:223], s[86:87], 0, v[134:135]
	v_readfirstlane_b32 s9, v157
	v_lshl_add_u64 v[158:159], v[222:223], 0, s[72:73]
	s_mov_b32 m0, s9
	ds_read_b128 v[176:179], v144
	ds_read_b128 v[182:185], v144 offset:1024
	ds_read_b128 v[186:189], v144 offset:2048
	ds_read_b128 v[190:193], v144 offset:3072
	ds_read_b128 v[194:197], v144 offset:4096
	ds_read_b128 v[198:201], v144 offset:5120
	ds_read_b128 v[202:205], v144 offset:6144
	ds_read_b128 v[206:209], v144 offset:7168
	global_load_lds_dwordx4 v[158:159], off
	v_add_u32_e32 v158, 0xe000, v145
	v_lshl_add_u64 v[226:227], s[86:87], 0, v[136:137]
	v_readfirstlane_b32 s9, v158
	v_lshl_add_u64 v[210:211], v[226:227], 0, s[72:73]
	s_mov_b32 m0, s9
	s_nop 0
	global_load_lds_dwordx4 v[210:211], off
	s_waitcnt lgkmcnt(8)
	s_barrier
	s_waitcnt lgkmcnt(0)
	s_setprio 1
	s_waitcnt lgkmcnt(0)
	v_mfma_f32_16x16x32_bf16 v[124:127], v[160:163], v[176:179], v[124:127]
	v_mfma_f32_16x16x32_bf16 v[120:123], v[168:171], v[176:179], v[120:123]
	v_mfma_f32_16x16x32_bf16 v[116:119], v[160:163], v[186:189], v[116:119]
	v_mfma_f32_16x16x32_bf16 v[112:115], v[168:171], v[186:189], v[112:115]
	v_mfma_f32_16x16x32_bf16 v[108:111], v[160:163], v[194:197], v[108:111]
	v_mfma_f32_16x16x32_bf16 v[104:107], v[168:171], v[194:197], v[104:107]
	v_mfma_f32_16x16x32_bf16 v[100:103], v[160:163], v[202:205], v[100:103]
	v_mfma_f32_16x16x32_bf16 v[96:99], v[168:171], v[202:205], v[96:99]
	v_mfma_f32_16x16x32_bf16 v[124:127], v[164:167], v[182:185], v[124:127]
	v_mfma_f32_16x16x32_bf16 v[120:123], v[172:175], v[182:185], v[120:123]
	v_mfma_f32_16x16x32_bf16 v[116:119], v[164:167], v[190:193], v[116:119]
	v_mfma_f32_16x16x32_bf16 v[112:115], v[172:175], v[190:193], v[112:115]
	v_mfma_f32_16x16x32_bf16 v[108:111], v[164:167], v[198:201], v[108:111]
	v_mfma_f32_16x16x32_bf16 v[104:107], v[172:175], v[198:201], v[104:107]
	s_setprio 2
	s_barrier
	v_mfma_f32_16x16x32_bf16 v[100:103], v[164:167], v[206:209], v[100:103]
	v_mfma_f32_16x16x32_bf16 v[96:99], v[172:175], v[206:209], v[96:99]
	s_setprio 0
	v_lshl_add_u64 v[234:235], s[86:87], 0, v[130:131]
	v_readfirstlane_b32 s9, v143
	v_lshl_add_u64 v[236:237], v[234:235], 0, s[74:75]
	s_mov_b32 m0, s9
	v_add_u32_e32 v159, 0x2000, v143
	ds_read_b128 v[210:213], v147 offset:16384
	ds_read_b128 v[214:217], v147 offset:17408
	ds_read_b128 v[218:221], v147 offset:18432
	ds_read_b128 v[230:233], v147 offset:19456
	global_load_lds_dwordx4 v[236:237], off
	v_lshl_add_u64 v[236:237], s[86:87], 0, v[132:133]
	v_readfirstlane_b32 s9, v159
	v_lshl_add_u64 v[238:239], v[236:237], 0, s[74:75]
	s_mov_b32 m0, s9
	s_nop 0
	global_load_lds_dwordx4 v[238:239], off
	s_barrier
	s_waitcnt lgkmcnt(0)
	s_setprio 1
	s_waitcnt lgkmcnt(0)
	v_mfma_f32_16x16x32_bf16 v[92:95], v[210:213], v[176:179], v[92:95]
	v_mfma_f32_16x16x32_bf16 v[88:91], v[218:221], v[176:179], v[88:91]
	v_mfma_f32_16x16x32_bf16 v[84:87], v[210:213], v[186:189], v[84:87]
	v_mfma_f32_16x16x32_bf16 v[80:83], v[218:221], v[186:189], v[80:83]
	v_mfma_f32_16x16x32_bf16 v[76:79], v[210:213], v[194:197], v[76:79]
	v_mfma_f32_16x16x32_bf16 v[72:75], v[218:221], v[194:197], v[72:75]
	v_mfma_f32_16x16x32_bf16 v[68:71], v[210:213], v[202:205], v[68:71]
	v_mfma_f32_16x16x32_bf16 v[64:67], v[218:221], v[202:205], v[64:67]
	v_mfma_f32_16x16x32_bf16 v[92:95], v[214:217], v[182:185], v[92:95]
	v_mfma_f32_16x16x32_bf16 v[88:91], v[230:233], v[182:185], v[88:91]
	v_mfma_f32_16x16x32_bf16 v[84:87], v[214:217], v[190:193], v[84:87]
	v_mfma_f32_16x16x32_bf16 v[80:83], v[230:233], v[190:193], v[80:83]
	v_mfma_f32_16x16x32_bf16 v[76:79], v[214:217], v[198:201], v[76:79]
	v_mfma_f32_16x16x32_bf16 v[72:75], v[230:233], v[198:201], v[72:75]
	s_setprio 2
	s_barrier
	v_mfma_f32_16x16x32_bf16 v[68:71], v[214:217], v[206:209], v[68:71]
	v_mfma_f32_16x16x32_bf16 v[64:67], v[230:233], v[206:209], v[64:67]
	s_setprio 0
	v_readfirstlane_b32 s9, v145
	v_lshl_add_u64 v[238:239], v[222:223], 0, s[76:77]
	s_mov_b32 m0, s9
	v_readfirstlane_b32 s9, v146
	ds_read_b128 v[176:179], v144 offset:16384
	ds_read_b128 v[182:185], v144 offset:17408
	ds_read_b128 v[186:189], v144 offset:18432
	ds_read_b128 v[190:193], v144 offset:19456
	ds_read_b128 v[194:197], v144 offset:20480
	ds_read_b128 v[198:201], v144 offset:21504
	ds_read_b128 v[202:205], v144 offset:22528
	ds_read_b128 v[206:209], v144 offset:23552
	global_load_lds_dwordx4 v[238:239], off
	v_lshl_add_u64 v[238:239], v[226:227], 0, s[76:77]
	s_mov_b32 m0, s9
	s_nop 0
	global_load_lds_dwordx4 v[238:239], off
	s_waitcnt vmcnt(10)
	s_barrier
	s_waitcnt lgkmcnt(0)
	s_setprio 1
	s_waitcnt lgkmcnt(0)
	v_mfma_f32_16x16x32_bf16 v[60:63], v[160:163], v[176:179], v[60:63]
	v_mfma_f32_16x16x32_bf16 v[56:59], v[168:171], v[176:179], v[56:59]
	v_mfma_f32_16x16x32_bf16 v[52:55], v[160:163], v[186:189], v[52:55]
	v_mfma_f32_16x16x32_bf16 v[48:51], v[168:171], v[186:189], v[48:51]
	v_mfma_f32_16x16x32_bf16 v[44:47], v[160:163], v[194:197], v[44:47]
	v_mfma_f32_16x16x32_bf16 v[40:43], v[168:171], v[194:197], v[40:43]
	v_mfma_f32_16x16x32_bf16 v[36:39], v[160:163], v[202:205], v[36:39]
	v_mfma_f32_16x16x32_bf16 v[32:35], v[168:171], v[202:205], v[32:35]
	v_mfma_f32_16x16x32_bf16 v[60:63], v[164:167], v[182:185], v[60:63]
	v_mfma_f32_16x16x32_bf16 v[56:59], v[172:175], v[182:185], v[56:59]
	v_mfma_f32_16x16x32_bf16 v[52:55], v[164:167], v[190:193], v[52:55]
	v_mfma_f32_16x16x32_bf16 v[48:51], v[172:175], v[190:193], v[48:51]
	v_mfma_f32_16x16x32_bf16 v[44:47], v[164:167], v[198:201], v[44:47]
	v_mfma_f32_16x16x32_bf16 v[40:43], v[172:175], v[198:201], v[40:43]
	s_setprio 2
	s_barrier
; #define STAGE_A(P, br, kt) do { const char* _base = (const char*)(((kt) < G.ksplit ? G.A1 : A2m) + (long)(br) * G.lda + (long)(kt) * BK); \
;     __builtin_amdgcn_global_load_lds((const unsigned*)(_base + aoff0), (unsigned*)((char*)(P) + sb0), 16, 0, 0); \
;     __builtin_amdgcn_global_load_lds((const unsigned*)(_base + aoff1), (unsigned*)((char*)(P) + sb1), 16, 0, 0); } while (0)
; #define STAGE_B(P, br, kt) do { const char* _base = (const char*)(G.Bt + (long)(br) * G.ldb + (long)(kt) * BK); \
;     __builtin_amdgcn_global_load_lds((const unsigned*)(_base + boff0), (unsigned*)((char*)(P) + sb0), 16, 0, 0); \
;     __builtin_amdgcn_global_load_lds((const unsigned*)(_base + boff1), (unsigned*)((char*)(P) + sb1), 16, 0, 0); } while (0)
; #define LDA(dst, b, h) for (int m = 0; m < 4; ++m) for (int k = 0; k < 2; ++k) \
;     dst[m][k] = *reinterpret_cast<const bf16x8*>(a_rd + ((b) * 2 + (h)) * (HT * 2) + m * 2048 + k * 1024)
; #define LDB(dst, b, h) for (int n = 0; n < 2; ++n) for (int k = 0; k < 2; ++k) \
;     dst[n][k] = *reinterpret_cast<const bf16x8*>(b_rd + ((b) * 2 + (h)) * (HT * 2) + n * 2048 + k * 1024)
; #define MMA(ai, bj, At_, Bt_) do { __builtin_amdgcn_s_setprio(1); \
;     for (int m = 0; m < 4; ++m) for (int n = 0; n < 2; ++n) for (int k = 0; k < 2; ++k) \
;       acc[ai][bj][m][n] = __builtin_amdgcn_mfma_f32_16x16x32_bf16(Bt_[n][k], At_[m][k], acc[ai][bj][m][n], 0, 0, 0); \
;     __builtin_amdgcn_s_setprio(0); } while (0)
; #define WAIT_V(n) asm volatile("s_waitcnt vmcnt(" #n ")" ::: "memory")
; #define WAIT_L(n) asm volatile("s_waitcnt lgkmcnt(" #n ")" ::: "memory")
; #define BAR __builtin_amdgcn_s_barrier()
; #define SCHED __builtin_amdgcn_sched_barrier(0)
;     ...
;     BAR; WAIT_L(0); MMA(1, 0, At, B0); BAR; SCHED;
;     STAGE_B(SB(0, 1), bcol + HALF, t + 2);
;     WAIT_V(6); BAR; MMA(1, 1, At, B1); BAR;
;     LDB(B0, 1, 0); SCHED; LDA(At, 1, 0); STAGE_A(SA(0, 1), brow + HALF, t + 2);
;     WAIT_L(8); BAR; WAIT_L(0); MMA(0, 0, At, B0); BAR; SCHED;
;     LDB(B1, 1, 1); STAGE_B(SB(1, 0), bcol, t + 3);
;     BAR; WAIT_L(0); MMA(0, 1, At, B1); BAR;
	v_mfma_f32_16x16x32_bf16 v[36:39], v[164:167], v[206:209], v[36:39]
	v_mfma_f32_16x16x32_bf16 v[32:35], v[172:175], v[206:209], v[32:35]
	s_setprio 0
	v_lshl_add_u64 v[238:239], s[86:87], 0, v[138:139]
	v_readfirstlane_b32 s9, v148
	v_add_u32_e32 v159, 0x2000, v148
	v_lshl_add_u64 v[160:161], v[238:239], 0, s[78:79]
	s_mov_b32 m0, s9
	v_lshl_add_u64 v[240:241], s[86:87], 0, v[140:141]
	v_readfirstlane_b32 s9, v159
	global_load_lds_dwordx4 v[160:161], off
	v_lshl_add_u64 v[160:161], v[240:241], 0, s[78:79]
	s_mov_b32 m0, s9
	s_nop 0
	global_load_lds_dwordx4 v[160:161], off
	ds_read_b128 v[160:163], v147 offset:32768
	ds_read_b128 v[164:167], v147 offset:33792
	ds_read_b128 v[168:171], v147 offset:34816
	ds_read_b128 v[172:175], v147 offset:35840
	s_waitcnt vmcnt(6)
	s_barrier
	s_setprio 1
	v_mfma_f32_16x16x32_bf16 v[28:31], v[210:213], v[176:179], v[28:31]
	v_mfma_f32_16x16x32_bf16 v[24:27], v[218:221], v[176:179], v[24:27]
	v_mfma_f32_16x16x32_bf16 v[20:23], v[210:213], v[186:189], v[20:23]
	v_mfma_f32_16x16x32_bf16 v[16:19], v[218:221], v[186:189], v[16:19]
	v_mfma_f32_16x16x32_bf16 v[12:15], v[210:213], v[194:197], v[12:15]
	v_mfma_f32_16x16x32_bf16 v[8:11], v[218:221], v[194:197], v[8:11]
	v_mfma_f32_16x16x32_bf16 v[4:7], v[210:213], v[202:205], v[4:7]
	v_mfma_f32_16x16x32_bf16 v[0:3], v[218:221], v[202:205], v[0:3]
	v_mfma_f32_16x16x32_bf16 v[28:31], v[214:217], v[182:185], v[28:31]
	v_mfma_f32_16x16x32_bf16 v[24:27], v[230:233], v[182:185], v[24:27]
	v_mfma_f32_16x16x32_bf16 v[20:23], v[214:217], v[190:193], v[20:23]
	v_mfma_f32_16x16x32_bf16 v[16:19], v[230:233], v[190:193], v[16:19]
	v_mfma_f32_16x16x32_bf16 v[12:15], v[214:217], v[198:201], v[12:15]
	v_mfma_f32_16x16x32_bf16 v[8:11], v[230:233], v[198:201], v[8:11]
	s_setprio 2
	s_barrier
	v_mfma_f32_16x16x32_bf16 v[4:7], v[214:217], v[206:209], v[4:7]
	v_mfma_f32_16x16x32_bf16 v[0:3], v[230:233], v[206:209], v[0:3]
	s_setprio 0
	v_readfirstlane_b32 s9, v149
	v_lshl_add_u64 v[210:211], v[222:223], 0, s[80:81]
	s_mov_b32 m0, s9
	v_readfirstlane_b32 s9, v150
	ds_read_b128 v[176:179], v144 offset:32768
	ds_read_b128 v[182:185], v144 offset:33792
	ds_read_b128 v[186:189], v144 offset:34816
	ds_read_b128 v[190:193], v144 offset:35840
	ds_read_b128 v[194:197], v144 offset:36864
	ds_read_b128 v[198:201], v144 offset:37888
	ds_read_b128 v[202:205], v144 offset:38912
	ds_read_b128 v[206:209], v144 offset:39936
	global_load_lds_dwordx4 v[210:211], off
	v_lshl_add_u64 v[210:211], v[226:227], 0, s[80:81]
	s_mov_b32 m0, s9
	s_nop 0
	global_load_lds_dwordx4 v[210:211], off
	s_waitcnt lgkmcnt(8)
	s_barrier
	s_waitcnt lgkmcnt(0)
	s_setprio 1
	s_waitcnt lgkmcnt(0)
	v_mfma_f32_16x16x32_bf16 v[124:127], v[160:163], v[176:179], v[124:127]
	v_mfma_f32_16x16x32_bf16 v[120:123], v[168:171], v[176:179], v[120:123]
	v_mfma_f32_16x16x32_bf16 v[116:119], v[160:163], v[186:189], v[116:119]
	v_mfma_f32_16x16x32_bf16 v[112:115], v[168:171], v[186:189], v[112:115]
	v_mfma_f32_16x16x32_bf16 v[108:111], v[160:163], v[194:197], v[108:111]
	v_mfma_f32_16x16x32_bf16 v[104:107], v[168:171], v[194:197], v[104:107]
	v_mfma_f32_16x16x32_bf16 v[100:103], v[160:163], v[202:205], v[100:103]
	v_mfma_f32_16x16x32_bf16 v[96:99], v[168:171], v[202:205], v[96:99]
	v_mfma_f32_16x16x32_bf16 v[124:127], v[164:167], v[182:185], v[124:127]
	v_mfma_f32_16x16x32_bf16 v[120:123], v[172:175], v[182:185], v[120:123]
	v_mfma_f32_16x16x32_bf16 v[116:119], v[164:167], v[190:193], v[116:119]
	v_mfma_f32_16x16x32_bf16 v[112:115], v[172:175], v[190:193], v[112:115]
	v_mfma_f32_16x16x32_bf16 v[108:111], v[164:167], v[198:201], v[108:111]
	v_mfma_f32_16x16x32_bf16 v[104:107], v[172:175], v[198:201], v[104:107]
	s_setprio 2
	s_barrier
	v_mfma_f32_16x16x32_bf16 v[100:103], v[164:167], v[206:209], v[100:103]
	v_mfma_f32_16x16x32_bf16 v[96:99], v[172:175], v[206:209], v[96:99]
	s_setprio 0
	v_readfirstlane_b32 s9, v151
	v_lshl_add_u64 v[234:235], v[234:235], 0, s[82:83]
	s_mov_b32 m0, s9
	v_readfirstlane_b32 s9, v152
	ds_read_b128 v[210:213], v147 offset:49152
	ds_read_b128 v[214:217], v147 offset:50176
	ds_read_b128 v[218:221], v147 offset:51200
	ds_read_b128 v[230:233], v147 offset:52224
	global_load_lds_dwordx4 v[234:235], off
	v_lshl_add_u64 v[234:235], v[236:237], 0, s[82:83]
	s_mov_b32 m0, s9
	s_nop 0
	global_load_lds_dwordx4 v[234:235], off
	s_barrier
	s_waitcnt lgkmcnt(0)
	s_setprio 1
	s_waitcnt lgkmcnt(0)
	v_mfma_f32_16x16x32_bf16 v[92:95], v[210:213], v[176:179], v[92:95]
	v_mfma_f32_16x16x32_bf16 v[88:91], v[218:221], v[176:179], v[88:91]
	v_mfma_f32_16x16x32_bf16 v[84:87], v[210:213], v[186:189], v[84:87]
	v_mfma_f32_16x16x32_bf16 v[80:83], v[218:221], v[186:189], v[80:83]
	v_mfma_f32_16x16x32_bf16 v[76:79], v[210:213], v[194:197], v[76:79]
	v_mfma_f32_16x16x32_bf16 v[72:75], v[218:221], v[194:197], v[72:75]
	v_mfma_f32_16x16x32_bf16 v[68:71], v[210:213], v[202:205], v[68:71]
	v_mfma_f32_16x16x32_bf16 v[64:67], v[218:221], v[202:205], v[64:67]
	v_mfma_f32_16x16x32_bf16 v[92:95], v[214:217], v[182:185], v[92:95]
	v_mfma_f32_16x16x32_bf16 v[88:91], v[230:233], v[182:185], v[88:91]
	v_mfma_f32_16x16x32_bf16 v[84:87], v[214:217], v[190:193], v[84:87]
	v_mfma_f32_16x16x32_bf16 v[80:83], v[230:233], v[190:193], v[80:83]
	v_mfma_f32_16x16x32_bf16 v[76:79], v[214:217], v[198:201], v[76:79]
	v_mfma_f32_16x16x32_bf16 v[72:75], v[230:233], v[198:201], v[72:75]
	s_setprio 2
	s_barrier
; #define STAGE_A(P, br, kt) do { const char* _base = (const char*)(((kt) < G.ksplit ? G.A1 : A2m) + (long)(br) * G.lda + (long)(kt) * BK); \
;     __builtin_amdgcn_global_load_lds((const unsigned*)(_base + aoff0), (unsigned*)((char*)(P) + sb0), 16, 0, 0); \
;     __builtin_amdgcn_global_load_lds((const unsigned*)(_base + aoff1), (unsigned*)((char*)(P) + sb1), 16, 0, 0); } while (0)
; #define STAGE_B(P, br, kt) do { const char* _base = (const char*)(G.Bt + (long)(br) * G.ldb + (long)(kt) * BK); \
;     __builtin_amdgcn_global_load_lds((const unsigned*)(_base + boff0), (unsigned*)((char*)(P) + sb0), 16, 0, 0); \
;     __builtin_amdgcn_global_load_lds((const unsigned*)(_base + boff1), (unsigned*)((char*)(P) + sb1), 16, 0, 0); } while (0)
; #define LDA(dst, b, h) for (int m = 0; m < 4; ++m) for (int k = 0; k < 2; ++k) \
;     dst[m][k] = *reinterpret_cast<const bf16x8*>(a_rd + ((b) * 2 + (h)) * (HT * 2) + m * 2048 + k * 1024)
; #define LDB(dst, b, h) for (int n = 0; n < 2; ++n) for (int k = 0; k < 2; ++k) \
;     dst[n][k] = *reinterpret_cast<const bf16x8*>(b_rd + ((b) * 2 + (h)) * (HT * 2) + n * 2048 + k * 1024)
; #define MMA(ai, bj, At_, Bt_) do { __builtin_amdgcn_s_setprio(1); \
;     for (int m = 0; m < 4; ++m) for (int n = 0; n < 2; ++n) for (int k = 0; k < 2; ++k) \
;       acc[ai][bj][m][n] = __builtin_amdgcn_mfma_f32_16x16x32_bf16(Bt_[n][k], At_[m][k], acc[ai][bj][m][n], 0, 0, 0); \
;     __builtin_amdgcn_s_setprio(0); } while (0)
; #define WAIT_V(n) asm volatile("s_waitcnt vmcnt(" #n ")" ::: "memory")
; #define WAIT_L(n) asm volatile("s_waitcnt lgkmcnt(" #n ")" ::: "memory")
; #define BAR __builtin_amdgcn_s_barrier()
; #define SCHED __builtin_amdgcn_sched_barrier(0)
;     ...
;     LDA(At, 1, 1); STAGE_A(SA(1, 0), brow, t + 3);
;     BAR; WAIT_L(0); MMA(1, 0, At, B0); BAR; SCHED;
;     STAGE_B(SB(1, 1), bcol + HALF, t + 3);
;     WAIT_V(6); BAR; MMA(1, 1, At, B1); BAR;
;   }
;   float ssv[2][4] = {};
;   if constexpr (EPI == EPI_GU || EPI == EPI_EVIN || EPI == EPI_ODIN) {
; #pragma unroll
;     for (int ai = 0; ai < 2; ++ai)
; #pragma unroll
;       for (int m = 0; m < 4; ++m) ssv[ai][m] = G.ssr[brow + ai * HALF + wr * 64 + m * 16 + fr];
;   }
;   { LDB(B0, 0, 0); LDA(At, 0, 0); STAGE_A(SA(1, 1), brow + HALF, nt - 1);
;     BAR; WAIT_L(0); MMA(0, 0, At, B0); BAR;
	v_mfma_f32_16x16x32_bf16 v[68:71], v[214:217], v[206:209], v[68:71]
	v_mfma_f32_16x16x32_bf16 v[64:67], v[230:233], v[206:209], v[64:67]
	s_setprio 0
	v_readfirstlane_b32 s9, v153
	v_lshl_add_u64 v[222:223], v[222:223], 0, s[54:55]
	s_mov_b32 m0, s9
	v_readfirstlane_b32 s9, v154
	ds_read_b128 v[176:179], v144 offset:49152
	ds_read_b128 v[182:185], v144 offset:50176
	ds_read_b128 v[186:189], v144 offset:51200
	ds_read_b128 v[190:193], v144 offset:52224
	ds_read_b128 v[194:197], v144 offset:53248
	ds_read_b128 v[198:201], v144 offset:54272
	ds_read_b128 v[202:205], v144 offset:55296
	ds_read_b128 v[206:209], v144 offset:56320
	global_load_lds_dwordx4 v[222:223], off
	v_lshl_add_u64 v[222:223], v[226:227], 0, s[54:55]
	s_mov_b32 m0, s9
	s_nop 0
	global_load_lds_dwordx4 v[222:223], off
	s_waitcnt vmcnt(10)
	s_barrier
	s_waitcnt lgkmcnt(0)
	s_setprio 1
	s_waitcnt lgkmcnt(0)
	v_mfma_f32_16x16x32_bf16 v[60:63], v[160:163], v[176:179], v[60:63]
	v_mfma_f32_16x16x32_bf16 v[56:59], v[168:171], v[176:179], v[56:59]
	v_mfma_f32_16x16x32_bf16 v[52:55], v[160:163], v[186:189], v[52:55]
	v_mfma_f32_16x16x32_bf16 v[48:51], v[168:171], v[186:189], v[48:51]
	v_mfma_f32_16x16x32_bf16 v[44:47], v[160:163], v[194:197], v[44:47]
	v_mfma_f32_16x16x32_bf16 v[40:43], v[168:171], v[194:197], v[40:43]
	v_mfma_f32_16x16x32_bf16 v[36:39], v[160:163], v[202:205], v[36:39]
	v_mfma_f32_16x16x32_bf16 v[32:35], v[168:171], v[202:205], v[32:35]
	v_mfma_f32_16x16x32_bf16 v[60:63], v[164:167], v[182:185], v[60:63]
	v_mfma_f32_16x16x32_bf16 v[56:59], v[172:175], v[182:185], v[56:59]
	v_mfma_f32_16x16x32_bf16 v[52:55], v[164:167], v[190:193], v[52:55]
	v_mfma_f32_16x16x32_bf16 v[48:51], v[172:175], v[190:193], v[48:51]
	v_mfma_f32_16x16x32_bf16 v[44:47], v[164:167], v[198:201], v[44:47]
	v_mfma_f32_16x16x32_bf16 v[40:43], v[172:175], v[198:201], v[40:43]
	s_setprio 2
	s_barrier
	v_mfma_f32_16x16x32_bf16 v[36:39], v[164:167], v[206:209], v[36:39]
	v_mfma_f32_16x16x32_bf16 v[32:35], v[172:175], v[206:209], v[32:35]
	s_setprio 0
	v_readfirstlane_b32 s9, v155
	v_lshl_add_u64 v[160:161], v[238:239], 0, s[92:93]
	s_mov_b32 m0, s9
	v_readfirstlane_b32 s9, v156
	global_load_lds_dwordx4 v[160:161], off
	v_lshl_add_u64 v[160:161], v[240:241], 0, s[92:93]
	s_mov_b32 m0, s9
	s_nop 0
	global_load_lds_dwordx4 v[160:161], off
	ds_read_b128 v[160:163], v147
	ds_read_b128 v[164:167], v147 offset:1024
	ds_read_b128 v[168:171], v147 offset:2048
	ds_read_b128 v[172:175], v147 offset:3072
	s_waitcnt vmcnt(6)
	s_barrier
	s_setprio 1
	v_mfma_f32_16x16x32_bf16 v[28:31], v[210:213], v[176:179], v[28:31]
	v_mfma_f32_16x16x32_bf16 v[24:27], v[218:221], v[176:179], v[24:27]
	v_mfma_f32_16x16x32_bf16 v[20:23], v[210:213], v[186:189], v[20:23]
	v_mfma_f32_16x16x32_bf16 v[16:19], v[218:221], v[186:189], v[16:19]
	v_mfma_f32_16x16x32_bf16 v[12:15], v[210:213], v[194:197], v[12:15]
	v_mfma_f32_16x16x32_bf16 v[8:11], v[218:221], v[194:197], v[8:11]
	v_mfma_f32_16x16x32_bf16 v[4:7], v[210:213], v[202:205], v[4:7]
	v_mfma_f32_16x16x32_bf16 v[0:3], v[218:221], v[202:205], v[0:3]
	v_mfma_f32_16x16x32_bf16 v[28:31], v[214:217], v[182:185], v[28:31]
	v_mfma_f32_16x16x32_bf16 v[24:27], v[230:233], v[182:185], v[24:27]
	v_mfma_f32_16x16x32_bf16 v[20:23], v[214:217], v[190:193], v[20:23]
	v_mfma_f32_16x16x32_bf16 v[16:19], v[230:233], v[190:193], v[16:19]
	v_mfma_f32_16x16x32_bf16 v[12:15], v[214:217], v[198:201], v[12:15]
	v_mfma_f32_16x16x32_bf16 v[8:11], v[230:233], v[198:201], v[8:11]
	s_setprio 2
	s_barrier
	v_mfma_f32_16x16x32_bf16 v[4:7], v[214:217], v[206:209], v[4:7]
	v_mfma_f32_16x16x32_bf16 v[0:3], v[230:233], v[206:209], v[0:3]
	s_setprio 0
	s_add_i32 s8, s8, 2
	v_lshl_add_u64 v[130:131], v[130:131], 0, s[90:91]
	v_lshl_add_u64 v[132:133], v[132:133], 0, s[90:91]
	v_lshl_add_u64 v[134:135], v[134:135], 0, s[90:91]
	v_lshl_add_u64 v[136:137], v[136:137], 0, s[90:91]
	v_lshl_add_u64 v[138:139], v[138:139], 0, s[90:91]
	s_cmpk_lt_u32 s8, 0x54
	v_lshl_add_u64 v[140:141], v[140:141], 0, s[90:91]
	s_cbranch_scc1 .LBB0_2622
	s_waitcnt lgkmcnt(0)
	s_add_u32 s6, s6, 0x2b80
	s_addc_u32 s7, s7, 0
	v_readfirstlane_b32 s8, v157
	v_lshl_add_u64 v[190:191], s[6:7], 0, v[180:181]
	s_mov_b32 m0, s8
	v_lshl_add_u64 v[128:129], s[6:7], 0, v[128:129]
	v_readfirstlane_b32 s6, v158
	ds_read_b128 v[130:133], v147
	ds_read_b128 v[134:137], v147 offset:1024
	ds_read_b128 v[138:141], v147 offset:2048
	ds_read_b128 v[148:151], v147 offset:3072
	ds_read_b128 v[152:155], v144
	ds_read_b128 v[160:163], v144 offset:1024
	ds_read_b128 v[164:167], v144 offset:2048
	ds_read_b128 v[168:171], v144 offset:3072
	ds_read_b128 v[172:175], v144 offset:4096
	ds_read_b128 v[176:179], v144 offset:5120
	ds_read_b128 v[182:185], v144 offset:6144
	ds_read_b128 v[186:189], v144 offset:7168
	global_load_lds_dwordx4 v[190:191], off
	s_mov_b32 m0, s6
	s_nop 0
	global_load_lds_dwordx4 v[128:129], off
	s_barrier
	s_waitcnt lgkmcnt(0)
	s_setprio 1
	s_waitcnt lgkmcnt(0)
	v_mfma_f32_16x16x32_bf16 v[124:127], v[130:133], v[152:155], v[124:127]
	v_mfma_f32_16x16x32_bf16 v[120:123], v[138:141], v[152:155], v[120:123]
	v_mfma_f32_16x16x32_bf16 v[116:119], v[130:133], v[164:167], v[116:119]
	v_mfma_f32_16x16x32_bf16 v[112:115], v[138:141], v[164:167], v[112:115]
	v_mfma_f32_16x16x32_bf16 v[108:111], v[130:133], v[172:175], v[108:111]
	v_mfma_f32_16x16x32_bf16 v[104:107], v[138:141], v[172:175], v[104:107]
	v_mfma_f32_16x16x32_bf16 v[100:103], v[130:133], v[182:185], v[100:103]
	v_mfma_f32_16x16x32_bf16 v[96:99], v[138:141], v[182:185], v[96:99]
	v_mfma_f32_16x16x32_bf16 v[124:127], v[134:137], v[160:163], v[124:127]
	v_mfma_f32_16x16x32_bf16 v[120:123], v[148:151], v[160:163], v[120:123]
	v_mfma_f32_16x16x32_bf16 v[116:119], v[134:137], v[168:171], v[116:119]
	v_mfma_f32_16x16x32_bf16 v[112:115], v[148:151], v[168:171], v[112:115]
	v_mfma_f32_16x16x32_bf16 v[108:111], v[134:137], v[176:179], v[108:111]
	v_mfma_f32_16x16x32_bf16 v[104:107], v[148:151], v[176:179], v[104:107]
	s_setprio 2
	s_barrier
; #define LDA(dst, b, h) for (int m = 0; m < 4; ++m) for (int k = 0; k < 2; ++k) \
;     dst[m][k] = *reinterpret_cast<const bf16x8*>(a_rd + ((b) * 2 + (h)) * (HT * 2) + m * 2048 + k * 1024)
; #define LDB(dst, b, h) for (int n = 0; n < 2; ++n) for (int k = 0; k < 2; ++k) \
;     dst[n][k] = *reinterpret_cast<const bf16x8*>(b_rd + ((b) * 2 + (h)) * (HT * 2) + n * 2048 + k * 1024)
; #define MMA(ai, bj, At_, Bt_) do { __builtin_amdgcn_s_setprio(1); \
;     for (int m = 0; m < 4; ++m) for (int n = 0; n < 2; ++n) for (int k = 0; k < 2; ++k) \
;       acc[ai][bj][m][n] = __builtin_amdgcn_mfma_f32_16x16x32_bf16(Bt_[n][k], At_[m][k], acc[ai][bj][m][n], 0, 0, 0); \
;     __builtin_amdgcn_s_setprio(0); } while (0)
; #define WAIT_V(n) asm volatile("s_waitcnt vmcnt(" #n ")" ::: "memory")
; #define WAIT_L(n) asm volatile("s_waitcnt lgkmcnt(" #n ")" ::: "memory")
; #define BAR __builtin_amdgcn_s_barrier()
;     ...
;     BAR; WAIT_L(0); MMA(0, 0, At, B0); BAR;
;     LDB(B1, 0, 1); BAR; WAIT_L(0); MMA(0, 1, At, B1); BAR;
;     LDA(At, 0, 1); WAIT_V(4); BAR; WAIT_L(0); MMA(1, 0, At, B0); MMA(1, 1, At, B1); BAR; }
;   { LDB(B0, 1, 0); LDA(At, 1, 0); WAIT_V(2); BAR; WAIT_L(0); MMA(0, 0, At, B0); BAR;
	v_mfma_f32_16x16x32_bf16 v[100:103], v[134:137], v[186:189], v[100:103]
	v_mfma_f32_16x16x32_bf16 v[96:99], v[148:151], v[186:189], v[96:99]
	s_setprio 0
	ds_read_b128 v[156:159], v147 offset:16384
	ds_read_b128 v[190:193], v147 offset:17408
	ds_read_b128 v[194:197], v147 offset:18432
	ds_read_b128 v[198:201], v147 offset:19456
	s_barrier
	s_waitcnt lgkmcnt(0)
	s_setprio 1
	s_waitcnt lgkmcnt(0)
	v_mfma_f32_16x16x32_bf16 v[92:95], v[156:159], v[152:155], v[92:95]
	v_mfma_f32_16x16x32_bf16 v[88:91], v[194:197], v[152:155], v[88:91]
	v_mfma_f32_16x16x32_bf16 v[84:87], v[156:159], v[164:167], v[84:87]
	v_mfma_f32_16x16x32_bf16 v[80:83], v[194:197], v[164:167], v[80:83]
	v_mfma_f32_16x16x32_bf16 v[76:79], v[156:159], v[172:175], v[76:79]
	v_mfma_f32_16x16x32_bf16 v[72:75], v[194:197], v[172:175], v[72:75]
	v_mfma_f32_16x16x32_bf16 v[68:71], v[156:159], v[182:185], v[68:71]
	v_mfma_f32_16x16x32_bf16 v[64:67], v[194:197], v[182:185], v[64:67]
	v_mfma_f32_16x16x32_bf16 v[202:205], v[190:193], v[160:163], v[92:95]
	v_mfma_f32_16x16x32_bf16 v[152:155], v[198:201], v[160:163], v[88:91]
	v_mfma_f32_16x16x32_bf16 v[160:163], v[190:193], v[168:171], v[84:87]
	v_mfma_f32_16x16x32_bf16 v[164:167], v[198:201], v[168:171], v[80:83]
	v_mfma_f32_16x16x32_bf16 v[168:171], v[190:193], v[176:179], v[76:79]
	v_mfma_f32_16x16x32_bf16 v[172:175], v[198:201], v[176:179], v[72:75]
	s_setprio 2
	s_barrier
	v_mfma_f32_16x16x32_bf16 v[176:179], v[190:193], v[186:189], v[68:71]
	v_mfma_f32_16x16x32_bf16 v[182:185], v[198:201], v[186:189], v[64:67]
	s_setprio 0
	s_nop 0
	ds_read_b128 v[64:67], v144 offset:16384
	ds_read_b128 v[68:71], v144 offset:17408
	ds_read_b128 v[72:75], v144 offset:18432
	ds_read_b128 v[76:79], v144 offset:19456
	ds_read_b128 v[80:83], v144 offset:20480
	ds_read_b128 v[84:87], v144 offset:21504
	ds_read_b128 v[88:91], v144 offset:22528
	ds_read_b128 v[92:95], v144 offset:23552
	s_waitcnt vmcnt(4)
	s_barrier
	s_waitcnt lgkmcnt(0)
	s_setprio 1
	s_waitcnt lgkmcnt(0)
	v_mfma_f32_16x16x32_bf16 v[60:63], v[130:133], v[64:67], v[60:63]
	v_mfma_f32_16x16x32_bf16 v[56:59], v[138:141], v[64:67], v[56:59]
	v_mfma_f32_16x16x32_bf16 v[52:55], v[130:133], v[72:75], v[52:55]
	v_mfma_f32_16x16x32_bf16 v[48:51], v[138:141], v[72:75], v[48:51]
	v_mfma_f32_16x16x32_bf16 v[44:47], v[130:133], v[80:83], v[44:47]
	v_mfma_f32_16x16x32_bf16 v[40:43], v[138:141], v[80:83], v[40:43]
	v_mfma_f32_16x16x32_bf16 v[36:39], v[130:133], v[88:91], v[36:39]
	v_mfma_f32_16x16x32_bf16 v[32:35], v[138:141], v[88:91], v[32:35]
	v_mfma_f32_16x16x32_bf16 v[60:63], v[134:137], v[68:71], v[60:63]
	v_mfma_f32_16x16x32_bf16 v[56:59], v[148:151], v[68:71], v[56:59]
	v_mfma_f32_16x16x32_bf16 v[52:55], v[134:137], v[76:79], v[52:55]
	v_mfma_f32_16x16x32_bf16 v[48:51], v[148:151], v[76:79], v[48:51]
	v_mfma_f32_16x16x32_bf16 v[44:47], v[134:137], v[84:87], v[44:47]
	v_mfma_f32_16x16x32_bf16 v[40:43], v[148:151], v[84:87], v[40:43]
	v_mfma_f32_16x16x32_bf16 v[36:39], v[134:137], v[92:95], v[36:39]
	v_mfma_f32_16x16x32_bf16 v[32:35], v[148:151], v[92:95], v[32:35]
	s_setprio 0
	s_setprio 1
	v_mfma_f32_16x16x32_bf16 v[28:31], v[156:159], v[64:67], v[28:31]
	v_mfma_f32_16x16x32_bf16 v[24:27], v[194:197], v[64:67], v[24:27]
	v_mfma_f32_16x16x32_bf16 v[20:23], v[156:159], v[72:75], v[20:23]
	v_mfma_f32_16x16x32_bf16 v[16:19], v[194:197], v[72:75], v[16:19]
	v_mfma_f32_16x16x32_bf16 v[12:15], v[156:159], v[80:83], v[12:15]
	v_mfma_f32_16x16x32_bf16 v[8:11], v[194:197], v[80:83], v[8:11]
	v_mfma_f32_16x16x32_bf16 v[4:7], v[156:159], v[88:91], v[4:7]
	v_mfma_f32_16x16x32_bf16 v[0:3], v[194:197], v[88:91], v[0:3]
	v_mfma_f32_16x16x32_bf16 v[128:131], v[190:193], v[68:71], v[28:31]
	v_mfma_f32_16x16x32_bf16 v[132:135], v[198:201], v[68:71], v[24:27]
	v_mfma_f32_16x16x32_bf16 v[136:139], v[190:193], v[76:79], v[20:23]
	v_mfma_f32_16x16x32_bf16 v[148:151], v[198:201], v[76:79], v[16:19]
	v_mfma_f32_16x16x32_bf16 v[186:189], v[190:193], v[84:87], v[12:15]
	v_mfma_f32_16x16x32_bf16 v[206:209], v[198:201], v[84:87], v[8:11]
	s_setprio 2
	s_barrier
	v_mfma_f32_16x16x32_bf16 v[156:159], v[190:193], v[92:95], v[4:7]
	v_mfma_f32_16x16x32_bf16 v[190:193], v[198:201], v[92:95], v[0:3]
	s_setprio 0
	ds_read_b128 v[24:27], v147 offset:32768
	ds_read_b128 v[28:31], v147 offset:33792
	ds_read_b128 v[194:197], v147 offset:34816
	ds_read_b128 v[198:201], v147 offset:35840
	ds_read_b128 v[0:3], v144 offset:32768
	ds_read_b128 v[4:7], v144 offset:33792
	ds_read_b128 v[8:11], v144 offset:34816
	ds_read_b128 v[12:15], v144 offset:35840
	ds_read_b128 v[16:19], v144 offset:36864
	ds_read_b128 v[20:23], v144 offset:37888
	ds_read_b128 v[210:213], v144 offset:38912
	ds_read_b128 v[214:217], v144 offset:39936
	s_waitcnt vmcnt(2)
	s_barrier
; #define LDA(dst, b, h) for (int m = 0; m < 4; ++m) for (int k = 0; k < 2; ++k) \
;     dst[m][k] = *reinterpret_cast<const bf16x8*>(a_rd + ((b) * 2 + (h)) * (HT * 2) + m * 2048 + k * 1024)
; #define LDB(dst, b, h) for (int n = 0; n < 2; ++n) for (int k = 0; k < 2; ++k) \
;     dst[n][k] = *reinterpret_cast<const bf16x8*>(b_rd + ((b) * 2 + (h)) * (HT * 2) + n * 2048 + k * 1024)
; #define MMA(ai, bj, At_, Bt_) do { __builtin_amdgcn_s_setprio(1); \
;     for (int m = 0; m < 4; ++m) for (int n = 0; n < 2; ++n) for (int k = 0; k < 2; ++k) \
;       acc[ai][bj][m][n] = __builtin_amdgcn_mfma_f32_16x16x32_bf16(Bt_[n][k], At_[m][k], acc[ai][bj][m][n], 0, 0, 0); \
;     __builtin_amdgcn_s_setprio(0); } while (0)
; #define WAIT_V(n) asm volatile("s_waitcnt vmcnt(" #n ")" ::: "memory")
; #define WAIT_L(n) asm volatile("s_waitcnt lgkmcnt(" #n ")" ::: "memory")
; #define BAR __builtin_amdgcn_s_barrier()
;     ...
;   { LDB(B0, 1, 0); LDA(At, 1, 0); WAIT_V(2); BAR; WAIT_L(0); MMA(0, 0, At, B0); BAR;
;     LDB(B1, 1, 1); WAIT_V(0); BAR; WAIT_L(0); MMA(0, 1, At, B1); BAR;
;     LDA(At, 1, 1); BAR; WAIT_L(0); MMA(1, 0, At, B0); MMA(1, 1, At, B1); BAR; }
;   if (wr == 0) BAR;
	s_waitcnt lgkmcnt(0)
	s_setprio 1
	s_waitcnt lgkmcnt(0)
	v_mfma_f32_16x16x32_bf16 v[64:67], v[24:27], v[0:3], v[124:127]
	v_mfma_f32_16x16x32_bf16 v[68:71], v[194:197], v[0:3], v[120:123]
	v_mfma_f32_16x16x32_bf16 v[72:75], v[24:27], v[8:11], v[116:119]
	v_mfma_f32_16x16x32_bf16 v[76:79], v[194:197], v[8:11], v[112:115]
	v_mfma_f32_16x16x32_bf16 v[80:83], v[24:27], v[16:19], v[108:111]
	v_mfma_f32_16x16x32_bf16 v[84:87], v[194:197], v[16:19], v[104:107]
	v_mfma_f32_16x16x32_bf16 v[88:91], v[24:27], v[210:213], v[100:103]
	v_mfma_f32_16x16x32_bf16 v[92:95], v[194:197], v[210:213], v[96:99]
	v_mfma_f32_16x16x32_bf16 v[64:67], v[28:31], v[4:7], v[64:67]
	v_mfma_f32_16x16x32_bf16 v[68:71], v[198:201], v[4:7], v[68:71]
	v_mfma_f32_16x16x32_bf16 v[72:75], v[28:31], v[12:15], v[72:75]
	v_mfma_f32_16x16x32_bf16 v[76:79], v[198:201], v[12:15], v[76:79]
	v_mfma_f32_16x16x32_bf16 v[80:83], v[28:31], v[20:23], v[80:83]
	v_mfma_f32_16x16x32_bf16 v[84:87], v[198:201], v[20:23], v[84:87]
	s_setprio 2
	s_barrier
	v_mfma_f32_16x16x32_bf16 v[88:91], v[28:31], v[214:217], v[88:91]
	v_mfma_f32_16x16x32_bf16 v[92:95], v[198:201], v[214:217], v[92:95]
	s_setprio 0
	ds_read_b128 v[218:221], v147 offset:49152
	ds_read_b128 v[230:233], v147 offset:50176
	ds_read_b128 v[234:237], v147 offset:51200
	ds_read_b128 v[238:241], v147 offset:52224
	s_waitcnt vmcnt(0)
	s_barrier
	s_waitcnt lgkmcnt(0)
	s_setprio 1
	s_waitcnt lgkmcnt(0)
	v_mfma_f32_16x16x32_bf16 v[96:99], v[218:221], v[0:3], v[202:205]
	v_mfma_f32_16x16x32_bf16 v[0:3], v[234:237], v[0:3], v[152:155]
	v_mfma_f32_16x16x32_bf16 v[100:103], v[238:241], v[4:7], v[0:3]
	v_mfma_f32_16x16x32_bf16 v[0:3], v[218:221], v[8:11], v[160:163]
	v_mfma_f32_16x16x32_bf16 v[104:107], v[230:233], v[12:15], v[0:3]
	v_mfma_f32_16x16x32_bf16 v[0:3], v[234:237], v[8:11], v[164:167]
	v_mfma_f32_16x16x32_bf16 v[108:111], v[238:241], v[12:15], v[0:3]
	v_mfma_f32_16x16x32_bf16 v[0:3], v[218:221], v[16:19], v[168:171]
	v_mfma_f32_16x16x32_bf16 v[112:115], v[230:233], v[20:23], v[0:3]
	v_mfma_f32_16x16x32_bf16 v[0:3], v[234:237], v[16:19], v[172:175]
	v_mfma_f32_16x16x32_bf16 v[116:119], v[238:241], v[20:23], v[0:3]
	v_mfma_f32_16x16x32_bf16 v[0:3], v[218:221], v[210:213], v[176:179]
	v_mfma_f32_16x16x32_bf16 v[120:123], v[230:233], v[214:217], v[0:3]
	v_mfma_f32_16x16x32_bf16 v[0:3], v[234:237], v[210:213], v[182:185]
	s_setprio 2
	s_barrier
	v_mfma_f32_16x16x32_bf16 v[96:99], v[230:233], v[4:7], v[96:99]
	v_mfma_f32_16x16x32_bf16 v[124:127], v[238:241], v[214:217], v[0:3]
	s_setprio 0
	ds_read_b128 v[152:155], v144 offset:49152
	ds_read_b128 v[160:163], v144 offset:50176
	ds_read_b128 v[164:167], v144 offset:51200
	ds_read_b128 v[168:171], v144 offset:52224
	ds_read_b128 v[172:175], v144 offset:53248
	ds_read_b128 v[176:179], v144 offset:54272
	ds_read_b128 v[182:185], v144 offset:55296
	ds_read_b128 v[144:147], v144 offset:56320
	s_barrier
	s_waitcnt lgkmcnt(0)
	s_setprio 1
	s_waitcnt lgkmcnt(0)
	v_mfma_f32_16x16x32_bf16 v[0:3], v[24:27], v[152:155], v[60:63]
	v_mfma_f32_16x16x32_bf16 v[8:11], v[24:27], v[164:167], v[52:55]
	v_mfma_f32_16x16x32_bf16 v[16:19], v[24:27], v[172:175], v[44:47]
	v_mfma_f32_16x16x32_bf16 v[24:27], v[24:27], v[182:185], v[36:39]
	v_mfma_f32_16x16x32_bf16 v[0:3], v[28:31], v[160:163], v[0:3]
	v_mfma_f32_16x16x32_bf16 v[4:7], v[194:197], v[152:155], v[56:59]
	v_mfma_f32_16x16x32_bf16 v[8:11], v[28:31], v[168:171], v[8:11]
	v_mfma_f32_16x16x32_bf16 v[12:15], v[194:197], v[164:167], v[48:51]
	v_mfma_f32_16x16x32_bf16 v[16:19], v[28:31], v[176:179], v[16:19]
	v_mfma_f32_16x16x32_bf16 v[20:23], v[194:197], v[172:175], v[40:43]
	v_mfma_f32_16x16x32_bf16 v[24:27], v[28:31], v[144:147], v[24:27]
	v_mfma_f32_16x16x32_bf16 v[28:31], v[194:197], v[182:185], v[32:35]
	v_mfma_f32_16x16x32_bf16 v[4:7], v[198:201], v[160:163], v[4:7]
	v_mfma_f32_16x16x32_bf16 v[12:15], v[198:201], v[168:171], v[12:15]
	v_mfma_f32_16x16x32_bf16 v[20:23], v[198:201], v[176:179], v[20:23]
	v_mfma_f32_16x16x32_bf16 v[28:31], v[198:201], v[144:147], v[28:31]
	s_setprio 0
	s_setprio 1
	v_mfma_f32_16x16x32_bf16 v[32:35], v[218:221], v[152:155], v[128:131]
	v_mfma_f32_16x16x32_bf16 v[36:39], v[234:237], v[152:155], v[132:135]
	v_mfma_f32_16x16x32_bf16 v[40:43], v[218:221], v[164:167], v[136:139]
	v_mfma_f32_16x16x32_bf16 v[44:47], v[234:237], v[164:167], v[148:151]
	v_mfma_f32_16x16x32_bf16 v[48:51], v[218:221], v[172:175], v[186:189]
	v_mfma_f32_16x16x32_bf16 v[52:55], v[234:237], v[172:175], v[206:209]
	v_mfma_f32_16x16x32_bf16 v[56:59], v[218:221], v[182:185], v[156:159]
	v_mfma_f32_16x16x32_bf16 v[60:63], v[234:237], v[182:185], v[190:193]
	v_mfma_f32_16x16x32_bf16 v[32:35], v[230:233], v[160:163], v[32:35]
	v_mfma_f32_16x16x32_bf16 v[36:39], v[238:241], v[160:163], v[36:39]
	v_mfma_f32_16x16x32_bf16 v[40:43], v[230:233], v[168:171], v[40:43]
	v_mfma_f32_16x16x32_bf16 v[44:47], v[238:241], v[168:171], v[44:47]
	v_mfma_f32_16x16x32_bf16 v[48:51], v[230:233], v[176:179], v[48:51]
	v_mfma_f32_16x16x32_bf16 v[52:55], v[238:241], v[176:179], v[52:55]
	s_setprio 2
	s_barrier
	v_mfma_f32_16x16x32_bf16 v[56:59], v[230:233], v[144:147], v[56:59]
	v_mfma_f32_16x16x32_bf16 v[60:63], v[238:241], v[144:147], v[60:63]
	s_setprio 0
	v_cmp_gt_u32_e32 vcc, s60, v142
	s_and_saveexec_b64 s[6:7], vcc
	s_cbranch_execz .LBB0_2625
	s_barrier
